# P3 SW-attention rewrite + scan XCD remap, P10 cmp/cndmask hazard-free scheduling, P7 rebalance + sample-wave rewrite, P11 v-pass 16-slot gather
# speedup vs baseline: 1.0579x; 1.0448x over previous
; #define AS1 __attribute__((address_space(1)))
; DI void scan_load(const Params& p, int bh, int s, int n, int j, int lane, ScanOps& o) {
;   n = n > 127 ? 127 : n;
;   const char AS1* base = (const char AS1*)p.dnops + (size_t)(bh * 128 + n) * DN_ITEM;
;   gb8p negW = (gb8p)base;
;   gb8p qg = (gb8p)(base + 16384);
;   gb8p kdT = (gb8p)(base + 32768);
;   gb8p aqk = (gb8p)(base + 49152);
;   const u32x2 AS1* u0 = (const u32x2 AS1*)(base + 57344);
; #pragma unroll
;   for (int ks = 0; ks < 4; ++ks) o.nW[ks] = negW[(j * 4 + ks) * 64 + lane];
; #pragma unroll
;   for (int ks = 0; ks < 4; ++ks) o.qg[ks] = qg[(j * 4 + ks) * 64 + lane];
; #pragma unroll
;   for (int k2 = 0; k2 < 2; ++k2) o.aq[k2] = aqk[(j * 2 + k2) * 64 + lane];
; #pragma unroll
;   for (int mm = 0; mm < 2; ++mm)
; #pragma unroll
;     for (int k2 = 0; k2 < 2; ++k2) o.kd[mm * 2 + k2] = kdT[((2 * j + mm) * 2 + k2) * 64 + lane];
;   o.u0 = u0[(s * 4 + j) * 64 + lane];
;   o.dl = ((const float AS1*)p.dl)[bh * 128 + n];
; }
; DI void dn_scan_block(const Params& p, int item, char* smem) {
;   const int lane = threadIdx.x & 63, j = threadIdx.x >> 6, r = lane & 15, kg = lane >> 4;
;   const int bh = item >> 3, s = item & 7, b = bh >> 2, h = bh & 3;
;   bf16x8* sSb = (bf16x8*)smem;
;   u32x2* sUb = (u32x2*)(smem + 4096);
;   f32x4 S0 = (f32x4){0.f, 0.f, 0.f, 0.f}, S1 = (f32x4){0.f, 0.f, 0.f, 0.f};
;   __syncthreads();
;   sSb[j * 64 + lane] = pack8(S0, S1);
;   ScanOps A, B;
;   scan_load(p, bh, s, 0, j, lane, A);
;   scan_load(p, bh, s, 1, j, lane, B);
;   __syncthreads();
.LBB0_620:
	v_lshlrev_b32_e32 v203, 8, v174
	s_andn2_b64 vcc, exec, s[0:1]
	v_lshlrev_b32_e32 v197, 4, v191
	s_cbranch_vccnz .LBB0_624
	s_and_b32 s98, s86, 7
	s_lshr_b32 s99, s86, 3
	s_lshl_b32 s98, s98, 1
	s_lshr_b32 s100, s99, 3
	s_add_i32 s98, s98, s100
	s_and_b32 s99, s99, 7
	s_lshl_b32 s98, s98, 3
	s_or_b32 s98, s98, s99
	v_mov_b32_e32 v141, 0x10180
	s_waitcnt lgkmcnt(0)
	s_barrier
	ds_read_b64 v[8:9], v141
	s_lshl_b32 s16, s98, 4
	s_and_b32 s18, s16, 0x780
	s_mov_b32 s1, 0
	s_mul_i32 s2, s18, 0x12000
	s_mov_b32 s3, s1
	v_mov_b32_e32 v145, 0x10148
	v_or_b32_e32 v120, v203, v191
	ds_read_b64 v[24:25], v145
	s_waitcnt lgkmcnt(0)
	v_lshl_add_u64 v[26:27], v[8:9], 0, s[2:3]
	v_lshlrev_b32_e32 v44, 4, v120
	v_readfirstlane_b32 s8, v26
	v_readfirstlane_b32 s9, v27
	v_mov_b32_e32 v100, 0
	v_lshl_or_b32 v128, v174, 7, v191
	v_lshl_add_u32 v0, s99, 8, v198
	s_nop 1
	global_load_dwordx4 v[112:115], v44, s[8:9]
	global_load_dwordx4 v[104:107], v44, s[8:9] offset:1024
	global_load_dwordx4 v[96:99], v44, s[8:9] offset:2048
	global_load_dwordx4 v[32:35], v44, s[8:9] offset:3072
	s_mov_b64 s[8:9], 0x4000
	v_or_b32_e32 v130, v0, v191
	v_lshl_add_u64 v[0:1], v[26:27], 0, s[8:9]
	v_lshlrev_b32_e32 v36, 4, v128
	v_mov_b32_e32 v37, v100
	v_readfirstlane_b32 s12, v0
	v_readfirstlane_b32 s13, v1
	v_lshl_add_u64 v[0:1], v[26:27], 0, v[36:37]
	s_mov_b32 s19, 0xc000
	s_mov_b64 s[2:3], 0x8000
	v_add_co_u32_e32 v12, vcc, s19, v0
	v_lshlrev_b32_e32 v102, 3, v130
	v_mov_b32_e32 v103, v100
	v_lshl_add_u64 v[4:5], v[26:27], 0, s[2:3]
	s_mov_b64 s[10:11], 0xc000
	v_addc_co_u32_e32 v13, vcc, 0, v1, vcc
	v_lshl_add_u64 v[26:27], v[26:27], 0, v[102:103]
	s_mov_b32 s20, 0xe000
	v_or_b32_e32 v124, 0x80, v120
	s_or_b32 s0, s18, 1
	v_lshl_add_u64 v[6:7], v[0:1], 0, s[10:11]
	v_readfirstlane_b32 s14, v4
	v_readfirstlane_b32 s15, v5
	v_add_co_u32_e32 v26, vcc, s20, v26
	s_mul_i32 s0, s0, 0x12000
	v_lshlrev_b32_e32 v46, 4, v124
	global_load_dwordx4 v[40:43], v[12:13], off
	global_load_dwordx4 v[0:3], v[6:7], off offset:1024
	global_load_dwordx4 v[16:19], v44, s[14:15]
	s_nop 0
	global_load_dwordx4 v[4:7], v44, s[14:15] offset:1024
	global_load_dwordx4 v[84:87], v46, s[12:13]
	global_load_dwordx4 v[20:23], v46, s[14:15]
	global_load_dwordx4 v[116:119], v44, s[12:13]
	global_load_dwordx4 v[12:15], v44, s[14:15] offset:3072
	v_addc_co_u32_e32 v27, vcc, 0, v27, vcc
	s_lshl_b32 s14, s18, 2
	global_load_dwordx2 v[168:169], v[26:27], off
	v_mov_b32_e32 v26, s14
	v_readfirstlane_b32 s14, v24
	v_readfirstlane_b32 s15, v25
	v_lshl_add_u64 v[8:9], v[8:9], 0, s[0:1]
	v_lshl_add_u64 v[24:25], v[8:9], 0, s[8:9]
	v_or_b32_e32 v122, 64, v120
	v_or_b32_e32 v126, 0xc0, v120
	v_lshlrev_b32_e32 v45, 4, v122
	global_load_dwordx2 v[164:165], v26, s[14:15]
	v_readfirstlane_b32 s14, v8
	v_readfirstlane_b32 s15, v9
	s_nop 4
	global_load_dwordx4 v[72:75], v44, s[14:15]
	global_load_dwordx4 v[56:59], v44, s[14:15] offset:1024
	global_load_dwordx4 v[48:51], v44, s[14:15] offset:2048
	global_load_dwordx4 v[28:31], v44, s[14:15] offset:3072
	v_readfirstlane_b32 s14, v24
	v_readfirstlane_b32 s15, v25
	v_lshl_add_u64 v[24:25], v[8:9], 0, v[36:37]
	v_lshl_add_u64 v[38:39], v[8:9], 0, s[2:3]
	v_lshl_add_u64 v[26:27], v[24:25], 0, s[10:11]
	v_add_co_u32_e32 v24, vcc, s19, v24
	v_lshlrev_b32_e32 v47, 4, v126
	global_load_dwordx4 v[108:111], v45, s[12:13]
	global_load_dwordx4 v[76:79], v45, s[14:15]
	global_load_dwordx4 v[88:91], v47, s[12:13]
	global_load_dwordx4 v[68:71], v47, s[14:15]
	v_addc_co_u32_e32 v25, vcc, 0, v25, vcc
	v_readfirstlane_b32 s12, v38
	v_readfirstlane_b32 s13, v39
	global_load_dwordx4 v[52:55], v[24:25], off
	s_nop 0
	global_load_dwordx4 v[24:27], v[26:27], off offset:1024
	s_nop 1
	global_load_dwordx4 v[60:63], v44, s[12:13]
	global_load_dwordx4 v[36:39], v44, s[12:13] offset:1024
	global_load_dwordx4 v[80:83], v46, s[14:15]
	global_load_dwordx4 v[64:67], v46, s[12:13]
	global_load_dwordx4 v[92:95], v44, s[14:15]
	s_nop 0
	global_load_dwordx4 v[44:47], v44, s[12:13] offset:3072
	v_lshl_add_u64 v[8:9], v[8:9], 0, v[102:103]
	v_add_co_u32_e32 v8, vcc, s20, v8
	s_movk_i32 s0, 0x1c0
	s_nop 0
	v_addc_co_u32_e32 v9, vcc, 0, v9, vcc
	global_load_dwordx2 v[166:167], v[8:9], off
	v_and_or_b32 v8, v178, s0, v191
	s_lshl_b32 s0, s98, 8
	v_lshlrev_b32_e32 v9, 3, v196
	s_and_b32 s0, s0, 0x6000
	v_lshl_or_b32 v147, v8, 4, v9
	v_or_b32_e32 v8, s0, v201
	s_lshl_b32 s0, s98, 5
	s_and_b32 s0, s0, 0x300
	s_lshl_b32 s13, s99, 5
	s_and_b32 s12, s16, 0x180
	s_lshl_b32 s21, s99, 4
	v_mov_b32_e32 v101, v100
	v_mov_b32_e32 v102, v100
	v_add_lshl_u32 v8, v8, v200, 10
	s_or_b32 s0, s0, s13
	v_lshl_add_u32 v151, v191, 4, v202
	s_or_b32 s22, s18, 3
	ds_write_b128 v149, v[100:103]
	v_add_u32_e32 v152, 0x10000, v8
	v_mov_b32_e32 v153, v100
	v_lshl_or_b32 v154, v134, 1, s0
	v_mov_b32_e32 v155, v100
	v_mov_b32_e32 v9, v100
	s_mov_b32 s0, -2
	s_mov_b32 s23, 0xffff0000
	s_movk_i32 s24, 0x7fff
	v_mov_b32_e32 v149, 0x101d0
	s_lshl_b32 s12, s12, 1
	s_mov_b32 s13, s1
	s_lshl_b32 s14, s21, 1
	s_mov_b32 s15, s1
	v_lshlrev_b32_e32 v156, 1, v134
	v_mov_b32_e32 v157, v100
	v_lshlrev_b32_e32 v198, 4, v120
	v_lshlrev_b32_e32 v201, 4, v122
	v_lshlrev_b32_e32 v202, 4, v124
	v_lshlrev_b32_e32 v204, 4, v126
	v_lshlrev_b32_e32 v158, 4, v128
	v_mov_b32_e32 v159, v100
	v_lshlrev_b32_e32 v160, 3, v130
	v_mov_b32_e32 v161, v100
	s_mov_b64 s[16:17], 0x20000
	v_mov_b32_e32 v120, v100
	v_mov_b32_e32 v121, v100
	v_mov_b32_e32 v122, v100
	v_mov_b32_e32 v123, v100
	s_waitcnt lgkmcnt(0)
	s_barrier
	s_waitcnt vmcnt(0)
	v_mov_b32_e32 v162, v165
; #define MFMA(a, b, c) __builtin_amdgcn_mfma_f32_16x16x32_bf16((a), (b), (c), 0, 0, 0)
; DI u16 f2bf(float x) { unsigned u = __float_as_uint(x); u += 0x7fffu + ((u >> 16) & 1u); return (u16)(u >> 16); }
; DI unsigned pack2(float a, float b) { return (unsigned)f2bf(a) | ((unsigned)f2bf(b) << 16); }
; DI float bflo(unsigned d) { return __uint_as_float(d << 16); }
; DI float bfhi(unsigned d) { return __uint_as_float(d & 0xffff0000u); }
; DI void scan_step(const Params& p, const ScanOps& ops, int n, int b, int h, int s, int j, int lane, f32x4& S0, f32x4& S1,
;                   bf16x8* sSb, u32x2* sUb) {
;   const int r = lane & 15, kg = lane >> 4;
;   bf16x8 sb[4];
; #pragma unroll
;   for (int ks = 0; ks < 4; ++ks) sb[ks] = sSb[ks * 64 + lane];
;   f32x4 u = (f32x4){bflo(ops.u0[0]), bfhi(ops.u0[0]), bflo(ops.u0[1]), bfhi(ops.u0[1])};
; #pragma unroll
;   for (int ks = 0; ks < 4; ++ks) u = MFMA(ops.nW[ks], sb[ks], u);
;   {
;     u32x2 t; t[0] = pack2(u[0], u[1]); t[1] = pack2(u[2], u[3]);
;     sUb[((j >> 1) * 64 + lane) * 2 + (j & 1)] = t;
;   }
;   __syncthreads();
;   bf16x8 ub[2];
; #pragma unroll
;   for (int k2 = 0; k2 < 2; ++k2) ub[k2] = *(const bf16x8*)&sUb[(k2 * 64 + lane) * 2];
;   f32x4 o = (f32x4){0.f, 0.f, 0.f, 0.f};
; #pragma unroll
;   for (int ks = 0; ks < 4; ++ks) o = MFMA(ops.qg[ks], sb[ks], o);
; #pragma unroll
;   for (int k2 = 0; k2 < 2; ++k2) o = MFMA(ops.aq[k2], ub[k2], o);
;   S0 = S0 * ops.dl; S1 = S1 * ops.dl;
; #pragma unroll
;   for (int k2 = 0; k2 < 2; ++k2) { S0 = MFMA(ops.kd[k2], ub[k2], S0); S1 = MFMA(ops.kd[2 + k2], ub[k2], S1); }
;   sSb[j * 64 + lane] = pack8(S0, S1);
; #pragma unroll
;   for (int jj = 0; jj < 4; ++jj) {
;     const size_t token = (size_t)b * SEQ + n * 64 + j * 16 + kg * 4 + jj;
;     G(p.odn)[token * 512 + h * 128 + s * 16 + r] = f2bf(o[jj]);
;   }
;   __syncthreads();
; }
.LBB0_622:
	ds_read_b128 v[206:209], v197
	ds_read_b128 v[210:213], v197 offset:1024
	ds_read_b128 v[128:131], v197 offset:2048
	ds_read_b128 v[124:127], v197 offset:3072
	s_waitcnt vmcnt(20)
	v_lshlrev_b32_e32 v214, 16, v168
	v_and_b32_e32 v215, 0xffff0000, v168
	v_lshlrev_b32_e32 v216, 16, v169
	v_and_b32_e32 v217, 0xffff0000, v169
	v_pk_mul_f32 v[102:103], v[102:103], v[164:165] op_sel_hi:[1,0]
	v_pk_mul_f32 v[100:101], v[100:101], v[164:165] op_sel_hi:[1,0]
	s_waitcnt lgkmcnt(3)
	v_mfma_f32_16x16x32_bf16 v[214:217], v[112:115], v[206:209], v[214:217]
	v_mul_f32_e64 v122, v122, v164
	v_mul_f32_e64 v123, v123, v164
	v_pk_mul_f32 v[120:121], v[120:121], v[164:165] op_sel_hi:[1,0]
	v_or_b32_e32 v112, 0x400, v8
	v_mfma_f32_16x16x32_bf16 v[206:209], v[116:119], v[206:209], 0
	v_mov_b32_e32 v113, v9
	v_or_b32_e32 v114, 0x800, v8
	v_mov_b32_e32 v115, v9
	s_waitcnt lgkmcnt(2)
	v_mfma_f32_16x16x32_bf16 v[214:217], v[104:107], v[210:213], v[214:217]
	v_or_b32_e32 v116, 0xc00, v8
	v_mov_b32_e32 v117, v9
	v_mfma_f32_16x16x32_bf16 v[108:111], v[108:111], v[210:213], v[206:209]
	s_waitcnt lgkmcnt(1)
	v_mfma_f32_16x16x32_bf16 v[96:99], v[96:99], v[128:131], v[214:217]
	s_add_i32 s25, s0, 2
	s_add_i32 s0, s0, 4
	s_min_u32 s0, s0, 0x7f
	v_mfma_f32_16x16x32_bf16 v[84:87], v[84:87], v[128:131], v[108:111]
	s_or_b32 s27, s0, s18
	s_min_u32 s26, s25, 0x7c
	s_mul_i32 s0, s27, 0x12000
	s_waitcnt lgkmcnt(0)
	v_mfma_f32_16x16x32_bf16 v[32:35], v[32:35], v[124:127], v[96:99]
	s_add_i32 s30, s22, s26
	s_add_i32 s26, s18, s26
	s_lshl_b32 s27, s27, 2
	v_mfma_f32_16x16x32_bf16 v[84:87], v[88:91], v[124:127], v[84:87]
	s_lshl_b32 s31, s26, 2
	s_nop 2
	v_bfe_u32 v88, v32, 16, 1
	v_bfe_u32 v90, v34, 16, 1
	v_bfe_u32 v89, v33, 16, 1
	v_bfe_u32 v91, v35, 16, 1
	v_add3_u32 v32, v32, v88, s24
	v_add3_u32 v34, v34, v90, s24
	v_add3_u32 v33, v33, v89, s24
	v_add3_u32 v35, v35, v91, s24
	v_lshrrev_b32_e32 v32, 16, v32
	v_lshrrev_b32_e32 v34, 16, v34
	v_and_or_b32 v32, v33, s23, v32
	v_and_or_b32 v33, v35, s23, v34
	ds_write_b64 v147, v[32:33] offset:4096
	s_waitcnt lgkmcnt(0)
	s_barrier
	ds_read_b128 v[32:35], v197 offset:4096
	ds_read_b128 v[88:91], v197 offset:5120
	s_waitcnt lgkmcnt(1)
	v_mfma_f32_16x16x32_bf16 v[16:19], v[16:19], v[32:35], v[100:103]
	v_or_b32_e32 v218, 0x400, v152
	v_mov_b32_e32 v219, v153
	v_or_b32_e32 v194, 0x800, v152
	v_mfma_f32_16x16x32_bf16 v[20:23], v[20:23], v[32:35], v[120:123]
	v_mov_b32_e32 v195, v153
	v_or_b32_e32 v128, 0xc00, v152
	v_mov_b32_e32 v129, v153
	v_mfma_f32_16x16x32_bf16 v[40:43], v[40:43], v[32:35], v[84:87]
	ds_read_b64 v[32:33], v149
	s_cmpk_lt_u32 s25, 0x7e
	s_waitcnt lgkmcnt(0)
	v_lshl_add_u64 v[34:35], v[32:33], 0, s[12:13]
	v_mfma_f32_16x16x32_bf16 v[100:103], v[4:7], v[88:91], v[16:19]
	v_lshl_add_u64 v[34:35], v[34:35], 0, s[14:15]
	v_lshl_add_u64 v[34:35], v[34:35], 0, v[156:157]
	v_lshl_add_u64 v[4:5], v[34:35], 0, v[112:113]
	v_mfma_f32_16x16x32_bf16 v[120:123], v[12:15], v[88:91], v[20:23]
	v_lshl_add_u64 v[6:7], v[34:35], 0, v[114:115]
	s_nop 2
	v_bfe_u32 v12, v100, 16, 1
	v_bfe_u32 v14, v102, 16, 1
	v_mfma_f32_16x16x32_bf16 v[0:3], v[0:3], v[88:91], v[40:43]
	v_lshl_add_u64 v[16:17], v[34:35], 0, v[116:117]
	v_bfe_u32 v18, v120, 16, 1
	v_bfe_u32 v20, v122, 16, 1
	v_bfe_u32 v13, v101, 16, 1
	v_bfe_u32 v15, v103, 16, 1
	v_bfe_u32 v19, v121, 16, 1
	v_bfe_u32 v21, v123, 16, 1
	s_nop 0
	v_bfe_u32 v22, v0, 16, 1
	v_bfe_u32 v23, v1, 16, 1
	v_bfe_u32 v34, v2, 16, 1
	v_bfe_u32 v35, v3, 16, 1
	v_add3_u32 v12, v100, v12, s24
	v_add3_u32 v14, v102, v14, s24
	v_add3_u32 v18, v120, v18, s24
	v_add3_u32 v20, v122, v20, s24
	v_lshl_add_u64 v[32:33], v[32:33], 0, v[154:155]
	v_add3_u32 v13, v101, v13, s24
	v_add3_u32 v15, v103, v15, s24
	v_add3_u32 v19, v121, v19, s24
	v_add3_u32 v21, v123, v21, s24
	v_add3_u32 v22, v0, v22, s24
	v_add3_u32 v23, v1, v23, s24
	v_add3_u32 v34, v2, v34, s24
	v_add3_u32 v35, v3, v35, s24
	v_lshrrev_b32_e32 v0, 16, v12
	v_lshrrev_b32_e32 v1, 16, v14
	v_lshrrev_b32_e32 v2, 16, v18
	v_lshrrev_b32_e32 v3, 16, v20
	v_lshl_add_u64 v[32:33], v[32:33], 0, v[8:9]
	v_and_or_b32 v0, v13, s23, v0
	v_and_or_b32 v1, v15, s23, v1
	v_and_or_b32 v2, v19, s23, v2
	v_and_or_b32 v3, v21, s23, v3
	ds_write_b128 v151, v[0:3]
	global_store_short_d16_hi v[32:33], v22, off
	global_store_short_d16_hi v[4:5], v23, off
	global_store_short_d16_hi v[6:7], v34, off
	global_store_short_d16_hi v[16:17], v35, off
	s_waitcnt lgkmcnt(0)
	s_barrier
; #define MFMA(a, b, c) __builtin_amdgcn_mfma_f32_16x16x32_bf16((a), (b), (c), 0, 0, 0)
; #define AS1 __attribute__((address_space(1)))
; DI float bflo(unsigned d) { return __uint_as_float(d << 16); }
; DI float bfhi(unsigned d) { return __uint_as_float(d & 0xffff0000u); }
; DI void scan_load(const Params& p, int bh, int s, int n, int j, int lane, ScanOps& o) {
;   n = n > 127 ? 127 : n;
;   const char AS1* base = (const char AS1*)p.dnops + (size_t)(bh * 128 + n) * DN_ITEM;
;   gb8p negW = (gb8p)base;
;   gb8p qg = (gb8p)(base + 16384);
;   gb8p kdT = (gb8p)(base + 32768);
;   gb8p aqk = (gb8p)(base + 49152);
;   const u32x2 AS1* u0 = (const u32x2 AS1*)(base + 57344);
; #pragma unroll
;   for (int ks = 0; ks < 4; ++ks) o.nW[ks] = negW[(j * 4 + ks) * 64 + lane];
; #pragma unroll
;   for (int ks = 0; ks < 4; ++ks) o.qg[ks] = qg[(j * 4 + ks) * 64 + lane];
; #pragma unroll
;   for (int k2 = 0; k2 < 2; ++k2) o.aq[k2] = aqk[(j * 2 + k2) * 64 + lane];
; #pragma unroll
;   for (int mm = 0; mm < 2; ++mm)
; #pragma unroll
;     for (int k2 = 0; k2 < 2; ++k2) o.kd[mm * 2 + k2] = kdT[((2 * j + mm) * 2 + k2) * 64 + lane];
;   o.u0 = u0[(s * 4 + j) * 64 + lane];
;   o.dl = ((const float AS1*)p.dl)[bh * 128 + n];
; }
; DI void scan_step(const Params& p, const ScanOps& ops, int n, int b, int h, int s, int j, int lane, f32x4& S0, f32x4& S1,
;                   bf16x8* sSb, u32x2* sUb) {
;   const int r = lane & 15, kg = lane >> 4;
;   bf16x8 sb[4];
; #pragma unroll
;   for (int ks = 0; ks < 4; ++ks) sb[ks] = sSb[ks * 64 + lane];
;   f32x4 u = (f32x4){bflo(ops.u0[0]), bfhi(ops.u0[0]), bflo(ops.u0[1]), bfhi(ops.u0[1])};
; #pragma unroll
;   for (int ks = 0; ks < 4; ++ks) u = MFMA(ops.nW[ks], sb[ks], u);
	ds_read_b128 v[0:3], v197
	ds_read_b64 v[20:21], v141
	ds_read_b64 v[22:23], v145
	ds_read_b128 v[4:7], v197 offset:1024
	ds_read_b128 v[12:15], v197 offset:2048
	ds_read_b128 v[124:127], v197 offset:3072
	s_waitcnt vmcnt(4)
	v_lshlrev_b32_e32 v104, 16, v166
	v_and_b32_e32 v105, 0xffff0000, v166
	v_lshlrev_b32_e32 v106, 16, v167
	v_and_b32_e32 v107, 0xffff0000, v167
	s_waitcnt lgkmcnt(0)
	s_nop 0
	v_mfma_f32_16x16x32_bf16 v[16:19], v[72:75], v[0:3], v[104:107]
	v_lshl_add_u64 v[20:21], v[20:21], 0, s[0:1]
	v_mov_b32_e32 v84, s27
	v_readfirstlane_b32 s26, v22
	v_mfma_f32_16x16x32_bf16 v[0:3], v[92:95], v[0:3], 0
	v_readfirstlane_b32 s27, v23
	v_lshl_add_u64 v[40:41], v[20:21], 0, s[8:9]
	v_lshl_add_u64 v[42:43], v[20:21], 0, v[158:159]
	v_mfma_f32_16x16x32_bf16 v[16:19], v[56:59], v[4:7], v[16:19]
	v_readfirstlane_b32 s28, v20
	v_readfirstlane_b32 s29, v21
	global_load_dword v164, v84, s[26:27]
	s_nop 3
	global_load_dwordx4 v[112:115], v198, s[28:29]
	global_load_dwordx4 v[104:107], v198, s[28:29] offset:1024
	global_load_dwordx4 v[96:99], v198, s[28:29] offset:2048
	global_load_dwordx4 v[32:35], v198, s[28:29] offset:3072
	v_mfma_f32_16x16x32_bf16 v[4:7], v[76:79], v[4:7], v[0:3]
	v_readfirstlane_b32 s26, v40
	v_add_co_u32_e32 v40, vcc, s19, v42
	v_mfma_f32_16x16x32_bf16 v[48:51], v[48:51], v[12:15], v[16:19]
	v_lshl_add_u64 v[22:23], v[20:21], 0, s[2:3]
	v_lshl_add_u64 v[20:21], v[20:21], 0, v[160:161]
	v_readfirstlane_b32 s27, v41
	v_mfma_f32_16x16x32_bf16 v[56:59], v[80:83], v[12:15], v[4:7]
	v_addc_co_u32_e32 v41, vcc, 0, v43, vcc
	v_readfirstlane_b32 s28, v22
	v_mfma_f32_16x16x32_bf16 v[28:31], v[28:31], v[124:127], v[48:51]
	v_readfirstlane_b32 s29, v23
	v_add_co_u32_e32 v74, vcc, s20, v20
	v_mfma_f32_16x16x32_bf16 v[48:51], v[68:71], v[124:127], v[56:59]
	v_lshl_add_u64 v[72:73], v[42:43], 0, s[10:11]
	v_addc_co_u32_e32 v75, vcc, 0, v21, vcc
	s_nop 2
	v_bfe_u32 v56, v28, 16, 1
	v_bfe_u32 v58, v30, 16, 1
	v_bfe_u32 v57, v29, 16, 1
	v_bfe_u32 v59, v31, 16, 1
	v_add3_u32 v28, v28, v56, s24
	v_add3_u32 v30, v30, v58, s24
	v_add3_u32 v29, v29, v57, s24
	v_add3_u32 v31, v31, v59, s24
	v_lshrrev_b32_e32 v28, 16, v28
	v_lshrrev_b32_e32 v30, 16, v30
	v_and_or_b32 v28, v29, s23, v28
	v_and_or_b32 v29, v31, s23, v30
	global_load_dwordx4 v[84:87], v202, s[26:27]
	global_load_dwordx4 v[88:91], v204, s[26:27]
	s_nop 0
	global_load_dwordx4 v[40:43], v[40:41], off
	s_nop 0
	global_load_dwordx4 v[0:3], v[72:73], off offset:1024
	global_load_dwordx4 v[16:19], v198, s[28:29]
	global_load_dwordx4 v[4:7], v198, s[28:29] offset:1024
	global_load_dwordx4 v[108:111], v201, s[26:27]
	global_load_dwordx4 v[20:23], v202, s[28:29]
	global_load_dwordx4 v[116:119], v198, s[26:27]
	global_load_dwordx4 v[12:15], v198, s[28:29] offset:3072
	global_load_dwordx2 v[168:169], v[74:75], off
	ds_write_b64 v147, v[28:29] offset:4096
	s_waitcnt lgkmcnt(0)
	s_barrier
; #define MFMA(a, b, c) __builtin_amdgcn_mfma_f32_16x16x32_bf16((a), (b), (c), 0, 0, 0)
; DI u16 f2bf(float x) { unsigned u = __float_as_uint(x); u += 0x7fffu + ((u >> 16) & 1u); return (u16)(u >> 16); }
; DI void scan_step(const Params& p, const ScanOps& ops, int n, int b, int h, int s, int j, int lane, f32x4& S0, f32x4& S1,
;                   bf16x8* sSb, u32x2* sUb) {
;     ...
;   __syncthreads();
;   bf16x8 ub[2];
; #pragma unroll
;   for (int k2 = 0; k2 < 2; ++k2) ub[k2] = *(const bf16x8*)&sUb[(k2 * 64 + lane) * 2];
;   f32x4 o = (f32x4){0.f, 0.f, 0.f, 0.f};
; #pragma unroll
;   for (int ks = 0; ks < 4; ++ks) o = MFMA(ops.qg[ks], sb[ks], o);
; #pragma unroll
;   for (int k2 = 0; k2 < 2; ++k2) o = MFMA(ops.aq[k2], ub[k2], o);
;   S0 = S0 * ops.dl; S1 = S1 * ops.dl;
; #pragma unroll
;   for (int k2 = 0; k2 < 2; ++k2) { S0 = MFMA(ops.kd[k2], ub[k2], S0); S1 = MFMA(ops.kd[2 + k2], ub[k2], S1); }
;   sSb[j * 64 + lane] = pack8(S0, S1);
; #pragma unroll
;   for (int jj = 0; jj < 4; ++jj) {
;     const size_t token = (size_t)b * SEQ + n * 64 + j * 16 + kg * 4 + jj;
;     G(p.odn)[token * 512 + h * 128 + s * 16 + r] = f2bf(o[jj]);
;   }
;   __syncthreads();
; }
; DI void dn_scan_block(const Params& p, int item, char* smem) {
;     ...
;   for (int n0 = 0; n0 < 128; n0 += 2) {
;     scan_step(p, A, n0, b, h, s, j, lane, S0, S1, sSb, sUb);
;     scan_load(p, bh, s, n0 + 2, j, lane, A);
;     scan_step(p, B, n0 + 1, b, h, s, j, lane, S0, S1, sSb, sUb);
;     scan_load(p, bh, s, n0 + 3, j, lane, B);
;   }
; #pragma unroll
;   for (int jj = 0; jj < 4; ++jj) {
;     p.out[O_PDELTA + ((size_t)bh * 128 + 32 * j + kg * 4 + jj) * 128 + s * 16 + r] = S0[jj];
;     p.out[O_PDELTA + ((size_t)bh * 128 + 32 * j + 16 + kg * 4 + jj) * 128 + s * 16 + r] = S1[jj];
;   }
	ds_read_b128 v[28:31], v197 offset:4096
	ds_read_b128 v[56:59], v197 offset:5120
	s_waitcnt lgkmcnt(0)
	v_mfma_f32_16x16x32_bf16 v[48:51], v[52:55], v[28:31], v[48:51]
	v_mul_f32_e64 v54, v162, v102
	v_mul_f32_e64 v55, v162, v103
	v_pk_mul_f32 v[52:53], v[162:163], v[100:101] op_sel_hi:[0,1]
	s_mul_i32 s0, s30, 0x12000
	v_mfma_f32_16x16x32_bf16 v[24:27], v[24:27], v[56:59], v[48:51]
	v_mov_b32_e32 v68, s31
	v_lshl_add_u64 v[8:9], v[8:9], 0, s[16:17]
	v_mfma_f32_16x16x32_bf16 v[52:55], v[60:63], v[28:31], v[52:55]
	v_mul_f32_e64 v62, v162, v122
	v_mul_f32_e64 v63, v162, v123
	v_pk_mul_f32 v[60:61], v[162:163], v[120:121] op_sel_hi:[0,1]
	v_mfma_f32_16x16x32_bf16 v[100:103], v[36:39], v[56:59], v[52:55]
	s_nop 0
	v_mfma_f32_16x16x32_bf16 v[28:31], v[64:67], v[28:31], v[60:63]
	s_nop 1
	v_bfe_u32 v52, v24, 16, 1
	v_bfe_u32 v53, v25, 16, 1
	v_bfe_u32 v54, v26, 16, 1
	ds_read_b64 v[60:61], v149
	v_mfma_f32_16x16x32_bf16 v[120:123], v[44:47], v[56:59], v[28:31]
	v_bfe_u32 v55, v27, 16, 1
	v_add3_u32 v52, v24, v52, s24
	v_add3_u32 v53, v25, v53, s24
	v_bfe_u32 v28, v100, 16, 1
	v_bfe_u32 v30, v102, 16, 1
	s_nop 2
	v_bfe_u32 v44, v120, 16, 1
	v_bfe_u32 v46, v122, 16, 1
	s_waitcnt lgkmcnt(0)
	v_lshl_add_u64 v[62:63], v[60:61], 0, s[12:13]
	v_bfe_u32 v29, v101, 16, 1
	v_bfe_u32 v31, v103, 16, 1
	v_bfe_u32 v45, v121, 16, 1
	v_bfe_u32 v47, v123, 16, 1
	v_add3_u32 v28, v100, v28, s24
	v_add3_u32 v30, v102, v30, s24
	v_add3_u32 v44, v120, v44, s24
	v_add3_u32 v46, v122, v46, s24
	v_lshl_add_u64 v[60:61], v[60:61], 0, v[154:155]
	v_lshl_add_u64 v[48:49], v[62:63], 0, s[14:15]
	v_add3_u32 v29, v101, v29, s24
	v_add3_u32 v31, v103, v31, s24
	v_add3_u32 v45, v121, v45, s24
	v_add3_u32 v47, v123, v47, s24
	v_add3_u32 v54, v26, v54, s24
	v_add3_u32 v55, v27, v55, s24
	v_lshrrev_b32_e32 v24, 16, v28
	v_lshrrev_b32_e32 v25, 16, v30
	v_lshrrev_b32_e32 v26, 16, v44
	v_lshrrev_b32_e32 v27, 16, v46
	v_lshl_add_u64 v[50:51], v[60:61], 0, v[152:153]
	v_lshl_add_u64 v[48:49], v[48:49], 0, v[156:157]
	v_and_or_b32 v24, v29, s23, v24
	v_and_or_b32 v25, v31, s23, v25
	v_and_or_b32 v26, v45, s23, v26
	v_and_or_b32 v27, v47, s23, v27
	v_lshl_add_u64 v[36:37], v[48:49], 0, v[218:219]
	v_lshl_add_u64 v[38:39], v[48:49], 0, v[194:195]
	v_lshl_add_u64 v[48:49], v[48:49], 0, v[128:129]
	ds_write_b128 v151, v[24:27]
	global_store_short_d16_hi v[50:51], v52, off
	global_store_short_d16_hi v[36:37], v53, off
	global_store_short_d16_hi v[38:39], v54, off
	global_store_short_d16_hi v[48:49], v55, off
	s_waitcnt lgkmcnt(0)
	s_barrier
	ds_read_b64 v[24:25], v141
	ds_read_b64 v[26:27], v145
	v_lshl_add_u64 v[152:153], v[152:153], 0, s[16:17]
	s_waitcnt lgkmcnt(0)
	v_lshl_add_u64 v[24:25], v[24:25], 0, s[0:1]
	v_readfirstlane_b32 s26, v26
	v_readfirstlane_b32 s27, v27
	v_lshl_add_u64 v[36:37], v[24:25], 0, s[8:9]
	v_lshl_add_u64 v[38:39], v[24:25], 0, v[158:159]
	v_readfirstlane_b32 s28, v24
	v_readfirstlane_b32 s29, v25
	s_nop 0
	global_load_dword v162, v68, s[26:27] offset:12
	s_nop 2
	global_load_dwordx4 v[72:75], v198, s[28:29]
	global_load_dwordx4 v[56:59], v198, s[28:29] offset:1024
	global_load_dwordx4 v[48:51], v198, s[28:29] offset:2048
	global_load_dwordx4 v[28:31], v198, s[28:29] offset:3072
	v_readfirstlane_b32 s26, v36
	v_readfirstlane_b32 s27, v37
	v_lshl_add_u64 v[36:37], v[38:39], 0, s[10:11]
	v_add_co_u32_e32 v38, vcc, s19, v38
	v_lshl_add_u64 v[26:27], v[24:25], 0, s[2:3]
	v_lshl_add_u64 v[24:25], v[24:25], 0, v[160:161]
	v_addc_co_u32_e32 v39, vcc, 0, v39, vcc
	v_add_co_u32_e32 v124, vcc, s20, v24
	v_readfirstlane_b32 s28, v26
	v_readfirstlane_b32 s29, v27
	v_addc_co_u32_e32 v125, vcc, 0, v25, vcc
	global_load_dwordx4 v[80:83], v202, s[26:27]
	global_load_dwordx4 v[68:71], v204, s[26:27]
	global_load_dwordx4 v[52:55], v[38:39], off
	global_load_dwordx4 v[24:27], v[36:37], off offset:1024
	global_load_dwordx4 v[60:63], v198, s[28:29]
	s_nop 0
	global_load_dwordx4 v[36:39], v198, s[28:29] offset:1024
	global_load_dwordx4 v[76:79], v201, s[26:27]
	global_load_dwordx4 v[64:67], v202, s[28:29]
	global_load_dwordx4 v[92:95], v198, s[26:27]
	global_load_dwordx4 v[44:47], v198, s[28:29] offset:3072
	global_load_dwordx2 v[166:167], v[124:125], off
	s_mov_b32 s0, s25
	s_cbranch_scc1 .LBB0_622
	s_waitcnt vmcnt(0)
	v_mov_b32_e32 v0, 0x100d8
	ds_read_b64 v[0:1], v0
	v_add_u32_e32 v2, s18, v178
	v_or_b32_e32 v2, v2, v200
	v_lshlrev_b32_e32 v2, 9, v2
	v_mov_b32_e32 v3, 0
	s_mov_b32 s1, 0
	s_waitcnt lgkmcnt(0)
	v_lshl_add_u64 v[0:1], v[0:1], 0, v[2:3]
	s_lshl_b32 s0, s21, 2
	v_mov_b32_e32 v151, v3
	v_lshl_add_u64 v[0:1], v[0:1], 0, s[0:1]
	v_lshl_add_u64 v[0:1], v[0:1], 0, v[150:151]
	v_add_co_u32_e32 v2, vcc, 0x8080000, v0
	s_nop 1
	v_addc_co_u32_e32 v3, vcc, 0, v1, vcc
	v_add_co_u32_e32 v0, vcc, 0x8082000, v0
	flat_store_dword v[2:3], v100
	s_nop 0
	v_addc_co_u32_e32 v1, vcc, 0, v1, vcc
	flat_store_dword v[0:1], v120
	flat_store_dword v[2:3], v101 offset:512
	flat_store_dword v[0:1], v121 offset:512
	flat_store_dword v[2:3], v102 offset:1024
	flat_store_dword v[0:1], v122 offset:1024
	flat_store_dword v[2:3], v103 offset:1536
	flat_store_dword v[0:1], v123 offset:1536

; DI void phase7(const Params& p, char* smem) {
;   const int w = threadIdx.x >> 6;
;   float* lds = (float*)smem + w * 1280;
;   for (int it = blockIdx.x; it < 32 + 2048; it += gridDim.x) {
;     if (it < 32) { __syncthreads(); mem_attn_sample_wave(p, it * 4 + w, lds); }
;     else mem_attn_prompt_block(p, it - 32, smem);
;   }
; }
.LBB0_884:
	s_or_b64 exec, exec, s[2:3]
	s_cmpk_gt_i32 s86, 0x81f
	s_waitcnt lgkmcnt(0)
	s_barrier
	s_cbranch_scc1 .LBB0_903
	v_lshrrev_b32_e32 v2, 5, v142
	v_lshlrev_b32_e32 v96, 9, v2
	v_mul_u32_u24_e32 v3, 0x210, v2
	v_add_u32_e32 v2, 0x100, v142
	v_lshrrev_b32_e32 v2, 5, v2
	v_lshlrev_b32_e32 v98, 9, v2
	v_mul_u32_u24_e32 v4, 0x210, v2
	v_add_u32_e32 v2, 0x200, v142
	v_lshrrev_b32_e32 v2, 5, v2
	v_lshlrev_b32_e32 v100, 9, v2
	v_mul_u32_u24_e32 v5, 0x210, v2
	v_add_u32_e32 v2, 0x300, v142
	v_lshrrev_b32_e32 v2, 5, v2
	v_lshlrev_b32_e32 v102, 9, v2
	v_mul_u32_u24_e32 v6, 0x210, v2
	v_add_u32_e32 v2, 0x500, v142
	v_lshrrev_b32_e32 v2, 5, v2
	v_lshlrev_b32_e32 v106, 9, v2
	v_mul_u32_u24_e32 v7, 0x210, v2
	v_add_u32_e32 v2, 0x600, v142
	v_lshrrev_b32_e32 v2, 5, v2
	v_lshlrev_b32_e32 v108, 9, v2
	v_mul_u32_u24_e32 v8, 0x210, v2
	v_add_u32_e32 v2, 0x700, v142
	s_movk_i32 s1, 0xf0
	v_lshrrev_b32_e32 v2, 5, v2
	v_mov_b32_e32 v11, 0xf00
	s_movk_i32 s0, 0x1400
	v_mul_u32_u24_e32 v113, 0x1400, v174
	v_and_or_b32 v120, v192, s1, v134
	v_and_b32_e32 v0, 0xf8, v173
	s_movk_i32 s1, 0x210
	v_lshlrev_b32_e32 v110, 9, v2
	v_mul_u32_u24_e32 v9, 0x210, v2
	v_and_b32_e32 v2, 48, v142
	v_lshl_or_b32 v11, v142, 2, v11
	v_mov_b32_e32 v95, 0
	v_lshlrev_b32_e32 v1, 1, v0
	v_mad_u32_u24 v121, v134, s1, v2
	v_lshl_or_b32 v123, v144, 2, v113
	v_lshlrev_b32_e32 v2, 11, v191
	v_mul_i32_i24_e32 v10, -12, v191
	v_mad_u32_u24 v124, v174, s0, v11
	v_readlane_b32 s0, v255, 3
	v_lshlrev_b32_e32 v114, 1, v0
	v_and_b32_e32 v0, 64, v128
	v_mov_b32_e32 v97, v95
	v_mov_b32_e32 v99, v95
	v_mov_b32_e32 v101, v95
	v_mov_b32_e32 v103, v95
	s_movk_i32 s26, 0x4000
	v_or_b32_e32 v104, 0x4000, v96
	v_mov_b32_e32 v105, v95
	v_mov_b32_e32 v107, v95
	v_mov_b32_e32 v109, v95
	v_mov_b32_e32 v111, v95
	v_lshlrev_b32_e32 v122, 1, v173
	v_and_b32_e32 v112, 0x300, v203
	s_add_i32 s27, s0, 0xfffffe00
	v_lshlrev_b32_e32 v125, 1, v148
	s_mov_b32 s1, 0
	v_mov_b32_e32 v126, 0x10198
	v_mov_b32_e32 v127, 0x10150
	v_add_u32_e32 v130, v1, v3
	v_add_u32_e32 v131, v1, v4
	v_add_u32_e32 v137, v1, v5
	v_add_u32_e32 v142, v1, v6
	v_add_u32_e32 v145, v1, v7
	v_add_u32_e32 v146, v1, v8
	v_add_u32_e32 v147, v1, v9
	s_mov_b32 s28, 0x8000
	s_mov_b32 s29, 0xc000
	s_mov_b32 s30, 0x10000
	s_mov_b32 s31, 0x14000
	s_mov_b32 s34, 0x18000
	s_mov_b32 s35, 0x1c000
	s_mov_b32 s36, 0x3d800000
	s_mov_b32 s37, 0xff61b1e6
	s_movk_i32 s38, 0x7fff
	s_mov_b32 s39, 0xffff0000
	v_mov_b32_e32 v148, 0x10158
	s_movk_i32 s40, 0x1000
	s_movk_i32 s41, 0x3000
	s_movk_i32 s42, 0x5000
	s_movk_i32 s43, 0x7000
	v_mov_b32_e32 v149, 0x101a0
	s_movk_i32 s44, 0xffa0
	s_movk_i32 s45, 0xffc0
	s_movk_i32 s46, 0xffe0
	s_mov_b64 s[2:3], 0x80
	s_mov_b64 s[10:11], 0x4000000
	s_mov_b64 s[12:13], 0x4000800
	s_mov_b64 s[14:15], 0x4001000
	s_mov_b64 s[16:17], 0x4001800
	v_mov_b32_e32 v150, 0x10038
	v_lshlrev_b32_e32 v116, 2, v2
	s_mov_b64 s[18:19], 0x80000
	s_mov_b64 s[20:21], 0x100000
	s_mov_b64 s[22:23], 0x180000
	v_add_u32_e32 v151, v123, v10
	v_xor_b32_e32 v152, 16, v128
	v_add_u32_e32 v153, 64, v0
	v_xor_b32_e32 v154, 32, v128
	v_mov_b32_e32 v155, 1
	s_mov_b32 s47, s86
	s_mov_b32 s48, s86
	s_mov_b32 s101, 0
	s_branch .LBB0_887
.LBB0_886:
	s_cmp_lt_i32 s86, 32
	s_cbranch_scc1 .LBB0_903
	s_cmp_eq_u32 s101, 1
	s_cbranch_scc1 .LBB0_903
	s_add_i32 s48, s48, s84
	s_cmpk_lt_i32 s48, 0x800
	s_cbranch_scc1 .Lp7_set
	s_mov_b32 s101, 1
	s_sub_i32 s0, s86, 32
	s_cmpk_gt_i32 s0, 0x7f
	s_cbranch_scc1 .LBB0_903
	s_and_b32 s24, s0, 31
	s_lshr_b32 s0, s0, 5
	s_add_i32 s0, s0, 1
	s_lshl_b32 s0, s0, 9
	s_add_i32 s48, s24, s0
.Lp7_set:
	s_mov_b32 s47, s48
	s_sub_i32 s27, s48, 32
	s_lshl_b32 s27, s27, 4

; DI float bflo(unsigned d) { return __uint_as_float(d << 16); }
; DI float bfhi(unsigned d) { return __uint_as_float(d & 0xffff0000u); }
; DI void mem_attn_sample_wave(const Params& p, int item, float* lds) {
;   const int lane = threadIdx.x & 63;
;   const int b = item >> 2, h = item & 3;
;   float* sq = lds;
; #pragma unroll
;   for (int t = 0; t < 4; ++t) {
;     uint2 v = *(const uint2*)&p.qb[((size_t)MP + b * 4 + t) * 1024 + h * 256 + lane * 4];
;     *(float4*)&sq[t * 256 + lane * 4] = make_float4(bflo(v.x), bfhi(v.x), bflo(v.y), bfhi(v.y));
;   }
;   __builtin_amdgcn_s_waitcnt(0);
;   __builtin_amdgcn_wave_barrier();
;   float sc[4][4];
; #pragma unroll
;   for (int mi = 0; mi < 4; ++mi) {
;     const int m = lane + 64 * mi;
;     const float* kr = &p.cache_mem[(((size_t)b * 256 + m) * 2 + 0) * 1024 + h * 256];
;     float d0 = 0.f, d1 = 0.f, d2 = 0.f, d3 = 0.f;
; #pragma unroll 2
;     for (int c = 0; c < 256; c += 4) {
;       float4 kv = *(const float4*)&kr[c];
;       float4 q0 = *(const float4*)&sq[c], q1 = *(const float4*)&sq[256 + c], q2 = *(const float4*)&sq[512 + c], q3 = *(const float4*)&sq[768 + c];
.LBB0_891:
	s_and_b64 vcc, exec, s[24:25]
	s_cbranch_vccz .LBB0_886
	s_waitcnt lgkmcnt(0)
	s_barrier
	v_lshl_add_u32 v246, s48, 2, v174
	v_mbcnt_lo_u32_b32 v245, -1, 0
	v_mbcnt_hi_u32_b32 v245, -1, v245
	v_readfirstlane_b32 s0, v246
	v_mov_b32_e32 v247, 0x10198
	v_mov_b32_e32 v248, 0x101a0
	v_mov_b32_e32 v249, 0x10038
	ds_read_b64 v[0:1], v247
	ds_read_b64 v[2:3], v248
	ds_read_b64 v[4:5], v249
	s_lshr_b32 s24, s0, 2
	s_and_b32 s25, s0, 3
	v_lshlrev_b32_e32 v250, 3, v245
	v_lshlrev_b32_e32 v252, 4, v245
	v_mul_u32_u24_e32 v251, 0x1400, v174
	v_lshlrev_b32_e32 v240, 13, v245
	v_lshlrev_b32_e32 v241, 13, v245
	v_add_u32_e32 v241, 0x80000, v241
	v_lshlrev_b32_e32 v242, 13, v245
	v_add_u32_e32 v242, 0x100000, v242
	v_lshlrev_b32_e32 v243, 13, v245
	v_add_u32_e32 v243, 0x180000, v243
	v_mov_b32_e32 v144, v252
	v_add_u32_e32 v145, 0x2000, v252
	v_add_u32_e32 v146, 0x4000, v252
	v_add_u32_e32 v147, 0x6000, v252
	v_add_u32_e32 v148, 0x8000, v252
	v_add_u32_e32 v149, 0xa000, v252
	v_add_u32_e32 v150, 0xc000, v252
	v_add_u32_e32 v151, 0xe000, v252
	v_xor_b32_e32 v152, 32, v245
	v_lshlrev_b32_e32 v152, 2, v152
	v_xor_b32_e32 v153, 16, v245
	v_lshlrev_b32_e32 v153, 2, v153
	v_xor_b32_e32 v154, 8, v245
	v_lshlrev_b32_e32 v154, 2, v154
	v_xor_b32_e32 v155, 4, v245
	v_lshlrev_b32_e32 v155, 2, v155
	v_xor_b32_e32 v156, 2, v245
	v_lshlrev_b32_e32 v156, 2, v156
	v_xor_b32_e32 v157, 1, v245
	v_lshlrev_b32_e32 v157, 2, v157
	s_waitcnt lgkmcnt(0)
	v_readfirstlane_b32 s14, v0
	v_readfirstlane_b32 s15, v1
	v_readfirstlane_b32 s16, v2
	v_readfirstlane_b32 s17, v3
	v_readfirstlane_b32 s10, v4
	v_readfirstlane_b32 s11, v5
	s_lshl_b32 s98, s24, 13
	s_add_i32 s98, s98, 0x4000000
	s_lshl_b32 s99, s25, 9
	s_add_i32 s98, s98, s99
	s_add_u32 s14, s14, s98
	s_addc_u32 s15, s15, 0
	s_add_u32 s16, s16, s98
	s_addc_u32 s17, s17, 0
	s_lshl_b32 s98, s24, 21
	s_lshl_b32 s99, s25, 10
	s_add_i32 s98, s98, s99
	s_add_u32 s10, s10, s98
	s_addc_u32 s11, s11, 0
	s_add_u32 s12, s10, 0x1000
	s_addc_u32 s13, s11, 0
	s_nop 2
	v_add_u32_e32 v247, 0x1000, v250
	global_load_dwordx2 v[8:9], v250, s[14:15] offset:0
	global_load_dwordx2 v[10:11], v250, s[14:15] offset:2048
	global_load_dwordx2 v[12:13], v247, s[14:15] offset:0
	global_load_dwordx2 v[14:15], v247, s[14:15] offset:2048
	v_add_u32_e32 v244, v251, v252
	s_waitcnt vmcnt(0)
	v_lshlrev_b32_e32 v192, 16, v8
	v_and_b32_e32 v193, 0xffff0000, v8
	v_lshlrev_b32_e32 v194, 16, v9
	v_and_b32_e32 v195, 0xffff0000, v9
	ds_write_b128 v244, v[192:195] offset:0
	v_lshlrev_b32_e32 v196, 16, v10
	v_and_b32_e32 v197, 0xffff0000, v10
	v_lshlrev_b32_e32 v198, 16, v11
	v_and_b32_e32 v199, 0xffff0000, v11
	ds_write_b128 v244, v[196:199] offset:1024
	v_lshlrev_b32_e32 v200, 16, v12
	v_and_b32_e32 v201, 0xffff0000, v12
	v_lshlrev_b32_e32 v202, 16, v13
	v_and_b32_e32 v203, 0xffff0000, v13
	ds_write_b128 v244, v[200:203] offset:2048
	v_lshlrev_b32_e32 v204, 16, v14
	v_and_b32_e32 v205, 0xffff0000, v14
	v_lshlrev_b32_e32 v206, 16, v15
	v_and_b32_e32 v207, 0xffff0000, v15
	ds_write_b128 v244, v[204:207] offset:3072
	global_load_dwordx4 v[0:3], v240, s[10:11] offset:0
	global_load_dwordx4 v[4:7], v240, s[10:11] offset:16
	global_load_dwordx4 v[8:11], v241, s[10:11] offset:0
	global_load_dwordx4 v[12:15], v241, s[10:11] offset:16
	global_load_dwordx4 v[16:19], v242, s[10:11] offset:0
	global_load_dwordx4 v[20:23], v242, s[10:11] offset:16
	global_load_dwordx4 v[24:27], v243, s[10:11] offset:0
	global_load_dwordx4 v[28:31], v243, s[10:11] offset:16
	global_load_dwordx4 v[32:35], v240, s[10:11] offset:32
	global_load_dwordx4 v[36:39], v240, s[10:11] offset:48
	global_load_dwordx4 v[40:43], v241, s[10:11] offset:32
	global_load_dwordx4 v[44:47], v241, s[10:11] offset:48
	global_load_dwordx4 v[48:51], v242, s[10:11] offset:32
	global_load_dwordx4 v[52:55], v242, s[10:11] offset:48
	global_load_dwordx4 v[56:59], v243, s[10:11] offset:32
	global_load_dwordx4 v[60:63], v243, s[10:11] offset:48
	global_load_dwordx4 v[64:67], v240, s[10:11] offset:64
	global_load_dwordx4 v[68:71], v240, s[10:11] offset:80
	global_load_dwordx4 v[72:75], v241, s[10:11] offset:64
	global_load_dwordx4 v[76:79], v241, s[10:11] offset:80
	global_load_dwordx4 v[80:83], v242, s[10:11] offset:64
	global_load_dwordx4 v[84:87], v242, s[10:11] offset:80
	global_load_dwordx4 v[88:91], v243, s[10:11] offset:64
	global_load_dwordx4 v[92:95], v243, s[10:11] offset:80
	v_mov_b32_e32 v224, 0
	v_mov_b32_e32 v225, 0
	v_mov_b32_e32 v226, 0
	v_mov_b32_e32 v227, 0
	v_mov_b32_e32 v228, 0
	v_mov_b32_e32 v229, 0
	v_mov_b32_e32 v230, 0
	v_mov_b32_e32 v231, 0
	v_mov_b32_e32 v232, 0
	v_mov_b32_e32 v233, 0
	v_mov_b32_e32 v234, 0
	v_mov_b32_e32 v235, 0
	v_mov_b32_e32 v236, 0
	v_mov_b32_e32 v237, 0
	v_mov_b32_e32 v238, 0
	v_mov_b32_e32 v239, 0
	v_mov_b32_e32 v244, v251
	s_waitcnt lgkmcnt(0)
	s_mov_b32 s0, 0
; DI void mem_attn_sample_wave(const Params& p, int item, float* lds) {
;     ...
;   float sc[4][4];
; #pragma unroll
;   for (int mi = 0; mi < 4; ++mi) {
;     const int m = lane + 64 * mi;
;     const float* kr = &p.cache_mem[(((size_t)b * 256 + m) * 2 + 0) * 1024 + h * 256];
;     float d0 = 0.f, d1 = 0.f, d2 = 0.f, d3 = 0.f;
; #pragma unroll 2
;     for (int c = 0; c < 256; c += 4) {
;       float4 kv = *(const float4*)&kr[c];
;       float4 q0 = *(const float4*)&sq[c], q1 = *(const float4*)&sq[256 + c], q2 = *(const float4*)&sq[512 + c], q3 = *(const float4*)&sq[768 + c];
;       d0 += kv.x * q0.x + kv.y * q0.y + kv.z * q0.z + kv.w * q0.w;
;       d1 += kv.x * q1.x + kv.y * q1.y + kv.z * q1.z + kv.w * q1.w;
;       d2 += kv.x * q2.x + kv.y * q2.y + kv.z * q2.z + kv.w * q2.w;
;       d3 += kv.x * q3.x + kv.y * q3.y + kv.z * q3.z + kv.w * q3.w;
;     }
;     sc[0][mi] = d0 * 0.0625f; sc[1][mi] = d1 * 0.0625f; sc[2][mi] = d2 * 0.0625f; sc[3][mi] = d3 * 0.0625f;
;   }
.Lp7s_kloop:
	global_load_dwordx4 v[96:99], v240, s[10:11] offset:96
	global_load_dwordx4 v[100:103], v240, s[10:11] offset:112
	global_load_dwordx4 v[104:107], v241, s[10:11] offset:96
	global_load_dwordx4 v[108:111], v241, s[10:11] offset:112
	global_load_dwordx4 v[112:115], v242, s[10:11] offset:96
	global_load_dwordx4 v[116:119], v242, s[10:11] offset:112
	global_load_dwordx4 v[120:123], v243, s[10:11] offset:96
	global_load_dwordx4 v[124:127], v243, s[10:11] offset:112
	s_waitcnt vmcnt(24)
	ds_read_b128 v[192:195], v244 offset:0
	ds_read_b128 v[196:199], v244 offset:16
	ds_read_b128 v[200:203], v244 offset:1024
	ds_read_b128 v[204:207], v244 offset:1040
	ds_read_b128 v[208:211], v244 offset:2048
	ds_read_b128 v[212:215], v244 offset:2064
	ds_read_b128 v[216:219], v244 offset:3072
	ds_read_b128 v[220:223], v244 offset:3088
	s_waitcnt lgkmcnt(0)
	v_fmac_f32_e32 v224, v0, v192
	v_fmac_f32_e32 v224, v1, v193
	v_fmac_f32_e32 v224, v2, v194
	v_fmac_f32_e32 v224, v3, v195
	v_fmac_f32_e32 v224, v4, v196
	v_fmac_f32_e32 v224, v5, v197
	v_fmac_f32_e32 v224, v6, v198
	v_fmac_f32_e32 v224, v7, v199
	v_fmac_f32_e32 v225, v0, v200
	v_fmac_f32_e32 v225, v1, v201
	v_fmac_f32_e32 v225, v2, v202
	v_fmac_f32_e32 v225, v3, v203
	v_fmac_f32_e32 v225, v4, v204
	v_fmac_f32_e32 v225, v5, v205
	v_fmac_f32_e32 v225, v6, v206
	v_fmac_f32_e32 v225, v7, v207
	v_fmac_f32_e32 v226, v0, v208
	v_fmac_f32_e32 v226, v1, v209
	v_fmac_f32_e32 v226, v2, v210
	v_fmac_f32_e32 v226, v3, v211
	v_fmac_f32_e32 v226, v4, v212
	v_fmac_f32_e32 v226, v5, v213
	v_fmac_f32_e32 v226, v6, v214
	v_fmac_f32_e32 v226, v7, v215
	v_fmac_f32_e32 v227, v0, v216
	v_fmac_f32_e32 v227, v1, v217
	v_fmac_f32_e32 v227, v2, v218
	v_fmac_f32_e32 v227, v3, v219
	v_fmac_f32_e32 v227, v4, v220
	v_fmac_f32_e32 v227, v5, v221
	v_fmac_f32_e32 v227, v6, v222
	v_fmac_f32_e32 v227, v7, v223
	v_fmac_f32_e32 v228, v8, v192
	v_fmac_f32_e32 v228, v9, v193
	v_fmac_f32_e32 v228, v10, v194
	v_fmac_f32_e32 v228, v11, v195
	v_fmac_f32_e32 v228, v12, v196
	v_fmac_f32_e32 v228, v13, v197
	v_fmac_f32_e32 v228, v14, v198
	v_fmac_f32_e32 v228, v15, v199
	v_fmac_f32_e32 v229, v8, v200
	v_fmac_f32_e32 v229, v9, v201
	v_fmac_f32_e32 v229, v10, v202
	v_fmac_f32_e32 v229, v11, v203
	v_fmac_f32_e32 v229, v12, v204
	v_fmac_f32_e32 v229, v13, v205
	v_fmac_f32_e32 v229, v14, v206
	v_fmac_f32_e32 v229, v15, v207
	v_fmac_f32_e32 v230, v8, v208
	v_fmac_f32_e32 v230, v9, v209
	v_fmac_f32_e32 v230, v10, v210
	v_fmac_f32_e32 v230, v11, v211
	v_fmac_f32_e32 v230, v12, v212
	v_fmac_f32_e32 v230, v13, v213
	v_fmac_f32_e32 v230, v14, v214
	v_fmac_f32_e32 v230, v15, v215
	v_fmac_f32_e32 v231, v8, v216
	v_fmac_f32_e32 v231, v9, v217
	v_fmac_f32_e32 v231, v10, v218
	v_fmac_f32_e32 v231, v11, v219
	v_fmac_f32_e32 v231, v12, v220
	v_fmac_f32_e32 v231, v13, v221
	v_fmac_f32_e32 v231, v14, v222
	v_fmac_f32_e32 v231, v15, v223
	v_fmac_f32_e32 v232, v16, v192
	v_fmac_f32_e32 v232, v17, v193
	v_fmac_f32_e32 v232, v18, v194
	v_fmac_f32_e32 v232, v19, v195
	v_fmac_f32_e32 v232, v20, v196
	v_fmac_f32_e32 v232, v21, v197
	v_fmac_f32_e32 v232, v22, v198
	v_fmac_f32_e32 v232, v23, v199
	v_fmac_f32_e32 v233, v16, v200
	v_fmac_f32_e32 v233, v17, v201
	v_fmac_f32_e32 v233, v18, v202
	v_fmac_f32_e32 v233, v19, v203
	v_fmac_f32_e32 v233, v20, v204
	v_fmac_f32_e32 v233, v21, v205
	v_fmac_f32_e32 v233, v22, v206
	v_fmac_f32_e32 v233, v23, v207
	v_fmac_f32_e32 v234, v16, v208
	v_fmac_f32_e32 v234, v17, v209
	v_fmac_f32_e32 v234, v18, v210
	v_fmac_f32_e32 v234, v19, v211
	v_fmac_f32_e32 v234, v20, v212
	v_fmac_f32_e32 v234, v21, v213
	v_fmac_f32_e32 v234, v22, v214
	v_fmac_f32_e32 v234, v23, v215
	v_fmac_f32_e32 v235, v16, v216
	v_fmac_f32_e32 v235, v17, v217
	v_fmac_f32_e32 v235, v18, v218
	v_fmac_f32_e32 v235, v19, v219
	v_fmac_f32_e32 v235, v20, v220
	v_fmac_f32_e32 v235, v21, v221
	v_fmac_f32_e32 v235, v22, v222
	v_fmac_f32_e32 v235, v23, v223
	v_fmac_f32_e32 v236, v24, v192
	v_fmac_f32_e32 v236, v25, v193
	v_fmac_f32_e32 v236, v26, v194
	v_fmac_f32_e32 v236, v27, v195
	v_fmac_f32_e32 v236, v28, v196
	v_fmac_f32_e32 v236, v29, v197
	v_fmac_f32_e32 v236, v30, v198
	v_fmac_f32_e32 v236, v31, v199
	v_fmac_f32_e32 v237, v24, v200
	v_fmac_f32_e32 v237, v25, v201
	v_fmac_f32_e32 v237, v26, v202
	v_fmac_f32_e32 v237, v27, v203
	v_fmac_f32_e32 v237, v28, v204
	v_fmac_f32_e32 v237, v29, v205
	v_fmac_f32_e32 v237, v30, v206
	v_fmac_f32_e32 v237, v31, v207
	v_fmac_f32_e32 v238, v24, v208
	v_fmac_f32_e32 v238, v25, v209
	v_fmac_f32_e32 v238, v26, v210
	v_fmac_f32_e32 v238, v27, v211
	v_fmac_f32_e32 v238, v28, v212
	v_fmac_f32_e32 v238, v29, v213
	v_fmac_f32_e32 v238, v30, v214
	v_fmac_f32_e32 v238, v31, v215
	v_fmac_f32_e32 v239, v24, v216
	v_fmac_f32_e32 v239, v25, v217
	v_fmac_f32_e32 v239, v26, v218
	v_fmac_f32_e32 v239, v27, v219
	v_fmac_f32_e32 v239, v28, v220
	v_fmac_f32_e32 v239, v29, v221
	v_fmac_f32_e32 v239, v30, v222
	v_fmac_f32_e32 v239, v31, v223
	global_load_dwordx4 v[0:3], v240, s[10:11] offset:128
	global_load_dwordx4 v[4:7], v240, s[10:11] offset:144
	global_load_dwordx4 v[8:11], v241, s[10:11] offset:128
	global_load_dwordx4 v[12:15], v241, s[10:11] offset:144
	global_load_dwordx4 v[16:19], v242, s[10:11] offset:128
	global_load_dwordx4 v[20:23], v242, s[10:11] offset:144
	global_load_dwordx4 v[24:27], v243, s[10:11] offset:128
	global_load_dwordx4 v[28:31], v243, s[10:11] offset:144
	s_waitcnt vmcnt(24)
	ds_read_b128 v[192:195], v244 offset:32
	ds_read_b128 v[196:199], v244 offset:48
	ds_read_b128 v[200:203], v244 offset:1056
	ds_read_b128 v[204:207], v244 offset:1072
	ds_read_b128 v[208:211], v244 offset:2080
	ds_read_b128 v[212:215], v244 offset:2096
	ds_read_b128 v[216:219], v244 offset:3104
	ds_read_b128 v[220:223], v244 offset:3120
	s_waitcnt lgkmcnt(0)
; DI void mem_attn_sample_wave(const Params& p, int item, float* lds) {
;     ...
;   float sc[4][4];
; #pragma unroll
;   for (int mi = 0; mi < 4; ++mi) {
;     const int m = lane + 64 * mi;
;     const float* kr = &p.cache_mem[(((size_t)b * 256 + m) * 2 + 0) * 1024 + h * 256];
;     float d0 = 0.f, d1 = 0.f, d2 = 0.f, d3 = 0.f;
; #pragma unroll 2
;     for (int c = 0; c < 256; c += 4) {
;       float4 kv = *(const float4*)&kr[c];
;       float4 q0 = *(const float4*)&sq[c], q1 = *(const float4*)&sq[256 + c], q2 = *(const float4*)&sq[512 + c], q3 = *(const float4*)&sq[768 + c];
;       d0 += kv.x * q0.x + kv.y * q0.y + kv.z * q0.z + kv.w * q0.w;
;       d1 += kv.x * q1.x + kv.y * q1.y + kv.z * q1.z + kv.w * q1.w;
;       d2 += kv.x * q2.x + kv.y * q2.y + kv.z * q2.z + kv.w * q2.w;
;       d3 += kv.x * q3.x + kv.y * q3.y + kv.z * q3.z + kv.w * q3.w;
;     }
;     sc[0][mi] = d0 * 0.0625f; sc[1][mi] = d1 * 0.0625f; sc[2][mi] = d2 * 0.0625f; sc[3][mi] = d3 * 0.0625f;
;   }
	v_fmac_f32_e32 v224, v32, v192
	v_fmac_f32_e32 v224, v33, v193
	v_fmac_f32_e32 v224, v34, v194
	v_fmac_f32_e32 v224, v35, v195
	v_fmac_f32_e32 v224, v36, v196
	v_fmac_f32_e32 v224, v37, v197
	v_fmac_f32_e32 v224, v38, v198
	v_fmac_f32_e32 v224, v39, v199
	v_fmac_f32_e32 v225, v32, v200
	v_fmac_f32_e32 v225, v33, v201
	v_fmac_f32_e32 v225, v34, v202
	v_fmac_f32_e32 v225, v35, v203
	v_fmac_f32_e32 v225, v36, v204
	v_fmac_f32_e32 v225, v37, v205
	v_fmac_f32_e32 v225, v38, v206
	v_fmac_f32_e32 v225, v39, v207
	v_fmac_f32_e32 v226, v32, v208
	v_fmac_f32_e32 v226, v33, v209
	v_fmac_f32_e32 v226, v34, v210
	v_fmac_f32_e32 v226, v35, v211
	v_fmac_f32_e32 v226, v36, v212
	v_fmac_f32_e32 v226, v37, v213
	v_fmac_f32_e32 v226, v38, v214
	v_fmac_f32_e32 v226, v39, v215
	v_fmac_f32_e32 v227, v32, v216
	v_fmac_f32_e32 v227, v33, v217
	v_fmac_f32_e32 v227, v34, v218
	v_fmac_f32_e32 v227, v35, v219
	v_fmac_f32_e32 v227, v36, v220
	v_fmac_f32_e32 v227, v37, v221
	v_fmac_f32_e32 v227, v38, v222
	v_fmac_f32_e32 v227, v39, v223
	v_fmac_f32_e32 v228, v40, v192
	v_fmac_f32_e32 v228, v41, v193
	v_fmac_f32_e32 v228, v42, v194
	v_fmac_f32_e32 v228, v43, v195
	v_fmac_f32_e32 v228, v44, v196
	v_fmac_f32_e32 v228, v45, v197
	v_fmac_f32_e32 v228, v46, v198
	v_fmac_f32_e32 v228, v47, v199
	v_fmac_f32_e32 v229, v40, v200
	v_fmac_f32_e32 v229, v41, v201
	v_fmac_f32_e32 v229, v42, v202
	v_fmac_f32_e32 v229, v43, v203
	v_fmac_f32_e32 v229, v44, v204
	v_fmac_f32_e32 v229, v45, v205
	v_fmac_f32_e32 v229, v46, v206
	v_fmac_f32_e32 v229, v47, v207
	v_fmac_f32_e32 v230, v40, v208
	v_fmac_f32_e32 v230, v41, v209
	v_fmac_f32_e32 v230, v42, v210
	v_fmac_f32_e32 v230, v43, v211
	v_fmac_f32_e32 v230, v44, v212
	v_fmac_f32_e32 v230, v45, v213
	v_fmac_f32_e32 v230, v46, v214
	v_fmac_f32_e32 v230, v47, v215
	v_fmac_f32_e32 v231, v40, v216
	v_fmac_f32_e32 v231, v41, v217
	v_fmac_f32_e32 v231, v42, v218
	v_fmac_f32_e32 v231, v43, v219
	v_fmac_f32_e32 v231, v44, v220
	v_fmac_f32_e32 v231, v45, v221
	v_fmac_f32_e32 v231, v46, v222
	v_fmac_f32_e32 v231, v47, v223
	v_fmac_f32_e32 v232, v48, v192
	v_fmac_f32_e32 v232, v49, v193
	v_fmac_f32_e32 v232, v50, v194
	v_fmac_f32_e32 v232, v51, v195
	v_fmac_f32_e32 v232, v52, v196
	v_fmac_f32_e32 v232, v53, v197
	v_fmac_f32_e32 v232, v54, v198
	v_fmac_f32_e32 v232, v55, v199
	v_fmac_f32_e32 v233, v48, v200
	v_fmac_f32_e32 v233, v49, v201
	v_fmac_f32_e32 v233, v50, v202
	v_fmac_f32_e32 v233, v51, v203
	v_fmac_f32_e32 v233, v52, v204
	v_fmac_f32_e32 v233, v53, v205
	v_fmac_f32_e32 v233, v54, v206
	v_fmac_f32_e32 v233, v55, v207
	v_fmac_f32_e32 v234, v48, v208
	v_fmac_f32_e32 v234, v49, v209
	v_fmac_f32_e32 v234, v50, v210
	v_fmac_f32_e32 v234, v51, v211
	v_fmac_f32_e32 v234, v52, v212
	v_fmac_f32_e32 v234, v53, v213
	v_fmac_f32_e32 v234, v54, v214
	v_fmac_f32_e32 v234, v55, v215
	v_fmac_f32_e32 v235, v48, v216
	v_fmac_f32_e32 v235, v49, v217
	v_fmac_f32_e32 v235, v50, v218
	v_fmac_f32_e32 v235, v51, v219
	v_fmac_f32_e32 v235, v52, v220
	v_fmac_f32_e32 v235, v53, v221
	v_fmac_f32_e32 v235, v54, v222
	v_fmac_f32_e32 v235, v55, v223
	v_fmac_f32_e32 v236, v56, v192
	v_fmac_f32_e32 v236, v57, v193
	v_fmac_f32_e32 v236, v58, v194
	v_fmac_f32_e32 v236, v59, v195
	v_fmac_f32_e32 v236, v60, v196
	v_fmac_f32_e32 v236, v61, v197
	v_fmac_f32_e32 v236, v62, v198
	v_fmac_f32_e32 v236, v63, v199
	v_fmac_f32_e32 v237, v56, v200
	v_fmac_f32_e32 v237, v57, v201
	v_fmac_f32_e32 v237, v58, v202
	v_fmac_f32_e32 v237, v59, v203
	v_fmac_f32_e32 v237, v60, v204
	v_fmac_f32_e32 v237, v61, v205
	v_fmac_f32_e32 v237, v62, v206
	v_fmac_f32_e32 v237, v63, v207
	v_fmac_f32_e32 v238, v56, v208
	v_fmac_f32_e32 v238, v57, v209
	v_fmac_f32_e32 v238, v58, v210
	v_fmac_f32_e32 v238, v59, v211
	v_fmac_f32_e32 v238, v60, v212
	v_fmac_f32_e32 v238, v61, v213
	v_fmac_f32_e32 v238, v62, v214
	v_fmac_f32_e32 v238, v63, v215
	v_fmac_f32_e32 v239, v56, v216
	v_fmac_f32_e32 v239, v57, v217
	v_fmac_f32_e32 v239, v58, v218
	v_fmac_f32_e32 v239, v59, v219
	v_fmac_f32_e32 v239, v60, v220
	v_fmac_f32_e32 v239, v61, v221
	v_fmac_f32_e32 v239, v62, v222
	v_fmac_f32_e32 v239, v63, v223
	global_load_dwordx4 v[32:35], v240, s[10:11] offset:160
	global_load_dwordx4 v[36:39], v240, s[10:11] offset:176
	global_load_dwordx4 v[40:43], v241, s[10:11] offset:160
	global_load_dwordx4 v[44:47], v241, s[10:11] offset:176
	global_load_dwordx4 v[48:51], v242, s[10:11] offset:160
	global_load_dwordx4 v[52:55], v242, s[10:11] offset:176
	global_load_dwordx4 v[56:59], v243, s[10:11] offset:160
	global_load_dwordx4 v[60:63], v243, s[10:11] offset:176
	s_waitcnt vmcnt(24)
	ds_read_b128 v[192:195], v244 offset:64
	ds_read_b128 v[196:199], v244 offset:80
	ds_read_b128 v[200:203], v244 offset:1088
	ds_read_b128 v[204:207], v244 offset:1104
	ds_read_b128 v[208:211], v244 offset:2112
	ds_read_b128 v[212:215], v244 offset:2128
	ds_read_b128 v[216:219], v244 offset:3136
	ds_read_b128 v[220:223], v244 offset:3152
	s_waitcnt lgkmcnt(0)
; DI void mem_attn_sample_wave(const Params& p, int item, float* lds) {
;     ...
;   float sc[4][4];
; #pragma unroll
;   for (int mi = 0; mi < 4; ++mi) {
;     const int m = lane + 64 * mi;
;     const float* kr = &p.cache_mem[(((size_t)b * 256 + m) * 2 + 0) * 1024 + h * 256];
;     float d0 = 0.f, d1 = 0.f, d2 = 0.f, d3 = 0.f;
; #pragma unroll 2
;     for (int c = 0; c < 256; c += 4) {
;       float4 kv = *(const float4*)&kr[c];
;       float4 q0 = *(const float4*)&sq[c], q1 = *(const float4*)&sq[256 + c], q2 = *(const float4*)&sq[512 + c], q3 = *(const float4*)&sq[768 + c];
;       d0 += kv.x * q0.x + kv.y * q0.y + kv.z * q0.z + kv.w * q0.w;
;       d1 += kv.x * q1.x + kv.y * q1.y + kv.z * q1.z + kv.w * q1.w;
;       d2 += kv.x * q2.x + kv.y * q2.y + kv.z * q2.z + kv.w * q2.w;
;       d3 += kv.x * q3.x + kv.y * q3.y + kv.z * q3.z + kv.w * q3.w;
;     }
;     sc[0][mi] = d0 * 0.0625f; sc[1][mi] = d1 * 0.0625f; sc[2][mi] = d2 * 0.0625f; sc[3][mi] = d3 * 0.0625f;
;   }
	v_fmac_f32_e32 v224, v64, v192
	v_fmac_f32_e32 v224, v65, v193
	v_fmac_f32_e32 v224, v66, v194
	v_fmac_f32_e32 v224, v67, v195
	v_fmac_f32_e32 v224, v68, v196
	v_fmac_f32_e32 v224, v69, v197
	v_fmac_f32_e32 v224, v70, v198
	v_fmac_f32_e32 v224, v71, v199
	v_fmac_f32_e32 v225, v64, v200
	v_fmac_f32_e32 v225, v65, v201
	v_fmac_f32_e32 v225, v66, v202
	v_fmac_f32_e32 v225, v67, v203
	v_fmac_f32_e32 v225, v68, v204
	v_fmac_f32_e32 v225, v69, v205
	v_fmac_f32_e32 v225, v70, v206
	v_fmac_f32_e32 v225, v71, v207
	v_fmac_f32_e32 v226, v64, v208
	v_fmac_f32_e32 v226, v65, v209
	v_fmac_f32_e32 v226, v66, v210
	v_fmac_f32_e32 v226, v67, v211
	v_fmac_f32_e32 v226, v68, v212
	v_fmac_f32_e32 v226, v69, v213
	v_fmac_f32_e32 v226, v70, v214
	v_fmac_f32_e32 v226, v71, v215
	v_fmac_f32_e32 v227, v64, v216
	v_fmac_f32_e32 v227, v65, v217
	v_fmac_f32_e32 v227, v66, v218
	v_fmac_f32_e32 v227, v67, v219
	v_fmac_f32_e32 v227, v68, v220
	v_fmac_f32_e32 v227, v69, v221
	v_fmac_f32_e32 v227, v70, v222
	v_fmac_f32_e32 v227, v71, v223
	v_fmac_f32_e32 v228, v72, v192
	v_fmac_f32_e32 v228, v73, v193
	v_fmac_f32_e32 v228, v74, v194
	v_fmac_f32_e32 v228, v75, v195
	v_fmac_f32_e32 v228, v76, v196
	v_fmac_f32_e32 v228, v77, v197
	v_fmac_f32_e32 v228, v78, v198
	v_fmac_f32_e32 v228, v79, v199
	v_fmac_f32_e32 v229, v72, v200
	v_fmac_f32_e32 v229, v73, v201
	v_fmac_f32_e32 v229, v74, v202
	v_fmac_f32_e32 v229, v75, v203
	v_fmac_f32_e32 v229, v76, v204
	v_fmac_f32_e32 v229, v77, v205
	v_fmac_f32_e32 v229, v78, v206
	v_fmac_f32_e32 v229, v79, v207
	v_fmac_f32_e32 v230, v72, v208
	v_fmac_f32_e32 v230, v73, v209
	v_fmac_f32_e32 v230, v74, v210
	v_fmac_f32_e32 v230, v75, v211
	v_fmac_f32_e32 v230, v76, v212
	v_fmac_f32_e32 v230, v77, v213
	v_fmac_f32_e32 v230, v78, v214
	v_fmac_f32_e32 v230, v79, v215
	v_fmac_f32_e32 v231, v72, v216
	v_fmac_f32_e32 v231, v73, v217
	v_fmac_f32_e32 v231, v74, v218
	v_fmac_f32_e32 v231, v75, v219
	v_fmac_f32_e32 v231, v76, v220
	v_fmac_f32_e32 v231, v77, v221
	v_fmac_f32_e32 v231, v78, v222
	v_fmac_f32_e32 v231, v79, v223
	v_fmac_f32_e32 v232, v80, v192
	v_fmac_f32_e32 v232, v81, v193
	v_fmac_f32_e32 v232, v82, v194
	v_fmac_f32_e32 v232, v83, v195
	v_fmac_f32_e32 v232, v84, v196
	v_fmac_f32_e32 v232, v85, v197
	v_fmac_f32_e32 v232, v86, v198
	v_fmac_f32_e32 v232, v87, v199
	v_fmac_f32_e32 v233, v80, v200
	v_fmac_f32_e32 v233, v81, v201
	v_fmac_f32_e32 v233, v82, v202
	v_fmac_f32_e32 v233, v83, v203
	v_fmac_f32_e32 v233, v84, v204
	v_fmac_f32_e32 v233, v85, v205
	v_fmac_f32_e32 v233, v86, v206
	v_fmac_f32_e32 v233, v87, v207
	v_fmac_f32_e32 v234, v80, v208
	v_fmac_f32_e32 v234, v81, v209
	v_fmac_f32_e32 v234, v82, v210
	v_fmac_f32_e32 v234, v83, v211
	v_fmac_f32_e32 v234, v84, v212
	v_fmac_f32_e32 v234, v85, v213
	v_fmac_f32_e32 v234, v86, v214
	v_fmac_f32_e32 v234, v87, v215
	v_fmac_f32_e32 v235, v80, v216
	v_fmac_f32_e32 v235, v81, v217
	v_fmac_f32_e32 v235, v82, v218
	v_fmac_f32_e32 v235, v83, v219
	v_fmac_f32_e32 v235, v84, v220
	v_fmac_f32_e32 v235, v85, v221
	v_fmac_f32_e32 v235, v86, v222
	v_fmac_f32_e32 v235, v87, v223
	v_fmac_f32_e32 v236, v88, v192
	v_fmac_f32_e32 v236, v89, v193
	v_fmac_f32_e32 v236, v90, v194
	v_fmac_f32_e32 v236, v91, v195
	v_fmac_f32_e32 v236, v92, v196
	v_fmac_f32_e32 v236, v93, v197
	v_fmac_f32_e32 v236, v94, v198
	v_fmac_f32_e32 v236, v95, v199
	v_fmac_f32_e32 v237, v88, v200
	v_fmac_f32_e32 v237, v89, v201
	v_fmac_f32_e32 v237, v90, v202
	v_fmac_f32_e32 v237, v91, v203
	v_fmac_f32_e32 v237, v92, v204
	v_fmac_f32_e32 v237, v93, v205
	v_fmac_f32_e32 v237, v94, v206
	v_fmac_f32_e32 v237, v95, v207
	v_fmac_f32_e32 v238, v88, v208
	v_fmac_f32_e32 v238, v89, v209
	v_fmac_f32_e32 v238, v90, v210
	v_fmac_f32_e32 v238, v91, v211
	v_fmac_f32_e32 v238, v92, v212
	v_fmac_f32_e32 v238, v93, v213
	v_fmac_f32_e32 v238, v94, v214
	v_fmac_f32_e32 v238, v95, v215
	v_fmac_f32_e32 v239, v88, v216
	v_fmac_f32_e32 v239, v89, v217
	v_fmac_f32_e32 v239, v90, v218
	v_fmac_f32_e32 v239, v91, v219
	v_fmac_f32_e32 v239, v92, v220
	v_fmac_f32_e32 v239, v93, v221
	v_fmac_f32_e32 v239, v94, v222
	v_fmac_f32_e32 v239, v95, v223
	global_load_dwordx4 v[64:67], v240, s[10:11] offset:192
	global_load_dwordx4 v[68:71], v240, s[10:11] offset:208
	global_load_dwordx4 v[72:75], v241, s[10:11] offset:192
	global_load_dwordx4 v[76:79], v241, s[10:11] offset:208
	global_load_dwordx4 v[80:83], v242, s[10:11] offset:192
	global_load_dwordx4 v[84:87], v242, s[10:11] offset:208
	global_load_dwordx4 v[88:91], v243, s[10:11] offset:192
	global_load_dwordx4 v[92:95], v243, s[10:11] offset:208
	s_waitcnt vmcnt(24)
	ds_read_b128 v[192:195], v244 offset:96
	ds_read_b128 v[196:199], v244 offset:112
	ds_read_b128 v[200:203], v244 offset:1120
	ds_read_b128 v[204:207], v244 offset:1136
	ds_read_b128 v[208:211], v244 offset:2144
	ds_read_b128 v[212:215], v244 offset:2160
	ds_read_b128 v[216:219], v244 offset:3168
	ds_read_b128 v[220:223], v244 offset:3184
	s_waitcnt lgkmcnt(0)
; DI void mem_attn_sample_wave(const Params& p, int item, float* lds) {
;     ...
;   float sc[4][4];
; #pragma unroll
;   for (int mi = 0; mi < 4; ++mi) {
;     const int m = lane + 64 * mi;
;     const float* kr = &p.cache_mem[(((size_t)b * 256 + m) * 2 + 0) * 1024 + h * 256];
;     float d0 = 0.f, d1 = 0.f, d2 = 0.f, d3 = 0.f;
; #pragma unroll 2
;     for (int c = 0; c < 256; c += 4) {
;       float4 kv = *(const float4*)&kr[c];
;       float4 q0 = *(const float4*)&sq[c], q1 = *(const float4*)&sq[256 + c], q2 = *(const float4*)&sq[512 + c], q3 = *(const float4*)&sq[768 + c];
;       d0 += kv.x * q0.x + kv.y * q0.y + kv.z * q0.z + kv.w * q0.w;
;       d1 += kv.x * q1.x + kv.y * q1.y + kv.z * q1.z + kv.w * q1.w;
;       d2 += kv.x * q2.x + kv.y * q2.y + kv.z * q2.z + kv.w * q2.w;
;       d3 += kv.x * q3.x + kv.y * q3.y + kv.z * q3.z + kv.w * q3.w;
;     }
;     sc[0][mi] = d0 * 0.0625f; sc[1][mi] = d1 * 0.0625f; sc[2][mi] = d2 * 0.0625f; sc[3][mi] = d3 * 0.0625f;
;   }
	v_fmac_f32_e32 v224, v96, v192
	v_fmac_f32_e32 v224, v97, v193
	v_fmac_f32_e32 v224, v98, v194
	v_fmac_f32_e32 v224, v99, v195
	v_fmac_f32_e32 v224, v100, v196
	v_fmac_f32_e32 v224, v101, v197
	v_fmac_f32_e32 v224, v102, v198
	v_fmac_f32_e32 v224, v103, v199
	v_fmac_f32_e32 v225, v96, v200
	v_fmac_f32_e32 v225, v97, v201
	v_fmac_f32_e32 v225, v98, v202
	v_fmac_f32_e32 v225, v99, v203
	v_fmac_f32_e32 v225, v100, v204
	v_fmac_f32_e32 v225, v101, v205
	v_fmac_f32_e32 v225, v102, v206
	v_fmac_f32_e32 v225, v103, v207
	v_fmac_f32_e32 v226, v96, v208
	v_fmac_f32_e32 v226, v97, v209
	v_fmac_f32_e32 v226, v98, v210
	v_fmac_f32_e32 v226, v99, v211
	v_fmac_f32_e32 v226, v100, v212
	v_fmac_f32_e32 v226, v101, v213
	v_fmac_f32_e32 v226, v102, v214
	v_fmac_f32_e32 v226, v103, v215
	v_fmac_f32_e32 v227, v96, v216
	v_fmac_f32_e32 v227, v97, v217
	v_fmac_f32_e32 v227, v98, v218
	v_fmac_f32_e32 v227, v99, v219
	v_fmac_f32_e32 v227, v100, v220
	v_fmac_f32_e32 v227, v101, v221
	v_fmac_f32_e32 v227, v102, v222
	v_fmac_f32_e32 v227, v103, v223
	v_fmac_f32_e32 v228, v104, v192
	v_fmac_f32_e32 v228, v105, v193
	v_fmac_f32_e32 v228, v106, v194
	v_fmac_f32_e32 v228, v107, v195
	v_fmac_f32_e32 v228, v108, v196
	v_fmac_f32_e32 v228, v109, v197
	v_fmac_f32_e32 v228, v110, v198
	v_fmac_f32_e32 v228, v111, v199
	v_fmac_f32_e32 v229, v104, v200
	v_fmac_f32_e32 v229, v105, v201
	v_fmac_f32_e32 v229, v106, v202
	v_fmac_f32_e32 v229, v107, v203
	v_fmac_f32_e32 v229, v108, v204
	v_fmac_f32_e32 v229, v109, v205
	v_fmac_f32_e32 v229, v110, v206
	v_fmac_f32_e32 v229, v111, v207
	v_fmac_f32_e32 v230, v104, v208
	v_fmac_f32_e32 v230, v105, v209
	v_fmac_f32_e32 v230, v106, v210
	v_fmac_f32_e32 v230, v107, v211
	v_fmac_f32_e32 v230, v108, v212
	v_fmac_f32_e32 v230, v109, v213
	v_fmac_f32_e32 v230, v110, v214
	v_fmac_f32_e32 v230, v111, v215
	v_fmac_f32_e32 v231, v104, v216
	v_fmac_f32_e32 v231, v105, v217
	v_fmac_f32_e32 v231, v106, v218
	v_fmac_f32_e32 v231, v107, v219
	v_fmac_f32_e32 v231, v108, v220
	v_fmac_f32_e32 v231, v109, v221
	v_fmac_f32_e32 v231, v110, v222
	v_fmac_f32_e32 v231, v111, v223
	v_fmac_f32_e32 v232, v112, v192
	v_fmac_f32_e32 v232, v113, v193
	v_fmac_f32_e32 v232, v114, v194
	v_fmac_f32_e32 v232, v115, v195
	v_fmac_f32_e32 v232, v116, v196
	v_fmac_f32_e32 v232, v117, v197
	v_fmac_f32_e32 v232, v118, v198
	v_fmac_f32_e32 v232, v119, v199
	v_fmac_f32_e32 v233, v112, v200
	v_fmac_f32_e32 v233, v113, v201
	v_fmac_f32_e32 v233, v114, v202
	v_fmac_f32_e32 v233, v115, v203
	v_fmac_f32_e32 v233, v116, v204
	v_fmac_f32_e32 v233, v117, v205
	v_fmac_f32_e32 v233, v118, v206
	v_fmac_f32_e32 v233, v119, v207
	v_fmac_f32_e32 v234, v112, v208
	v_fmac_f32_e32 v234, v113, v209
	v_fmac_f32_e32 v234, v114, v210
	v_fmac_f32_e32 v234, v115, v211
	v_fmac_f32_e32 v234, v116, v212
	v_fmac_f32_e32 v234, v117, v213
	v_fmac_f32_e32 v234, v118, v214
	v_fmac_f32_e32 v234, v119, v215
	v_fmac_f32_e32 v235, v112, v216
	v_fmac_f32_e32 v235, v113, v217
	v_fmac_f32_e32 v235, v114, v218
	v_fmac_f32_e32 v235, v115, v219
	v_fmac_f32_e32 v235, v116, v220
	v_fmac_f32_e32 v235, v117, v221
	v_fmac_f32_e32 v235, v118, v222
	v_fmac_f32_e32 v235, v119, v223
	v_fmac_f32_e32 v236, v120, v192
	v_fmac_f32_e32 v236, v121, v193
	v_fmac_f32_e32 v236, v122, v194
	v_fmac_f32_e32 v236, v123, v195
	v_fmac_f32_e32 v236, v124, v196
	v_fmac_f32_e32 v236, v125, v197
	v_fmac_f32_e32 v236, v126, v198
	v_fmac_f32_e32 v236, v127, v199
	v_fmac_f32_e32 v237, v120, v200
	v_fmac_f32_e32 v237, v121, v201
	v_fmac_f32_e32 v237, v122, v202
	v_fmac_f32_e32 v237, v123, v203
	v_fmac_f32_e32 v237, v124, v204
	v_fmac_f32_e32 v237, v125, v205
	v_fmac_f32_e32 v237, v126, v206
	v_fmac_f32_e32 v237, v127, v207
	v_fmac_f32_e32 v238, v120, v208
	v_fmac_f32_e32 v238, v121, v209
	v_fmac_f32_e32 v238, v122, v210
	v_fmac_f32_e32 v238, v123, v211
	v_fmac_f32_e32 v238, v124, v212
	v_fmac_f32_e32 v238, v125, v213
	v_fmac_f32_e32 v238, v126, v214
	v_fmac_f32_e32 v238, v127, v215
	v_fmac_f32_e32 v239, v120, v216
	v_fmac_f32_e32 v239, v121, v217
	v_fmac_f32_e32 v239, v122, v218
	v_fmac_f32_e32 v239, v123, v219
	v_fmac_f32_e32 v239, v124, v220
	v_fmac_f32_e32 v239, v125, v221
	v_fmac_f32_e32 v239, v126, v222
	v_fmac_f32_e32 v239, v127, v223
	s_add_u32 s10, s10, 0x80
	s_addc_u32 s11, s11, 0
	v_add_u32_e32 v244, 0x80, v244
	s_add_i32 s0, s0, 1
	s_cmp_lt_u32 s0, 8
	s_cbranch_scc1 .Lp7s_kloop
; DI void mem_attn_sample_wave(const Params& p, int item, float* lds) {
;     ...
;     sc[0][mi] = d0 * 0.0625f; sc[1][mi] = d1 * 0.0625f; sc[2][mi] = d2 * 0.0625f; sc[3][mi] = d3 * 0.0625f;
;   }
;   float inv[4];
;   __builtin_amdgcn_wave_barrier();
; #pragma unroll
;   for (int t = 0; t < 4; ++t) {
;     float mx = wave_max(fmaxf(fmaxf(sc[t][0], sc[t][1]), fmaxf(sc[t][2], sc[t][3])));
;     float sum = 0.f;
; #pragma unroll
;     for (int mi = 0; mi < 4; ++mi) { sc[t][mi] = __expf(sc[t][mi] - mx); sum += sc[t][mi]; }
;     sum = wave_sum(sum);
;     inv[t] = 1.f / sum;
	s_waitcnt vmcnt(0)
	v_mul_f32_e32 v224, 0x3d800000, v224
	v_mul_f32_e32 v225, 0x3d800000, v225
	v_mul_f32_e32 v226, 0x3d800000, v226
	v_mul_f32_e32 v227, 0x3d800000, v227
	v_mul_f32_e32 v228, 0x3d800000, v228
	v_mul_f32_e32 v229, 0x3d800000, v229
	v_mul_f32_e32 v230, 0x3d800000, v230
	v_mul_f32_e32 v231, 0x3d800000, v231
	v_mul_f32_e32 v232, 0x3d800000, v232
	v_mul_f32_e32 v233, 0x3d800000, v233
	v_mul_f32_e32 v234, 0x3d800000, v234
	v_mul_f32_e32 v235, 0x3d800000, v235
	v_mul_f32_e32 v236, 0x3d800000, v236
	v_mul_f32_e32 v237, 0x3d800000, v237
	v_mul_f32_e32 v238, 0x3d800000, v238
	v_mul_f32_e32 v239, 0x3d800000, v239
	v_max3_f32 v166, v224, v228, v232
	v_max_f32_e32 v166, v166, v236
	v_max3_f32 v167, v225, v229, v233
	v_max_f32_e32 v167, v167, v237
	v_max3_f32 v168, v226, v230, v234
	v_max_f32_e32 v168, v168, v238
	v_max3_f32 v169, v227, v231, v235
	v_max_f32_e32 v169, v169, v239
	ds_bpermute_b32 v158, v152, v166
	ds_bpermute_b32 v159, v152, v167
	ds_bpermute_b32 v160, v152, v168
	ds_bpermute_b32 v161, v152, v169
	s_waitcnt lgkmcnt(0)
	v_max_f32_e32 v166, v166, v158
	v_max_f32_e32 v167, v167, v159
	v_max_f32_e32 v168, v168, v160
	v_max_f32_e32 v169, v169, v161
	ds_bpermute_b32 v158, v153, v166
	ds_bpermute_b32 v159, v153, v167
	ds_bpermute_b32 v160, v153, v168
	ds_bpermute_b32 v161, v153, v169
	s_waitcnt lgkmcnt(0)
	v_max_f32_e32 v166, v166, v158
	v_max_f32_e32 v167, v167, v159
	v_max_f32_e32 v168, v168, v160
	v_max_f32_e32 v169, v169, v161
	ds_bpermute_b32 v158, v154, v166
	ds_bpermute_b32 v159, v154, v167
	ds_bpermute_b32 v160, v154, v168
	ds_bpermute_b32 v161, v154, v169
	s_waitcnt lgkmcnt(0)
	v_max_f32_e32 v166, v166, v158
	v_max_f32_e32 v167, v167, v159
	v_max_f32_e32 v168, v168, v160
	v_max_f32_e32 v169, v169, v161
	ds_bpermute_b32 v158, v155, v166
	ds_bpermute_b32 v159, v155, v167
	ds_bpermute_b32 v160, v155, v168
	ds_bpermute_b32 v161, v155, v169
	s_waitcnt lgkmcnt(0)
	v_max_f32_e32 v166, v166, v158
	v_max_f32_e32 v167, v167, v159
	v_max_f32_e32 v168, v168, v160
	v_max_f32_e32 v169, v169, v161
	ds_bpermute_b32 v158, v156, v166
	ds_bpermute_b32 v159, v156, v167
	ds_bpermute_b32 v160, v156, v168
	ds_bpermute_b32 v161, v156, v169
	s_waitcnt lgkmcnt(0)
	v_max_f32_e32 v166, v166, v158
	v_max_f32_e32 v167, v167, v159
	v_max_f32_e32 v168, v168, v160
	v_max_f32_e32 v169, v169, v161
	ds_bpermute_b32 v158, v157, v166
	ds_bpermute_b32 v159, v157, v167
	ds_bpermute_b32 v160, v157, v168
	ds_bpermute_b32 v161, v157, v169
	s_waitcnt lgkmcnt(0)
	v_max_f32_e32 v166, v166, v158
	v_max_f32_e32 v167, v167, v159
	v_max_f32_e32 v168, v168, v160
	v_max_f32_e32 v169, v169, v161
	v_sub_f32_e32 v224, v224, v166
	v_sub_f32_e32 v225, v225, v167
	v_sub_f32_e32 v226, v226, v168
	v_sub_f32_e32 v227, v227, v169
	v_sub_f32_e32 v228, v228, v166
	v_sub_f32_e32 v229, v229, v167
	v_sub_f32_e32 v230, v230, v168
	v_sub_f32_e32 v231, v231, v169
	v_sub_f32_e32 v232, v232, v166
	v_sub_f32_e32 v233, v233, v167
	v_sub_f32_e32 v234, v234, v168
	v_sub_f32_e32 v235, v235, v169
	v_sub_f32_e32 v236, v236, v166
	v_sub_f32_e32 v237, v237, v167
	v_sub_f32_e32 v238, v238, v168
	v_sub_f32_e32 v239, v239, v169
	v_mul_f32_e32 v224, 0x3fb8aa3b, v224
	v_mul_f32_e32 v225, 0x3fb8aa3b, v225
	v_mul_f32_e32 v226, 0x3fb8aa3b, v226
	v_mul_f32_e32 v227, 0x3fb8aa3b, v227
	v_mul_f32_e32 v228, 0x3fb8aa3b, v228
	v_mul_f32_e32 v229, 0x3fb8aa3b, v229
	v_mul_f32_e32 v230, 0x3fb8aa3b, v230
	v_mul_f32_e32 v231, 0x3fb8aa3b, v231
	v_mul_f32_e32 v232, 0x3fb8aa3b, v232
	v_mul_f32_e32 v233, 0x3fb8aa3b, v233
	v_mul_f32_e32 v234, 0x3fb8aa3b, v234
	v_mul_f32_e32 v235, 0x3fb8aa3b, v235
	v_mul_f32_e32 v236, 0x3fb8aa3b, v236
	v_mul_f32_e32 v237, 0x3fb8aa3b, v237
	v_mul_f32_e32 v238, 0x3fb8aa3b, v238
	v_mul_f32_e32 v239, 0x3fb8aa3b, v239
	v_exp_f32_e32 v224, v224
	v_exp_f32_e32 v225, v225
	v_exp_f32_e32 v226, v226
	v_exp_f32_e32 v227, v227
	v_exp_f32_e32 v228, v228
	v_exp_f32_e32 v229, v229
	v_exp_f32_e32 v230, v230
	v_exp_f32_e32 v231, v231
	v_exp_f32_e32 v232, v232
	v_exp_f32_e32 v233, v233
	v_exp_f32_e32 v234, v234
	v_exp_f32_e32 v235, v235
	v_exp_f32_e32 v236, v236
	v_exp_f32_e32 v237, v237
	v_exp_f32_e32 v238, v238
	v_exp_f32_e32 v239, v239
	s_nop 0
	v_add_f32_e32 v172, v224, v228
	v_add_f32_e32 v158, v232, v236
	v_add_f32_e32 v173, v225, v229
	v_add_f32_e32 v159, v233, v237
	v_add_f32_e32 v176, v226, v230
	v_add_f32_e32 v160, v234, v238
	v_add_f32_e32 v140, v227, v231
	v_add_f32_e32 v161, v235, v239
	v_add_f32_e32 v172, v172, v158
	v_add_f32_e32 v173, v173, v159
	v_add_f32_e32 v176, v176, v160
	v_add_f32_e32 v140, v140, v161
	ds_bpermute_b32 v158, v152, v172
	ds_bpermute_b32 v159, v152, v173
	ds_bpermute_b32 v160, v152, v176
	ds_bpermute_b32 v161, v152, v140
	s_waitcnt lgkmcnt(0)
	v_add_f32_e32 v172, v172, v158
	v_add_f32_e32 v173, v173, v159
	v_add_f32_e32 v176, v176, v160
	v_add_f32_e32 v140, v140, v161
	ds_bpermute_b32 v158, v153, v172
	ds_bpermute_b32 v159, v153, v173
	ds_bpermute_b32 v160, v153, v176
	ds_bpermute_b32 v161, v153, v140
	s_waitcnt lgkmcnt(0)
	v_add_f32_e32 v172, v172, v158
	v_add_f32_e32 v173, v173, v159
	v_add_f32_e32 v176, v176, v160
	v_add_f32_e32 v140, v140, v161
	ds_bpermute_b32 v158, v154, v172
	ds_bpermute_b32 v159, v154, v173
	ds_bpermute_b32 v160, v154, v176
	ds_bpermute_b32 v161, v154, v140
	s_waitcnt lgkmcnt(0)
	v_add_f32_e32 v172, v172, v158
	v_add_f32_e32 v173, v173, v159
	v_add_f32_e32 v176, v176, v160
	v_add_f32_e32 v140, v140, v161
	ds_bpermute_b32 v158, v155, v172
	ds_bpermute_b32 v159, v155, v173
	ds_bpermute_b32 v160, v155, v176
	ds_bpermute_b32 v161, v155, v140
	s_waitcnt lgkmcnt(0)
; DI void mem_attn_sample_wave(const Params& p, int item, float* lds) {
;     ...
;     float mx = wave_max(fmaxf(fmaxf(sc[t][0], sc[t][1]), fmaxf(sc[t][2], sc[t][3])));
;     float sum = 0.f;
; #pragma unroll
;     for (int mi = 0; mi < 4; ++mi) { sc[t][mi] = __expf(sc[t][mi] - mx); sum += sc[t][mi]; }
;     sum = wave_sum(sum);
;     inv[t] = 1.f / sum;
; #pragma unroll
;     for (int mi = 0; mi < 4; ++mi) sq[t * 256 + lane + 64 * mi] = sc[t][mi];
;   }
;   __builtin_amdgcn_s_waitcnt(0);
;   __builtin_amdgcn_wave_barrier();
;   float4 o[4];
; #pragma unroll
;   for (int t = 0; t < 4; ++t) o[t] = make_float4(0.f, 0.f, 0.f, 0.f);
; #pragma unroll 4
;   for (int m = 0; m < 256; ++m) {
;     float4 vv = *(const float4*)&p.cache_mem[(((size_t)b * 256 + m) * 2 + 1) * 1024 + h * 256 + lane * 4];
	v_add_f32_e32 v172, v172, v158
	v_add_f32_e32 v173, v173, v159
	v_add_f32_e32 v176, v176, v160
	v_add_f32_e32 v140, v140, v161
	ds_bpermute_b32 v158, v156, v172
	ds_bpermute_b32 v159, v156, v173
	ds_bpermute_b32 v160, v156, v176
	ds_bpermute_b32 v161, v156, v140
	s_waitcnt lgkmcnt(0)
	v_add_f32_e32 v172, v172, v158
	v_add_f32_e32 v173, v173, v159
	v_add_f32_e32 v176, v176, v160
	v_add_f32_e32 v140, v140, v161
	ds_bpermute_b32 v158, v157, v172
	ds_bpermute_b32 v159, v157, v173
	ds_bpermute_b32 v160, v157, v176
	ds_bpermute_b32 v161, v157, v140
	s_waitcnt lgkmcnt(0)
	v_add_f32_e32 v172, v172, v158
	v_add_f32_e32 v173, v173, v159
	v_add_f32_e32 v176, v176, v160
	v_add_f32_e32 v140, v140, v161
	v_add_u32_e32 v244, v251, v252
	ds_write_b128 v244, v[224:227] offset:0
	ds_write_b128 v244, v[228:231] offset:1024
	ds_write_b128 v244, v[232:235] offset:2048
	ds_write_b128 v244, v[236:239] offset:3072
	v_div_scale_f32 v192, s[98:99], v172, v172, 1.0
	v_rcp_f32_e32 v193, v192
	s_nop 0
	v_fma_f32 v194, -v192, v193, 1.0
	v_fmac_f32_e32 v193, v194, v193
	v_div_scale_f32 v194, vcc, 1.0, v172, 1.0
	v_mul_f32_e32 v195, v194, v193
	v_fma_f32 v196, -v192, v195, v194
	v_fmac_f32_e32 v195, v196, v193
	v_fma_f32 v194, -v192, v195, v194
	s_nop 1
	v_div_fmas_f32 v194, v194, v193, v195
	v_div_fixup_f32 v141, v194, v172, 1.0
	v_div_scale_f32 v192, s[98:99], v173, v173, 1.0
	v_rcp_f32_e32 v193, v192
	s_nop 0
	v_fma_f32 v194, -v192, v193, 1.0
	v_fmac_f32_e32 v193, v194, v193
	v_div_scale_f32 v194, vcc, 1.0, v173, 1.0
	v_mul_f32_e32 v195, v194, v193
	v_fma_f32 v196, -v192, v195, v194
	v_fmac_f32_e32 v195, v196, v193
	v_fma_f32 v194, -v192, v195, v194
	s_nop 1
	v_div_fmas_f32 v194, v194, v193, v195
	v_div_fixup_f32 v142, v194, v173, 1.0
	v_div_scale_f32 v192, s[98:99], v176, v176, 1.0
	v_rcp_f32_e32 v193, v192
	s_nop 0
	v_fma_f32 v194, -v192, v193, 1.0
	v_fmac_f32_e32 v193, v194, v193
	v_div_scale_f32 v194, vcc, 1.0, v176, 1.0
	v_mul_f32_e32 v195, v194, v193
	v_fma_f32 v196, -v192, v195, v194
	v_fmac_f32_e32 v195, v196, v193
	v_fma_f32 v194, -v192, v195, v194
	s_nop 1
	v_div_fmas_f32 v194, v194, v193, v195
	v_div_fixup_f32 v253, v194, v176, 1.0
	v_div_scale_f32 v192, s[98:99], v140, v140, 1.0
	v_rcp_f32_e32 v193, v192
	s_nop 0
	v_fma_f32 v194, -v192, v193, 1.0
	v_fmac_f32_e32 v193, v194, v193
	v_div_scale_f32 v194, vcc, 1.0, v140, 1.0
	v_mul_f32_e32 v195, v194, v193
	v_fma_f32 v196, -v192, v195, v194
	v_fmac_f32_e32 v195, v196, v193
	v_fma_f32 v194, -v192, v195, v194
	s_nop 1
	v_div_fmas_f32 v194, v194, v193, v195
	v_div_fixup_f32 v254, v194, v140, 1.0
	s_waitcnt lgkmcnt(0)
	s_mov_b32 s25, 0
	s_min_u32 s24, s25, 31
	s_lshl_b32 s24, s24, 16
	s_add_u32 s98, s12, s24
	s_addc_u32 s99, s13, 0
	global_load_dwordx4 v[0:3], v144, s[98:99]
	global_load_dwordx4 v[4:7], v145, s[98:99]
	global_load_dwordx4 v[8:11], v146, s[98:99]
	global_load_dwordx4 v[12:15], v147, s[98:99]
	global_load_dwordx4 v[16:19], v148, s[98:99]
	global_load_dwordx4 v[20:23], v149, s[98:99]
	global_load_dwordx4 v[24:27], v150, s[98:99]
	global_load_dwordx4 v[28:31], v151, s[98:99]
	s_mov_b32 s25, 1
	s_min_u32 s24, s25, 31
	s_lshl_b32 s24, s24, 16
	s_add_u32 s98, s12, s24
	s_addc_u32 s99, s13, 0
	global_load_dwordx4 v[32:35], v144, s[98:99]
	global_load_dwordx4 v[36:39], v145, s[98:99]
	global_load_dwordx4 v[40:43], v146, s[98:99]
	global_load_dwordx4 v[44:47], v147, s[98:99]
	global_load_dwordx4 v[48:51], v148, s[98:99]
	global_load_dwordx4 v[52:55], v149, s[98:99]
	global_load_dwordx4 v[56:59], v150, s[98:99]
	global_load_dwordx4 v[60:63], v151, s[98:99]
	s_mov_b32 s25, 2
	s_min_u32 s24, s25, 31
	s_lshl_b32 s24, s24, 16
	s_add_u32 s98, s12, s24
	s_addc_u32 s99, s13, 0
	global_load_dwordx4 v[64:67], v144, s[98:99]
	global_load_dwordx4 v[68:71], v145, s[98:99]
	global_load_dwordx4 v[72:75], v146, s[98:99]
	global_load_dwordx4 v[76:79], v147, s[98:99]
	global_load_dwordx4 v[80:83], v148, s[98:99]
	global_load_dwordx4 v[84:87], v149, s[98:99]
	global_load_dwordx4 v[88:91], v150, s[98:99]
	global_load_dwordx4 v[92:95], v151, s[98:99]
	v_mov_b32_e32 v224, 0
	v_mov_b32_e32 v225, 0
	v_mov_b32_e32 v226, 0
	v_mov_b32_e32 v227, 0
	v_mov_b32_e32 v228, 0
	v_mov_b32_e32 v229, 0
	v_mov_b32_e32 v230, 0
	v_mov_b32_e32 v231, 0
	v_mov_b32_e32 v232, 0
	v_mov_b32_e32 v233, 0
	v_mov_b32_e32 v234, 0
	v_mov_b32_e32 v235, 0
	v_mov_b32_e32 v236, 0
	v_mov_b32_e32 v237, 0
	v_mov_b32_e32 v238, 0
	v_mov_b32_e32 v239, 0
	v_mov_b32_e32 v244, v251
	s_mov_b32 s0, 0
; DI void mem_attn_sample_wave(const Params& p, int item, float* lds) {
;     ...
;   float4 o[4];
; #pragma unroll
;   for (int t = 0; t < 4; ++t) o[t] = make_float4(0.f, 0.f, 0.f, 0.f);
; #pragma unroll 4
;   for (int m = 0; m < 256; ++m) {
;     float4 vv = *(const float4*)&p.cache_mem[(((size_t)b * 256 + m) * 2 + 1) * 1024 + h * 256 + lane * 4];
; #pragma unroll
;     for (int t = 0; t < 4; ++t) {
;       const float pv = sq[t * 256 + m];
;       o[t].x += pv * vv.x; o[t].y += pv * vv.y; o[t].z += pv * vv.z; o[t].w += pv * vv.w;
;     }
;   }
.Lp7s_vloop:
	s_add_i32 s25, s0, 3
	s_min_u32 s24, s25, 31
	s_lshl_b32 s24, s24, 16
	s_add_u32 s98, s12, s24
	s_addc_u32 s99, s13, 0
	global_load_dwordx4 v[96:99], v144, s[98:99]
	global_load_dwordx4 v[100:103], v145, s[98:99]
	global_load_dwordx4 v[104:107], v146, s[98:99]
	global_load_dwordx4 v[108:111], v147, s[98:99]
	global_load_dwordx4 v[112:115], v148, s[98:99]
	global_load_dwordx4 v[116:119], v149, s[98:99]
	global_load_dwordx4 v[120:123], v150, s[98:99]
	global_load_dwordx4 v[124:127], v151, s[98:99]
	s_waitcnt vmcnt(24)
	ds_read_b128 v[192:195], v244 offset:0
	ds_read_b128 v[196:199], v244 offset:16
	ds_read_b128 v[200:203], v244 offset:32
	ds_read_b128 v[204:207], v244 offset:48
	ds_read_b128 v[208:211], v244 offset:64
	ds_read_b128 v[212:215], v244 offset:80
	ds_read_b128 v[216:219], v244 offset:96
	ds_read_b128 v[220:223], v244 offset:112
	s_waitcnt lgkmcnt(0)
	v_fmac_f32_e32 v224, v192, v0
	v_fmac_f32_e32 v225, v192, v1
	v_fmac_f32_e32 v226, v192, v2
	v_fmac_f32_e32 v227, v192, v3
	v_fmac_f32_e32 v228, v193, v0
	v_fmac_f32_e32 v229, v193, v1
	v_fmac_f32_e32 v230, v193, v2
	v_fmac_f32_e32 v231, v193, v3
	v_fmac_f32_e32 v232, v194, v0
	v_fmac_f32_e32 v233, v194, v1
	v_fmac_f32_e32 v234, v194, v2
	v_fmac_f32_e32 v235, v194, v3
	v_fmac_f32_e32 v236, v195, v0
	v_fmac_f32_e32 v237, v195, v1
	v_fmac_f32_e32 v238, v195, v2
	v_fmac_f32_e32 v239, v195, v3
	v_fmac_f32_e32 v224, v196, v4
	v_fmac_f32_e32 v225, v196, v5
	v_fmac_f32_e32 v226, v196, v6
	v_fmac_f32_e32 v227, v196, v7
	v_fmac_f32_e32 v228, v197, v4
	v_fmac_f32_e32 v229, v197, v5
	v_fmac_f32_e32 v230, v197, v6
	v_fmac_f32_e32 v231, v197, v7
	v_fmac_f32_e32 v232, v198, v4
	v_fmac_f32_e32 v233, v198, v5
	v_fmac_f32_e32 v234, v198, v6
	v_fmac_f32_e32 v235, v198, v7
	v_fmac_f32_e32 v236, v199, v4
	v_fmac_f32_e32 v237, v199, v5
	v_fmac_f32_e32 v238, v199, v6
	v_fmac_f32_e32 v239, v199, v7
	v_fmac_f32_e32 v224, v200, v8
	v_fmac_f32_e32 v225, v200, v9
	v_fmac_f32_e32 v226, v200, v10
	v_fmac_f32_e32 v227, v200, v11
	v_fmac_f32_e32 v228, v201, v8
	v_fmac_f32_e32 v229, v201, v9
	v_fmac_f32_e32 v230, v201, v10
	v_fmac_f32_e32 v231, v201, v11
	v_fmac_f32_e32 v232, v202, v8
	v_fmac_f32_e32 v233, v202, v9
	v_fmac_f32_e32 v234, v202, v10
	v_fmac_f32_e32 v235, v202, v11
	v_fmac_f32_e32 v236, v203, v8
	v_fmac_f32_e32 v237, v203, v9
	v_fmac_f32_e32 v238, v203, v10
	v_fmac_f32_e32 v239, v203, v11
	v_fmac_f32_e32 v224, v204, v12
	v_fmac_f32_e32 v225, v204, v13
	v_fmac_f32_e32 v226, v204, v14
	v_fmac_f32_e32 v227, v204, v15
	v_fmac_f32_e32 v228, v205, v12
	v_fmac_f32_e32 v229, v205, v13
	v_fmac_f32_e32 v230, v205, v14
	v_fmac_f32_e32 v231, v205, v15
	v_fmac_f32_e32 v232, v206, v12
	v_fmac_f32_e32 v233, v206, v13
	v_fmac_f32_e32 v234, v206, v14
	v_fmac_f32_e32 v235, v206, v15
	v_fmac_f32_e32 v236, v207, v12
	v_fmac_f32_e32 v237, v207, v13
	v_fmac_f32_e32 v238, v207, v14
	v_fmac_f32_e32 v239, v207, v15
	v_fmac_f32_e32 v224, v208, v16
	v_fmac_f32_e32 v225, v208, v17
	v_fmac_f32_e32 v226, v208, v18
	v_fmac_f32_e32 v227, v208, v19
	v_fmac_f32_e32 v228, v209, v16
	v_fmac_f32_e32 v229, v209, v17
	v_fmac_f32_e32 v230, v209, v18
	v_fmac_f32_e32 v231, v209, v19
	v_fmac_f32_e32 v232, v210, v16
	v_fmac_f32_e32 v233, v210, v17
	v_fmac_f32_e32 v234, v210, v18
	v_fmac_f32_e32 v235, v210, v19
	v_fmac_f32_e32 v236, v211, v16
	v_fmac_f32_e32 v237, v211, v17
	v_fmac_f32_e32 v238, v211, v18
	v_fmac_f32_e32 v239, v211, v19
	v_fmac_f32_e32 v224, v212, v20
	v_fmac_f32_e32 v225, v212, v21
	v_fmac_f32_e32 v226, v212, v22
	v_fmac_f32_e32 v227, v212, v23
	v_fmac_f32_e32 v228, v213, v20
	v_fmac_f32_e32 v229, v213, v21
	v_fmac_f32_e32 v230, v213, v22
	v_fmac_f32_e32 v231, v213, v23
	v_fmac_f32_e32 v232, v214, v20
	v_fmac_f32_e32 v233, v214, v21
	v_fmac_f32_e32 v234, v214, v22
	v_fmac_f32_e32 v235, v214, v23
	v_fmac_f32_e32 v236, v215, v20
	v_fmac_f32_e32 v237, v215, v21
	v_fmac_f32_e32 v238, v215, v22
	v_fmac_f32_e32 v239, v215, v23
	v_fmac_f32_e32 v224, v216, v24
	v_fmac_f32_e32 v225, v216, v25
	v_fmac_f32_e32 v226, v216, v26
	v_fmac_f32_e32 v227, v216, v27
	v_fmac_f32_e32 v228, v217, v24
	v_fmac_f32_e32 v229, v217, v25
	v_fmac_f32_e32 v230, v217, v26
	v_fmac_f32_e32 v231, v217, v27
	v_fmac_f32_e32 v232, v218, v24
	v_fmac_f32_e32 v233, v218, v25
	v_fmac_f32_e32 v234, v218, v26
	v_fmac_f32_e32 v235, v218, v27
	v_fmac_f32_e32 v236, v219, v24
	v_fmac_f32_e32 v237, v219, v25
	v_fmac_f32_e32 v238, v219, v26
	v_fmac_f32_e32 v239, v219, v27
	v_fmac_f32_e32 v224, v220, v28
	v_fmac_f32_e32 v225, v220, v29
	v_fmac_f32_e32 v226, v220, v30
	v_fmac_f32_e32 v227, v220, v31
	v_fmac_f32_e32 v228, v221, v28
	v_fmac_f32_e32 v229, v221, v29
	v_fmac_f32_e32 v230, v221, v30
	v_fmac_f32_e32 v231, v221, v31
	v_fmac_f32_e32 v232, v222, v28
	v_fmac_f32_e32 v233, v222, v29
	v_fmac_f32_e32 v234, v222, v30
	v_fmac_f32_e32 v235, v222, v31
	v_fmac_f32_e32 v236, v223, v28
	v_fmac_f32_e32 v237, v223, v29
	v_fmac_f32_e32 v238, v223, v30
	v_fmac_f32_e32 v239, v223, v31
	s_add_i32 s25, s0, 4
	s_min_u32 s24, s25, 31
	s_lshl_b32 s24, s24, 16
	s_add_u32 s98, s12, s24
	s_addc_u32 s99, s13, 0
	global_load_dwordx4 v[0:3], v144, s[98:99]
	global_load_dwordx4 v[4:7], v145, s[98:99]
	global_load_dwordx4 v[8:11], v146, s[98:99]
	global_load_dwordx4 v[12:15], v147, s[98:99]
	global_load_dwordx4 v[16:19], v148, s[98:99]
	global_load_dwordx4 v[20:23], v149, s[98:99]
	global_load_dwordx4 v[24:27], v150, s[98:99]
	global_load_dwordx4 v[28:31], v151, s[98:99]
	s_waitcnt vmcnt(24)
	ds_read_b128 v[192:195], v244 offset:128
	ds_read_b128 v[196:199], v244 offset:144
	ds_read_b128 v[200:203], v244 offset:160
	ds_read_b128 v[204:207], v244 offset:176
	ds_read_b128 v[208:211], v244 offset:192
	ds_read_b128 v[212:215], v244 offset:208
	ds_read_b128 v[216:219], v244 offset:224
	ds_read_b128 v[220:223], v244 offset:240
	s_waitcnt lgkmcnt(0)
; DI void mem_attn_sample_wave(const Params& p, int item, float* lds) {
;     ...
;   float4 o[4];
; #pragma unroll
;   for (int t = 0; t < 4; ++t) o[t] = make_float4(0.f, 0.f, 0.f, 0.f);
; #pragma unroll 4
;   for (int m = 0; m < 256; ++m) {
;     float4 vv = *(const float4*)&p.cache_mem[(((size_t)b * 256 + m) * 2 + 1) * 1024 + h * 256 + lane * 4];
; #pragma unroll
;     for (int t = 0; t < 4; ++t) {
;       const float pv = sq[t * 256 + m];
;       o[t].x += pv * vv.x; o[t].y += pv * vv.y; o[t].z += pv * vv.z; o[t].w += pv * vv.w;
;     }
;   }
	v_fmac_f32_e32 v224, v192, v32
	v_fmac_f32_e32 v225, v192, v33
	v_fmac_f32_e32 v226, v192, v34
	v_fmac_f32_e32 v227, v192, v35
	v_fmac_f32_e32 v228, v193, v32
	v_fmac_f32_e32 v229, v193, v33
	v_fmac_f32_e32 v230, v193, v34
	v_fmac_f32_e32 v231, v193, v35
	v_fmac_f32_e32 v232, v194, v32
	v_fmac_f32_e32 v233, v194, v33
	v_fmac_f32_e32 v234, v194, v34
	v_fmac_f32_e32 v235, v194, v35
	v_fmac_f32_e32 v236, v195, v32
	v_fmac_f32_e32 v237, v195, v33
	v_fmac_f32_e32 v238, v195, v34
	v_fmac_f32_e32 v239, v195, v35
	v_fmac_f32_e32 v224, v196, v36
	v_fmac_f32_e32 v225, v196, v37
	v_fmac_f32_e32 v226, v196, v38
	v_fmac_f32_e32 v227, v196, v39
	v_fmac_f32_e32 v228, v197, v36
	v_fmac_f32_e32 v229, v197, v37
	v_fmac_f32_e32 v230, v197, v38
	v_fmac_f32_e32 v231, v197, v39
	v_fmac_f32_e32 v232, v198, v36
	v_fmac_f32_e32 v233, v198, v37
	v_fmac_f32_e32 v234, v198, v38
	v_fmac_f32_e32 v235, v198, v39
	v_fmac_f32_e32 v236, v199, v36
	v_fmac_f32_e32 v237, v199, v37
	v_fmac_f32_e32 v238, v199, v38
	v_fmac_f32_e32 v239, v199, v39
	v_fmac_f32_e32 v224, v200, v40
	v_fmac_f32_e32 v225, v200, v41
	v_fmac_f32_e32 v226, v200, v42
	v_fmac_f32_e32 v227, v200, v43
	v_fmac_f32_e32 v228, v201, v40
	v_fmac_f32_e32 v229, v201, v41
	v_fmac_f32_e32 v230, v201, v42
	v_fmac_f32_e32 v231, v201, v43
	v_fmac_f32_e32 v232, v202, v40
	v_fmac_f32_e32 v233, v202, v41
	v_fmac_f32_e32 v234, v202, v42
	v_fmac_f32_e32 v235, v202, v43
	v_fmac_f32_e32 v236, v203, v40
	v_fmac_f32_e32 v237, v203, v41
	v_fmac_f32_e32 v238, v203, v42
	v_fmac_f32_e32 v239, v203, v43
	v_fmac_f32_e32 v224, v204, v44
	v_fmac_f32_e32 v225, v204, v45
	v_fmac_f32_e32 v226, v204, v46
	v_fmac_f32_e32 v227, v204, v47
	v_fmac_f32_e32 v228, v205, v44
	v_fmac_f32_e32 v229, v205, v45
	v_fmac_f32_e32 v230, v205, v46
	v_fmac_f32_e32 v231, v205, v47
	v_fmac_f32_e32 v232, v206, v44
	v_fmac_f32_e32 v233, v206, v45
	v_fmac_f32_e32 v234, v206, v46
	v_fmac_f32_e32 v235, v206, v47
	v_fmac_f32_e32 v236, v207, v44
	v_fmac_f32_e32 v237, v207, v45
	v_fmac_f32_e32 v238, v207, v46
	v_fmac_f32_e32 v239, v207, v47
	v_fmac_f32_e32 v224, v208, v48
	v_fmac_f32_e32 v225, v208, v49
	v_fmac_f32_e32 v226, v208, v50
	v_fmac_f32_e32 v227, v208, v51
	v_fmac_f32_e32 v228, v209, v48
	v_fmac_f32_e32 v229, v209, v49
	v_fmac_f32_e32 v230, v209, v50
	v_fmac_f32_e32 v231, v209, v51
	v_fmac_f32_e32 v232, v210, v48
	v_fmac_f32_e32 v233, v210, v49
	v_fmac_f32_e32 v234, v210, v50
	v_fmac_f32_e32 v235, v210, v51
	v_fmac_f32_e32 v236, v211, v48
	v_fmac_f32_e32 v237, v211, v49
	v_fmac_f32_e32 v238, v211, v50
	v_fmac_f32_e32 v239, v211, v51
	v_fmac_f32_e32 v224, v212, v52
	v_fmac_f32_e32 v225, v212, v53
	v_fmac_f32_e32 v226, v212, v54
	v_fmac_f32_e32 v227, v212, v55
	v_fmac_f32_e32 v228, v213, v52
	v_fmac_f32_e32 v229, v213, v53
	v_fmac_f32_e32 v230, v213, v54
	v_fmac_f32_e32 v231, v213, v55
	v_fmac_f32_e32 v232, v214, v52
	v_fmac_f32_e32 v233, v214, v53
	v_fmac_f32_e32 v234, v214, v54
	v_fmac_f32_e32 v235, v214, v55
	v_fmac_f32_e32 v236, v215, v52
	v_fmac_f32_e32 v237, v215, v53
	v_fmac_f32_e32 v238, v215, v54
	v_fmac_f32_e32 v239, v215, v55
	v_fmac_f32_e32 v224, v216, v56
	v_fmac_f32_e32 v225, v216, v57
	v_fmac_f32_e32 v226, v216, v58
	v_fmac_f32_e32 v227, v216, v59
	v_fmac_f32_e32 v228, v217, v56
	v_fmac_f32_e32 v229, v217, v57
	v_fmac_f32_e32 v230, v217, v58
	v_fmac_f32_e32 v231, v217, v59
	v_fmac_f32_e32 v232, v218, v56
	v_fmac_f32_e32 v233, v218, v57
	v_fmac_f32_e32 v234, v218, v58
	v_fmac_f32_e32 v235, v218, v59
	v_fmac_f32_e32 v236, v219, v56
	v_fmac_f32_e32 v237, v219, v57
	v_fmac_f32_e32 v238, v219, v58
	v_fmac_f32_e32 v239, v219, v59
	v_fmac_f32_e32 v224, v220, v60
	v_fmac_f32_e32 v225, v220, v61
	v_fmac_f32_e32 v226, v220, v62
	v_fmac_f32_e32 v227, v220, v63
	v_fmac_f32_e32 v228, v221, v60
	v_fmac_f32_e32 v229, v221, v61
	v_fmac_f32_e32 v230, v221, v62
	v_fmac_f32_e32 v231, v221, v63
	v_fmac_f32_e32 v232, v222, v60
	v_fmac_f32_e32 v233, v222, v61
	v_fmac_f32_e32 v234, v222, v62
	v_fmac_f32_e32 v235, v222, v63
	v_fmac_f32_e32 v236, v223, v60
	v_fmac_f32_e32 v237, v223, v61
	v_fmac_f32_e32 v238, v223, v62
	v_fmac_f32_e32 v239, v223, v63
	s_add_i32 s25, s0, 5
	s_min_u32 s24, s25, 31
	s_lshl_b32 s24, s24, 16
	s_add_u32 s98, s12, s24
	s_addc_u32 s99, s13, 0
	global_load_dwordx4 v[32:35], v144, s[98:99]
	global_load_dwordx4 v[36:39], v145, s[98:99]
	global_load_dwordx4 v[40:43], v146, s[98:99]
	global_load_dwordx4 v[44:47], v147, s[98:99]
	global_load_dwordx4 v[48:51], v148, s[98:99]
	global_load_dwordx4 v[52:55], v149, s[98:99]
	global_load_dwordx4 v[56:59], v150, s[98:99]
	global_load_dwordx4 v[60:63], v151, s[98:99]
	s_waitcnt vmcnt(24)
	ds_read_b128 v[192:195], v244 offset:256
	ds_read_b128 v[196:199], v244 offset:272
	ds_read_b128 v[200:203], v244 offset:288
	ds_read_b128 v[204:207], v244 offset:304
	ds_read_b128 v[208:211], v244 offset:320
	ds_read_b128 v[212:215], v244 offset:336
	ds_read_b128 v[216:219], v244 offset:352
	ds_read_b128 v[220:223], v244 offset:368
	s_waitcnt lgkmcnt(0)
; DI void mem_attn_sample_wave(const Params& p, int item, float* lds) {
;     ...
; #pragma unroll 4
;   for (int m = 0; m < 256; ++m) {
;     float4 vv = *(const float4*)&p.cache_mem[(((size_t)b * 256 + m) * 2 + 1) * 1024 + h * 256 + lane * 4];
; #pragma unroll
;     for (int t = 0; t < 4; ++t) {
;       const float pv = sq[t * 256 + m];
;       o[t].x += pv * vv.x; o[t].y += pv * vv.y; o[t].z += pv * vv.z; o[t].w += pv * vv.w;
;     }
;   }
	v_fmac_f32_e32 v224, v192, v64
	v_fmac_f32_e32 v225, v192, v65
	v_fmac_f32_e32 v226, v192, v66
	v_fmac_f32_e32 v227, v192, v67
	v_fmac_f32_e32 v228, v193, v64
	v_fmac_f32_e32 v229, v193, v65
	v_fmac_f32_e32 v230, v193, v66
	v_fmac_f32_e32 v231, v193, v67
	v_fmac_f32_e32 v232, v194, v64
	v_fmac_f32_e32 v233, v194, v65
	v_fmac_f32_e32 v234, v194, v66
	v_fmac_f32_e32 v235, v194, v67
	v_fmac_f32_e32 v236, v195, v64
	v_fmac_f32_e32 v237, v195, v65
	v_fmac_f32_e32 v238, v195, v66
	v_fmac_f32_e32 v239, v195, v67
	v_fmac_f32_e32 v224, v196, v68
	v_fmac_f32_e32 v225, v196, v69
	v_fmac_f32_e32 v226, v196, v70
	v_fmac_f32_e32 v227, v196, v71
	v_fmac_f32_e32 v228, v197, v68
	v_fmac_f32_e32 v229, v197, v69
	v_fmac_f32_e32 v230, v197, v70
	v_fmac_f32_e32 v231, v197, v71
	v_fmac_f32_e32 v232, v198, v68
	v_fmac_f32_e32 v233, v198, v69
	v_fmac_f32_e32 v234, v198, v70
	v_fmac_f32_e32 v235, v198, v71
	v_fmac_f32_e32 v236, v199, v68
	v_fmac_f32_e32 v237, v199, v69
	v_fmac_f32_e32 v238, v199, v70
	v_fmac_f32_e32 v239, v199, v71
	v_fmac_f32_e32 v224, v200, v72
	v_fmac_f32_e32 v225, v200, v73
	v_fmac_f32_e32 v226, v200, v74
	v_fmac_f32_e32 v227, v200, v75
	v_fmac_f32_e32 v228, v201, v72
	v_fmac_f32_e32 v229, v201, v73
	v_fmac_f32_e32 v230, v201, v74
	v_fmac_f32_e32 v231, v201, v75
	v_fmac_f32_e32 v232, v202, v72
	v_fmac_f32_e32 v233, v202, v73
	v_fmac_f32_e32 v234, v202, v74
	v_fmac_f32_e32 v235, v202, v75
	v_fmac_f32_e32 v236, v203, v72
	v_fmac_f32_e32 v237, v203, v73
	v_fmac_f32_e32 v238, v203, v74
	v_fmac_f32_e32 v239, v203, v75
	v_fmac_f32_e32 v224, v204, v76
	v_fmac_f32_e32 v225, v204, v77
	v_fmac_f32_e32 v226, v204, v78
	v_fmac_f32_e32 v227, v204, v79
	v_fmac_f32_e32 v228, v205, v76
	v_fmac_f32_e32 v229, v205, v77
	v_fmac_f32_e32 v230, v205, v78
	v_fmac_f32_e32 v231, v205, v79
	v_fmac_f32_e32 v232, v206, v76
	v_fmac_f32_e32 v233, v206, v77
	v_fmac_f32_e32 v234, v206, v78
	v_fmac_f32_e32 v235, v206, v79
	v_fmac_f32_e32 v236, v207, v76
	v_fmac_f32_e32 v237, v207, v77
	v_fmac_f32_e32 v238, v207, v78
	v_fmac_f32_e32 v239, v207, v79
	v_fmac_f32_e32 v224, v208, v80
	v_fmac_f32_e32 v225, v208, v81
	v_fmac_f32_e32 v226, v208, v82
	v_fmac_f32_e32 v227, v208, v83
	v_fmac_f32_e32 v228, v209, v80
	v_fmac_f32_e32 v229, v209, v81
	v_fmac_f32_e32 v230, v209, v82
	v_fmac_f32_e32 v231, v209, v83
	v_fmac_f32_e32 v232, v210, v80
	v_fmac_f32_e32 v233, v210, v81
	v_fmac_f32_e32 v234, v210, v82
	v_fmac_f32_e32 v235, v210, v83
	v_fmac_f32_e32 v236, v211, v80
	v_fmac_f32_e32 v237, v211, v81
	v_fmac_f32_e32 v238, v211, v82
	v_fmac_f32_e32 v239, v211, v83
	v_fmac_f32_e32 v224, v212, v84
	v_fmac_f32_e32 v225, v212, v85
	v_fmac_f32_e32 v226, v212, v86
	v_fmac_f32_e32 v227, v212, v87
	v_fmac_f32_e32 v228, v213, v84
	v_fmac_f32_e32 v229, v213, v85
	v_fmac_f32_e32 v230, v213, v86
	v_fmac_f32_e32 v231, v213, v87
	v_fmac_f32_e32 v232, v214, v84
	v_fmac_f32_e32 v233, v214, v85
	v_fmac_f32_e32 v234, v214, v86
	v_fmac_f32_e32 v235, v214, v87
	v_fmac_f32_e32 v236, v215, v84
	v_fmac_f32_e32 v237, v215, v85
	v_fmac_f32_e32 v238, v215, v86
	v_fmac_f32_e32 v239, v215, v87
	v_fmac_f32_e32 v224, v216, v88
	v_fmac_f32_e32 v225, v216, v89
	v_fmac_f32_e32 v226, v216, v90
	v_fmac_f32_e32 v227, v216, v91
	v_fmac_f32_e32 v228, v217, v88
	v_fmac_f32_e32 v229, v217, v89
	v_fmac_f32_e32 v230, v217, v90
	v_fmac_f32_e32 v231, v217, v91
	v_fmac_f32_e32 v232, v218, v88
	v_fmac_f32_e32 v233, v218, v89
	v_fmac_f32_e32 v234, v218, v90
	v_fmac_f32_e32 v235, v218, v91
	v_fmac_f32_e32 v236, v219, v88
	v_fmac_f32_e32 v237, v219, v89
	v_fmac_f32_e32 v238, v219, v90
	v_fmac_f32_e32 v239, v219, v91
	v_fmac_f32_e32 v224, v220, v92
	v_fmac_f32_e32 v225, v220, v93
	v_fmac_f32_e32 v226, v220, v94
	v_fmac_f32_e32 v227, v220, v95
	v_fmac_f32_e32 v228, v221, v92
	v_fmac_f32_e32 v229, v221, v93
	v_fmac_f32_e32 v230, v221, v94
	v_fmac_f32_e32 v231, v221, v95
	v_fmac_f32_e32 v232, v222, v92
	v_fmac_f32_e32 v233, v222, v93
	v_fmac_f32_e32 v234, v222, v94
	v_fmac_f32_e32 v235, v222, v95
	v_fmac_f32_e32 v236, v223, v92
	v_fmac_f32_e32 v237, v223, v93
	v_fmac_f32_e32 v238, v223, v94
	v_fmac_f32_e32 v239, v223, v95
	s_add_i32 s25, s0, 6
	s_min_u32 s24, s25, 31
	s_lshl_b32 s24, s24, 16
	s_add_u32 s98, s12, s24
	s_addc_u32 s99, s13, 0
	global_load_dwordx4 v[64:67], v144, s[98:99]
	global_load_dwordx4 v[68:71], v145, s[98:99]
	global_load_dwordx4 v[72:75], v146, s[98:99]
	global_load_dwordx4 v[76:79], v147, s[98:99]
	global_load_dwordx4 v[80:83], v148, s[98:99]
	global_load_dwordx4 v[84:87], v149, s[98:99]
	global_load_dwordx4 v[88:91], v150, s[98:99]
	global_load_dwordx4 v[92:95], v151, s[98:99]
	s_waitcnt vmcnt(24)
	ds_read_b128 v[192:195], v244 offset:384
	ds_read_b128 v[196:199], v244 offset:400
	ds_read_b128 v[200:203], v244 offset:416
	ds_read_b128 v[204:207], v244 offset:432
	ds_read_b128 v[208:211], v244 offset:448
	ds_read_b128 v[212:215], v244 offset:464
	ds_read_b128 v[216:219], v244 offset:480
	ds_read_b128 v[220:223], v244 offset:496
	s_waitcnt lgkmcnt(0)
; DI unsigned pack2(float a, float b) { return (unsigned)f2bf(a) | ((unsigned)f2bf(b) << 16); }
; DI void mem_attn_sample_wave(const Params& p, int item, float* lds) {
;     ...
; #pragma unroll 4
;   for (int m = 0; m < 256; ++m) {
;     float4 vv = *(const float4*)&p.cache_mem[(((size_t)b * 256 + m) * 2 + 1) * 1024 + h * 256 + lane * 4];
; #pragma unroll
;     for (int t = 0; t < 4; ++t) {
;       const float pv = sq[t * 256 + m];
;       o[t].x += pv * vv.x; o[t].y += pv * vv.y; o[t].z += pv * vv.z; o[t].w += pv * vv.w;
;     }
;   }
; #pragma unroll
;   for (int t = 0; t < 4; ++t) {
;     uint2 ov; ov.x = pack2(o[t].x * inv[t], o[t].y * inv[t]); ov.y = pack2(o[t].z * inv[t], o[t].w * inv[t]);
;     *(uint2*)&p.attn[((size_t)MP + b * 4 + t) * 1024 + h * 256 + lane * 4] = ov;
;   }
	v_fmac_f32_e32 v224, v192, v96
	v_fmac_f32_e32 v225, v192, v97
	v_fmac_f32_e32 v226, v192, v98
	v_fmac_f32_e32 v227, v192, v99
	v_fmac_f32_e32 v228, v193, v96
	v_fmac_f32_e32 v229, v193, v97
	v_fmac_f32_e32 v230, v193, v98
	v_fmac_f32_e32 v231, v193, v99
	v_fmac_f32_e32 v232, v194, v96
	v_fmac_f32_e32 v233, v194, v97
	v_fmac_f32_e32 v234, v194, v98
	v_fmac_f32_e32 v235, v194, v99
	v_fmac_f32_e32 v236, v195, v96
	v_fmac_f32_e32 v237, v195, v97
	v_fmac_f32_e32 v238, v195, v98
	v_fmac_f32_e32 v239, v195, v99
	v_fmac_f32_e32 v224, v196, v100
	v_fmac_f32_e32 v225, v196, v101
	v_fmac_f32_e32 v226, v196, v102
	v_fmac_f32_e32 v227, v196, v103
	v_fmac_f32_e32 v228, v197, v100
	v_fmac_f32_e32 v229, v197, v101
	v_fmac_f32_e32 v230, v197, v102
	v_fmac_f32_e32 v231, v197, v103
	v_fmac_f32_e32 v232, v198, v100
	v_fmac_f32_e32 v233, v198, v101
	v_fmac_f32_e32 v234, v198, v102
	v_fmac_f32_e32 v235, v198, v103
	v_fmac_f32_e32 v236, v199, v100
	v_fmac_f32_e32 v237, v199, v101
	v_fmac_f32_e32 v238, v199, v102
	v_fmac_f32_e32 v239, v199, v103
	v_fmac_f32_e32 v224, v200, v104
	v_fmac_f32_e32 v225, v200, v105
	v_fmac_f32_e32 v226, v200, v106
	v_fmac_f32_e32 v227, v200, v107
	v_fmac_f32_e32 v228, v201, v104
	v_fmac_f32_e32 v229, v201, v105
	v_fmac_f32_e32 v230, v201, v106
	v_fmac_f32_e32 v231, v201, v107
	v_fmac_f32_e32 v232, v202, v104
	v_fmac_f32_e32 v233, v202, v105
	v_fmac_f32_e32 v234, v202, v106
	v_fmac_f32_e32 v235, v202, v107
	v_fmac_f32_e32 v236, v203, v104
	v_fmac_f32_e32 v237, v203, v105
	v_fmac_f32_e32 v238, v203, v106
	v_fmac_f32_e32 v239, v203, v107
	v_fmac_f32_e32 v224, v204, v108
	v_fmac_f32_e32 v225, v204, v109
	v_fmac_f32_e32 v226, v204, v110
	v_fmac_f32_e32 v227, v204, v111
	v_fmac_f32_e32 v228, v205, v108
	v_fmac_f32_e32 v229, v205, v109
	v_fmac_f32_e32 v230, v205, v110
	v_fmac_f32_e32 v231, v205, v111
	v_fmac_f32_e32 v232, v206, v108
	v_fmac_f32_e32 v233, v206, v109
	v_fmac_f32_e32 v234, v206, v110
	v_fmac_f32_e32 v235, v206, v111
	v_fmac_f32_e32 v236, v207, v108
	v_fmac_f32_e32 v237, v207, v109
	v_fmac_f32_e32 v238, v207, v110
	v_fmac_f32_e32 v239, v207, v111
	v_fmac_f32_e32 v224, v208, v112
	v_fmac_f32_e32 v225, v208, v113
	v_fmac_f32_e32 v226, v208, v114
	v_fmac_f32_e32 v227, v208, v115
	v_fmac_f32_e32 v228, v209, v112
	v_fmac_f32_e32 v229, v209, v113
	v_fmac_f32_e32 v230, v209, v114
	v_fmac_f32_e32 v231, v209, v115
	v_fmac_f32_e32 v232, v210, v112
	v_fmac_f32_e32 v233, v210, v113
	v_fmac_f32_e32 v234, v210, v114
	v_fmac_f32_e32 v235, v210, v115
	v_fmac_f32_e32 v236, v211, v112
	v_fmac_f32_e32 v237, v211, v113
	v_fmac_f32_e32 v238, v211, v114
	v_fmac_f32_e32 v239, v211, v115
	v_fmac_f32_e32 v224, v212, v116
	v_fmac_f32_e32 v225, v212, v117
	v_fmac_f32_e32 v226, v212, v118
	v_fmac_f32_e32 v227, v212, v119
	v_fmac_f32_e32 v228, v213, v116
	v_fmac_f32_e32 v229, v213, v117
	v_fmac_f32_e32 v230, v213, v118
	v_fmac_f32_e32 v231, v213, v119
	v_fmac_f32_e32 v232, v214, v116
	v_fmac_f32_e32 v233, v214, v117
	v_fmac_f32_e32 v234, v214, v118
	v_fmac_f32_e32 v235, v214, v119
	v_fmac_f32_e32 v236, v215, v116
	v_fmac_f32_e32 v237, v215, v117
	v_fmac_f32_e32 v238, v215, v118
	v_fmac_f32_e32 v239, v215, v119
	v_fmac_f32_e32 v224, v216, v120
	v_fmac_f32_e32 v225, v216, v121
	v_fmac_f32_e32 v226, v216, v122
	v_fmac_f32_e32 v227, v216, v123
	v_fmac_f32_e32 v228, v217, v120
	v_fmac_f32_e32 v229, v217, v121
	v_fmac_f32_e32 v230, v217, v122
	v_fmac_f32_e32 v231, v217, v123
	v_fmac_f32_e32 v232, v218, v120
	v_fmac_f32_e32 v233, v218, v121
	v_fmac_f32_e32 v234, v218, v122
	v_fmac_f32_e32 v235, v218, v123
	v_fmac_f32_e32 v236, v219, v120
	v_fmac_f32_e32 v237, v219, v121
	v_fmac_f32_e32 v238, v219, v122
	v_fmac_f32_e32 v239, v219, v123
	v_fmac_f32_e32 v224, v220, v124
	v_fmac_f32_e32 v225, v220, v125
	v_fmac_f32_e32 v226, v220, v126
	v_fmac_f32_e32 v227, v220, v127
	v_fmac_f32_e32 v228, v221, v124
	v_fmac_f32_e32 v229, v221, v125
	v_fmac_f32_e32 v230, v221, v126
	v_fmac_f32_e32 v231, v221, v127
	v_fmac_f32_e32 v232, v222, v124
	v_fmac_f32_e32 v233, v222, v125
	v_fmac_f32_e32 v234, v222, v126
	v_fmac_f32_e32 v235, v222, v127
	v_fmac_f32_e32 v236, v223, v124
	v_fmac_f32_e32 v237, v223, v125
	v_fmac_f32_e32 v238, v223, v126
	v_fmac_f32_e32 v239, v223, v127
	v_add_u32_e32 v244, 0x200, v244
	s_add_i32 s0, s0, 4
	s_cmp_lt_u32 s0, 32
	s_cbranch_scc1 .Lp7s_vloop
	s_waitcnt vmcnt(0)
	s_movk_i32 s24, 0x7fff
	s_mov_b32 s25, 0x7060302
	v_mul_f32_e32 v224, v224, v141
	v_mul_f32_e32 v225, v225, v141
	v_mul_f32_e32 v226, v226, v141
	v_mul_f32_e32 v227, v227, v141
	v_bfe_u32 v246, v224, 16, 1
	v_add3_u32 v224, v224, v246, s24
	v_bfe_u32 v246, v225, 16, 1
	v_add3_u32 v225, v225, v246, s24
	v_bfe_u32 v246, v226, 16, 1
	v_add3_u32 v226, v226, v246, s24
	v_bfe_u32 v246, v227, 16, 1
	v_add3_u32 v227, v227, v246, s24
	v_perm_b32 v224, v225, v224, s25
	v_perm_b32 v225, v227, v226, s25
	global_store_dwordx2 v250, v[224:225], s[16:17] offset:0
	v_mul_f32_e32 v228, v228, v142
	v_mul_f32_e32 v229, v229, v142
	v_mul_f32_e32 v230, v230, v142
	v_mul_f32_e32 v231, v231, v142
	v_bfe_u32 v246, v228, 16, 1
	v_add3_u32 v228, v228, v246, s24
	v_bfe_u32 v246, v229, 16, 1
	v_add3_u32 v229, v229, v246, s24
	v_bfe_u32 v246, v230, 16, 1
	v_add3_u32 v230, v230, v246, s24
	v_bfe_u32 v246, v231, 16, 1
	v_add3_u32 v231, v231, v246, s24
	v_perm_b32 v228, v229, v228, s25
	v_perm_b32 v229, v231, v230, s25
	global_store_dwordx2 v250, v[228:229], s[16:17] offset:2048
	v_mul_f32_e32 v232, v232, v253
	v_mul_f32_e32 v233, v233, v253
	v_mul_f32_e32 v234, v234, v253
	v_mul_f32_e32 v235, v235, v253
	v_bfe_u32 v246, v232, 16, 1
	v_add3_u32 v232, v232, v246, s24
	v_bfe_u32 v246, v233, 16, 1
	v_add3_u32 v233, v233, v246, s24
	v_bfe_u32 v246, v234, 16, 1
	v_add3_u32 v234, v234, v246, s24
	v_bfe_u32 v246, v235, 16, 1
	v_add3_u32 v235, v235, v246, s24
	v_perm_b32 v232, v233, v232, s25
	v_perm_b32 v233, v235, v234, s25
	global_store_dwordx2 v247, v[232:233], s[16:17] offset:0
	v_mul_f32_e32 v236, v236, v254
	v_mul_f32_e32 v237, v237, v254
	v_mul_f32_e32 v238, v238, v254
	v_mul_f32_e32 v239, v239, v254
	v_bfe_u32 v246, v236, 16, 1
	v_add3_u32 v236, v236, v246, s24
	v_bfe_u32 v246, v237, 16, 1
	v_add3_u32 v237, v237, v246, s24
	v_bfe_u32 v246, v238, 16, 1
	v_add3_u32 v238, v238, v246, s24
	v_bfe_u32 v246, v239, 16, 1
	v_add3_u32 v239, v239, v246, s24
	v_perm_b32 v236, v237, v236, s25
	v_perm_b32 v237, v239, v238, s25
	global_store_dwordx2 v247, v[236:237], s[16:17] offset:2048
	s_branch .LBB0_886

; #define MFMA(a, b, c) __builtin_amdgcn_mfma_f32_16x16x32_bf16((a), (b), (c), 0, 0, 0)
; DI unsigned ordf(float f) { unsigned u = __float_as_uint(f); return (u & 0x80000000u) ? ~u : (u | 0x80000000u); }
; DI void peer_topk_wave(const Params& p, int item, unsigned* lds  ) {
;     ...
;   for (int pp = 0; pp < 2; ++pp) {
;     bf16x8 qf[4];
; #pragma unroll
;     for (int ks = 0; ks < 4; ++ks) qf[ks] = *(const bf16x8*)&p.pq[(size_t)(row0 + r) * 2048 + h * 256 + pp * 128 + ks * 32 + kg * 8];
;     unsigned kk[32];
;     const u16* sk = p.subkb + (size_t)(h * 2 + pp) * 16384;
; #pragma unroll
;     for (int mt = 0; mt < 8; ++mt) {
;       f32x4 a = (f32x4){0.f, 0.f, 0.f, 0.f};
; #pragma unroll
;       for (int ks = 0; ks < 4; ++ks) {
;         bf16x8 kf = *(const bf16x8*)&sk[(mt * 16 + r) * 128 + ks * 32 + kg * 8];
;         a = MFMA(kf, qf[ks], a);
;       }
; #pragma unroll
;       for (int j = 0; j < 4; ++j) kk[mt * 4 + j] = (ordf(a[j]) & ~127u) | (unsigned)(mt * 16 + kg * 4 + j);
;     }
.LBB0_1091:
	ds_read_b64 v[0:1], v142
	ds_read_b64 v[86:87], v143
	v_and_or_b32 v84, v141, -16, v134
	v_ashrrev_i32_e32 v85, 31, v84
	v_and_b32_e32 v146, 7, v145
	v_lshlrev_b64 v[2:3], 12, v[84:85]
	s_waitcnt lgkmcnt(0)
	v_lshl_add_u64 v[0:1], v[0:1], 0, v[2:3]
	v_lshlrev_b32_e32 v16, 9, v146
	v_lshl_add_u64 v[0:1], v[0:1], 0, v[16:17]
	v_lshlrev_b32_e32 v16, 16, v146
	v_lshl_add_u64 v[86:87], v[86:87], 0, v[16:17]
	v_lshl_add_u64 v[88:89], v[0:1], 0, v[18:19]
	v_lshl_add_u64 v[156:157], v[86:87], 0, v[20:21]
	flat_load_dwordx4 v[12:15], v[88:89]
	flat_load_dwordx4 v[8:11], v[88:89] offset:64
	flat_load_dwordx4 v[4:7], v[88:89] offset:128
	flat_load_dwordx4 v[0:3], v[88:89] offset:192
	flat_load_dwordx4 v[148:151], v[156:157]
	flat_load_dwordx4 v[152:155], v[156:157] offset:64
	v_lshl_add_u64 v[160:161], v[86:87], 0, v[32:33]
	v_lshl_add_u64 v[168:169], v[86:87], 0, v[48:49]
	s_waitcnt vmcnt(0) lgkmcnt(0)
	v_mfma_f32_16x16x32_bf16 v[148:151], v[148:151], v[12:15], 0
	flat_load_dwordx4 v[164:167], v[160:161]
	v_lshl_add_u64 v[160:161], v[86:87], 0, v[34:35]
	v_mfma_f32_16x16x32_bf16 v[148:151], v[152:155], v[8:11], v[148:151]
	flat_load_dwordx4 v[152:155], v[156:157] offset:128
	s_waitcnt vmcnt(0) lgkmcnt(0)
	v_mfma_f32_16x16x32_bf16 v[148:151], v[152:155], v[4:7], v[148:151]
	flat_load_dwordx4 v[152:155], v[156:157] offset:192
	v_lshl_add_u64 v[156:157], v[86:87], 0, v[24:25]
	flat_load_dwordx4 v[156:159], v[156:157]
	s_waitcnt vmcnt(0) lgkmcnt(0)
	v_mfma_f32_16x16x32_bf16 v[148:151], v[152:155], v[0:3], v[148:151]
	v_lshl_add_u64 v[152:153], v[86:87], 0, v[22:23]
	flat_load_dwordx4 v[152:155], v[152:153]
	s_nop 5
	v_not_b32_e32 v16, v148
	s_waitcnt vmcnt(0) lgkmcnt(0)
	v_mfma_f32_16x16x32_bf16 v[152:155], v[152:155], v[12:15], 0
	v_or_b32_e32 v147, 0x80000000, v148
	v_cmp_gt_i32_e32 vcc, 0, v148
	v_or_b32_e32 v148, 0x80000000, v149
	v_mfma_f32_16x16x32_bf16 v[152:155], v[156:159], v[8:11], v[152:155]
	v_lshl_add_u64 v[156:157], v[86:87], 0, v[26:27]
	flat_load_dwordx4 v[156:159], v[156:157]
	v_cndmask_b32_e32 v16, v147, v16, vcc
	v_and_or_b32 v147, v16, s80, v170
	v_not_b32_e32 v16, v149
	v_cmp_gt_i32_e32 vcc, 0, v149
	v_or_b32_e32 v149, 0x80000000, v150
	s_waitcnt vmcnt(0) lgkmcnt(0)
	v_mfma_f32_16x16x32_bf16 v[152:155], v[156:159], v[4:7], v[152:155]
	v_lshl_add_u64 v[156:157], v[86:87], 0, v[28:29]
	flat_load_dwordx4 v[156:159], v[156:157]
	v_cndmask_b32_e32 v16, v148, v16, vcc
	v_and_or_b32 v148, v16, s80, v113
	v_not_b32_e32 v16, v150
	v_cmp_gt_i32_e32 vcc, 0, v150
	v_or_b32_e32 v150, 0x80000000, v151
	s_waitcnt vmcnt(0) lgkmcnt(0)
	v_mfma_f32_16x16x32_bf16 v[152:155], v[156:159], v[0:3], v[152:155]
	v_lshl_add_u64 v[156:157], v[86:87], 0, v[30:31]
	flat_load_dwordx4 v[156:159], v[156:157]
	v_cndmask_b32_e32 v16, v149, v16, vcc
	v_and_or_b32 v149, v16, s80, v114
	v_not_b32_e32 v16, v151
	v_cmp_gt_i32_e32 vcc, 0, v151
	s_nop 1
	v_or_b32_e32 v151, 0x80000000, v152
	s_waitcnt vmcnt(0) lgkmcnt(0)
	v_mfma_f32_16x16x32_bf16 v[156:159], v[156:159], v[12:15], 0
	v_cndmask_b32_e32 v16, v150, v16, vcc
	v_and_or_b32 v150, v16, s80, v115
	v_not_b32_e32 v16, v152
	v_mfma_f32_16x16x32_bf16 v[156:159], v[164:167], v[8:11], v[156:159]
	flat_load_dwordx4 v[164:167], v[160:161]
	v_lshl_add_u64 v[160:161], v[86:87], 0, v[36:37]
	v_cmp_gt_i32_e32 vcc, 0, v152
	v_or_b32_e32 v152, 0x80000000, v153
	s_waitcnt vmcnt(0) lgkmcnt(0)
	v_mfma_f32_16x16x32_bf16 v[156:159], v[164:167], v[4:7], v[156:159]
	flat_load_dwordx4 v[164:167], v[160:161]
	v_lshl_add_u64 v[160:161], v[86:87], 0, v[38:39]
	v_cndmask_b32_e32 v16, v151, v16, vcc
	v_and_or_b32 v151, v16, s80, v90
	v_not_b32_e32 v16, v153
	v_cmp_gt_i32_e32 vcc, 0, v153
	v_or_b32_e32 v153, 0x80000000, v154
	s_waitcnt vmcnt(0) lgkmcnt(0)
	v_mfma_f32_16x16x32_bf16 v[156:159], v[164:167], v[0:3], v[156:159]
	flat_load_dwordx4 v[164:167], v[160:161]
	v_lshl_add_u64 v[160:161], v[86:87], 0, v[40:41]
	flat_load_dwordx4 v[176:179], v[160:161]
	v_lshl_add_u64 v[160:161], v[86:87], 0, v[42:43]
	v_cndmask_b32_e32 v16, v152, v16, vcc
	v_and_or_b32 v152, v16, s80, v116
	v_not_b32_e32 v16, v154
	v_cmp_gt_i32_e32 vcc, 0, v154
	v_or_b32_e32 v154, 0x80000000, v155
	s_waitcnt vmcnt(0) lgkmcnt(0)
	v_mfma_f32_16x16x32_bf16 v[164:167], v[164:167], v[12:15], 0
	v_cndmask_b32_e32 v16, v153, v16, vcc
	v_and_or_b32 v153, v16, s80, v117
	v_not_b32_e32 v16, v155
	v_mfma_f32_16x16x32_bf16 v[164:167], v[176:179], v[8:11], v[164:167]
	flat_load_dwordx4 v[176:179], v[160:161]
	v_lshl_add_u64 v[160:161], v[86:87], 0, v[44:45]
	v_cmp_gt_i32_e32 vcc, 0, v155
	v_or_b32_e32 v155, 0x80000000, v156
	s_waitcnt vmcnt(0) lgkmcnt(0)
	v_mfma_f32_16x16x32_bf16 v[164:167], v[176:179], v[4:7], v[164:167]
	flat_load_dwordx4 v[176:179], v[160:161]
	v_cndmask_b32_e32 v16, v154, v16, vcc
	v_and_or_b32 v154, v16, s80, v118
	v_not_b32_e32 v16, v156
	v_cmp_gt_i32_e32 vcc, 0, v156
	v_or_b32_e32 v156, 0x80000000, v157
	s_waitcnt vmcnt(0) lgkmcnt(0)
	v_mfma_f32_16x16x32_bf16 v[164:167], v[176:179], v[0:3], v[164:167]
	v_cndmask_b32_e32 v16, v155, v16, vcc
	v_and_or_b32 v155, v16, s80, v91
	v_not_b32_e32 v16, v157
	v_cmp_gt_i32_e32 vcc, 0, v157
	v_or_b32_e32 v157, 0x80000000, v158
	s_nop 2
	v_or_b32_e32 v160, 0x80000000, v165
	v_cndmask_b32_e32 v16, v156, v16, vcc
	v_and_or_b32 v156, v16, s80, v119
	v_not_b32_e32 v16, v158
	v_cmp_gt_i32_e32 vcc, 0, v158
	v_or_b32_e32 v158, 0x80000000, v159
	v_or_b32_e32 v161, 0x80000000, v166
	v_cndmask_b32_e32 v16, v157, v16, vcc
	v_and_or_b32 v157, v16, s80, v120
	v_not_b32_e32 v16, v159
	v_cmp_gt_i32_e32 vcc, 0, v159
	v_or_b32_e32 v159, 0x80000000, v164
	v_or_b32_e32 v162, 0x80000000, v167
	v_cndmask_b32_e32 v16, v158, v16, vcc
	v_and_or_b32 v158, v16, s80, v121
	v_not_b32_e32 v16, v164
	v_cmp_gt_i32_e32 vcc, 0, v164
	flat_load_dwordx4 v[176:179], v[168:169]
	v_lshl_add_u64 v[168:169], v[86:87], 0, v[50:51]
	v_cndmask_b32_e32 v16, v159, v16, vcc
	v_and_or_b32 v159, v16, s80, v92
	v_not_b32_e32 v16, v165
	v_cmp_gt_i32_e32 vcc, 0, v165
	v_lshl_add_u64 v[164:165], v[86:87], 0, v[46:47]
	s_nop 0
	v_cndmask_b32_e32 v16, v160, v16, vcc
	v_and_or_b32 v160, v16, s80, v122
	v_not_b32_e32 v16, v166
	v_cmp_gt_i32_e32 vcc, 0, v166
	s_nop 1
	v_cndmask_b32_e32 v16, v161, v16, vcc
	v_and_or_b32 v161, v16, s80, v123
	v_not_b32_e32 v16, v167
	v_cmp_gt_i32_e32 vcc, 0, v167
	flat_load_dwordx4 v[164:167], v[164:165]
	s_waitcnt vmcnt(0) lgkmcnt(0)
; #define MFMA(a, b, c) __builtin_amdgcn_mfma_f32_16x16x32_bf16((a), (b), (c), 0, 0, 0)
; DI unsigned ordf(float f) { unsigned u = __float_as_uint(f); return (u & 0x80000000u) ? ~u : (u | 0x80000000u); }
; DI void peer_topk_wave(const Params& p, int item, unsigned* lds  ) {
;     ...
;     for (int mt = 0; mt < 8; ++mt) {
;       f32x4 a = (f32x4){0.f, 0.f, 0.f, 0.f};
; #pragma unroll
;       for (int ks = 0; ks < 4; ++ks) {
;         bf16x8 kf = *(const bf16x8*)&sk[(mt * 16 + r) * 128 + ks * 32 + kg * 8];
;         a = MFMA(kf, qf[ks], a);
;       }
; #pragma unroll
;       for (int j = 0; j < 4; ++j) kk[mt * 4 + j] = (ordf(a[j]) & ~127u) | (unsigned)(mt * 16 + kg * 4 + j);
;     }
; #pragma unroll
;     for (int rr = 0; rr < 16; ++rr) {
;       unsigned m = 0;
; #pragma unroll
;       for (int i = 0; i < 32; ++i) m = umax(m, kk[i]);
;       m = umax(m, (unsigned)__shfl_xor((int)m, 16));
;       m = umax(m, (unsigned)__shfl_xor((int)m, 32));
	v_mfma_f32_16x16x32_bf16 v[164:167], v[164:167], v[12:15], 0
	v_cndmask_b32_e32 v16, v162, v16, vcc
	v_and_or_b32 v162, v16, s80, v124
	v_mfma_f32_16x16x32_bf16 v[164:167], v[176:179], v[8:11], v[164:167]
	flat_load_dwordx4 v[176:179], v[168:169]
	v_lshl_add_u64 v[168:169], v[86:87], 0, v[52:53]
	s_waitcnt vmcnt(0) lgkmcnt(0)
	v_mfma_f32_16x16x32_bf16 v[164:167], v[176:179], v[4:7], v[164:167]
	flat_load_dwordx4 v[176:179], v[168:169]
	s_waitcnt vmcnt(0) lgkmcnt(0)
	v_mfma_f32_16x16x32_bf16 v[164:167], v[176:179], v[0:3], v[164:167]
	s_nop 7
	v_not_b32_e32 v16, v164
	v_or_b32_e32 v168, 0x80000000, v164
	v_cmp_gt_i32_e32 vcc, 0, v164
	s_nop 1
	v_cndmask_b32_e32 v16, v168, v16, vcc
	v_and_or_b32 v164, v16, s80, v93
	v_not_b32_e32 v16, v165
	v_or_b32_e32 v168, 0x80000000, v165
	v_cmp_gt_i32_e32 vcc, 0, v165
	s_nop 1
	v_cndmask_b32_e32 v16, v168, v16, vcc
	v_and_or_b32 v165, v16, s80, v125
	v_not_b32_e32 v16, v166
	v_or_b32_e32 v168, 0x80000000, v166
	v_cmp_gt_i32_e32 vcc, 0, v166
	s_nop 1
	v_cndmask_b32_e32 v16, v168, v16, vcc
	v_and_or_b32 v166, v16, s80, v126
	v_not_b32_e32 v16, v167
	v_or_b32_e32 v168, 0x80000000, v167
	v_cmp_gt_i32_e32 vcc, 0, v167
	s_nop 1
	v_cndmask_b32_e32 v16, v168, v16, vcc
	v_lshl_add_u64 v[168:169], v[86:87], 0, v[54:55]
	flat_load_dwordx4 v[176:179], v[168:169]
	v_lshl_add_u64 v[168:169], v[86:87], 0, v[56:57]
	flat_load_dwordx4 v[180:183], v[168:169]
	v_lshl_add_u64 v[168:169], v[86:87], 0, v[58:59]
	v_and_or_b32 v167, v16, s80, v127
	s_waitcnt vmcnt(0) lgkmcnt(0)
	v_mfma_f32_16x16x32_bf16 v[176:179], v[176:179], v[12:15], 0
	v_mfma_f32_16x16x32_bf16 v[176:179], v[180:183], v[8:11], v[176:179]
	flat_load_dwordx4 v[180:183], v[168:169]
	v_lshl_add_u64 v[168:169], v[86:87], 0, v[60:61]
	s_waitcnt vmcnt(0) lgkmcnt(0)
	v_mfma_f32_16x16x32_bf16 v[176:179], v[180:183], v[4:7], v[176:179]
	flat_load_dwordx4 v[180:183], v[168:169]
	s_waitcnt vmcnt(0) lgkmcnt(0)
	v_mfma_f32_16x16x32_bf16 v[176:179], v[180:183], v[0:3], v[176:179]
	v_lshl_add_u64 v[180:181], v[86:87], 0, v[64:65]
	flat_load_dwordx4 v[180:183], v[180:181]
	s_nop 5
	v_not_b32_e32 v16, v176
	v_or_b32_e32 v168, 0x80000000, v176
	v_cmp_gt_i32_e32 vcc, 0, v176
	v_or_b32_e32 v169, 0x80000000, v177
	v_or_b32_e32 v171, 0x80000000, v178
	v_cndmask_b32_e32 v16, v168, v16, vcc
	v_and_or_b32 v168, v16, s80, v94
	v_not_b32_e32 v16, v177
	v_cmp_gt_i32_e32 vcc, 0, v177
	v_lshl_add_u64 v[176:177], v[86:87], 0, v[62:63]
	v_or_b32_e32 v172, 0x80000000, v179
	v_cndmask_b32_e32 v16, v169, v16, vcc
	v_and_or_b32 v169, v16, s80, v129
	v_not_b32_e32 v16, v178
	v_cmp_gt_i32_e32 vcc, 0, v178
	s_nop 1
	v_cndmask_b32_e32 v16, v171, v16, vcc
	v_and_or_b32 v171, v16, s80, v130
	v_not_b32_e32 v16, v179
	v_cmp_gt_i32_e32 vcc, 0, v179
	flat_load_dwordx4 v[176:179], v[176:177]
	s_waitcnt vmcnt(0) lgkmcnt(0)
	v_mfma_f32_16x16x32_bf16 v[176:179], v[176:179], v[12:15], 0
	v_cndmask_b32_e32 v16, v172, v16, vcc
	v_and_or_b32 v172, v16, s80, v131
	v_mfma_f32_16x16x32_bf16 v[176:179], v[180:183], v[8:11], v[176:179]
	v_lshl_add_u64 v[180:181], v[86:87], 0, v[66:67]
	flat_load_dwordx4 v[180:183], v[180:181]
	s_waitcnt vmcnt(0) lgkmcnt(0)
	v_mfma_f32_16x16x32_bf16 v[176:179], v[180:183], v[4:7], v[176:179]
	v_lshl_add_u64 v[180:181], v[86:87], 0, v[68:69]
	flat_load_dwordx4 v[180:183], v[180:181]
	s_waitcnt vmcnt(0) lgkmcnt(0)
	v_mfma_f32_16x16x32_bf16 v[176:179], v[180:183], v[0:3], v[176:179]
	s_nop 7
	v_not_b32_e32 v16, v176
	v_or_b32_e32 v173, 0x80000000, v176
	v_cmp_gt_i32_e32 vcc, 0, v176
	v_or_b32_e32 v176, 0x80000000, v177
	s_nop 0
	v_cndmask_b32_e32 v16, v173, v16, vcc
	v_and_or_b32 v173, v16, s80, v95
	v_not_b32_e32 v16, v177
	v_cmp_gt_i32_e32 vcc, 0, v177
	s_nop 1
	v_cndmask_b32_e32 v16, v176, v16, vcc
	v_and_or_b32 v180, v16, s80, v135
	v_not_b32_e32 v16, v178
	v_or_b32_e32 v176, 0x80000000, v178
	v_cmp_gt_i32_e32 vcc, 0, v178
	s_nop 1
	v_cndmask_b32_e32 v16, v176, v16, vcc
	v_and_or_b32 v181, v16, s80, v136
	v_not_b32_e32 v16, v179
	v_or_b32_e32 v176, 0x80000000, v179
	v_cmp_gt_i32_e32 vcc, 0, v179
	s_nop 1
	v_cndmask_b32_e32 v16, v176, v16, vcc
	v_lshl_add_u64 v[176:177], v[86:87], 0, v[70:71]
	flat_load_dwordx4 v[176:179], v[176:177]
	v_and_or_b32 v182, v16, s80, v137
	s_waitcnt vmcnt(0) lgkmcnt(0)
	v_mfma_f32_16x16x32_bf16 v[12:15], v[176:179], v[12:15], 0
	v_lshl_add_u64 v[176:177], v[86:87], 0, v[72:73]
	flat_load_dwordx4 v[176:179], v[176:177]
	s_waitcnt vmcnt(0) lgkmcnt(0)
	v_mfma_f32_16x16x32_bf16 v[8:11], v[176:179], v[8:11], v[12:15]
	s_nop 3
	v_lshl_add_u64 v[12:13], v[86:87], 0, v[74:75]
	flat_load_dwordx4 v[12:15], v[12:13]
	s_waitcnt vmcnt(0) lgkmcnt(0)
	v_mfma_f32_16x16x32_bf16 v[4:7], v[12:15], v[4:7], v[8:11]
	s_nop 2
	v_lshl_add_u64 v[8:9], v[86:87], 0, v[76:77]
	flat_load_dwordx4 v[8:11], v[8:9]
	v_lshl_add_u64 v[86:87], v[86:87], 0, s[76:77]
	s_waitcnt vmcnt(0) lgkmcnt(0)
	v_mfma_f32_16x16x32_bf16 v[0:3], v[8:11], v[0:3], v[4:7]
	v_lshl_add_u64 v[186:187], v[86:87], 0, v[48:49]
	v_lshl_add_u64 v[190:191], v[86:87], 0, v[56:57]
	v_lshl_add_u64 v[194:195], v[86:87], 0, v[64:65]
	s_nop 4
	v_not_b32_e32 v4, v0
	v_or_b32_e32 v5, 0x80000000, v0
	v_cmp_gt_i32_e32 vcc, 0, v0
	s_nop 1
	v_cndmask_b32_e32 v0, v5, v4, vcc
	v_not_b32_e32 v4, v1
	v_or_b32_e32 v5, 0x80000000, v1
	v_cmp_gt_i32_e32 vcc, 0, v1
	v_and_or_b32 v0, v0, s80, v96
	s_nop 0
	v_cndmask_b32_e32 v1, v5, v4, vcc
	v_not_b32_e32 v4, v2
	v_or_b32_e32 v5, 0x80000000, v2
	v_cmp_gt_i32_e32 vcc, 0, v2
	v_and_or_b32 v1, v1, s80, v138
	s_nop 0
	v_cndmask_b32_e32 v2, v5, v4, vcc
	v_not_b32_e32 v4, v3
	v_or_b32_e32 v5, 0x80000000, v3
	v_cmp_gt_i32_e32 vcc, 0, v3
	v_and_or_b32 v2, v2, s80, v139
	s_nop 0
	v_cndmask_b32_e32 v3, v5, v4, vcc
	v_max_u32_e32 v4, v147, v148
	v_max3_u32 v4, v4, v149, v150
	v_max3_u32 v4, v4, v151, v152
	v_max3_u32 v4, v4, v153, v154
	v_max3_u32 v4, v4, v155, v156
	v_max3_u32 v4, v4, v157, v158
	v_max3_u32 v4, v4, v159, v160
	v_max3_u32 v4, v4, v161, v162
	v_max3_u32 v4, v4, v164, v165
	v_max3_u32 v4, v4, v166, v167
	v_max3_u32 v4, v4, v168, v169
	v_max3_u32 v4, v4, v171, v172
	v_max3_u32 v4, v4, v173, v180
	v_max3_u32 v4, v4, v181, v182
	v_and_or_b32 v3, v3, s80, v140
	v_max3_u32 v4, v4, v0, v1
	v_max3_u32 v4, v4, v2, v3
	ds_bpermute_b32 v5, v111, v4
	s_waitcnt lgkmcnt(0)
; DI void peer_topk_wave(const Params& p, int item, unsigned* lds  ) {
;     ...
;     for (int rr = 0; rr < 16; ++rr) {
;       unsigned m = 0;
; #pragma unroll
;       for (int i = 0; i < 32; ++i) m = umax(m, kk[i]);
;       m = umax(m, (unsigned)__shfl_xor((int)m, 16));
;       m = umax(m, (unsigned)__shfl_xor((int)m, 32));
;       win[pp][rr] = m;
; #pragma unroll
;       for (int i = 0; i < 32; ++i) kk[i] = (kk[i] == m) ? 0u : kk[i];
;     }
	v_max_u32_e32 v4, v4, v5
	ds_bpermute_b32 v5, v112, v4
	s_waitcnt lgkmcnt(0)
	v_max_u32_e32 v16, v4, v5
	v_cmp_ne_u32_e32 vcc, v147, v16
	v_cmp_ne_u32_e64 s[98:99], v148, v16
	v_cmp_ne_u32_e64 s[100:101], v149, v16
	v_cndmask_b32_e32 v4, 0, v147, vcc
	v_cndmask_b32_e64 v5, 0, v148, s[98:99]
	v_max_u32_e32 v147, v4, v5
	v_cndmask_b32_e64 v6, 0, v149, s[100:101]
	v_cmp_ne_u32_e32 vcc, v150, v16
	v_cmp_ne_u32_e64 s[98:99], v151, v16
	v_cmp_ne_u32_e64 s[100:101], v152, v16
	v_cndmask_b32_e32 v7, 0, v150, vcc
	v_max3_u32 v147, v147, v6, v7
	v_cndmask_b32_e64 v8, 0, v151, s[98:99]
	v_cndmask_b32_e64 v9, 0, v152, s[100:101]
	v_cmp_ne_u32_e32 vcc, v153, v16
	v_max3_u32 v147, v147, v8, v9
	v_cmp_ne_u32_e64 s[98:99], v154, v16
	v_cndmask_b32_e32 v10, 0, v153, vcc
	v_cmp_ne_u32_e64 s[100:101], v155, v16
	v_cndmask_b32_e64 v11, 0, v154, s[98:99]
	v_max3_u32 v147, v147, v10, v11
	v_cndmask_b32_e64 v12, 0, v155, s[100:101]
	v_cmp_ne_u32_e32 vcc, v156, v16
	v_cmp_ne_u32_e64 s[98:99], v157, v16
	v_cmp_ne_u32_e64 s[100:101], v158, v16
	v_cndmask_b32_e32 v13, 0, v156, vcc
	v_max3_u32 v147, v147, v12, v13
	v_cndmask_b32_e64 v14, 0, v157, s[98:99]
	v_cndmask_b32_e64 v15, 0, v158, s[100:101]
	v_cmp_ne_u32_e32 vcc, v159, v16
	v_max3_u32 v147, v147, v14, v15
	v_cmp_ne_u32_e64 s[98:99], v160, v16
	v_cndmask_b32_e32 v148, 0, v159, vcc
	v_cmp_ne_u32_e64 s[100:101], v161, v16
	v_cndmask_b32_e64 v149, 0, v160, s[98:99]
	v_max3_u32 v147, v147, v148, v149
	v_cndmask_b32_e64 v150, 0, v161, s[100:101]
	v_cmp_ne_u32_e32 vcc, v162, v16
	v_cmp_ne_u32_e64 s[98:99], v164, v16
	v_cmp_ne_u32_e64 s[100:101], v165, v16
	v_cndmask_b32_e32 v151, 0, v162, vcc
	v_max3_u32 v147, v147, v150, v151
	v_cndmask_b32_e64 v152, 0, v164, s[98:99]
	v_cndmask_b32_e64 v153, 0, v165, s[100:101]
	v_cmp_ne_u32_e32 vcc, v166, v16
	v_max3_u32 v147, v147, v152, v153
	v_cmp_ne_u32_e64 s[98:99], v167, v16
	v_cndmask_b32_e32 v154, 0, v166, vcc
	v_cmp_ne_u32_e64 s[100:101], v168, v16
	v_cndmask_b32_e64 v155, 0, v167, s[98:99]
	v_max3_u32 v147, v147, v154, v155
	v_cndmask_b32_e64 v156, 0, v168, s[100:101]
	v_cmp_ne_u32_e32 vcc, v169, v16
	v_cmp_ne_u32_e64 s[98:99], v171, v16
	v_cmp_ne_u32_e64 s[100:101], v172, v16
	v_cndmask_b32_e32 v157, 0, v169, vcc
	v_max3_u32 v147, v147, v156, v157
	v_cndmask_b32_e64 v158, 0, v171, s[98:99]
	v_cndmask_b32_e64 v159, 0, v172, s[100:101]
	v_cmp_ne_u32_e32 vcc, v173, v16
	v_max3_u32 v147, v147, v158, v159
	v_cmp_ne_u32_e64 s[98:99], v180, v16
	v_cndmask_b32_e32 v160, 0, v173, vcc
	v_cmp_ne_u32_e64 s[100:101], v181, v16
	v_cndmask_b32_e64 v161, 0, v180, s[98:99]
	v_max3_u32 v147, v147, v160, v161
	v_cndmask_b32_e64 v162, 0, v181, s[100:101]
	v_cmp_ne_u32_e32 vcc, v182, v16
	v_cmp_ne_u32_e64 s[98:99], v0, v16
	v_cmp_ne_u32_e64 s[100:101], v1, v16
	v_cndmask_b32_e32 v164, 0, v182, vcc
	v_max3_u32 v147, v147, v162, v164
	v_cndmask_b32_e64 v0, 0, v0, s[98:99]
	v_cndmask_b32_e64 v1, 0, v1, s[100:101]
	v_cmp_ne_u32_e32 vcc, v2, v16
	v_max3_u32 v147, v147, v0, v1
	v_cmp_ne_u32_e64 s[98:99], v3, v16
	v_cndmask_b32_e32 v2, 0, v2, vcc
	s_nop 0
	v_cndmask_b32_e64 v3, 0, v3, s[98:99]
	v_max3_u32 v147, v147, v2, v3
	ds_bpermute_b32 v165, v111, v147
	s_waitcnt lgkmcnt(0)
	v_max_u32_e32 v147, v147, v165
	ds_bpermute_b32 v165, v112, v147
	s_waitcnt lgkmcnt(0)
	v_max_u32_e32 v147, v147, v165
	v_cmp_ne_u32_e32 vcc, v4, v147
	v_cmp_ne_u32_e64 s[98:99], v5, v147
	v_cmp_ne_u32_e64 s[100:101], v6, v147
	v_cndmask_b32_e32 v4, 0, v4, vcc
	v_cndmask_b32_e64 v5, 0, v5, s[98:99]
	v_cndmask_b32_e64 v6, 0, v6, s[100:101]
	v_cmp_ne_u32_e32 vcc, v7, v147
	v_cmp_ne_u32_e64 s[98:99], v8, v147
	v_cmp_ne_u32_e64 s[100:101], v9, v147
	v_cndmask_b32_e32 v7, 0, v7, vcc
	v_cndmask_b32_e64 v8, 0, v8, s[98:99]
	v_cndmask_b32_e64 v9, 0, v9, s[100:101]
	v_cmp_ne_u32_e32 vcc, v10, v147
	v_cmp_ne_u32_e64 s[98:99], v11, v147
	v_cmp_ne_u32_e64 s[100:101], v12, v147
	v_cndmask_b32_e32 v10, 0, v10, vcc
	v_cndmask_b32_e64 v11, 0, v11, s[98:99]
	v_cndmask_b32_e64 v12, 0, v12, s[100:101]
	v_cmp_ne_u32_e32 vcc, v13, v147
	v_cmp_ne_u32_e64 s[98:99], v14, v147
	v_cmp_ne_u32_e64 s[100:101], v15, v147
	v_cndmask_b32_e32 v13, 0, v13, vcc
	v_cndmask_b32_e64 v14, 0, v14, s[98:99]
	v_cndmask_b32_e64 v15, 0, v15, s[100:101]
	v_cmp_ne_u32_e32 vcc, v148, v147
	v_cmp_ne_u32_e64 s[98:99], v149, v147
	v_cmp_ne_u32_e64 s[100:101], v150, v147
	v_cndmask_b32_e32 v165, 0, v148, vcc
	v_max_u32_e32 v148, v4, v5
	v_max3_u32 v148, v148, v6, v7
	v_cndmask_b32_e64 v149, 0, v149, s[98:99]
	v_max3_u32 v148, v148, v8, v9
	v_max3_u32 v148, v148, v10, v11
	v_cndmask_b32_e64 v150, 0, v150, s[100:101]
	v_cmp_ne_u32_e32 vcc, v151, v147
	v_max3_u32 v148, v148, v12, v13
	v_max3_u32 v148, v148, v14, v15
	v_cndmask_b32_e32 v151, 0, v151, vcc
	v_cmp_ne_u32_e64 s[98:99], v152, v147
	v_max3_u32 v148, v148, v165, v149
	v_max3_u32 v148, v148, v150, v151
	v_cndmask_b32_e64 v152, 0, v152, s[98:99]
	v_cmp_ne_u32_e64 s[100:101], v153, v147
	v_cmp_ne_u32_e32 vcc, v154, v147
	v_cmp_ne_u32_e64 s[98:99], v155, v147
	v_cndmask_b32_e64 v153, 0, v153, s[100:101]
	v_max3_u32 v148, v148, v152, v153
	v_cndmask_b32_e32 v154, 0, v154, vcc
	v_cndmask_b32_e64 v155, 0, v155, s[98:99]
	v_cmp_ne_u32_e64 s[100:101], v156, v147
	v_max3_u32 v148, v148, v154, v155
	v_cmp_ne_u32_e32 vcc, v157, v147
	v_cndmask_b32_e64 v156, 0, v156, s[100:101]
	v_cmp_ne_u32_e64 s[98:99], v158, v147
	v_cndmask_b32_e32 v157, 0, v157, vcc
	v_max3_u32 v148, v148, v156, v157
	v_cndmask_b32_e64 v158, 0, v158, s[98:99]
	v_cmp_ne_u32_e64 s[100:101], v159, v147
	v_cmp_ne_u32_e32 vcc, v160, v147
	v_cmp_ne_u32_e64 s[98:99], v161, v147
	v_cndmask_b32_e64 v159, 0, v159, s[100:101]
	v_max3_u32 v148, v148, v158, v159
	v_cndmask_b32_e32 v160, 0, v160, vcc
	v_cndmask_b32_e64 v161, 0, v161, s[98:99]
	v_cmp_ne_u32_e64 s[100:101], v162, v147
	v_max3_u32 v148, v148, v160, v161
	v_cmp_ne_u32_e32 vcc, v164, v147
	v_cndmask_b32_e64 v162, 0, v162, s[100:101]
	v_cmp_ne_u32_e64 s[98:99], v0, v147
	v_cndmask_b32_e32 v164, 0, v164, vcc
	v_max3_u32 v148, v148, v162, v164
	v_cndmask_b32_e64 v0, 0, v0, s[98:99]
	v_cmp_ne_u32_e64 s[100:101], v1, v147
	v_cmp_ne_u32_e32 vcc, v2, v147
	v_cmp_ne_u32_e64 s[98:99], v3, v147
	v_cndmask_b32_e64 v1, 0, v1, s[100:101]
	v_max3_u32 v148, v148, v0, v1
	v_cndmask_b32_e32 v2, 0, v2, vcc
	v_cndmask_b32_e64 v3, 0, v3, s[98:99]
	v_max3_u32 v148, v148, v2, v3
	ds_bpermute_b32 v166, v111, v148
	s_waitcnt lgkmcnt(0)
; DI void peer_topk_wave(const Params& p, int item, unsigned* lds  ) {
;     ...
;     for (int rr = 0; rr < 16; ++rr) {
;       unsigned m = 0;
; #pragma unroll
;       for (int i = 0; i < 32; ++i) m = umax(m, kk[i]);
;       m = umax(m, (unsigned)__shfl_xor((int)m, 16));
;       m = umax(m, (unsigned)__shfl_xor((int)m, 32));
;       win[pp][rr] = m;
; #pragma unroll
;       for (int i = 0; i < 32; ++i) kk[i] = (kk[i] == m) ? 0u : kk[i];
;     }
	v_max_u32_e32 v148, v148, v166
	ds_bpermute_b32 v166, v112, v148
	s_waitcnt lgkmcnt(0)
	v_max_u32_e32 v148, v148, v166
	v_cmp_ne_u32_e32 vcc, v4, v148
	v_cmp_ne_u32_e64 s[98:99], v5, v148
	v_cmp_ne_u32_e64 s[100:101], v6, v148
	v_cndmask_b32_e32 v4, 0, v4, vcc
	v_cndmask_b32_e64 v5, 0, v5, s[98:99]
	v_cndmask_b32_e64 v6, 0, v6, s[100:101]
	v_cmp_ne_u32_e32 vcc, v7, v148
	v_cmp_ne_u32_e64 s[98:99], v8, v148
	v_cmp_ne_u32_e64 s[100:101], v9, v148
	v_cndmask_b32_e32 v7, 0, v7, vcc
	v_cndmask_b32_e64 v8, 0, v8, s[98:99]
	v_cndmask_b32_e64 v9, 0, v9, s[100:101]
	v_cmp_ne_u32_e32 vcc, v10, v148
	v_cmp_ne_u32_e64 s[98:99], v11, v148
	v_cmp_ne_u32_e64 s[100:101], v12, v148
	v_cndmask_b32_e32 v10, 0, v10, vcc
	v_cndmask_b32_e64 v11, 0, v11, s[98:99]
	v_cndmask_b32_e64 v12, 0, v12, s[100:101]
	v_cmp_ne_u32_e32 vcc, v13, v148
	v_cmp_ne_u32_e64 s[98:99], v14, v148
	v_cmp_ne_u32_e64 s[100:101], v15, v148
	v_cndmask_b32_e32 v13, 0, v13, vcc
	v_cndmask_b32_e64 v14, 0, v14, s[98:99]
	v_cndmask_b32_e64 v15, 0, v15, s[100:101]
	v_cmp_ne_u32_e32 vcc, v165, v148
	v_cmp_ne_u32_e64 s[98:99], v149, v148
	v_cmp_ne_u32_e64 s[100:101], v150, v148
	v_cndmask_b32_e32 v165, 0, v165, vcc
	v_cndmask_b32_e64 v166, 0, v149, s[98:99]
	v_max_u32_e32 v149, v4, v5
	v_max3_u32 v149, v149, v6, v7
	v_cndmask_b32_e64 v150, 0, v150, s[100:101]
	v_cmp_ne_u32_e32 vcc, v151, v148
	v_max3_u32 v149, v149, v8, v9
	v_max3_u32 v149, v149, v10, v11
	v_cndmask_b32_e32 v151, 0, v151, vcc
	v_cmp_ne_u32_e64 s[98:99], v152, v148
	v_max3_u32 v149, v149, v12, v13
	v_max3_u32 v149, v149, v14, v15
	v_cndmask_b32_e64 v152, 0, v152, s[98:99]
	v_cmp_ne_u32_e64 s[100:101], v153, v148
	v_max3_u32 v149, v149, v165, v166
	v_max3_u32 v149, v149, v150, v151
	v_cndmask_b32_e64 v153, 0, v153, s[100:101]
	v_cmp_ne_u32_e32 vcc, v154, v148
	v_max3_u32 v149, v149, v152, v153
	v_cmp_ne_u32_e64 s[98:99], v155, v148
	v_cndmask_b32_e32 v154, 0, v154, vcc
	v_cmp_ne_u32_e64 s[100:101], v156, v148
	v_cndmask_b32_e64 v155, 0, v155, s[98:99]
	v_max3_u32 v149, v149, v154, v155
	v_cndmask_b32_e64 v156, 0, v156, s[100:101]
	v_cmp_ne_u32_e32 vcc, v157, v148
	v_cmp_ne_u32_e64 s[98:99], v158, v148
	v_cmp_ne_u32_e64 s[100:101], v159, v148
	v_cndmask_b32_e32 v157, 0, v157, vcc
	v_max3_u32 v149, v149, v156, v157
	v_cndmask_b32_e64 v158, 0, v158, s[98:99]
	v_cndmask_b32_e64 v159, 0, v159, s[100:101]
	v_cmp_ne_u32_e32 vcc, v160, v148
	v_max3_u32 v149, v149, v158, v159
	v_cmp_ne_u32_e64 s[98:99], v161, v148
	v_cndmask_b32_e32 v160, 0, v160, vcc
	v_cmp_ne_u32_e64 s[100:101], v162, v148
	v_cndmask_b32_e64 v161, 0, v161, s[98:99]
	v_max3_u32 v149, v149, v160, v161
	v_cndmask_b32_e64 v162, 0, v162, s[100:101]
	v_cmp_ne_u32_e32 vcc, v164, v148
	v_cmp_ne_u32_e64 s[98:99], v0, v148
	v_cmp_ne_u32_e64 s[100:101], v1, v148
	v_cndmask_b32_e32 v164, 0, v164, vcc
	v_max3_u32 v149, v149, v162, v164
	v_cndmask_b32_e64 v0, 0, v0, s[98:99]
	v_cndmask_b32_e64 v1, 0, v1, s[100:101]
	v_cmp_ne_u32_e32 vcc, v2, v148
	v_max3_u32 v149, v149, v0, v1
	v_cmp_ne_u32_e64 s[98:99], v3, v148
	v_cndmask_b32_e32 v2, 0, v2, vcc
	s_nop 0
	v_cndmask_b32_e64 v3, 0, v3, s[98:99]
	v_max3_u32 v149, v149, v2, v3
	ds_bpermute_b32 v167, v111, v149
	s_waitcnt lgkmcnt(0)
	v_max_u32_e32 v149, v149, v167
	ds_bpermute_b32 v167, v112, v149
	s_waitcnt lgkmcnt(0)
	v_max_u32_e32 v149, v149, v167
	v_cmp_ne_u32_e32 vcc, v4, v149
	v_cmp_ne_u32_e64 s[98:99], v5, v149
	v_cmp_ne_u32_e64 s[100:101], v6, v149
	v_cndmask_b32_e32 v4, 0, v4, vcc
	v_cndmask_b32_e64 v5, 0, v5, s[98:99]
	v_cndmask_b32_e64 v6, 0, v6, s[100:101]
	v_cmp_ne_u32_e32 vcc, v7, v149
	v_cmp_ne_u32_e64 s[98:99], v8, v149
	v_cmp_ne_u32_e64 s[100:101], v9, v149
	v_cndmask_b32_e32 v7, 0, v7, vcc
	v_cndmask_b32_e64 v8, 0, v8, s[98:99]
	v_cndmask_b32_e64 v9, 0, v9, s[100:101]
	v_cmp_ne_u32_e32 vcc, v10, v149
	v_cmp_ne_u32_e64 s[98:99], v11, v149
	v_cmp_ne_u32_e64 s[100:101], v12, v149
	v_cndmask_b32_e32 v10, 0, v10, vcc
	v_cndmask_b32_e64 v11, 0, v11, s[98:99]
	v_cndmask_b32_e64 v12, 0, v12, s[100:101]
	v_cmp_ne_u32_e32 vcc, v13, v149
	v_cmp_ne_u32_e64 s[98:99], v14, v149
	v_cmp_ne_u32_e64 s[100:101], v15, v149
	v_cndmask_b32_e32 v13, 0, v13, vcc
	v_cndmask_b32_e64 v14, 0, v14, s[98:99]
	v_cndmask_b32_e64 v15, 0, v15, s[100:101]
	v_cmp_ne_u32_e32 vcc, v165, v149
	v_cmp_ne_u32_e64 s[98:99], v166, v149
	v_cmp_ne_u32_e64 s[100:101], v150, v149
	v_cndmask_b32_e32 v165, 0, v165, vcc
	v_cndmask_b32_e64 v166, 0, v166, s[98:99]
	v_cndmask_b32_e64 v167, 0, v150, s[100:101]
	v_cmp_ne_u32_e32 vcc, v151, v149
	v_max_u32_e32 v150, v4, v5
	v_max3_u32 v150, v150, v6, v7
	v_cndmask_b32_e32 v151, 0, v151, vcc
	v_cmp_ne_u32_e64 s[98:99], v152, v149
	v_max3_u32 v150, v150, v8, v9
	v_max3_u32 v150, v150, v10, v11
	v_cndmask_b32_e64 v152, 0, v152, s[98:99]
	v_cmp_ne_u32_e64 s[100:101], v153, v149
	v_max3_u32 v150, v150, v12, v13
	v_max3_u32 v150, v150, v14, v15
	v_cndmask_b32_e64 v153, 0, v153, s[100:101]
	v_cmp_ne_u32_e32 vcc, v154, v149
	v_max3_u32 v150, v150, v165, v166
	v_max3_u32 v150, v150, v167, v151
	v_cndmask_b32_e32 v154, 0, v154, vcc
	v_cmp_ne_u32_e64 s[98:99], v155, v149
	v_max3_u32 v150, v150, v152, v153
	v_cmp_ne_u32_e64 s[100:101], v156, v149
	v_cndmask_b32_e64 v155, 0, v155, s[98:99]
	v_max3_u32 v150, v150, v154, v155
	v_cndmask_b32_e64 v156, 0, v156, s[100:101]
	v_cmp_ne_u32_e32 vcc, v157, v149
	v_cmp_ne_u32_e64 s[98:99], v158, v149
	v_cmp_ne_u32_e64 s[100:101], v159, v149
	v_cndmask_b32_e32 v157, 0, v157, vcc
	v_max3_u32 v150, v150, v156, v157
	v_cndmask_b32_e64 v158, 0, v158, s[98:99]
	v_cndmask_b32_e64 v159, 0, v159, s[100:101]
	v_cmp_ne_u32_e32 vcc, v160, v149
	v_max3_u32 v150, v150, v158, v159
	v_cmp_ne_u32_e64 s[98:99], v161, v149
	v_cndmask_b32_e32 v160, 0, v160, vcc
	v_cmp_ne_u32_e64 s[100:101], v162, v149
	v_cndmask_b32_e64 v161, 0, v161, s[98:99]
	v_max3_u32 v150, v150, v160, v161
	v_cndmask_b32_e64 v162, 0, v162, s[100:101]
	v_cmp_ne_u32_e32 vcc, v164, v149
	v_cmp_ne_u32_e64 s[98:99], v0, v149
	v_cmp_ne_u32_e64 s[100:101], v1, v149
	v_cndmask_b32_e32 v164, 0, v164, vcc
	v_max3_u32 v150, v150, v162, v164
	v_cndmask_b32_e64 v0, 0, v0, s[98:99]
	v_cndmask_b32_e64 v1, 0, v1, s[100:101]
	v_cmp_ne_u32_e32 vcc, v2, v149
	v_max3_u32 v150, v150, v0, v1
	v_cmp_ne_u32_e64 s[98:99], v3, v149
	v_cndmask_b32_e32 v2, 0, v2, vcc
	s_nop 0
	v_cndmask_b32_e64 v3, 0, v3, s[98:99]
	v_max3_u32 v150, v150, v2, v3
	ds_bpermute_b32 v168, v111, v150
	s_waitcnt lgkmcnt(0)
; DI void peer_topk_wave(const Params& p, int item, unsigned* lds  ) {
;     ...
;     for (int rr = 0; rr < 16; ++rr) {
;       unsigned m = 0;
; #pragma unroll
;       for (int i = 0; i < 32; ++i) m = umax(m, kk[i]);
;       m = umax(m, (unsigned)__shfl_xor((int)m, 16));
;       m = umax(m, (unsigned)__shfl_xor((int)m, 32));
;       win[pp][rr] = m;
; #pragma unroll
;       for (int i = 0; i < 32; ++i) kk[i] = (kk[i] == m) ? 0u : kk[i];
;     }
	v_max_u32_e32 v150, v150, v168
	ds_bpermute_b32 v168, v112, v150
	s_waitcnt lgkmcnt(0)
	v_max_u32_e32 v150, v150, v168
	v_cmp_ne_u32_e32 vcc, v4, v150
	v_cmp_ne_u32_e64 s[98:99], v5, v150
	v_cmp_ne_u32_e64 s[100:101], v6, v150
	v_cndmask_b32_e32 v4, 0, v4, vcc
	v_cndmask_b32_e64 v5, 0, v5, s[98:99]
	v_cndmask_b32_e64 v6, 0, v6, s[100:101]
	v_cmp_ne_u32_e32 vcc, v7, v150
	v_cmp_ne_u32_e64 s[98:99], v8, v150
	v_cmp_ne_u32_e64 s[100:101], v9, v150
	v_cndmask_b32_e32 v7, 0, v7, vcc
	v_cndmask_b32_e64 v8, 0, v8, s[98:99]
	v_cndmask_b32_e64 v9, 0, v9, s[100:101]
	v_cmp_ne_u32_e32 vcc, v10, v150
	v_cmp_ne_u32_e64 s[98:99], v11, v150
	v_cmp_ne_u32_e64 s[100:101], v12, v150
	v_cndmask_b32_e32 v10, 0, v10, vcc
	v_cndmask_b32_e64 v11, 0, v11, s[98:99]
	v_cndmask_b32_e64 v12, 0, v12, s[100:101]
	v_cmp_ne_u32_e32 vcc, v13, v150
	v_cmp_ne_u32_e64 s[98:99], v14, v150
	v_cmp_ne_u32_e64 s[100:101], v15, v150
	v_cndmask_b32_e32 v13, 0, v13, vcc
	v_cndmask_b32_e64 v14, 0, v14, s[98:99]
	v_cndmask_b32_e64 v15, 0, v15, s[100:101]
	v_cmp_ne_u32_e32 vcc, v165, v150
	v_cmp_ne_u32_e64 s[98:99], v166, v150
	v_cmp_ne_u32_e64 s[100:101], v167, v150
	v_cndmask_b32_e32 v165, 0, v165, vcc
	v_cndmask_b32_e64 v166, 0, v166, s[98:99]
	v_cndmask_b32_e64 v167, 0, v167, s[100:101]
	v_cmp_ne_u32_e32 vcc, v151, v150
	v_cmp_ne_u32_e64 s[98:99], v152, v150
	v_cmp_ne_u32_e64 s[100:101], v153, v150
	v_cndmask_b32_e32 v168, 0, v151, vcc
	v_max_u32_e32 v151, v4, v5
	v_max3_u32 v151, v151, v6, v7
	v_cndmask_b32_e64 v152, 0, v152, s[98:99]
	v_max3_u32 v151, v151, v8, v9
	v_max3_u32 v151, v151, v10, v11
	v_cndmask_b32_e64 v153, 0, v153, s[100:101]
	v_cmp_ne_u32_e32 vcc, v154, v150
	v_max3_u32 v151, v151, v12, v13
	v_max3_u32 v151, v151, v14, v15
	v_cndmask_b32_e32 v154, 0, v154, vcc
	v_cmp_ne_u32_e64 s[98:99], v155, v150
	v_max3_u32 v151, v151, v165, v166
	v_max3_u32 v151, v151, v167, v168
	v_cndmask_b32_e64 v155, 0, v155, s[98:99]
	v_cmp_ne_u32_e64 s[100:101], v156, v150
	v_max3_u32 v151, v151, v152, v153
	v_max3_u32 v151, v151, v154, v155
	v_cndmask_b32_e64 v156, 0, v156, s[100:101]
	v_cmp_ne_u32_e32 vcc, v157, v150
	v_cmp_ne_u32_e64 s[98:99], v158, v150
	v_cmp_ne_u32_e64 s[100:101], v159, v150
	v_cndmask_b32_e32 v157, 0, v157, vcc
	v_max3_u32 v151, v151, v156, v157
	v_cndmask_b32_e64 v158, 0, v158, s[98:99]
	v_cndmask_b32_e64 v159, 0, v159, s[100:101]
	v_cmp_ne_u32_e32 vcc, v160, v150
	v_max3_u32 v151, v151, v158, v159
	v_cmp_ne_u32_e64 s[98:99], v161, v150
	v_cndmask_b32_e32 v160, 0, v160, vcc
	v_cmp_ne_u32_e64 s[100:101], v162, v150
	v_cndmask_b32_e64 v161, 0, v161, s[98:99]
	v_max3_u32 v151, v151, v160, v161
	v_cndmask_b32_e64 v162, 0, v162, s[100:101]
	v_cmp_ne_u32_e32 vcc, v164, v150
	v_cmp_ne_u32_e64 s[98:99], v0, v150
	v_cmp_ne_u32_e64 s[100:101], v1, v150
	v_cndmask_b32_e32 v164, 0, v164, vcc
	v_max3_u32 v151, v151, v162, v164
	v_cndmask_b32_e64 v0, 0, v0, s[98:99]
	v_cndmask_b32_e64 v1, 0, v1, s[100:101]
	v_cmp_ne_u32_e32 vcc, v2, v150
	v_max3_u32 v151, v151, v0, v1
	v_cmp_ne_u32_e64 s[98:99], v3, v150
	v_cndmask_b32_e32 v2, 0, v2, vcc
	s_nop 0
	v_cndmask_b32_e64 v3, 0, v3, s[98:99]
	v_max3_u32 v151, v151, v2, v3
	ds_bpermute_b32 v169, v111, v151
	s_waitcnt lgkmcnt(0)
	v_max_u32_e32 v151, v151, v169
	ds_bpermute_b32 v169, v112, v151
	s_waitcnt lgkmcnt(0)
	v_max_u32_e32 v151, v151, v169
	v_cmp_ne_u32_e32 vcc, v4, v151
	v_cmp_ne_u32_e64 s[98:99], v5, v151
	v_cmp_ne_u32_e64 s[100:101], v6, v151
	v_cndmask_b32_e32 v4, 0, v4, vcc
	v_cndmask_b32_e64 v5, 0, v5, s[98:99]
	v_cndmask_b32_e64 v6, 0, v6, s[100:101]
	v_cmp_ne_u32_e32 vcc, v7, v151
	v_cmp_ne_u32_e64 s[98:99], v8, v151
	v_cmp_ne_u32_e64 s[100:101], v9, v151
	v_cndmask_b32_e32 v7, 0, v7, vcc
	v_cndmask_b32_e64 v8, 0, v8, s[98:99]
	v_cndmask_b32_e64 v9, 0, v9, s[100:101]
	v_cmp_ne_u32_e32 vcc, v10, v151
	v_cmp_ne_u32_e64 s[98:99], v11, v151
	v_cmp_ne_u32_e64 s[100:101], v12, v151
	v_cndmask_b32_e32 v10, 0, v10, vcc
	v_cndmask_b32_e64 v11, 0, v11, s[98:99]
	v_cndmask_b32_e64 v12, 0, v12, s[100:101]
	v_cmp_ne_u32_e32 vcc, v13, v151
	v_cmp_ne_u32_e64 s[98:99], v14, v151
	v_cmp_ne_u32_e64 s[100:101], v15, v151
	v_cndmask_b32_e32 v13, 0, v13, vcc
	v_cndmask_b32_e64 v14, 0, v14, s[98:99]
	v_cndmask_b32_e64 v15, 0, v15, s[100:101]
	v_cmp_ne_u32_e32 vcc, v165, v151
	v_cmp_ne_u32_e64 s[98:99], v166, v151
	v_cmp_ne_u32_e64 s[100:101], v167, v151
	v_cndmask_b32_e32 v165, 0, v165, vcc
	v_cndmask_b32_e64 v166, 0, v166, s[98:99]
	v_cndmask_b32_e64 v167, 0, v167, s[100:101]
	v_cmp_ne_u32_e32 vcc, v168, v151
	v_cmp_ne_u32_e64 s[98:99], v152, v151
	v_cmp_ne_u32_e64 s[100:101], v153, v151
	v_cndmask_b32_e32 v168, 0, v168, vcc
	v_cndmask_b32_e64 v169, 0, v152, s[98:99]
	v_max_u32_e32 v152, v4, v5
	v_max3_u32 v152, v152, v6, v7
	v_cndmask_b32_e64 v153, 0, v153, s[100:101]
	v_cmp_ne_u32_e32 vcc, v154, v151
	v_max3_u32 v152, v152, v8, v9
	v_max3_u32 v152, v152, v10, v11
	v_cndmask_b32_e32 v154, 0, v154, vcc
	v_cmp_ne_u32_e64 s[98:99], v155, v151
	v_max3_u32 v152, v152, v12, v13
	v_max3_u32 v152, v152, v14, v15
	v_cndmask_b32_e64 v155, 0, v155, s[98:99]
	v_cmp_ne_u32_e64 s[100:101], v156, v151
	v_max3_u32 v152, v152, v165, v166
	v_max3_u32 v152, v152, v167, v168
	v_cndmask_b32_e64 v156, 0, v156, s[100:101]
	v_cmp_ne_u32_e32 vcc, v157, v151
	v_max3_u32 v152, v152, v169, v153
	v_max3_u32 v152, v152, v154, v155
	v_cndmask_b32_e32 v157, 0, v157, vcc
	v_cmp_ne_u32_e64 s[98:99], v158, v151
	v_max3_u32 v152, v152, v156, v157
	v_cmp_ne_u32_e64 s[100:101], v159, v151
	v_cndmask_b32_e64 v158, 0, v158, s[98:99]
	v_cmp_ne_u32_e32 vcc, v160, v151
	v_cndmask_b32_e64 v159, 0, v159, s[100:101]
	v_max3_u32 v152, v152, v158, v159
	v_cndmask_b32_e32 v160, 0, v160, vcc
	v_cmp_ne_u32_e64 s[98:99], v161, v151
	v_cmp_ne_u32_e64 s[100:101], v162, v151
	v_cmp_ne_u32_e32 vcc, v164, v151
	v_cndmask_b32_e64 v161, 0, v161, s[98:99]
	v_max3_u32 v152, v152, v160, v161
	v_cndmask_b32_e64 v162, 0, v162, s[100:101]
	v_cndmask_b32_e32 v164, 0, v164, vcc
	v_cmp_ne_u32_e64 s[98:99], v0, v151
	v_max3_u32 v152, v152, v162, v164
	v_cmp_ne_u32_e64 s[100:101], v1, v151
	v_cndmask_b32_e64 v0, 0, v0, s[98:99]
	v_cmp_ne_u32_e32 vcc, v2, v151
	v_cndmask_b32_e64 v1, 0, v1, s[100:101]
	v_max3_u32 v152, v152, v0, v1
	v_cndmask_b32_e32 v2, 0, v2, vcc
	v_cmp_ne_u32_e64 s[98:99], v3, v151
	s_nop 0
	s_nop 0
	v_cndmask_b32_e64 v3, 0, v3, s[98:99]
	v_max3_u32 v152, v152, v2, v3
	ds_bpermute_b32 v171, v111, v152
	s_waitcnt lgkmcnt(0)
; DI void peer_topk_wave(const Params& p, int item, unsigned* lds  ) {
;     ...
;     for (int rr = 0; rr < 16; ++rr) {
;       unsigned m = 0;
; #pragma unroll
;       for (int i = 0; i < 32; ++i) m = umax(m, kk[i]);
;       m = umax(m, (unsigned)__shfl_xor((int)m, 16));
;       m = umax(m, (unsigned)__shfl_xor((int)m, 32));
;       win[pp][rr] = m;
; #pragma unroll
;       for (int i = 0; i < 32; ++i) kk[i] = (kk[i] == m) ? 0u : kk[i];
;     }
	v_max_u32_e32 v152, v152, v171
	ds_bpermute_b32 v171, v112, v152
	s_waitcnt lgkmcnt(0)
	v_max_u32_e32 v152, v152, v171
	v_cmp_ne_u32_e32 vcc, v4, v152
	v_cmp_ne_u32_e64 s[98:99], v5, v152
	v_cmp_ne_u32_e64 s[100:101], v6, v152
	v_cndmask_b32_e32 v4, 0, v4, vcc
	v_cndmask_b32_e64 v5, 0, v5, s[98:99]
	v_cndmask_b32_e64 v6, 0, v6, s[100:101]
	v_cmp_ne_u32_e32 vcc, v7, v152
	v_cmp_ne_u32_e64 s[98:99], v8, v152
	v_cmp_ne_u32_e64 s[100:101], v9, v152
	v_cndmask_b32_e32 v7, 0, v7, vcc
	v_cndmask_b32_e64 v8, 0, v8, s[98:99]
	v_cndmask_b32_e64 v9, 0, v9, s[100:101]
	v_cmp_ne_u32_e32 vcc, v10, v152
	v_cmp_ne_u32_e64 s[98:99], v11, v152
	v_cmp_ne_u32_e64 s[100:101], v12, v152
	v_cndmask_b32_e32 v10, 0, v10, vcc
	v_cndmask_b32_e64 v11, 0, v11, s[98:99]
	v_cndmask_b32_e64 v12, 0, v12, s[100:101]
	v_cmp_ne_u32_e32 vcc, v13, v152
	v_cmp_ne_u32_e64 s[98:99], v14, v152
	v_cmp_ne_u32_e64 s[100:101], v15, v152
	v_cndmask_b32_e32 v13, 0, v13, vcc
	v_cndmask_b32_e64 v14, 0, v14, s[98:99]
	v_cndmask_b32_e64 v15, 0, v15, s[100:101]
	v_cmp_ne_u32_e32 vcc, v165, v152
	v_cmp_ne_u32_e64 s[98:99], v166, v152
	v_cmp_ne_u32_e64 s[100:101], v167, v152
	v_cndmask_b32_e32 v165, 0, v165, vcc
	v_cndmask_b32_e64 v166, 0, v166, s[98:99]
	v_cndmask_b32_e64 v167, 0, v167, s[100:101]
	v_cmp_ne_u32_e32 vcc, v168, v152
	v_cmp_ne_u32_e64 s[98:99], v169, v152
	v_cmp_ne_u32_e64 s[100:101], v153, v152
	v_cndmask_b32_e32 v168, 0, v168, vcc
	v_cndmask_b32_e64 v169, 0, v169, s[98:99]
	v_cndmask_b32_e64 v171, 0, v153, s[100:101]
	v_cmp_ne_u32_e32 vcc, v154, v152
	v_max_u32_e32 v153, v4, v5
	v_max3_u32 v153, v153, v6, v7
	v_cndmask_b32_e32 v154, 0, v154, vcc
	v_cmp_ne_u32_e64 s[98:99], v155, v152
	v_max3_u32 v153, v153, v8, v9
	v_max3_u32 v153, v153, v10, v11
	v_cndmask_b32_e64 v155, 0, v155, s[98:99]
	v_cmp_ne_u32_e64 s[100:101], v156, v152
	v_max3_u32 v153, v153, v12, v13
	v_max3_u32 v153, v153, v14, v15
	v_cndmask_b32_e64 v156, 0, v156, s[100:101]
	v_cmp_ne_u32_e32 vcc, v157, v152
	v_max3_u32 v153, v153, v165, v166
	v_max3_u32 v153, v153, v167, v168
	v_cndmask_b32_e32 v157, 0, v157, vcc
	v_cmp_ne_u32_e64 s[98:99], v158, v152
	v_max3_u32 v153, v153, v169, v171
	v_max3_u32 v153, v153, v154, v155
	v_cndmask_b32_e64 v158, 0, v158, s[98:99]
	v_cmp_ne_u32_e64 s[100:101], v159, v152
	v_max3_u32 v153, v153, v156, v157
	v_cmp_ne_u32_e32 vcc, v160, v152
	v_cndmask_b32_e64 v159, 0, v159, s[100:101]
	v_max3_u32 v153, v153, v158, v159
	v_cndmask_b32_e32 v160, 0, v160, vcc
	v_cmp_ne_u32_e64 s[98:99], v161, v152
	v_cmp_ne_u32_e64 s[100:101], v162, v152
	v_cmp_ne_u32_e32 vcc, v164, v152
	v_cndmask_b32_e64 v161, 0, v161, s[98:99]
	v_max3_u32 v153, v153, v160, v161
	v_cndmask_b32_e64 v162, 0, v162, s[100:101]
	v_cndmask_b32_e32 v164, 0, v164, vcc
	v_cmp_ne_u32_e64 s[98:99], v0, v152
	v_max3_u32 v153, v153, v162, v164
	v_cmp_ne_u32_e64 s[100:101], v1, v152
	v_cndmask_b32_e64 v0, 0, v0, s[98:99]
	v_cmp_ne_u32_e32 vcc, v2, v152
	v_cndmask_b32_e64 v1, 0, v1, s[100:101]
	v_max3_u32 v153, v153, v0, v1
	v_cndmask_b32_e32 v2, 0, v2, vcc
	v_cmp_ne_u32_e64 s[98:99], v3, v152
	s_nop 0
	s_nop 0
	v_cndmask_b32_e64 v3, 0, v3, s[98:99]
	v_max3_u32 v153, v153, v2, v3
	ds_bpermute_b32 v172, v111, v153
	s_waitcnt lgkmcnt(0)
	v_max_u32_e32 v153, v153, v172
	ds_bpermute_b32 v172, v112, v153
	s_waitcnt lgkmcnt(0)
	v_max_u32_e32 v153, v153, v172
	v_cmp_ne_u32_e32 vcc, v4, v153
	v_cmp_ne_u32_e64 s[98:99], v5, v153
	v_cmp_ne_u32_e64 s[100:101], v6, v153
	v_cndmask_b32_e32 v4, 0, v4, vcc
	v_cndmask_b32_e64 v5, 0, v5, s[98:99]
	v_cndmask_b32_e64 v6, 0, v6, s[100:101]
	v_cmp_ne_u32_e32 vcc, v7, v153
	v_cmp_ne_u32_e64 s[98:99], v8, v153
	v_cmp_ne_u32_e64 s[100:101], v9, v153
	v_cndmask_b32_e32 v7, 0, v7, vcc
	v_cndmask_b32_e64 v8, 0, v8, s[98:99]
	v_cndmask_b32_e64 v9, 0, v9, s[100:101]
	v_cmp_ne_u32_e32 vcc, v10, v153
	v_cmp_ne_u32_e64 s[98:99], v11, v153
	v_cmp_ne_u32_e64 s[100:101], v12, v153
	v_cndmask_b32_e32 v10, 0, v10, vcc
	v_cndmask_b32_e64 v11, 0, v11, s[98:99]
	v_cndmask_b32_e64 v12, 0, v12, s[100:101]
	v_cmp_ne_u32_e32 vcc, v13, v153
	v_cmp_ne_u32_e64 s[98:99], v14, v153
	v_cmp_ne_u32_e64 s[100:101], v15, v153
	v_cndmask_b32_e32 v13, 0, v13, vcc
	v_cndmask_b32_e64 v14, 0, v14, s[98:99]
	v_cndmask_b32_e64 v15, 0, v15, s[100:101]
	v_cmp_ne_u32_e32 vcc, v165, v153
	v_cmp_ne_u32_e64 s[98:99], v166, v153
	v_cmp_ne_u32_e64 s[100:101], v167, v153
	v_cndmask_b32_e32 v165, 0, v165, vcc
	v_cndmask_b32_e64 v166, 0, v166, s[98:99]
	v_cndmask_b32_e64 v167, 0, v167, s[100:101]
	v_cmp_ne_u32_e32 vcc, v168, v153
	v_cmp_ne_u32_e64 s[98:99], v169, v153
	v_cmp_ne_u32_e64 s[100:101], v171, v153
	v_cndmask_b32_e32 v168, 0, v168, vcc
	v_cndmask_b32_e64 v169, 0, v169, s[98:99]
	v_cndmask_b32_e64 v171, 0, v171, s[100:101]
	v_cmp_ne_u32_e32 vcc, v154, v153
	v_cmp_ne_u32_e64 s[98:99], v155, v153
	v_cmp_ne_u32_e64 s[100:101], v156, v153
	v_cndmask_b32_e32 v172, 0, v154, vcc
	v_max_u32_e32 v154, v4, v5
	v_max3_u32 v154, v154, v6, v7
	v_max3_u32 v154, v154, v8, v9
	v_cndmask_b32_e64 v155, 0, v155, s[98:99]
	v_max3_u32 v154, v154, v10, v11
	v_max3_u32 v154, v154, v12, v13
	v_cndmask_b32_e64 v156, 0, v156, s[100:101]
	v_cmp_ne_u32_e32 vcc, v157, v153
	v_max3_u32 v154, v154, v14, v15
	v_max3_u32 v154, v154, v165, v166
	v_cndmask_b32_e32 v157, 0, v157, vcc
	v_cmp_ne_u32_e64 s[98:99], v158, v153
	v_max3_u32 v154, v154, v167, v168
	v_max3_u32 v154, v154, v169, v171
	v_cndmask_b32_e64 v158, 0, v158, s[98:99]
	v_cmp_ne_u32_e64 s[100:101], v159, v153
	v_max3_u32 v154, v154, v172, v155
	v_max3_u32 v154, v154, v156, v157
	v_cndmask_b32_e64 v159, 0, v159, s[100:101]
	v_cmp_ne_u32_e32 vcc, v160, v153
	v_max3_u32 v154, v154, v158, v159
	v_cmp_ne_u32_e64 s[98:99], v161, v153
	v_cndmask_b32_e32 v160, 0, v160, vcc
	v_cmp_ne_u32_e64 s[100:101], v162, v153
	v_cndmask_b32_e64 v161, 0, v161, s[98:99]
	v_max3_u32 v154, v154, v160, v161
	v_cndmask_b32_e64 v162, 0, v162, s[100:101]
	v_cmp_ne_u32_e32 vcc, v164, v153
	v_cmp_ne_u32_e64 s[98:99], v0, v153
	v_cmp_ne_u32_e64 s[100:101], v1, v153
	v_cndmask_b32_e32 v164, 0, v164, vcc
	v_max3_u32 v154, v154, v162, v164
	v_cndmask_b32_e64 v0, 0, v0, s[98:99]
	v_cndmask_b32_e64 v1, 0, v1, s[100:101]
	v_cmp_ne_u32_e32 vcc, v2, v153
	v_max3_u32 v154, v154, v0, v1
	v_cmp_ne_u32_e64 s[98:99], v3, v153
	v_cndmask_b32_e32 v2, 0, v2, vcc
	s_nop 0
	v_cndmask_b32_e64 v3, 0, v3, s[98:99]
	v_max3_u32 v154, v154, v2, v3
	ds_bpermute_b32 v173, v111, v154
	s_waitcnt lgkmcnt(0)
; DI void peer_topk_wave(const Params& p, int item, unsigned* lds  ) {
;     ...
;     for (int rr = 0; rr < 16; ++rr) {
;       unsigned m = 0;
; #pragma unroll
;       for (int i = 0; i < 32; ++i) m = umax(m, kk[i]);
;       m = umax(m, (unsigned)__shfl_xor((int)m, 16));
;       m = umax(m, (unsigned)__shfl_xor((int)m, 32));
;       win[pp][rr] = m;
; #pragma unroll
;       for (int i = 0; i < 32; ++i) kk[i] = (kk[i] == m) ? 0u : kk[i];
;     }
	v_max_u32_e32 v154, v154, v173
	ds_bpermute_b32 v173, v112, v154
	s_waitcnt lgkmcnt(0)
	v_max_u32_e32 v154, v154, v173
	v_cmp_ne_u32_e32 vcc, v4, v154
	v_cmp_ne_u32_e64 s[98:99], v5, v154
	v_cmp_ne_u32_e64 s[100:101], v6, v154
	v_cndmask_b32_e32 v4, 0, v4, vcc
	v_cndmask_b32_e64 v5, 0, v5, s[98:99]
	v_cndmask_b32_e64 v6, 0, v6, s[100:101]
	v_cmp_ne_u32_e32 vcc, v7, v154
	v_cmp_ne_u32_e64 s[98:99], v8, v154
	v_cmp_ne_u32_e64 s[100:101], v9, v154
	v_cndmask_b32_e32 v7, 0, v7, vcc
	v_cndmask_b32_e64 v8, 0, v8, s[98:99]
	v_cndmask_b32_e64 v9, 0, v9, s[100:101]
	v_cmp_ne_u32_e32 vcc, v10, v154
	v_cmp_ne_u32_e64 s[98:99], v11, v154
	v_cmp_ne_u32_e64 s[100:101], v12, v154
	v_cndmask_b32_e32 v10, 0, v10, vcc
	v_cndmask_b32_e64 v11, 0, v11, s[98:99]
	v_cndmask_b32_e64 v12, 0, v12, s[100:101]
	v_cmp_ne_u32_e32 vcc, v13, v154
	v_cmp_ne_u32_e64 s[98:99], v14, v154
	v_cmp_ne_u32_e64 s[100:101], v15, v154
	v_cndmask_b32_e32 v13, 0, v13, vcc
	v_cndmask_b32_e64 v14, 0, v14, s[98:99]
	v_cndmask_b32_e64 v15, 0, v15, s[100:101]
	v_cmp_ne_u32_e32 vcc, v165, v154
	v_cmp_ne_u32_e64 s[98:99], v166, v154
	v_cmp_ne_u32_e64 s[100:101], v167, v154
	v_cndmask_b32_e32 v165, 0, v165, vcc
	v_cndmask_b32_e64 v166, 0, v166, s[98:99]
	v_cndmask_b32_e64 v167, 0, v167, s[100:101]
	v_cmp_ne_u32_e32 vcc, v168, v154
	v_cmp_ne_u32_e64 s[98:99], v169, v154
	v_cmp_ne_u32_e64 s[100:101], v171, v154
	v_cndmask_b32_e32 v168, 0, v168, vcc
	v_cndmask_b32_e64 v169, 0, v169, s[98:99]
	v_cndmask_b32_e64 v171, 0, v171, s[100:101]
	v_cmp_ne_u32_e32 vcc, v172, v154
	v_cmp_ne_u32_e64 s[98:99], v155, v154
	v_cmp_ne_u32_e64 s[100:101], v156, v154
	v_cndmask_b32_e32 v172, 0, v172, vcc
	v_cndmask_b32_e64 v173, 0, v155, s[98:99]
	v_max_u32_e32 v155, v4, v5
	v_max3_u32 v155, v155, v6, v7
	v_max3_u32 v155, v155, v8, v9
	v_max3_u32 v155, v155, v10, v11
	v_cndmask_b32_e64 v156, 0, v156, s[100:101]
	v_cmp_ne_u32_e32 vcc, v157, v154
	v_max3_u32 v155, v155, v12, v13
	v_max3_u32 v155, v155, v14, v15
	v_cndmask_b32_e32 v157, 0, v157, vcc
	v_cmp_ne_u32_e64 s[98:99], v158, v154
	v_max3_u32 v155, v155, v165, v166
	v_max3_u32 v155, v155, v167, v168
	v_cndmask_b32_e64 v158, 0, v158, s[98:99]
	v_cmp_ne_u32_e64 s[100:101], v159, v154
	v_max3_u32 v155, v155, v169, v171
	v_max3_u32 v155, v155, v172, v173
	v_cndmask_b32_e64 v159, 0, v159, s[100:101]
	v_cmp_ne_u32_e32 vcc, v160, v154
	v_max3_u32 v155, v155, v156, v157
	v_max3_u32 v155, v155, v158, v159
	v_cndmask_b32_e32 v160, 0, v160, vcc
	v_cmp_ne_u32_e64 s[98:99], v161, v154
	v_cmp_ne_u32_e64 s[100:101], v162, v154
	v_cmp_ne_u32_e32 vcc, v164, v154
	v_cndmask_b32_e64 v161, 0, v161, s[98:99]
	v_max3_u32 v155, v155, v160, v161
	v_cndmask_b32_e64 v162, 0, v162, s[100:101]
	v_cndmask_b32_e32 v164, 0, v164, vcc
	v_cmp_ne_u32_e64 s[98:99], v0, v154
	v_max3_u32 v155, v155, v162, v164
	v_cmp_ne_u32_e64 s[100:101], v1, v154
	v_cndmask_b32_e64 v0, 0, v0, s[98:99]
	v_cmp_ne_u32_e32 vcc, v2, v154
	v_cndmask_b32_e64 v1, 0, v1, s[100:101]
	v_max3_u32 v155, v155, v0, v1
	v_cndmask_b32_e32 v2, 0, v2, vcc
	v_cmp_ne_u32_e64 s[98:99], v3, v154
	s_nop 0
	s_nop 0
	v_cndmask_b32_e64 v3, 0, v3, s[98:99]
	v_max3_u32 v155, v155, v2, v3
	ds_bpermute_b32 v176, v111, v155
	s_waitcnt lgkmcnt(0)
	v_max_u32_e32 v155, v155, v176
	ds_bpermute_b32 v176, v112, v155
	s_waitcnt lgkmcnt(0)
	v_max_u32_e32 v155, v155, v176
	v_cmp_ne_u32_e32 vcc, v4, v155
	v_cmp_ne_u32_e64 s[98:99], v5, v155
	v_cmp_ne_u32_e64 s[100:101], v6, v155
	v_cndmask_b32_e32 v4, 0, v4, vcc
	v_cndmask_b32_e64 v5, 0, v5, s[98:99]
	v_cndmask_b32_e64 v6, 0, v6, s[100:101]
	v_cmp_ne_u32_e32 vcc, v7, v155
	v_cmp_ne_u32_e64 s[98:99], v8, v155
	v_cmp_ne_u32_e64 s[100:101], v9, v155
	v_cndmask_b32_e32 v7, 0, v7, vcc
	v_cndmask_b32_e64 v8, 0, v8, s[98:99]
	v_cndmask_b32_e64 v9, 0, v9, s[100:101]
	v_cmp_ne_u32_e32 vcc, v10, v155
	v_cmp_ne_u32_e64 s[98:99], v11, v155
	v_cmp_ne_u32_e64 s[100:101], v12, v155
	v_cndmask_b32_e32 v10, 0, v10, vcc
	v_cndmask_b32_e64 v11, 0, v11, s[98:99]
	v_cndmask_b32_e64 v12, 0, v12, s[100:101]
	v_cmp_ne_u32_e32 vcc, v13, v155
	v_cmp_ne_u32_e64 s[98:99], v14, v155
	v_cmp_ne_u32_e64 s[100:101], v15, v155
	v_cndmask_b32_e32 v13, 0, v13, vcc
	v_cndmask_b32_e64 v14, 0, v14, s[98:99]
	v_cndmask_b32_e64 v15, 0, v15, s[100:101]
	v_cmp_ne_u32_e32 vcc, v165, v155
	v_cmp_ne_u32_e64 s[98:99], v166, v155
	v_cmp_ne_u32_e64 s[100:101], v167, v155
	v_cndmask_b32_e32 v165, 0, v165, vcc
	v_cndmask_b32_e64 v166, 0, v166, s[98:99]
	v_cndmask_b32_e64 v167, 0, v167, s[100:101]
	v_cmp_ne_u32_e32 vcc, v168, v155
	v_cmp_ne_u32_e64 s[98:99], v169, v155
	v_cmp_ne_u32_e64 s[100:101], v171, v155
	v_cndmask_b32_e32 v168, 0, v168, vcc
	v_cndmask_b32_e64 v169, 0, v169, s[98:99]
	v_cndmask_b32_e64 v171, 0, v171, s[100:101]
	v_cmp_ne_u32_e32 vcc, v172, v155
	v_cmp_ne_u32_e64 s[98:99], v173, v155
	v_cmp_ne_u32_e64 s[100:101], v156, v155
	v_cndmask_b32_e32 v172, 0, v172, vcc
	v_cndmask_b32_e64 v173, 0, v173, s[98:99]
	v_cndmask_b32_e64 v176, 0, v156, s[100:101]
	v_max_u32_e32 v156, v4, v5
	v_max3_u32 v156, v156, v6, v7
	v_max3_u32 v156, v156, v8, v9
	v_cmp_ne_u32_e32 vcc, v157, v155
	v_max3_u32 v156, v156, v10, v11
	v_max3_u32 v156, v156, v12, v13
	v_cndmask_b32_e32 v157, 0, v157, vcc
	v_cmp_ne_u32_e64 s[98:99], v158, v155
	v_max3_u32 v156, v156, v14, v15
	v_max3_u32 v156, v156, v165, v166
	v_cndmask_b32_e64 v158, 0, v158, s[98:99]
	v_cmp_ne_u32_e64 s[100:101], v159, v155
	v_max3_u32 v156, v156, v167, v168
	v_max3_u32 v156, v156, v169, v171
	v_cndmask_b32_e64 v159, 0, v159, s[100:101]
	v_cmp_ne_u32_e32 vcc, v160, v155
	v_max3_u32 v156, v156, v172, v173
	v_max3_u32 v156, v156, v176, v157
	v_cndmask_b32_e32 v160, 0, v160, vcc
	v_cmp_ne_u32_e64 s[98:99], v161, v155
	v_max3_u32 v156, v156, v158, v159
	v_cmp_ne_u32_e64 s[100:101], v162, v155
	v_cndmask_b32_e64 v161, 0, v161, s[98:99]
	v_max3_u32 v156, v156, v160, v161
	v_cndmask_b32_e64 v162, 0, v162, s[100:101]
	v_cmp_ne_u32_e32 vcc, v164, v155
	v_cmp_ne_u32_e64 s[98:99], v0, v155
	v_cmp_ne_u32_e64 s[100:101], v1, v155
	v_cndmask_b32_e32 v164, 0, v164, vcc
	v_max3_u32 v156, v156, v162, v164
	v_cndmask_b32_e64 v0, 0, v0, s[98:99]
	v_cndmask_b32_e64 v1, 0, v1, s[100:101]
	v_cmp_ne_u32_e32 vcc, v2, v155
	v_max3_u32 v156, v156, v0, v1
	v_cmp_ne_u32_e64 s[98:99], v3, v155
	v_cndmask_b32_e32 v2, 0, v2, vcc
	s_nop 0
	v_cndmask_b32_e64 v3, 0, v3, s[98:99]
	v_max3_u32 v156, v156, v2, v3
	ds_bpermute_b32 v177, v111, v156
	s_waitcnt lgkmcnt(0)
; DI void peer_topk_wave(const Params& p, int item, unsigned* lds  ) {
;     ...
;     for (int rr = 0; rr < 16; ++rr) {
;       unsigned m = 0;
; #pragma unroll
;       for (int i = 0; i < 32; ++i) m = umax(m, kk[i]);
;       m = umax(m, (unsigned)__shfl_xor((int)m, 16));
;       m = umax(m, (unsigned)__shfl_xor((int)m, 32));
;       win[pp][rr] = m;
; #pragma unroll
;       for (int i = 0; i < 32; ++i) kk[i] = (kk[i] == m) ? 0u : kk[i];
;     }
	v_max_u32_e32 v156, v156, v177
	ds_bpermute_b32 v177, v112, v156
	s_waitcnt lgkmcnt(0)
	v_max_u32_e32 v156, v156, v177
	v_cmp_ne_u32_e32 vcc, v4, v156
	v_cmp_ne_u32_e64 s[98:99], v5, v156
	v_cmp_ne_u32_e64 s[100:101], v6, v156
	v_cndmask_b32_e32 v4, 0, v4, vcc
	v_cndmask_b32_e64 v5, 0, v5, s[98:99]
	v_cndmask_b32_e64 v6, 0, v6, s[100:101]
	v_cmp_ne_u32_e32 vcc, v7, v156
	v_cmp_ne_u32_e64 s[98:99], v8, v156
	v_cmp_ne_u32_e64 s[100:101], v9, v156
	v_cndmask_b32_e32 v7, 0, v7, vcc
	v_cndmask_b32_e64 v8, 0, v8, s[98:99]
	v_cndmask_b32_e64 v9, 0, v9, s[100:101]
	v_cmp_ne_u32_e32 vcc, v10, v156
	v_cmp_ne_u32_e64 s[98:99], v11, v156
	v_cmp_ne_u32_e64 s[100:101], v12, v156
	v_cndmask_b32_e32 v10, 0, v10, vcc
	v_cndmask_b32_e64 v11, 0, v11, s[98:99]
	v_cndmask_b32_e64 v12, 0, v12, s[100:101]
	v_cmp_ne_u32_e32 vcc, v13, v156
	v_cmp_ne_u32_e64 s[98:99], v14, v156
	v_cmp_ne_u32_e64 s[100:101], v15, v156
	v_cndmask_b32_e32 v13, 0, v13, vcc
	v_cndmask_b32_e64 v14, 0, v14, s[98:99]
	v_cndmask_b32_e64 v15, 0, v15, s[100:101]
	v_cmp_ne_u32_e32 vcc, v165, v156
	v_cmp_ne_u32_e64 s[98:99], v166, v156
	v_cmp_ne_u32_e64 s[100:101], v167, v156
	v_cndmask_b32_e32 v165, 0, v165, vcc
	v_cndmask_b32_e64 v166, 0, v166, s[98:99]
	v_cndmask_b32_e64 v167, 0, v167, s[100:101]
	v_cmp_ne_u32_e32 vcc, v168, v156
	v_cmp_ne_u32_e64 s[98:99], v169, v156
	v_cmp_ne_u32_e64 s[100:101], v171, v156
	v_cndmask_b32_e32 v168, 0, v168, vcc
	v_cndmask_b32_e64 v169, 0, v169, s[98:99]
	v_cndmask_b32_e64 v171, 0, v171, s[100:101]
	v_cmp_ne_u32_e32 vcc, v172, v156
	v_cmp_ne_u32_e64 s[98:99], v173, v156
	v_cmp_ne_u32_e64 s[100:101], v176, v156
	v_cndmask_b32_e32 v172, 0, v172, vcc
	v_cndmask_b32_e64 v173, 0, v173, s[98:99]
	v_cndmask_b32_e64 v176, 0, v176, s[100:101]
	v_cmp_ne_u32_e32 vcc, v157, v156
	v_cmp_ne_u32_e64 s[98:99], v158, v156
	v_cmp_ne_u32_e64 s[100:101], v159, v156
	v_cndmask_b32_e32 v177, 0, v157, vcc
	v_max_u32_e32 v157, v4, v5
	v_max3_u32 v157, v157, v6, v7
	v_max3_u32 v157, v157, v8, v9
	v_max3_u32 v157, v157, v10, v11
	v_max3_u32 v157, v157, v12, v13
	v_max3_u32 v157, v157, v14, v15
	v_cndmask_b32_e64 v158, 0, v158, s[98:99]
	v_max3_u32 v157, v157, v165, v166
	v_max3_u32 v157, v157, v167, v168
	v_cndmask_b32_e64 v159, 0, v159, s[100:101]
	v_cmp_ne_u32_e32 vcc, v160, v156
	v_max3_u32 v157, v157, v169, v171
	v_max3_u32 v157, v157, v172, v173
	v_cndmask_b32_e32 v160, 0, v160, vcc
	v_cmp_ne_u32_e64 s[98:99], v161, v156
	v_max3_u32 v157, v157, v176, v177
	v_max3_u32 v157, v157, v158, v159
	v_cndmask_b32_e64 v161, 0, v161, s[98:99]
	v_cmp_ne_u32_e64 s[100:101], v162, v156
	v_max3_u32 v157, v157, v160, v161
	v_cmp_ne_u32_e32 vcc, v164, v156
	v_cndmask_b32_e64 v162, 0, v162, s[100:101]
	v_cmp_ne_u32_e64 s[98:99], v0, v156
	v_cndmask_b32_e32 v164, 0, v164, vcc
	v_max3_u32 v157, v157, v162, v164
	v_cndmask_b32_e64 v0, 0, v0, s[98:99]
	v_cmp_ne_u32_e64 s[100:101], v1, v156
	v_cmp_ne_u32_e32 vcc, v2, v156
	v_cmp_ne_u32_e64 s[98:99], v3, v156
	v_cndmask_b32_e64 v1, 0, v1, s[100:101]
	v_max3_u32 v157, v157, v0, v1
	v_cndmask_b32_e32 v2, 0, v2, vcc
	v_cndmask_b32_e64 v3, 0, v3, s[98:99]
	v_max3_u32 v157, v157, v2, v3
	ds_bpermute_b32 v178, v111, v157
	s_waitcnt lgkmcnt(0)
	v_max_u32_e32 v157, v157, v178
	ds_bpermute_b32 v178, v112, v157
	s_waitcnt lgkmcnt(0)
	v_max_u32_e32 v157, v157, v178
	v_cmp_ne_u32_e32 vcc, v4, v157
	v_cmp_ne_u32_e64 s[98:99], v5, v157
	v_cmp_ne_u32_e64 s[100:101], v6, v157
	v_cndmask_b32_e32 v4, 0, v4, vcc
	v_cndmask_b32_e64 v5, 0, v5, s[98:99]
	v_cndmask_b32_e64 v6, 0, v6, s[100:101]
	v_cmp_ne_u32_e32 vcc, v7, v157
	v_cmp_ne_u32_e64 s[98:99], v8, v157
	v_cmp_ne_u32_e64 s[100:101], v9, v157
	v_cndmask_b32_e32 v7, 0, v7, vcc
	v_cndmask_b32_e64 v8, 0, v8, s[98:99]
	v_cndmask_b32_e64 v9, 0, v9, s[100:101]
	v_cmp_ne_u32_e32 vcc, v10, v157
	v_cmp_ne_u32_e64 s[98:99], v11, v157
	v_cmp_ne_u32_e64 s[100:101], v12, v157
	v_cndmask_b32_e32 v10, 0, v10, vcc
	v_cndmask_b32_e64 v11, 0, v11, s[98:99]
	v_cndmask_b32_e64 v12, 0, v12, s[100:101]
	v_cmp_ne_u32_e32 vcc, v13, v157
	v_cmp_ne_u32_e64 s[98:99], v14, v157
	v_cmp_ne_u32_e64 s[100:101], v15, v157
	v_cndmask_b32_e32 v13, 0, v13, vcc
	v_cndmask_b32_e64 v14, 0, v14, s[98:99]
	v_cndmask_b32_e64 v15, 0, v15, s[100:101]
	v_cmp_ne_u32_e32 vcc, v165, v157
	v_cmp_ne_u32_e64 s[98:99], v166, v157
	v_cmp_ne_u32_e64 s[100:101], v167, v157
	v_cndmask_b32_e32 v165, 0, v165, vcc
	v_cndmask_b32_e64 v166, 0, v166, s[98:99]
	v_cndmask_b32_e64 v167, 0, v167, s[100:101]
	v_cmp_ne_u32_e32 vcc, v168, v157
	v_cmp_ne_u32_e64 s[98:99], v169, v157
	v_cmp_ne_u32_e64 s[100:101], v171, v157
	v_cndmask_b32_e32 v168, 0, v168, vcc
	v_cndmask_b32_e64 v169, 0, v169, s[98:99]
	v_cndmask_b32_e64 v171, 0, v171, s[100:101]
	v_cmp_ne_u32_e32 vcc, v172, v157
	v_cmp_ne_u32_e64 s[98:99], v173, v157
	v_cmp_ne_u32_e64 s[100:101], v176, v157
	v_cndmask_b32_e32 v172, 0, v172, vcc
	v_cndmask_b32_e64 v173, 0, v173, s[98:99]
	v_cndmask_b32_e64 v176, 0, v176, s[100:101]
	v_cmp_ne_u32_e32 vcc, v177, v157
	v_cmp_ne_u32_e64 s[98:99], v158, v157
	v_cmp_ne_u32_e64 s[100:101], v159, v157
	v_cndmask_b32_e32 v177, 0, v177, vcc
	v_cndmask_b32_e64 v178, 0, v158, s[98:99]
	v_max_u32_e32 v158, v4, v5
	v_max3_u32 v158, v158, v6, v7
	v_max3_u32 v158, v158, v8, v9
	v_max3_u32 v158, v158, v10, v11
	v_max3_u32 v158, v158, v12, v13
	v_max3_u32 v158, v158, v14, v15
	v_max3_u32 v158, v158, v165, v166
	v_cndmask_b32_e64 v159, 0, v159, s[100:101]
	v_cmp_ne_u32_e32 vcc, v160, v157
	v_max3_u32 v158, v158, v167, v168
	v_max3_u32 v158, v158, v169, v171
	v_cndmask_b32_e32 v160, 0, v160, vcc
	v_cmp_ne_u32_e64 s[98:99], v161, v157
	v_max3_u32 v158, v158, v172, v173
	v_max3_u32 v158, v158, v176, v177
	v_cndmask_b32_e64 v161, 0, v161, s[98:99]
	v_cmp_ne_u32_e64 s[100:101], v162, v157
	v_max3_u32 v158, v158, v178, v159
	v_max3_u32 v158, v158, v160, v161
	v_cndmask_b32_e64 v162, 0, v162, s[100:101]
	v_cmp_ne_u32_e32 vcc, v164, v157
	v_cmp_ne_u32_e64 s[98:99], v0, v157
	v_cmp_ne_u32_e64 s[100:101], v1, v157
	v_cndmask_b32_e32 v164, 0, v164, vcc
	v_max3_u32 v158, v158, v162, v164
	v_cndmask_b32_e64 v0, 0, v0, s[98:99]
	v_cndmask_b32_e64 v1, 0, v1, s[100:101]
	v_cmp_ne_u32_e32 vcc, v2, v157
	v_max3_u32 v158, v158, v0, v1
	v_cmp_ne_u32_e64 s[98:99], v3, v157
	v_cndmask_b32_e32 v2, 0, v2, vcc
	s_nop 0
	v_cndmask_b32_e64 v3, 0, v3, s[98:99]
	v_max3_u32 v158, v158, v2, v3
	ds_bpermute_b32 v179, v111, v158
	s_waitcnt lgkmcnt(0)
; DI void peer_topk_wave(const Params& p, int item, unsigned* lds  ) {
;     ...
;     for (int rr = 0; rr < 16; ++rr) {
;       unsigned m = 0;
; #pragma unroll
;       for (int i = 0; i < 32; ++i) m = umax(m, kk[i]);
;       m = umax(m, (unsigned)__shfl_xor((int)m, 16));
;       m = umax(m, (unsigned)__shfl_xor((int)m, 32));
;       win[pp][rr] = m;
; #pragma unroll
;       for (int i = 0; i < 32; ++i) kk[i] = (kk[i] == m) ? 0u : kk[i];
;     }
	v_max_u32_e32 v158, v158, v179
	ds_bpermute_b32 v179, v112, v158
	s_waitcnt lgkmcnt(0)
	v_max_u32_e32 v158, v158, v179
	v_cmp_ne_u32_e32 vcc, v4, v158
	v_cmp_ne_u32_e64 s[98:99], v5, v158
	v_cmp_ne_u32_e64 s[100:101], v6, v158
	v_cndmask_b32_e32 v4, 0, v4, vcc
	v_cndmask_b32_e64 v5, 0, v5, s[98:99]
	v_cndmask_b32_e64 v6, 0, v6, s[100:101]
	v_cmp_ne_u32_e32 vcc, v7, v158
	v_cmp_ne_u32_e64 s[98:99], v8, v158
	v_cmp_ne_u32_e64 s[100:101], v9, v158
	v_cndmask_b32_e32 v7, 0, v7, vcc
	v_cndmask_b32_e64 v8, 0, v8, s[98:99]
	v_cndmask_b32_e64 v9, 0, v9, s[100:101]
	v_cmp_ne_u32_e32 vcc, v10, v158
	v_cmp_ne_u32_e64 s[98:99], v11, v158
	v_cmp_ne_u32_e64 s[100:101], v12, v158
	v_cndmask_b32_e32 v10, 0, v10, vcc
	v_cndmask_b32_e64 v11, 0, v11, s[98:99]
	v_cndmask_b32_e64 v12, 0, v12, s[100:101]
	v_cmp_ne_u32_e32 vcc, v13, v158
	v_cmp_ne_u32_e64 s[98:99], v14, v158
	v_cmp_ne_u32_e64 s[100:101], v15, v158
	v_cndmask_b32_e32 v13, 0, v13, vcc
	v_cndmask_b32_e64 v14, 0, v14, s[98:99]
	v_cndmask_b32_e64 v15, 0, v15, s[100:101]
	v_cmp_ne_u32_e32 vcc, v165, v158
	v_cmp_ne_u32_e64 s[98:99], v166, v158
	v_cmp_ne_u32_e64 s[100:101], v167, v158
	v_cndmask_b32_e32 v165, 0, v165, vcc
	v_cndmask_b32_e64 v166, 0, v166, s[98:99]
	v_cndmask_b32_e64 v167, 0, v167, s[100:101]
	v_cmp_ne_u32_e32 vcc, v168, v158
	v_cmp_ne_u32_e64 s[98:99], v169, v158
	v_cmp_ne_u32_e64 s[100:101], v171, v158
	v_cndmask_b32_e32 v168, 0, v168, vcc
	v_cndmask_b32_e64 v169, 0, v169, s[98:99]
	v_cndmask_b32_e64 v171, 0, v171, s[100:101]
	v_cmp_ne_u32_e32 vcc, v172, v158
	v_cmp_ne_u32_e64 s[98:99], v173, v158
	v_cmp_ne_u32_e64 s[100:101], v176, v158
	v_cndmask_b32_e32 v172, 0, v172, vcc
	v_cndmask_b32_e64 v173, 0, v173, s[98:99]
	v_cndmask_b32_e64 v176, 0, v176, s[100:101]
	v_cmp_ne_u32_e32 vcc, v177, v158
	v_cmp_ne_u32_e64 s[98:99], v178, v158
	v_cmp_ne_u32_e64 s[100:101], v159, v158
	v_cndmask_b32_e32 v177, 0, v177, vcc
	v_cndmask_b32_e64 v178, 0, v178, s[98:99]
	v_cndmask_b32_e64 v179, 0, v159, s[100:101]
	v_max_u32_e32 v159, v4, v5
	v_max3_u32 v159, v159, v6, v7
	v_max3_u32 v159, v159, v8, v9
	v_max3_u32 v159, v159, v10, v11
	v_max3_u32 v159, v159, v12, v13
	v_max3_u32 v159, v159, v14, v15
	v_cmp_ne_u32_e32 vcc, v160, v158
	v_max3_u32 v159, v159, v165, v166
	v_max3_u32 v159, v159, v167, v168
	v_cndmask_b32_e32 v160, 0, v160, vcc
	v_cmp_ne_u32_e64 s[98:99], v161, v158
	v_max3_u32 v159, v159, v169, v171
	v_max3_u32 v159, v159, v172, v173
	v_cndmask_b32_e64 v161, 0, v161, s[98:99]
	v_cmp_ne_u32_e64 s[100:101], v162, v158
	v_max3_u32 v159, v159, v176, v177
	v_max3_u32 v159, v159, v178, v179
	v_cndmask_b32_e64 v162, 0, v162, s[100:101]
	v_cmp_ne_u32_e32 vcc, v164, v158
	v_max3_u32 v159, v159, v160, v161
	v_cmp_ne_u32_e64 s[98:99], v0, v158
	v_cndmask_b32_e32 v164, 0, v164, vcc
	v_max3_u32 v159, v159, v162, v164
	v_cndmask_b32_e64 v0, 0, v0, s[98:99]
	v_cmp_ne_u32_e64 s[100:101], v1, v158
	v_cmp_ne_u32_e32 vcc, v2, v158
	v_cmp_ne_u32_e64 s[98:99], v3, v158
	v_cndmask_b32_e64 v1, 0, v1, s[100:101]
	v_max3_u32 v159, v159, v0, v1
	v_cndmask_b32_e32 v2, 0, v2, vcc
	v_cndmask_b32_e64 v3, 0, v3, s[98:99]
	v_max3_u32 v159, v159, v2, v3
	ds_bpermute_b32 v180, v111, v159
	s_waitcnt lgkmcnt(0)
	v_max_u32_e32 v159, v159, v180
	ds_bpermute_b32 v180, v112, v159
	s_waitcnt lgkmcnt(0)
	v_max_u32_e32 v159, v159, v180
	v_cmp_ne_u32_e32 vcc, v4, v159
	v_cmp_ne_u32_e64 s[98:99], v5, v159
	v_cmp_ne_u32_e64 s[100:101], v6, v159
	v_cndmask_b32_e32 v4, 0, v4, vcc
	v_cndmask_b32_e64 v5, 0, v5, s[98:99]
	v_cndmask_b32_e64 v6, 0, v6, s[100:101]
	v_cmp_ne_u32_e32 vcc, v7, v159
	v_cmp_ne_u32_e64 s[98:99], v8, v159
	v_cmp_ne_u32_e64 s[100:101], v9, v159
	v_cndmask_b32_e32 v7, 0, v7, vcc
	v_cndmask_b32_e64 v8, 0, v8, s[98:99]
	v_cndmask_b32_e64 v9, 0, v9, s[100:101]
	v_cmp_ne_u32_e32 vcc, v10, v159
	v_cmp_ne_u32_e64 s[98:99], v11, v159
	v_cmp_ne_u32_e64 s[100:101], v12, v159
	v_cndmask_b32_e32 v10, 0, v10, vcc
	v_cndmask_b32_e64 v11, 0, v11, s[98:99]
	v_cndmask_b32_e64 v12, 0, v12, s[100:101]
	v_cmp_ne_u32_e32 vcc, v13, v159
	v_cmp_ne_u32_e64 s[98:99], v14, v159
	v_cmp_ne_u32_e64 s[100:101], v15, v159
	v_cndmask_b32_e32 v13, 0, v13, vcc
	v_cndmask_b32_e64 v14, 0, v14, s[98:99]
	v_cndmask_b32_e64 v15, 0, v15, s[100:101]
	v_cmp_ne_u32_e32 vcc, v165, v159
	v_cmp_ne_u32_e64 s[98:99], v166, v159
	v_cmp_ne_u32_e64 s[100:101], v167, v159
	v_cndmask_b32_e32 v165, 0, v165, vcc
	v_cndmask_b32_e64 v166, 0, v166, s[98:99]
	v_cndmask_b32_e64 v167, 0, v167, s[100:101]
	v_cmp_ne_u32_e32 vcc, v168, v159
	v_cmp_ne_u32_e64 s[98:99], v169, v159
	v_cmp_ne_u32_e64 s[100:101], v171, v159
	v_cndmask_b32_e32 v168, 0, v168, vcc
	v_cndmask_b32_e64 v169, 0, v169, s[98:99]
	v_cndmask_b32_e64 v171, 0, v171, s[100:101]
	v_cmp_ne_u32_e32 vcc, v172, v159
	v_cmp_ne_u32_e64 s[98:99], v173, v159
	v_cmp_ne_u32_e64 s[100:101], v176, v159
	v_cndmask_b32_e32 v172, 0, v172, vcc
	v_cndmask_b32_e64 v173, 0, v173, s[98:99]
	v_cndmask_b32_e64 v176, 0, v176, s[100:101]
	v_cmp_ne_u32_e32 vcc, v177, v159
	v_cmp_ne_u32_e64 s[98:99], v178, v159
	v_cmp_ne_u32_e64 s[100:101], v179, v159
	v_cndmask_b32_e32 v177, 0, v177, vcc
	v_cndmask_b32_e64 v178, 0, v178, s[98:99]
	v_cndmask_b32_e64 v179, 0, v179, s[100:101]
	v_cmp_ne_u32_e32 vcc, v160, v159
	v_cmp_ne_u32_e64 s[98:99], v161, v159
	v_cmp_ne_u32_e64 s[100:101], v162, v159
	v_cndmask_b32_e32 v180, 0, v160, vcc
	v_max_u32_e32 v160, v4, v5
	v_max3_u32 v160, v160, v6, v7
	v_max3_u32 v160, v160, v8, v9
	v_max3_u32 v160, v160, v10, v11
	v_max3_u32 v160, v160, v12, v13
	v_max3_u32 v160, v160, v14, v15
	v_max3_u32 v160, v160, v165, v166
	v_max3_u32 v160, v160, v167, v168
	v_max3_u32 v160, v160, v169, v171
	v_cndmask_b32_e64 v161, 0, v161, s[98:99]
	v_max3_u32 v160, v160, v172, v173
	v_max3_u32 v160, v160, v176, v177
	v_cndmask_b32_e64 v162, 0, v162, s[100:101]
	v_cmp_ne_u32_e32 vcc, v164, v159
	v_max3_u32 v160, v160, v178, v179
	v_max3_u32 v160, v160, v180, v161
	v_cndmask_b32_e32 v164, 0, v164, vcc
	v_cmp_ne_u32_e64 s[98:99], v0, v159
	v_max3_u32 v160, v160, v162, v164
	v_cmp_ne_u32_e64 s[100:101], v1, v159
	v_cndmask_b32_e64 v0, 0, v0, s[98:99]
	v_cmp_ne_u32_e32 vcc, v2, v159
	v_cndmask_b32_e64 v1, 0, v1, s[100:101]
	v_max3_u32 v160, v160, v0, v1
	v_cndmask_b32_e32 v2, 0, v2, vcc
	v_cmp_ne_u32_e64 s[98:99], v3, v159
	s_nop 0
	s_nop 0
	v_cndmask_b32_e64 v3, 0, v3, s[98:99]
	v_max3_u32 v160, v160, v2, v3
	ds_bpermute_b32 v181, v111, v160
	s_waitcnt lgkmcnt(0)
; #define MFMA(a, b, c) __builtin_amdgcn_mfma_f32_16x16x32_bf16((a), (b), (c), 0, 0, 0)
; DI unsigned ordf(float f) { unsigned u = __float_as_uint(f); return (u & 0x80000000u) ? ~u : (u | 0x80000000u); }
; DI void peer_topk_wave(const Params& p, int item, unsigned* lds  ) {
;     ...
;   for (int pp = 0; pp < 2; ++pp) {
;     bf16x8 qf[4];
; #pragma unroll
;     for (int ks = 0; ks < 4; ++ks) qf[ks] = *(const bf16x8*)&p.pq[(size_t)(row0 + r) * 2048 + h * 256 + pp * 128 + ks * 32 + kg * 8];
;     unsigned kk[32];
;     const u16* sk = p.subkb + (size_t)(h * 2 + pp) * 16384;
; #pragma unroll
;     for (int mt = 0; mt < 8; ++mt) {
;       f32x4 a = (f32x4){0.f, 0.f, 0.f, 0.f};
; #pragma unroll
;       for (int ks = 0; ks < 4; ++ks) {
;         bf16x8 kf = *(const bf16x8*)&sk[(mt * 16 + r) * 128 + ks * 32 + kg * 8];
;         a = MFMA(kf, qf[ks], a);
;       }
; #pragma unroll
;       for (int j = 0; j < 4; ++j) kk[mt * 4 + j] = (ordf(a[j]) & ~127u) | (unsigned)(mt * 16 + kg * 4 + j);
;     }
;     ...
;     for (int rr = 0; rr < 16; ++rr) {
;       unsigned m = 0;
; #pragma unroll
;       for (int i = 0; i < 32; ++i) m = umax(m, kk[i]);
;       m = umax(m, (unsigned)__shfl_xor((int)m, 16));
;       m = umax(m, (unsigned)__shfl_xor((int)m, 32));
;       win[pp][rr] = m;
; #pragma unroll
;       for (int i = 0; i < 32; ++i) kk[i] = (kk[i] == m) ? 0u : kk[i];
;     }
	v_max_u32_e32 v160, v160, v181
	ds_bpermute_b32 v181, v112, v160
	s_waitcnt lgkmcnt(0)
	v_max_u32_e32 v160, v160, v181
	v_cmp_ne_u32_e64 s[0:1], v5, v160
	v_cmp_eq_u32_e32 vcc, v4, v160
	v_cmp_eq_u32_e64 s[2:3], v7, v160
	v_cndmask_b32_e64 v5, 0, v5, s[0:1]
	v_max_u32_e32 v4, v4, v5
	v_cndmask_b32_e32 v4, v4, v5, vcc
	v_cmp_eq_u32_e64 s[0:1], v6, v160
	v_max_u32_e32 v5, v4, v6
	v_cmp_eq_u32_e64 s[14:15], v8, v160
	v_cndmask_b32_e64 v4, v5, v4, s[0:1]
	v_max_u32_e32 v5, v4, v7
	v_cndmask_b32_e64 v4, v5, v4, s[2:3]
	v_max_u32_e32 v5, v4, v8
	v_cndmask_b32_e64 v4, v5, v4, s[14:15]
	v_cmp_eq_u32_e64 s[16:17], v9, v160
	v_max_u32_e32 v5, v4, v9
	v_cmp_eq_u32_e64 s[18:19], v10, v160
	v_cndmask_b32_e64 v4, v5, v4, s[16:17]
	v_max_u32_e32 v5, v4, v10
	v_cndmask_b32_e64 v4, v5, v4, s[18:19]
	v_cmp_eq_u32_e64 s[20:21], v11, v160
	v_max_u32_e32 v5, v4, v11
	v_cmp_eq_u32_e64 s[22:23], v12, v160
	v_cndmask_b32_e64 v4, v5, v4, s[20:21]
	v_max_u32_e32 v5, v4, v12
	v_cndmask_b32_e64 v4, v5, v4, s[22:23]
	v_cmp_eq_u32_e64 s[24:25], v13, v160
	v_max_u32_e32 v5, v4, v13
	v_cmp_eq_u32_e64 s[26:27], v14, v160
	v_cndmask_b32_e64 v4, v5, v4, s[24:25]
	v_max_u32_e32 v5, v4, v14
	v_cndmask_b32_e64 v4, v5, v4, s[26:27]
	v_cmp_eq_u32_e64 s[28:29], v15, v160
	v_max_u32_e32 v5, v4, v15
	v_cmp_eq_u32_e64 s[30:31], v165, v160
	v_cndmask_b32_e64 v4, v5, v4, s[28:29]
	v_max_u32_e32 v5, v4, v165
	v_cndmask_b32_e64 v4, v5, v4, s[30:31]
	v_cmp_eq_u32_e64 s[34:35], v166, v160
	v_max_u32_e32 v5, v4, v166
	v_cmp_eq_u32_e64 s[36:37], v167, v160
	v_cndmask_b32_e64 v4, v5, v4, s[34:35]
	v_max_u32_e32 v5, v4, v167
	v_cndmask_b32_e64 v4, v5, v4, s[36:37]
	v_cmp_eq_u32_e64 s[38:39], v168, v160
	v_max_u32_e32 v5, v4, v168
	v_cmp_eq_u32_e64 s[40:41], v169, v160
	v_cndmask_b32_e64 v4, v5, v4, s[38:39]
	v_max_u32_e32 v5, v4, v169
	v_cndmask_b32_e64 v4, v5, v4, s[40:41]
	v_cmp_eq_u32_e64 s[42:43], v171, v160
	v_max_u32_e32 v5, v4, v171
	v_cmp_eq_u32_e64 s[44:45], v172, v160
	v_cndmask_b32_e64 v4, v5, v4, s[42:43]
	v_max_u32_e32 v5, v4, v172
	v_cndmask_b32_e64 v4, v5, v4, s[44:45]
	v_cmp_eq_u32_e64 s[46:47], v173, v160
	v_max_u32_e32 v5, v4, v173
	v_cmp_eq_u32_e64 s[48:49], v176, v160
	v_cndmask_b32_e64 v4, v5, v4, s[46:47]
	v_max_u32_e32 v5, v4, v176
	v_cndmask_b32_e64 v4, v5, v4, s[48:49]
	v_cmp_eq_u32_e64 s[50:51], v177, v160
	v_max_u32_e32 v5, v4, v177
	v_cmp_eq_u32_e64 s[52:53], v178, v160
	v_cndmask_b32_e64 v4, v5, v4, s[50:51]
	v_max_u32_e32 v5, v4, v178
	v_cndmask_b32_e64 v4, v5, v4, s[52:53]
	v_cmp_eq_u32_e64 s[54:55], v179, v160
	v_max_u32_e32 v5, v4, v179
	v_cmp_eq_u32_e64 s[56:57], v180, v160
	v_cndmask_b32_e64 v4, v5, v4, s[54:55]
	v_max_u32_e32 v5, v4, v180
	v_cndmask_b32_e64 v4, v5, v4, s[56:57]
	v_cmp_eq_u32_e64 s[58:59], v161, v160
	v_max_u32_e32 v5, v4, v161
	v_cmp_eq_u32_e64 s[60:61], v162, v160
	v_cndmask_b32_e64 v4, v5, v4, s[58:59]
	v_max_u32_e32 v5, v4, v162
	v_cndmask_b32_e64 v4, v5, v4, s[60:61]
	v_cmp_eq_u32_e64 s[62:63], v164, v160
	v_max_u32_e32 v5, v4, v164
	v_cmp_eq_u32_e64 s[64:65], v0, v160
	v_cndmask_b32_e64 v4, v5, v4, s[62:63]
	v_max_u32_e32 v0, v4, v0
	v_cndmask_b32_e64 v0, v0, v4, s[64:65]
	v_cmp_eq_u32_e64 s[66:67], v1, v160
	v_max_u32_e32 v1, v0, v1
	v_cmp_eq_u32_e64 s[68:69], v2, v160
	v_cndmask_b32_e64 v0, v1, v0, s[66:67]
	v_max_u32_e32 v1, v0, v2
	v_cndmask_b32_e64 v0, v1, v0, s[68:69]
	v_cmp_eq_u32_e64 s[70:71], v3, v160
	v_max_u32_e32 v1, v0, v3
	v_lshl_add_u64 v[172:173], v[86:87], 0, v[24:25]
	v_cndmask_b32_e64 v0, v1, v0, s[70:71]
	ds_bpermute_b32 v1, v111, v0
	s_waitcnt lgkmcnt(0)
	v_max_u32_e32 v161, v0, v1
	flat_load_dwordx4 v[12:15], v[88:89] offset:256
	flat_load_dwordx4 v[8:11], v[88:89] offset:320
	flat_load_dwordx4 v[4:7], v[88:89] offset:384
	flat_load_dwordx4 v[0:3], v[88:89] offset:448
	v_lshl_add_u64 v[88:89], v[86:87], 0, v[20:21]
	flat_load_dwordx4 v[164:167], v[88:89]
	ds_bpermute_b32 v162, v112, v161
	flat_load_dwordx4 v[186:189], v[186:187]
	v_lshl_add_u64 v[88:89], v[86:87], 0, v[78:79]
	flat_load_dwordx4 v[176:179], v[88:89]
	s_waitcnt vmcnt(0) lgkmcnt(0)
	v_mfma_f32_16x16x32_bf16 v[164:167], v[164:167], v[12:15], 0
	flat_load_dwordx4 v[190:193], v[190:191]
	v_lshl_add_u64 v[88:89], v[86:87], 0, v[80:81]
	flat_load_dwordx4 v[194:197], v[194:195]
	v_mfma_f32_16x16x32_bf16 v[164:167], v[176:179], v[8:11], v[164:167]
	flat_load_dwordx4 v[176:179], v[88:89]
	v_lshl_add_u64 v[88:89], v[86:87], 0, v[82:83]
	s_waitcnt vmcnt(0) lgkmcnt(0)
	v_mfma_f32_16x16x32_bf16 v[164:167], v[176:179], v[4:7], v[164:167]
	flat_load_dwordx4 v[176:179], v[88:89]
	s_waitcnt vmcnt(0) lgkmcnt(0)
	v_mfma_f32_16x16x32_bf16 v[164:167], v[176:179], v[0:3], v[164:167]
	flat_load_dwordx4 v[176:179], v[172:173]
	v_lshl_add_u64 v[172:173], v[86:87], 0, v[26:27]
	s_nop 5
	v_not_b32_e32 v88, v164
	v_or_b32_e32 v89, 0x80000000, v164
	v_cmp_gt_i32_e32 vcc, 0, v164
	v_or_b32_e32 v164, 0x80000000, v165
	s_nop 0
	v_cndmask_b32_e32 v88, v89, v88, vcc
	v_not_b32_e32 v89, v165
	v_cmp_gt_i32_e32 vcc, 0, v165
	v_or_b32_e32 v165, 0x80000000, v166
	v_and_or_b32 v88, v88, s80, v170
	v_cndmask_b32_e32 v89, v164, v89, vcc
	v_not_b32_e32 v164, v166
	v_cmp_gt_i32_e32 vcc, 0, v166
	v_or_b32_e32 v166, 0x80000000, v167
	v_and_or_b32 v89, v89, s80, v113
	v_cndmask_b32_e32 v164, v165, v164, vcc
	v_not_b32_e32 v165, v167
	v_cmp_gt_i32_e32 vcc, 0, v167
	v_and_or_b32 v164, v164, s80, v114
	s_nop 0
	v_cndmask_b32_e32 v165, v166, v165, vcc
	v_lshl_add_u64 v[166:167], v[86:87], 0, v[22:23]
	flat_load_dwordx4 v[166:169], v[166:167]
	v_and_or_b32 v165, v165, s80, v115
	s_waitcnt vmcnt(0) lgkmcnt(0)
; #define MFMA(a, b, c) __builtin_amdgcn_mfma_f32_16x16x32_bf16((a), (b), (c), 0, 0, 0)
; DI unsigned ordf(float f) { unsigned u = __float_as_uint(f); return (u & 0x80000000u) ? ~u : (u | 0x80000000u); }
; DI void peer_topk_wave(const Params& p, int item, unsigned* lds  ) {
;     ...
;     for (int mt = 0; mt < 8; ++mt) {
;       f32x4 a = (f32x4){0.f, 0.f, 0.f, 0.f};
; #pragma unroll
;       for (int ks = 0; ks < 4; ++ks) {
;         bf16x8 kf = *(const bf16x8*)&sk[(mt * 16 + r) * 128 + ks * 32 + kg * 8];
;         a = MFMA(kf, qf[ks], a);
;       }
; #pragma unroll
;       for (int j = 0; j < 4; ++j) kk[mt * 4 + j] = (ordf(a[j]) & ~127u) | (unsigned)(mt * 16 + kg * 4 + j);
;     }
	v_mfma_f32_16x16x32_bf16 v[166:169], v[166:169], v[12:15], 0
	v_mfma_f32_16x16x32_bf16 v[166:169], v[176:179], v[8:11], v[166:169]
	flat_load_dwordx4 v[176:179], v[172:173]
	v_lshl_add_u64 v[172:173], v[86:87], 0, v[28:29]
	s_waitcnt vmcnt(0) lgkmcnt(0)
	v_mfma_f32_16x16x32_bf16 v[166:169], v[176:179], v[4:7], v[166:169]
	flat_load_dwordx4 v[176:179], v[172:173]
	s_waitcnt vmcnt(0) lgkmcnt(0)
	v_mfma_f32_16x16x32_bf16 v[166:169], v[176:179], v[0:3], v[166:169]
	s_nop 7
	v_not_b32_e32 v171, v166
	v_or_b32_e32 v172, 0x80000000, v166
	v_cmp_gt_i32_e32 vcc, 0, v166
	s_nop 1
	v_cndmask_b32_e32 v166, v172, v171, vcc
	v_not_b32_e32 v171, v167
	v_or_b32_e32 v172, 0x80000000, v167
	v_cmp_gt_i32_e32 vcc, 0, v167
	v_and_or_b32 v166, v166, s80, v90
	s_nop 0
	v_cndmask_b32_e32 v167, v172, v171, vcc
	v_not_b32_e32 v171, v168
	v_or_b32_e32 v172, 0x80000000, v168
	v_cmp_gt_i32_e32 vcc, 0, v168
	v_and_or_b32 v167, v167, s80, v116
	s_nop 0
	v_cndmask_b32_e32 v168, v172, v171, vcc
	v_not_b32_e32 v171, v169
	v_or_b32_e32 v172, 0x80000000, v169
	v_cmp_gt_i32_e32 vcc, 0, v169
	v_and_or_b32 v168, v168, s80, v117
	s_nop 0
	v_cndmask_b32_e32 v169, v172, v171, vcc
	v_lshl_add_u64 v[172:173], v[86:87], 0, v[30:31]
	flat_load_dwordx4 v[176:179], v[172:173]
	v_lshl_add_u64 v[172:173], v[86:87], 0, v[32:33]
	flat_load_dwordx4 v[180:183], v[172:173]
	s_waitcnt vmcnt(0) lgkmcnt(0)
	v_mfma_f32_16x16x32_bf16 v[176:179], v[176:179], v[12:15], 0
	v_lshl_add_u64 v[172:173], v[86:87], 0, v[34:35]
	v_and_or_b32 v169, v169, s80, v118
	v_mfma_f32_16x16x32_bf16 v[176:179], v[180:183], v[8:11], v[176:179]
	flat_load_dwordx4 v[180:183], v[172:173]
	v_lshl_add_u64 v[172:173], v[86:87], 0, v[36:37]
	s_waitcnt vmcnt(0) lgkmcnt(0)
	v_mfma_f32_16x16x32_bf16 v[176:179], v[180:183], v[4:7], v[176:179]
	flat_load_dwordx4 v[180:183], v[172:173]
	s_waitcnt vmcnt(0) lgkmcnt(0)
	v_mfma_f32_16x16x32_bf16 v[176:179], v[180:183], v[0:3], v[176:179]
	v_lshl_add_u64 v[182:183], v[86:87], 0, v[40:41]
	flat_load_dwordx4 v[182:185], v[182:183]
	s_nop 5
	v_not_b32_e32 v171, v176
	v_or_b32_e32 v172, 0x80000000, v176
	v_cmp_gt_i32_e32 vcc, 0, v176
	v_or_b32_e32 v173, 0x80000000, v177
	v_or_b32_e32 v176, 0x80000000, v178
	v_cndmask_b32_e32 v171, v172, v171, vcc
	v_not_b32_e32 v172, v177
	v_cmp_gt_i32_e32 vcc, 0, v177
	v_or_b32_e32 v177, 0x80000000, v179
	v_and_or_b32 v171, v171, s80, v91
	v_cndmask_b32_e32 v172, v173, v172, vcc
	v_not_b32_e32 v173, v178
	v_cmp_gt_i32_e32 vcc, 0, v178
	v_and_or_b32 v172, v172, s80, v119
	s_nop 0
	v_cndmask_b32_e32 v173, v176, v173, vcc
	v_not_b32_e32 v176, v179
	v_cmp_gt_i32_e32 vcc, 0, v179
	v_lshl_add_u64 v[178:179], v[86:87], 0, v[38:39]
	flat_load_dwordx4 v[178:181], v[178:179]
	v_cndmask_b32_e32 v176, v177, v176, vcc
	s_waitcnt vmcnt(0) lgkmcnt(0)
	v_mfma_f32_16x16x32_bf16 v[178:181], v[178:181], v[12:15], 0
	v_and_or_b32 v173, v173, s80, v120
	v_and_or_b32 v176, v176, s80, v121
	v_mfma_f32_16x16x32_bf16 v[178:181], v[182:185], v[8:11], v[178:181]
	v_lshl_add_u64 v[182:183], v[86:87], 0, v[42:43]
	flat_load_dwordx4 v[182:185], v[182:183]
	s_waitcnt vmcnt(0) lgkmcnt(0)
	v_mfma_f32_16x16x32_bf16 v[178:181], v[182:185], v[4:7], v[178:181]
	v_lshl_add_u64 v[182:183], v[86:87], 0, v[44:45]
	flat_load_dwordx4 v[182:185], v[182:183]
	s_waitcnt vmcnt(0) lgkmcnt(0)
	v_mfma_f32_16x16x32_bf16 v[178:181], v[182:185], v[0:3], v[178:181]
	s_nop 7
	v_not_b32_e32 v177, v178
	v_or_b32_e32 v182, 0x80000000, v178
	v_cmp_gt_i32_e32 vcc, 0, v178
	v_not_b32_e32 v178, v179
	s_nop 0
	v_cndmask_b32_e32 v177, v182, v177, vcc
	v_or_b32_e32 v182, 0x80000000, v179
	v_cmp_gt_i32_e32 vcc, 0, v179
	v_not_b32_e32 v179, v180
	v_and_or_b32 v177, v177, s80, v92
	v_cndmask_b32_e32 v178, v182, v178, vcc
	v_or_b32_e32 v182, 0x80000000, v180
	v_cmp_gt_i32_e32 vcc, 0, v180
	v_not_b32_e32 v180, v181
	v_and_or_b32 v178, v178, s80, v122
	v_cndmask_b32_e32 v179, v182, v179, vcc
	v_or_b32_e32 v182, 0x80000000, v181
	v_cmp_gt_i32_e32 vcc, 0, v181
	v_and_or_b32 v179, v179, s80, v123
	s_nop 0
	v_cndmask_b32_e32 v180, v182, v180, vcc
	v_lshl_add_u64 v[182:183], v[86:87], 0, v[46:47]
	flat_load_dwordx4 v[182:185], v[182:183]
	v_and_or_b32 v180, v180, s80, v124
	s_waitcnt vmcnt(0) lgkmcnt(0)
	v_mfma_f32_16x16x32_bf16 v[182:185], v[182:185], v[12:15], 0
	v_mfma_f32_16x16x32_bf16 v[182:185], v[186:189], v[8:11], v[182:185]
	v_lshl_add_u64 v[186:187], v[86:87], 0, v[50:51]
	flat_load_dwordx4 v[186:189], v[186:187]
	s_waitcnt vmcnt(0) lgkmcnt(0)
	v_mfma_f32_16x16x32_bf16 v[182:185], v[186:189], v[4:7], v[182:185]
	v_lshl_add_u64 v[186:187], v[86:87], 0, v[52:53]
	flat_load_dwordx4 v[186:189], v[186:187]
	s_waitcnt vmcnt(0) lgkmcnt(0)
	v_mfma_f32_16x16x32_bf16 v[182:185], v[186:189], v[0:3], v[182:185]
	s_nop 7
	v_not_b32_e32 v181, v182
	v_or_b32_e32 v186, 0x80000000, v182
	v_cmp_gt_i32_e32 vcc, 0, v182
	v_not_b32_e32 v182, v183
	s_nop 0
	v_cndmask_b32_e32 v181, v186, v181, vcc
	v_or_b32_e32 v186, 0x80000000, v183
	v_cmp_gt_i32_e32 vcc, 0, v183
	v_not_b32_e32 v183, v184
	v_and_or_b32 v181, v181, s80, v93
	v_cndmask_b32_e32 v182, v186, v182, vcc
	v_or_b32_e32 v186, 0x80000000, v184
	v_cmp_gt_i32_e32 vcc, 0, v184
	v_not_b32_e32 v184, v185
	v_and_or_b32 v182, v182, s80, v125
	v_cndmask_b32_e32 v183, v186, v183, vcc
	v_or_b32_e32 v186, 0x80000000, v185
	v_cmp_gt_i32_e32 vcc, 0, v185
	v_and_or_b32 v183, v183, s80, v126
	s_nop 0
	v_cndmask_b32_e32 v184, v186, v184, vcc
	v_lshl_add_u64 v[186:187], v[86:87], 0, v[54:55]
	flat_load_dwordx4 v[186:189], v[186:187]
	v_and_or_b32 v184, v184, s80, v127
	s_waitcnt vmcnt(0) lgkmcnt(0)
; #define MFMA(a, b, c) __builtin_amdgcn_mfma_f32_16x16x32_bf16((a), (b), (c), 0, 0, 0)
; DI unsigned ordf(float f) { unsigned u = __float_as_uint(f); return (u & 0x80000000u) ? ~u : (u | 0x80000000u); }
; DI void peer_topk_wave(const Params& p, int item, unsigned* lds  ) {
;     ...
;     for (int mt = 0; mt < 8; ++mt) {
;       f32x4 a = (f32x4){0.f, 0.f, 0.f, 0.f};
; #pragma unroll
;       for (int ks = 0; ks < 4; ++ks) {
;         bf16x8 kf = *(const bf16x8*)&sk[(mt * 16 + r) * 128 + ks * 32 + kg * 8];
;         a = MFMA(kf, qf[ks], a);
;       }
; #pragma unroll
;       for (int j = 0; j < 4; ++j) kk[mt * 4 + j] = (ordf(a[j]) & ~127u) | (unsigned)(mt * 16 + kg * 4 + j);
;     }
; #pragma unroll
;     for (int rr = 0; rr < 16; ++rr) {
;       unsigned m = 0;
; #pragma unroll
;       for (int i = 0; i < 32; ++i) m = umax(m, kk[i]);
;       m = umax(m, (unsigned)__shfl_xor((int)m, 16));
;       m = umax(m, (unsigned)__shfl_xor((int)m, 32));
	v_mfma_f32_16x16x32_bf16 v[186:189], v[186:189], v[12:15], 0
	v_mfma_f32_16x16x32_bf16 v[186:189], v[190:193], v[8:11], v[186:189]
	v_lshl_add_u64 v[190:191], v[86:87], 0, v[58:59]
	flat_load_dwordx4 v[190:193], v[190:191]
	s_waitcnt vmcnt(0) lgkmcnt(0)
	v_mfma_f32_16x16x32_bf16 v[186:189], v[190:193], v[4:7], v[186:189]
	v_lshl_add_u64 v[190:191], v[86:87], 0, v[60:61]
	flat_load_dwordx4 v[190:193], v[190:191]
	s_waitcnt vmcnt(0) lgkmcnt(0)
	v_mfma_f32_16x16x32_bf16 v[186:189], v[190:193], v[0:3], v[186:189]
	s_nop 7
	v_not_b32_e32 v185, v186
	v_or_b32_e32 v190, 0x80000000, v186
	v_cmp_gt_i32_e32 vcc, 0, v186
	v_not_b32_e32 v186, v187
	s_nop 0
	v_cndmask_b32_e32 v185, v190, v185, vcc
	v_or_b32_e32 v190, 0x80000000, v187
	v_cmp_gt_i32_e32 vcc, 0, v187
	v_not_b32_e32 v187, v188
	v_and_or_b32 v185, v185, s80, v94
	v_cndmask_b32_e32 v186, v190, v186, vcc
	v_or_b32_e32 v190, 0x80000000, v188
	v_cmp_gt_i32_e32 vcc, 0, v188
	v_not_b32_e32 v188, v189
	v_and_or_b32 v186, v186, s80, v129
	v_cndmask_b32_e32 v187, v190, v187, vcc
	v_or_b32_e32 v190, 0x80000000, v189
	v_cmp_gt_i32_e32 vcc, 0, v189
	v_and_or_b32 v187, v187, s80, v130
	s_nop 0
	v_cndmask_b32_e32 v188, v190, v188, vcc
	v_lshl_add_u64 v[190:191], v[86:87], 0, v[62:63]
	flat_load_dwordx4 v[190:193], v[190:191]
	v_and_or_b32 v188, v188, s80, v131
	s_waitcnt vmcnt(0) lgkmcnt(0)
	v_mfma_f32_16x16x32_bf16 v[190:193], v[190:193], v[12:15], 0
	v_mfma_f32_16x16x32_bf16 v[190:193], v[194:197], v[8:11], v[190:193]
	v_lshl_add_u64 v[194:195], v[86:87], 0, v[66:67]
	flat_load_dwordx4 v[194:197], v[194:195]
	s_waitcnt vmcnt(0) lgkmcnt(0)
	v_mfma_f32_16x16x32_bf16 v[190:193], v[194:197], v[4:7], v[190:193]
	v_lshl_add_u64 v[194:195], v[86:87], 0, v[68:69]
	flat_load_dwordx4 v[194:197], v[194:195]
	s_waitcnt vmcnt(0) lgkmcnt(0)
	v_mfma_f32_16x16x32_bf16 v[190:193], v[194:197], v[0:3], v[190:193]
	s_nop 7
	v_not_b32_e32 v189, v190
	v_or_b32_e32 v194, 0x80000000, v190
	v_cmp_gt_i32_e32 vcc, 0, v190
	v_not_b32_e32 v190, v191
	s_nop 0
	v_cndmask_b32_e32 v189, v194, v189, vcc
	v_or_b32_e32 v194, 0x80000000, v191
	v_cmp_gt_i32_e32 vcc, 0, v191
	v_or_b32_e32 v191, 0x80000000, v192
	v_and_or_b32 v189, v189, s80, v95
	v_cndmask_b32_e32 v190, v194, v190, vcc
	v_and_or_b32 v194, v190, s80, v135
	v_not_b32_e32 v190, v192
	v_cmp_gt_i32_e32 vcc, 0, v192
	s_nop 1
	v_cndmask_b32_e32 v190, v191, v190, vcc
	v_and_or_b32 v195, v190, s80, v136
	v_not_b32_e32 v190, v193
	v_or_b32_e32 v191, 0x80000000, v193
	v_cmp_gt_i32_e32 vcc, 0, v193
	s_nop 1
	v_cndmask_b32_e32 v190, v191, v190, vcc
	v_and_or_b32 v196, v190, s80, v137
	v_lshl_add_u64 v[190:191], v[86:87], 0, v[70:71]
	flat_load_dwordx4 v[190:193], v[190:191]
	s_waitcnt vmcnt(0) lgkmcnt(0)
	v_mfma_f32_16x16x32_bf16 v[12:15], v[190:193], v[12:15], 0
	v_lshl_add_u64 v[190:191], v[86:87], 0, v[72:73]
	flat_load_dwordx4 v[190:193], v[190:191]
	s_waitcnt vmcnt(0) lgkmcnt(0)
	v_mfma_f32_16x16x32_bf16 v[8:11], v[190:193], v[8:11], v[12:15]
	s_nop 3
	v_lshl_add_u64 v[12:13], v[86:87], 0, v[74:75]
	flat_load_dwordx4 v[12:15], v[12:13]
	s_waitcnt vmcnt(0) lgkmcnt(0)
	v_mfma_f32_16x16x32_bf16 v[4:7], v[12:15], v[4:7], v[8:11]
	s_nop 2
	v_lshl_add_u64 v[8:9], v[86:87], 0, v[76:77]
	flat_load_dwordx4 v[8:11], v[8:9]
	s_waitcnt vmcnt(0) lgkmcnt(0)
	v_mfma_f32_16x16x32_bf16 v[0:3], v[8:11], v[0:3], v[4:7]
	s_nop 7
	v_not_b32_e32 v4, v0
	v_or_b32_e32 v5, 0x80000000, v0
	v_cmp_gt_i32_e32 vcc, 0, v0
	s_nop 1
	v_cndmask_b32_e32 v0, v5, v4, vcc
	v_and_or_b32 v4, v0, s80, v96
	v_not_b32_e32 v0, v1
	v_or_b32_e32 v5, 0x80000000, v1
	v_cmp_gt_i32_e32 vcc, 0, v1
	s_nop 1
	v_cndmask_b32_e32 v0, v5, v0, vcc
	v_and_or_b32 v1, v0, s80, v138
	v_not_b32_e32 v0, v2
	v_or_b32_e32 v5, 0x80000000, v2
	v_cmp_gt_i32_e32 vcc, 0, v2
	s_nop 1
	v_cndmask_b32_e32 v0, v5, v0, vcc
	v_and_or_b32 v2, v0, s80, v139
	v_not_b32_e32 v0, v3
	v_or_b32_e32 v5, 0x80000000, v3
	v_cmp_gt_i32_e32 vcc, 0, v3
	s_nop 1
	v_cndmask_b32_e32 v0, v5, v0, vcc
	v_and_or_b32 v3, v0, s80, v140
	v_max_u32_e32 v0, v88, v89
	v_max3_u32 v0, v0, v164, v165
	v_max3_u32 v0, v0, v166, v167
	v_max3_u32 v0, v0, v168, v169
	v_max3_u32 v0, v0, v171, v172
	v_max3_u32 v0, v0, v173, v176
	v_max3_u32 v0, v0, v177, v178
	v_max3_u32 v0, v0, v179, v180
	v_max3_u32 v0, v0, v181, v182
	v_max3_u32 v0, v0, v183, v184
	v_max3_u32 v0, v0, v185, v186
	v_max3_u32 v0, v0, v187, v188
	v_max3_u32 v0, v0, v189, v194
	v_max3_u32 v0, v0, v195, v196
	v_max3_u32 v0, v0, v4, v1
	v_max3_u32 v0, v0, v2, v3
	ds_bpermute_b32 v5, v111, v0
	s_waitcnt lgkmcnt(0)
	v_max_u32_e32 v0, v0, v5
	ds_bpermute_b32 v5, v112, v0
	s_waitcnt lgkmcnt(0)
; DI void peer_topk_wave(const Params& p, int item, unsigned* lds  ) {
;     ...
;     for (int rr = 0; rr < 16; ++rr) {
;       unsigned m = 0;
; #pragma unroll
;       for (int i = 0; i < 32; ++i) m = umax(m, kk[i]);
;       m = umax(m, (unsigned)__shfl_xor((int)m, 16));
;       m = umax(m, (unsigned)__shfl_xor((int)m, 32));
;       win[pp][rr] = m;
; #pragma unroll
;       for (int i = 0; i < 32; ++i) kk[i] = (kk[i] == m) ? 0u : kk[i];
;     }
	v_max_u32_e32 v0, v0, v5
	v_cmp_ne_u32_e32 vcc, v88, v0
	v_cmp_ne_u32_e64 s[98:99], v89, v0
	v_cmp_ne_u32_e64 s[100:101], v164, v0
	v_cndmask_b32_e32 v5, 0, v88, vcc
	v_cndmask_b32_e64 v6, 0, v89, s[98:99]
	v_cndmask_b32_e64 v7, 0, v164, s[100:101]
	v_cmp_ne_u32_e32 vcc, v165, v0
	v_cmp_ne_u32_e64 s[98:99], v166, v0
	v_cmp_ne_u32_e64 s[100:101], v167, v0
	v_cndmask_b32_e32 v8, 0, v165, vcc
	v_cndmask_b32_e64 v9, 0, v166, s[98:99]
	v_cndmask_b32_e64 v10, 0, v167, s[100:101]
	v_cmp_ne_u32_e32 vcc, v168, v0
	v_cmp_ne_u32_e64 s[98:99], v169, v0
	v_cmp_ne_u32_e64 s[100:101], v171, v0
	v_cndmask_b32_e32 v11, 0, v168, vcc
	v_cndmask_b32_e64 v12, 0, v169, s[98:99]
	v_cndmask_b32_e64 v13, 0, v171, s[100:101]
	v_cmp_ne_u32_e32 vcc, v172, v0
	v_cmp_ne_u32_e64 s[98:99], v173, v0
	v_cmp_ne_u32_e64 s[100:101], v176, v0
	v_cndmask_b32_e32 v14, 0, v172, vcc
	v_cndmask_b32_e64 v15, 0, v173, s[98:99]
	v_cndmask_b32_e64 v86, 0, v176, s[100:101]
	v_cmp_ne_u32_e32 vcc, v177, v0
	v_cmp_ne_u32_e64 s[98:99], v178, v0
	v_cmp_ne_u32_e64 s[100:101], v179, v0
	v_cndmask_b32_e32 v87, 0, v177, vcc
	v_cndmask_b32_e64 v88, 0, v178, s[98:99]
	v_cndmask_b32_e64 v89, 0, v179, s[100:101]
	v_cmp_ne_u32_e32 vcc, v180, v0
	v_cmp_ne_u32_e64 s[98:99], v181, v0
	v_cmp_ne_u32_e64 s[100:101], v182, v0
	v_cndmask_b32_e32 v164, 0, v180, vcc
	v_cndmask_b32_e64 v165, 0, v181, s[98:99]
	v_cndmask_b32_e64 v166, 0, v182, s[100:101]
	v_cmp_ne_u32_e32 vcc, v183, v0
	v_cmp_ne_u32_e64 s[98:99], v184, v0
	v_cmp_ne_u32_e64 s[100:101], v185, v0
	v_cndmask_b32_e32 v167, 0, v183, vcc
	v_cndmask_b32_e64 v168, 0, v184, s[98:99]
	v_cndmask_b32_e64 v169, 0, v185, s[100:101]
	v_cmp_ne_u32_e32 vcc, v186, v0
	v_cmp_ne_u32_e64 s[98:99], v187, v0
	v_cmp_ne_u32_e64 s[100:101], v188, v0
	v_cndmask_b32_e32 v171, 0, v186, vcc
	v_cndmask_b32_e64 v172, 0, v187, s[98:99]
	v_cndmask_b32_e64 v173, 0, v188, s[100:101]
	v_cmp_ne_u32_e32 vcc, v189, v0
	v_cmp_ne_u32_e64 s[98:99], v194, v0
	v_cmp_ne_u32_e64 s[100:101], v195, v0
	v_cndmask_b32_e32 v176, 0, v189, vcc
	v_cndmask_b32_e64 v177, 0, v194, s[98:99]
	v_cndmask_b32_e64 v178, 0, v195, s[100:101]
	v_cmp_ne_u32_e32 vcc, v196, v0
	v_cmp_ne_u32_e64 s[98:99], v4, v0
	v_cmp_ne_u32_e64 s[100:101], v1, v0
	v_cndmask_b32_e32 v179, 0, v196, vcc
	v_cndmask_b32_e64 v4, 0, v4, s[98:99]
	v_cndmask_b32_e64 v180, 0, v1, s[100:101]
	v_max_u32_e32 v1, v5, v6
	v_max3_u32 v1, v1, v7, v8
	v_max3_u32 v1, v1, v9, v10
	v_max3_u32 v1, v1, v11, v12
	v_max3_u32 v1, v1, v13, v14
	v_max3_u32 v1, v1, v15, v86
	v_max3_u32 v1, v1, v87, v88
	v_max3_u32 v1, v1, v89, v164
	v_max3_u32 v1, v1, v165, v166
	v_max3_u32 v1, v1, v167, v168
	v_max3_u32 v1, v1, v169, v171
	v_max3_u32 v1, v1, v172, v173
	v_cmp_ne_u32_e32 vcc, v2, v0
	v_max3_u32 v1, v1, v176, v177
	v_max3_u32 v1, v1, v178, v179
	v_cndmask_b32_e32 v2, 0, v2, vcc
	v_cmp_ne_u32_e64 s[98:99], v3, v0
	v_max3_u32 v1, v1, v4, v180
	s_nop 0
	v_cndmask_b32_e64 v3, 0, v3, s[98:99]
	v_max3_u32 v1, v1, v2, v3
	ds_bpermute_b32 v181, v111, v1
	s_waitcnt lgkmcnt(0)
	v_max_u32_e32 v1, v1, v181
	ds_bpermute_b32 v181, v112, v1
	s_waitcnt lgkmcnt(0)
	v_max_u32_e32 v1, v1, v181
	v_cmp_ne_u32_e32 vcc, v5, v1
	v_cmp_ne_u32_e64 s[98:99], v6, v1
	v_cmp_ne_u32_e64 s[100:101], v7, v1
	v_cndmask_b32_e32 v5, 0, v5, vcc
	v_cndmask_b32_e64 v6, 0, v6, s[98:99]
	v_cndmask_b32_e64 v7, 0, v7, s[100:101]
	v_cmp_ne_u32_e32 vcc, v8, v1
	v_cmp_ne_u32_e64 s[98:99], v9, v1
	v_cmp_ne_u32_e64 s[100:101], v10, v1
	v_cndmask_b32_e32 v8, 0, v8, vcc
	v_cndmask_b32_e64 v9, 0, v9, s[98:99]
	v_cndmask_b32_e64 v10, 0, v10, s[100:101]
	v_cmp_ne_u32_e32 vcc, v11, v1
	v_cmp_ne_u32_e64 s[98:99], v12, v1
	v_cmp_ne_u32_e64 s[100:101], v13, v1
	v_cndmask_b32_e32 v11, 0, v11, vcc
	v_cndmask_b32_e64 v12, 0, v12, s[98:99]
	v_cndmask_b32_e64 v13, 0, v13, s[100:101]
	v_cmp_ne_u32_e32 vcc, v14, v1
	v_cmp_ne_u32_e64 s[98:99], v15, v1
	v_cmp_ne_u32_e64 s[100:101], v86, v1
	v_cndmask_b32_e32 v14, 0, v14, vcc
	v_cndmask_b32_e64 v15, 0, v15, s[98:99]
	v_cndmask_b32_e64 v86, 0, v86, s[100:101]
	v_cmp_ne_u32_e32 vcc, v87, v1
	v_cmp_ne_u32_e64 s[98:99], v88, v1
	v_cmp_ne_u32_e64 s[100:101], v89, v1
	v_cndmask_b32_e32 v87, 0, v87, vcc
	v_cndmask_b32_e64 v88, 0, v88, s[98:99]
	v_cndmask_b32_e64 v89, 0, v89, s[100:101]
	v_cmp_ne_u32_e32 vcc, v164, v1
	v_cmp_ne_u32_e64 s[98:99], v165, v1
	v_cmp_ne_u32_e64 s[100:101], v166, v1
	v_cndmask_b32_e32 v164, 0, v164, vcc
	v_cndmask_b32_e64 v165, 0, v165, s[98:99]
	v_cndmask_b32_e64 v166, 0, v166, s[100:101]
	v_cmp_ne_u32_e32 vcc, v167, v1
	v_cmp_ne_u32_e64 s[98:99], v168, v1
	v_cmp_ne_u32_e64 s[100:101], v169, v1
	v_cndmask_b32_e32 v167, 0, v167, vcc
	v_cndmask_b32_e64 v168, 0, v168, s[98:99]
	v_cndmask_b32_e64 v169, 0, v169, s[100:101]
	v_cmp_ne_u32_e32 vcc, v171, v1
	v_cmp_ne_u32_e64 s[98:99], v172, v1
	v_cmp_ne_u32_e64 s[100:101], v173, v1
	v_cndmask_b32_e32 v171, 0, v171, vcc
	v_cndmask_b32_e64 v172, 0, v172, s[98:99]
	v_cndmask_b32_e64 v173, 0, v173, s[100:101]
	v_cmp_ne_u32_e32 vcc, v176, v1
	v_cmp_ne_u32_e64 s[98:99], v177, v1
	v_cmp_ne_u32_e64 s[100:101], v178, v1
	v_cndmask_b32_e32 v176, 0, v176, vcc
	v_cndmask_b32_e64 v177, 0, v177, s[98:99]
	v_cndmask_b32_e64 v178, 0, v178, s[100:101]
	v_cmp_ne_u32_e32 vcc, v179, v1
	v_cmp_ne_u32_e64 s[98:99], v4, v1
	v_cmp_ne_u32_e64 s[100:101], v180, v1
	v_cndmask_b32_e32 v179, 0, v179, vcc
	v_cndmask_b32_e64 v4, 0, v4, s[98:99]
	v_cndmask_b32_e64 v180, 0, v180, s[100:101]
	v_cmp_ne_u32_e32 vcc, v2, v1
	v_cmp_ne_u32_e64 s[98:99], v3, v1
	s_nop 0
	v_cndmask_b32_e32 v181, 0, v2, vcc
	v_max_u32_e32 v2, v5, v6
	v_max3_u32 v2, v2, v7, v8
	v_max3_u32 v2, v2, v9, v10
	v_max3_u32 v2, v2, v11, v12
	v_max3_u32 v2, v2, v13, v14
	v_max3_u32 v2, v2, v15, v86
	v_max3_u32 v2, v2, v87, v88
	v_max3_u32 v2, v2, v89, v164
	v_max3_u32 v2, v2, v165, v166
	v_max3_u32 v2, v2, v167, v168
	v_max3_u32 v2, v2, v169, v171
	v_max3_u32 v2, v2, v172, v173
	v_max3_u32 v2, v2, v176, v177
	v_max3_u32 v2, v2, v178, v179
	v_max3_u32 v2, v2, v4, v180
	v_cndmask_b32_e64 v3, 0, v3, s[98:99]
	v_max3_u32 v2, v2, v181, v3
	ds_bpermute_b32 v182, v111, v2
	s_waitcnt lgkmcnt(0)
; DI void peer_topk_wave(const Params& p, int item, unsigned* lds  ) {
;     ...
; #pragma unroll
;     for (int rr = 0; rr < 16; ++rr) {
;       unsigned m = 0;
; #pragma unroll
;       for (int i = 0; i < 32; ++i) m = umax(m, kk[i]);
;       m = umax(m, (unsigned)__shfl_xor((int)m, 16));
;       m = umax(m, (unsigned)__shfl_xor((int)m, 32));
;       win[pp][rr] = m;
; #pragma unroll
;       for (int i = 0; i < 32; ++i) kk[i] = (kk[i] == m) ? 0u : kk[i];
;     }
	v_max_u32_e32 v2, v2, v182
	ds_bpermute_b32 v182, v112, v2
	s_waitcnt lgkmcnt(0)
	v_max_u32_e32 v2, v2, v182
	v_cmp_ne_u32_e32 vcc, v5, v2
	v_cmp_ne_u32_e64 s[98:99], v6, v2
	v_cmp_ne_u32_e64 s[100:101], v7, v2
	v_cndmask_b32_e32 v5, 0, v5, vcc
	v_cndmask_b32_e64 v6, 0, v6, s[98:99]
	v_cndmask_b32_e64 v7, 0, v7, s[100:101]
	v_cmp_ne_u32_e32 vcc, v8, v2
	v_cmp_ne_u32_e64 s[98:99], v9, v2
	v_cmp_ne_u32_e64 s[100:101], v10, v2
	v_cndmask_b32_e32 v8, 0, v8, vcc
	v_cndmask_b32_e64 v9, 0, v9, s[98:99]
	v_cndmask_b32_e64 v10, 0, v10, s[100:101]
	v_cmp_ne_u32_e32 vcc, v11, v2
	v_cmp_ne_u32_e64 s[98:99], v12, v2
	v_cmp_ne_u32_e64 s[100:101], v13, v2
	v_cndmask_b32_e32 v11, 0, v11, vcc
	v_cndmask_b32_e64 v12, 0, v12, s[98:99]
	v_cndmask_b32_e64 v13, 0, v13, s[100:101]
	v_cmp_ne_u32_e32 vcc, v14, v2
	v_cmp_ne_u32_e64 s[98:99], v15, v2
	v_cmp_ne_u32_e64 s[100:101], v86, v2
	v_cndmask_b32_e32 v14, 0, v14, vcc
	v_cndmask_b32_e64 v15, 0, v15, s[98:99]
	v_cndmask_b32_e64 v86, 0, v86, s[100:101]
	v_cmp_ne_u32_e32 vcc, v87, v2
	v_cmp_ne_u32_e64 s[98:99], v88, v2
	v_cmp_ne_u32_e64 s[100:101], v89, v2
	v_cndmask_b32_e32 v87, 0, v87, vcc
	v_cndmask_b32_e64 v88, 0, v88, s[98:99]
	v_cndmask_b32_e64 v89, 0, v89, s[100:101]
	v_cmp_ne_u32_e32 vcc, v164, v2
	v_cmp_ne_u32_e64 s[98:99], v165, v2
	v_cmp_ne_u32_e64 s[100:101], v166, v2
	v_cndmask_b32_e32 v164, 0, v164, vcc
	v_cndmask_b32_e64 v165, 0, v165, s[98:99]
	v_cndmask_b32_e64 v166, 0, v166, s[100:101]
	v_cmp_ne_u32_e32 vcc, v167, v2
	v_cmp_ne_u32_e64 s[98:99], v168, v2
	v_cmp_ne_u32_e64 s[100:101], v169, v2
	v_cndmask_b32_e32 v167, 0, v167, vcc
	v_cndmask_b32_e64 v168, 0, v168, s[98:99]
	v_cndmask_b32_e64 v169, 0, v169, s[100:101]
	v_cmp_ne_u32_e32 vcc, v171, v2
	v_cmp_ne_u32_e64 s[98:99], v172, v2
	v_cmp_ne_u32_e64 s[100:101], v173, v2
	v_cndmask_b32_e32 v171, 0, v171, vcc
	v_cndmask_b32_e64 v172, 0, v172, s[98:99]
	v_cndmask_b32_e64 v173, 0, v173, s[100:101]
	v_cmp_ne_u32_e32 vcc, v176, v2
	v_cmp_ne_u32_e64 s[98:99], v177, v2
	v_cmp_ne_u32_e64 s[100:101], v178, v2
	v_cndmask_b32_e32 v176, 0, v176, vcc
	v_cndmask_b32_e64 v177, 0, v177, s[98:99]
	v_cndmask_b32_e64 v178, 0, v178, s[100:101]
	v_cmp_ne_u32_e32 vcc, v179, v2
	v_cmp_ne_u32_e64 s[98:99], v4, v2
	v_cmp_ne_u32_e64 s[100:101], v180, v2
	v_cndmask_b32_e32 v179, 0, v179, vcc
	v_cndmask_b32_e64 v4, 0, v4, s[98:99]
	v_cndmask_b32_e64 v180, 0, v180, s[100:101]
	v_cmp_ne_u32_e32 vcc, v181, v2
	v_cmp_ne_u32_e64 s[98:99], v3, v2
	s_nop 0
	v_cndmask_b32_e32 v181, 0, v181, vcc
	v_cndmask_b32_e64 v182, 0, v3, s[98:99]
	v_max_u32_e32 v3, v5, v6
	v_max3_u32 v3, v3, v7, v8
	v_max3_u32 v3, v3, v9, v10
	v_max3_u32 v3, v3, v11, v12
	v_max3_u32 v3, v3, v13, v14
	v_max3_u32 v3, v3, v15, v86
	v_max3_u32 v3, v3, v87, v88
	v_max3_u32 v3, v3, v89, v164
	v_max3_u32 v3, v3, v165, v166
	v_max3_u32 v3, v3, v167, v168
	v_max3_u32 v3, v3, v169, v171
	v_max3_u32 v3, v3, v172, v173
	v_max3_u32 v3, v3, v176, v177
	v_max3_u32 v3, v3, v178, v179
	v_max3_u32 v3, v3, v4, v180
	v_max3_u32 v3, v3, v181, v182
	ds_bpermute_b32 v183, v111, v3
	s_waitcnt lgkmcnt(0)
	v_max_u32_e32 v3, v3, v183
	ds_bpermute_b32 v183, v112, v3
	s_waitcnt lgkmcnt(0)
	v_max_u32_e32 v3, v3, v183
	v_cmp_ne_u32_e32 vcc, v5, v3
	v_cmp_ne_u32_e64 s[98:99], v6, v3
	v_cmp_ne_u32_e64 s[100:101], v7, v3
	v_cndmask_b32_e32 v5, 0, v5, vcc
	v_cndmask_b32_e64 v6, 0, v6, s[98:99]
	v_cndmask_b32_e64 v7, 0, v7, s[100:101]
	v_cmp_ne_u32_e32 vcc, v8, v3
	v_cmp_ne_u32_e64 s[98:99], v9, v3
	v_cmp_ne_u32_e64 s[100:101], v10, v3
	v_cndmask_b32_e32 v8, 0, v8, vcc
	v_cndmask_b32_e64 v9, 0, v9, s[98:99]
	v_cndmask_b32_e64 v10, 0, v10, s[100:101]
	v_cmp_ne_u32_e32 vcc, v11, v3
	v_cmp_ne_u32_e64 s[98:99], v12, v3
	v_cmp_ne_u32_e64 s[100:101], v13, v3
	v_cndmask_b32_e32 v11, 0, v11, vcc
	v_cndmask_b32_e64 v12, 0, v12, s[98:99]
	v_cndmask_b32_e64 v13, 0, v13, s[100:101]
	v_cmp_ne_u32_e32 vcc, v14, v3
	v_cmp_ne_u32_e64 s[98:99], v15, v3
	v_cmp_ne_u32_e64 s[100:101], v86, v3
	v_cndmask_b32_e32 v14, 0, v14, vcc
	v_cndmask_b32_e64 v15, 0, v15, s[98:99]
	v_cndmask_b32_e64 v86, 0, v86, s[100:101]
	v_cmp_ne_u32_e32 vcc, v87, v3
	v_cmp_ne_u32_e64 s[98:99], v88, v3
	v_cmp_ne_u32_e64 s[100:101], v89, v3
	v_cndmask_b32_e32 v87, 0, v87, vcc
	v_cndmask_b32_e64 v88, 0, v88, s[98:99]
	v_cndmask_b32_e64 v89, 0, v89, s[100:101]
	v_cmp_ne_u32_e32 vcc, v164, v3
	v_cmp_ne_u32_e64 s[98:99], v165, v3
	v_cmp_ne_u32_e64 s[100:101], v166, v3
	v_cndmask_b32_e32 v164, 0, v164, vcc
	v_cndmask_b32_e64 v165, 0, v165, s[98:99]
	v_cndmask_b32_e64 v166, 0, v166, s[100:101]
	v_cmp_ne_u32_e32 vcc, v167, v3
	v_cmp_ne_u32_e64 s[98:99], v168, v3
	v_cmp_ne_u32_e64 s[100:101], v169, v3
	v_cndmask_b32_e32 v167, 0, v167, vcc
	v_cndmask_b32_e64 v168, 0, v168, s[98:99]
	v_cndmask_b32_e64 v169, 0, v169, s[100:101]
	v_cmp_ne_u32_e32 vcc, v171, v3
	v_cmp_ne_u32_e64 s[98:99], v172, v3
	v_cmp_ne_u32_e64 s[100:101], v173, v3
	v_cndmask_b32_e32 v171, 0, v171, vcc
	v_cndmask_b32_e64 v172, 0, v172, s[98:99]
	v_cndmask_b32_e64 v173, 0, v173, s[100:101]
	v_cmp_ne_u32_e32 vcc, v176, v3
	v_cmp_ne_u32_e64 s[98:99], v177, v3
	v_cmp_ne_u32_e64 s[100:101], v178, v3
	v_cndmask_b32_e32 v176, 0, v176, vcc
	v_cndmask_b32_e64 v177, 0, v177, s[98:99]
	v_cndmask_b32_e64 v178, 0, v178, s[100:101]
	v_cmp_ne_u32_e32 vcc, v179, v3
	v_cmp_ne_u32_e64 s[98:99], v4, v3
	v_cmp_ne_u32_e64 s[100:101], v180, v3
	v_cndmask_b32_e32 v179, 0, v179, vcc
	v_cndmask_b32_e64 v183, 0, v4, s[98:99]
	v_max_u32_e32 v4, v5, v6
	v_max3_u32 v4, v4, v7, v8
	v_max3_u32 v4, v4, v9, v10
	v_max3_u32 v4, v4, v11, v12
	v_max3_u32 v4, v4, v13, v14
	v_max3_u32 v4, v4, v15, v86
	v_max3_u32 v4, v4, v87, v88
	v_max3_u32 v4, v4, v89, v164
	v_max3_u32 v4, v4, v165, v166
	v_max3_u32 v4, v4, v167, v168
	v_max3_u32 v4, v4, v169, v171
	v_max3_u32 v4, v4, v172, v173
	v_max3_u32 v4, v4, v176, v177
	v_cndmask_b32_e64 v180, 0, v180, s[100:101]
	v_cmp_ne_u32_e32 vcc, v181, v3
	v_max3_u32 v4, v4, v178, v179
	v_max3_u32 v4, v4, v183, v180
	v_cndmask_b32_e32 v181, 0, v181, vcc
	v_cmp_ne_u32_e64 s[98:99], v182, v3
	s_nop 0
	s_nop 0
	v_cndmask_b32_e64 v182, 0, v182, s[98:99]
	v_max3_u32 v4, v4, v181, v182
	ds_bpermute_b32 v184, v111, v4
	s_waitcnt lgkmcnt(0)
; DI void peer_topk_wave(const Params& p, int item, unsigned* lds  ) {
;     ...
; #pragma unroll
;     for (int rr = 0; rr < 16; ++rr) {
;       unsigned m = 0;
; #pragma unroll
;       for (int i = 0; i < 32; ++i) m = umax(m, kk[i]);
;       m = umax(m, (unsigned)__shfl_xor((int)m, 16));
;       m = umax(m, (unsigned)__shfl_xor((int)m, 32));
;       win[pp][rr] = m;
; #pragma unroll
;       for (int i = 0; i < 32; ++i) kk[i] = (kk[i] == m) ? 0u : kk[i];
;     }
	v_max_u32_e32 v4, v4, v184
	ds_bpermute_b32 v184, v112, v4
	s_waitcnt lgkmcnt(0)
	v_max_u32_e32 v4, v4, v184
	v_cmp_ne_u32_e32 vcc, v5, v4
	v_cmp_ne_u32_e64 s[98:99], v6, v4
	v_cmp_ne_u32_e64 s[100:101], v7, v4
	v_cndmask_b32_e32 v184, 0, v5, vcc
	v_cndmask_b32_e64 v6, 0, v6, s[98:99]
	v_max_u32_e32 v5, v184, v6
	v_cndmask_b32_e64 v7, 0, v7, s[100:101]
	v_cmp_ne_u32_e32 vcc, v8, v4
	v_cmp_ne_u32_e64 s[98:99], v9, v4
	v_cmp_ne_u32_e64 s[100:101], v10, v4
	v_cndmask_b32_e32 v8, 0, v8, vcc
	v_max3_u32 v5, v5, v7, v8
	v_cndmask_b32_e64 v9, 0, v9, s[98:99]
	v_cndmask_b32_e64 v10, 0, v10, s[100:101]
	v_cmp_ne_u32_e32 vcc, v11, v4
	v_max3_u32 v5, v5, v9, v10
	v_cmp_ne_u32_e64 s[98:99], v12, v4
	v_cndmask_b32_e32 v11, 0, v11, vcc
	v_cmp_ne_u32_e64 s[100:101], v13, v4
	v_cndmask_b32_e64 v12, 0, v12, s[98:99]
	v_max3_u32 v5, v5, v11, v12
	v_cndmask_b32_e64 v13, 0, v13, s[100:101]
	v_cmp_ne_u32_e32 vcc, v14, v4
	v_cmp_ne_u32_e64 s[98:99], v15, v4
	v_cmp_ne_u32_e64 s[100:101], v86, v4
	v_cndmask_b32_e32 v14, 0, v14, vcc
	v_max3_u32 v5, v5, v13, v14
	v_cndmask_b32_e64 v15, 0, v15, s[98:99]
	v_cndmask_b32_e64 v86, 0, v86, s[100:101]
	v_cmp_ne_u32_e32 vcc, v87, v4
	v_max3_u32 v5, v5, v15, v86
	v_cmp_ne_u32_e64 s[98:99], v88, v4
	v_cndmask_b32_e32 v87, 0, v87, vcc
	v_cmp_ne_u32_e64 s[100:101], v89, v4
	v_cndmask_b32_e64 v88, 0, v88, s[98:99]
	v_max3_u32 v5, v5, v87, v88
	v_cndmask_b32_e64 v89, 0, v89, s[100:101]
	v_cmp_ne_u32_e32 vcc, v164, v4
	v_cmp_ne_u32_e64 s[98:99], v165, v4
	v_cmp_ne_u32_e64 s[100:101], v166, v4
	v_cndmask_b32_e32 v164, 0, v164, vcc
	v_max3_u32 v5, v5, v89, v164
	v_cndmask_b32_e64 v165, 0, v165, s[98:99]
	v_cndmask_b32_e64 v166, 0, v166, s[100:101]
	v_cmp_ne_u32_e32 vcc, v167, v4
	v_max3_u32 v5, v5, v165, v166
	v_cmp_ne_u32_e64 s[98:99], v168, v4
	v_cndmask_b32_e32 v167, 0, v167, vcc
	v_cmp_ne_u32_e64 s[100:101], v169, v4
	v_cndmask_b32_e64 v168, 0, v168, s[98:99]
	v_max3_u32 v5, v5, v167, v168
	v_cndmask_b32_e64 v169, 0, v169, s[100:101]
	v_cmp_ne_u32_e32 vcc, v171, v4
	v_cmp_ne_u32_e64 s[98:99], v172, v4
	v_cmp_ne_u32_e64 s[100:101], v173, v4
	v_cndmask_b32_e32 v171, 0, v171, vcc
	v_max3_u32 v5, v5, v169, v171
	v_cndmask_b32_e64 v172, 0, v172, s[98:99]
	v_cndmask_b32_e64 v173, 0, v173, s[100:101]
	v_cmp_ne_u32_e32 vcc, v176, v4
	v_max3_u32 v5, v5, v172, v173
	v_cmp_ne_u32_e64 s[98:99], v177, v4
	v_cndmask_b32_e32 v176, 0, v176, vcc
	v_cmp_ne_u32_e64 s[100:101], v178, v4
	v_cndmask_b32_e64 v177, 0, v177, s[98:99]
	v_max3_u32 v5, v5, v176, v177
	v_cndmask_b32_e64 v178, 0, v178, s[100:101]
	v_cmp_ne_u32_e32 vcc, v179, v4
	v_cmp_ne_u32_e64 s[98:99], v183, v4
	v_cmp_ne_u32_e64 s[100:101], v180, v4
	v_cndmask_b32_e32 v179, 0, v179, vcc
	v_max3_u32 v5, v5, v178, v179
	v_cndmask_b32_e64 v183, 0, v183, s[98:99]
	v_cndmask_b32_e64 v180, 0, v180, s[100:101]
	v_cmp_ne_u32_e32 vcc, v181, v4
	v_max3_u32 v5, v5, v183, v180
	v_cmp_ne_u32_e64 s[98:99], v182, v4
	v_cndmask_b32_e32 v181, 0, v181, vcc
	s_nop 0
	v_cndmask_b32_e64 v182, 0, v182, s[98:99]
	v_max3_u32 v5, v5, v181, v182
	ds_bpermute_b32 v185, v111, v5
	s_waitcnt lgkmcnt(0)
	v_max_u32_e32 v5, v5, v185
	ds_bpermute_b32 v185, v112, v5
	s_waitcnt lgkmcnt(0)
	v_max_u32_e32 v5, v5, v185
	v_cmp_ne_u32_e32 vcc, v184, v5
	v_cmp_ne_u32_e64 s[98:99], v6, v5
	v_cmp_ne_u32_e64 s[100:101], v7, v5
	v_cndmask_b32_e32 v184, 0, v184, vcc
	v_cndmask_b32_e64 v185, 0, v6, s[98:99]
	v_max_u32_e32 v6, v184, v185
	v_cndmask_b32_e64 v7, 0, v7, s[100:101]
	v_cmp_ne_u32_e32 vcc, v8, v5
	v_cmp_ne_u32_e64 s[98:99], v9, v5
	v_cmp_ne_u32_e64 s[100:101], v10, v5
	v_cndmask_b32_e32 v8, 0, v8, vcc
	v_max3_u32 v6, v6, v7, v8
	v_cndmask_b32_e64 v9, 0, v9, s[98:99]
	v_cndmask_b32_e64 v10, 0, v10, s[100:101]
	v_cmp_ne_u32_e32 vcc, v11, v5
	v_max3_u32 v6, v6, v9, v10
	v_cmp_ne_u32_e64 s[98:99], v12, v5
	v_cndmask_b32_e32 v11, 0, v11, vcc
	v_cmp_ne_u32_e64 s[100:101], v13, v5
	v_cndmask_b32_e64 v12, 0, v12, s[98:99]
	v_max3_u32 v6, v6, v11, v12
	v_cndmask_b32_e64 v13, 0, v13, s[100:101]
	v_cmp_ne_u32_e32 vcc, v14, v5
	v_cmp_ne_u32_e64 s[98:99], v15, v5
	v_cmp_ne_u32_e64 s[100:101], v86, v5
	v_cndmask_b32_e32 v14, 0, v14, vcc
	v_max3_u32 v6, v6, v13, v14
	v_cndmask_b32_e64 v15, 0, v15, s[98:99]
	v_cndmask_b32_e64 v86, 0, v86, s[100:101]
	v_cmp_ne_u32_e32 vcc, v87, v5
	v_max3_u32 v6, v6, v15, v86
	v_cmp_ne_u32_e64 s[98:99], v88, v5
	v_cndmask_b32_e32 v87, 0, v87, vcc
	v_cmp_ne_u32_e64 s[100:101], v89, v5
	v_cndmask_b32_e64 v88, 0, v88, s[98:99]
	v_max3_u32 v6, v6, v87, v88
	v_cndmask_b32_e64 v89, 0, v89, s[100:101]
	v_cmp_ne_u32_e32 vcc, v164, v5
	v_cmp_ne_u32_e64 s[98:99], v165, v5
	v_cmp_ne_u32_e64 s[100:101], v166, v5
	v_cndmask_b32_e32 v164, 0, v164, vcc
	v_max3_u32 v6, v6, v89, v164
	v_cndmask_b32_e64 v165, 0, v165, s[98:99]
	v_cndmask_b32_e64 v166, 0, v166, s[100:101]
	v_cmp_ne_u32_e32 vcc, v167, v5
	v_max3_u32 v6, v6, v165, v166
	v_cmp_ne_u32_e64 s[98:99], v168, v5
	v_cndmask_b32_e32 v167, 0, v167, vcc
	v_cmp_ne_u32_e64 s[100:101], v169, v5
	v_cndmask_b32_e64 v168, 0, v168, s[98:99]
	v_max3_u32 v6, v6, v167, v168
	v_cndmask_b32_e64 v169, 0, v169, s[100:101]
	v_cmp_ne_u32_e32 vcc, v171, v5
	v_cmp_ne_u32_e64 s[98:99], v172, v5
	v_cmp_ne_u32_e64 s[100:101], v173, v5
	v_cndmask_b32_e32 v171, 0, v171, vcc
	v_max3_u32 v6, v6, v169, v171
	v_cndmask_b32_e64 v172, 0, v172, s[98:99]
	v_cndmask_b32_e64 v173, 0, v173, s[100:101]
	v_cmp_ne_u32_e32 vcc, v176, v5
	v_max3_u32 v6, v6, v172, v173
	v_cmp_ne_u32_e64 s[98:99], v177, v5
	v_cndmask_b32_e32 v176, 0, v176, vcc
	v_cmp_ne_u32_e64 s[100:101], v178, v5
	v_cndmask_b32_e64 v177, 0, v177, s[98:99]
	v_max3_u32 v6, v6, v176, v177
	v_cndmask_b32_e64 v178, 0, v178, s[100:101]
	v_cmp_ne_u32_e32 vcc, v179, v5
	v_cmp_ne_u32_e64 s[98:99], v183, v5
	v_cmp_ne_u32_e64 s[100:101], v180, v5
	v_cndmask_b32_e32 v179, 0, v179, vcc
	v_max3_u32 v6, v6, v178, v179
	v_cndmask_b32_e64 v183, 0, v183, s[98:99]
	v_cndmask_b32_e64 v180, 0, v180, s[100:101]
	v_cmp_ne_u32_e32 vcc, v181, v5
	v_max3_u32 v6, v6, v183, v180
	v_cmp_ne_u32_e64 s[98:99], v182, v5
	v_cndmask_b32_e32 v181, 0, v181, vcc
	s_nop 0
	v_cndmask_b32_e64 v182, 0, v182, s[98:99]
	v_max3_u32 v6, v6, v181, v182
	ds_bpermute_b32 v186, v111, v6
	s_waitcnt lgkmcnt(0)
; DI void peer_topk_wave(const Params& p, int item, unsigned* lds  ) {
;     ...
; #pragma unroll
;     for (int rr = 0; rr < 16; ++rr) {
;       unsigned m = 0;
; #pragma unroll
;       for (int i = 0; i < 32; ++i) m = umax(m, kk[i]);
;       m = umax(m, (unsigned)__shfl_xor((int)m, 16));
;       m = umax(m, (unsigned)__shfl_xor((int)m, 32));
;       win[pp][rr] = m;
; #pragma unroll
;       for (int i = 0; i < 32; ++i) kk[i] = (kk[i] == m) ? 0u : kk[i];
;     }
	v_max_u32_e32 v6, v6, v186
	ds_bpermute_b32 v186, v112, v6
	s_waitcnt lgkmcnt(0)
	v_max_u32_e32 v6, v6, v186
	v_cmp_ne_u32_e32 vcc, v184, v6
	v_cmp_ne_u32_e64 s[98:99], v185, v6
	v_cmp_ne_u32_e64 s[100:101], v7, v6
	v_cndmask_b32_e32 v184, 0, v184, vcc
	v_cndmask_b32_e64 v185, 0, v185, s[98:99]
	v_cndmask_b32_e64 v186, 0, v7, s[100:101]
	v_cmp_ne_u32_e32 vcc, v8, v6
	v_max_u32_e32 v7, v184, v185
	v_cmp_ne_u32_e64 s[98:99], v9, v6
	v_cndmask_b32_e32 v8, 0, v8, vcc
	v_max3_u32 v7, v7, v186, v8
	v_cndmask_b32_e64 v9, 0, v9, s[98:99]
	v_cmp_ne_u32_e64 s[100:101], v10, v6
	v_cmp_ne_u32_e32 vcc, v11, v6
	v_cmp_ne_u32_e64 s[98:99], v12, v6
	v_cndmask_b32_e64 v10, 0, v10, s[100:101]
	v_max3_u32 v7, v7, v9, v10
	v_cndmask_b32_e32 v11, 0, v11, vcc
	v_cndmask_b32_e64 v12, 0, v12, s[98:99]
	v_cmp_ne_u32_e64 s[100:101], v13, v6
	v_max3_u32 v7, v7, v11, v12
	v_cmp_ne_u32_e32 vcc, v14, v6
	v_cndmask_b32_e64 v13, 0, v13, s[100:101]
	v_cmp_ne_u32_e64 s[98:99], v15, v6
	v_cndmask_b32_e32 v14, 0, v14, vcc
	v_max3_u32 v7, v7, v13, v14
	v_cndmask_b32_e64 v15, 0, v15, s[98:99]
	v_cmp_ne_u32_e64 s[100:101], v86, v6
	v_cmp_ne_u32_e32 vcc, v87, v6
	v_cmp_ne_u32_e64 s[98:99], v88, v6
	v_cndmask_b32_e64 v86, 0, v86, s[100:101]
	v_max3_u32 v7, v7, v15, v86
	v_cndmask_b32_e32 v87, 0, v87, vcc
	v_cndmask_b32_e64 v88, 0, v88, s[98:99]
	v_cmp_ne_u32_e64 s[100:101], v89, v6
	v_max3_u32 v7, v7, v87, v88
	v_cmp_ne_u32_e32 vcc, v164, v6
	v_cndmask_b32_e64 v89, 0, v89, s[100:101]
	v_cmp_ne_u32_e64 s[98:99], v165, v6
	v_cndmask_b32_e32 v164, 0, v164, vcc
	v_max3_u32 v7, v7, v89, v164
	v_cndmask_b32_e64 v165, 0, v165, s[98:99]
	v_cmp_ne_u32_e64 s[100:101], v166, v6
	v_cmp_ne_u32_e32 vcc, v167, v6
	v_cmp_ne_u32_e64 s[98:99], v168, v6
	v_cndmask_b32_e64 v166, 0, v166, s[100:101]
	v_max3_u32 v7, v7, v165, v166
	v_cndmask_b32_e32 v167, 0, v167, vcc
	v_cndmask_b32_e64 v168, 0, v168, s[98:99]
	v_cmp_ne_u32_e64 s[100:101], v169, v6
	v_max3_u32 v7, v7, v167, v168
	v_cmp_ne_u32_e32 vcc, v171, v6
	v_cndmask_b32_e64 v169, 0, v169, s[100:101]
	v_cmp_ne_u32_e64 s[98:99], v172, v6
	v_cndmask_b32_e32 v171, 0, v171, vcc
	v_max3_u32 v7, v7, v169, v171
	v_cndmask_b32_e64 v172, 0, v172, s[98:99]
	v_cmp_ne_u32_e64 s[100:101], v173, v6
	v_cmp_ne_u32_e32 vcc, v176, v6
	v_cmp_ne_u32_e64 s[98:99], v177, v6
	v_cndmask_b32_e64 v173, 0, v173, s[100:101]
	v_max3_u32 v7, v7, v172, v173
	v_cndmask_b32_e32 v176, 0, v176, vcc
	v_cndmask_b32_e64 v177, 0, v177, s[98:99]
	v_cmp_ne_u32_e64 s[100:101], v178, v6
	v_max3_u32 v7, v7, v176, v177
	v_cmp_ne_u32_e32 vcc, v179, v6
	v_cndmask_b32_e64 v178, 0, v178, s[100:101]
	v_cmp_ne_u32_e64 s[98:99], v183, v6
	v_cndmask_b32_e32 v179, 0, v179, vcc
	v_max3_u32 v7, v7, v178, v179
	v_cndmask_b32_e64 v183, 0, v183, s[98:99]
	v_cmp_ne_u32_e64 s[100:101], v180, v6
	v_cmp_ne_u32_e32 vcc, v181, v6
	v_cmp_ne_u32_e64 s[98:99], v182, v6
	v_cndmask_b32_e64 v180, 0, v180, s[100:101]
	v_max3_u32 v7, v7, v183, v180
	v_cndmask_b32_e32 v181, 0, v181, vcc
	v_cndmask_b32_e64 v182, 0, v182, s[98:99]
	v_max3_u32 v7, v7, v181, v182
	ds_bpermute_b32 v187, v111, v7
	s_waitcnt lgkmcnt(0)
	v_max_u32_e32 v7, v7, v187
	ds_bpermute_b32 v187, v112, v7
	s_waitcnt lgkmcnt(0)
	v_max_u32_e32 v7, v7, v187
	v_cmp_ne_u32_e32 vcc, v184, v7
	v_cmp_ne_u32_e64 s[98:99], v185, v7
	v_cmp_ne_u32_e64 s[100:101], v186, v7
	v_cndmask_b32_e32 v184, 0, v184, vcc
	v_cndmask_b32_e64 v185, 0, v185, s[98:99]
	v_cndmask_b32_e64 v186, 0, v186, s[100:101]
	v_cmp_ne_u32_e32 vcc, v8, v7
	v_cmp_ne_u32_e64 s[98:99], v9, v7
	v_cmp_ne_u32_e64 s[100:101], v10, v7
	v_cndmask_b32_e32 v187, 0, v8, vcc
	v_max_u32_e32 v8, v184, v185
	v_max3_u32 v8, v8, v186, v187
	v_cndmask_b32_e64 v9, 0, v9, s[98:99]
	v_cndmask_b32_e64 v10, 0, v10, s[100:101]
	v_cmp_ne_u32_e32 vcc, v11, v7
	v_max3_u32 v8, v8, v9, v10
	v_cmp_ne_u32_e64 s[98:99], v12, v7
	v_cndmask_b32_e32 v11, 0, v11, vcc
	v_cmp_ne_u32_e64 s[100:101], v13, v7
	v_cndmask_b32_e64 v12, 0, v12, s[98:99]
	v_max3_u32 v8, v8, v11, v12
	v_cndmask_b32_e64 v13, 0, v13, s[100:101]
	v_cmp_ne_u32_e32 vcc, v14, v7
	v_cmp_ne_u32_e64 s[98:99], v15, v7
	v_cmp_ne_u32_e64 s[100:101], v86, v7
	v_cndmask_b32_e32 v14, 0, v14, vcc
	v_max3_u32 v8, v8, v13, v14
	v_cndmask_b32_e64 v15, 0, v15, s[98:99]
	v_cndmask_b32_e64 v86, 0, v86, s[100:101]
	v_cmp_ne_u32_e32 vcc, v87, v7
	v_max3_u32 v8, v8, v15, v86
	v_cmp_ne_u32_e64 s[98:99], v88, v7
	v_cndmask_b32_e32 v87, 0, v87, vcc
	v_cmp_ne_u32_e64 s[100:101], v89, v7
	v_cndmask_b32_e64 v88, 0, v88, s[98:99]
	v_max3_u32 v8, v8, v87, v88
	v_cndmask_b32_e64 v89, 0, v89, s[100:101]
	v_cmp_ne_u32_e32 vcc, v164, v7
	v_cmp_ne_u32_e64 s[98:99], v165, v7
	v_cmp_ne_u32_e64 s[100:101], v166, v7
	v_cndmask_b32_e32 v164, 0, v164, vcc
	v_max3_u32 v8, v8, v89, v164
	v_cndmask_b32_e64 v165, 0, v165, s[98:99]
	v_cndmask_b32_e64 v166, 0, v166, s[100:101]
	v_cmp_ne_u32_e32 vcc, v167, v7
	v_max3_u32 v8, v8, v165, v166
	v_cmp_ne_u32_e64 s[98:99], v168, v7
	v_cndmask_b32_e32 v167, 0, v167, vcc
	v_cmp_ne_u32_e64 s[100:101], v169, v7
	v_cndmask_b32_e64 v168, 0, v168, s[98:99]
	v_max3_u32 v8, v8, v167, v168
	v_cndmask_b32_e64 v169, 0, v169, s[100:101]
	v_cmp_ne_u32_e32 vcc, v171, v7
	v_cmp_ne_u32_e64 s[98:99], v172, v7
	v_cmp_ne_u32_e64 s[100:101], v173, v7
	v_cndmask_b32_e32 v171, 0, v171, vcc
	v_max3_u32 v8, v8, v169, v171
	v_cndmask_b32_e64 v172, 0, v172, s[98:99]
	v_cndmask_b32_e64 v173, 0, v173, s[100:101]
	v_cmp_ne_u32_e32 vcc, v176, v7
	v_max3_u32 v8, v8, v172, v173
	v_cmp_ne_u32_e64 s[98:99], v177, v7
	v_cndmask_b32_e32 v176, 0, v176, vcc
	v_cmp_ne_u32_e64 s[100:101], v178, v7
	v_cndmask_b32_e64 v177, 0, v177, s[98:99]
	v_max3_u32 v8, v8, v176, v177
	v_cndmask_b32_e64 v178, 0, v178, s[100:101]
	v_cmp_ne_u32_e32 vcc, v179, v7
	v_cmp_ne_u32_e64 s[98:99], v183, v7
	v_cmp_ne_u32_e64 s[100:101], v180, v7
	v_cndmask_b32_e32 v179, 0, v179, vcc
	v_max3_u32 v8, v8, v178, v179
	v_cndmask_b32_e64 v183, 0, v183, s[98:99]
	v_cndmask_b32_e64 v180, 0, v180, s[100:101]
	v_cmp_ne_u32_e32 vcc, v181, v7
	v_max3_u32 v8, v8, v183, v180
	v_cmp_ne_u32_e64 s[98:99], v182, v7
	v_cndmask_b32_e32 v181, 0, v181, vcc
	s_nop 0
	v_cndmask_b32_e64 v182, 0, v182, s[98:99]
	v_max3_u32 v8, v8, v181, v182
	ds_bpermute_b32 v188, v111, v8
	s_waitcnt lgkmcnt(0)
; DI void peer_topk_wave(const Params& p, int item, unsigned* lds  ) {
;     ...
; #pragma unroll
;     for (int rr = 0; rr < 16; ++rr) {
;       unsigned m = 0;
; #pragma unroll
;       for (int i = 0; i < 32; ++i) m = umax(m, kk[i]);
;       m = umax(m, (unsigned)__shfl_xor((int)m, 16));
;       m = umax(m, (unsigned)__shfl_xor((int)m, 32));
;       win[pp][rr] = m;
; #pragma unroll
;       for (int i = 0; i < 32; ++i) kk[i] = (kk[i] == m) ? 0u : kk[i];
;     }
	v_max_u32_e32 v8, v8, v188
	ds_bpermute_b32 v188, v112, v8
	s_waitcnt lgkmcnt(0)
	v_max_u32_e32 v8, v8, v188
	v_cmp_ne_u32_e32 vcc, v184, v8
	v_cmp_ne_u32_e64 s[98:99], v185, v8
	v_cmp_ne_u32_e64 s[100:101], v186, v8
	v_cndmask_b32_e32 v184, 0, v184, vcc
	v_cndmask_b32_e64 v185, 0, v185, s[98:99]
	v_cndmask_b32_e64 v186, 0, v186, s[100:101]
	v_cmp_ne_u32_e32 vcc, v187, v8
	v_cmp_ne_u32_e64 s[98:99], v9, v8
	v_cmp_ne_u32_e64 s[100:101], v10, v8
	v_cndmask_b32_e32 v187, 0, v187, vcc
	v_cndmask_b32_e64 v188, 0, v9, s[98:99]
	v_max_u32_e32 v9, v184, v185
	v_max3_u32 v9, v9, v186, v187
	v_cndmask_b32_e64 v10, 0, v10, s[100:101]
	v_cmp_ne_u32_e32 vcc, v11, v8
	v_max3_u32 v9, v9, v188, v10
	v_cmp_ne_u32_e64 s[98:99], v12, v8
	v_cndmask_b32_e32 v11, 0, v11, vcc
	v_cmp_ne_u32_e64 s[100:101], v13, v8
	v_cndmask_b32_e64 v12, 0, v12, s[98:99]
	v_max3_u32 v9, v9, v11, v12
	v_cndmask_b32_e64 v13, 0, v13, s[100:101]
	v_cmp_ne_u32_e32 vcc, v14, v8
	v_cmp_ne_u32_e64 s[98:99], v15, v8
	v_cmp_ne_u32_e64 s[100:101], v86, v8
	v_cndmask_b32_e32 v14, 0, v14, vcc
	v_max3_u32 v9, v9, v13, v14
	v_cndmask_b32_e64 v15, 0, v15, s[98:99]
	v_cndmask_b32_e64 v86, 0, v86, s[100:101]
	v_cmp_ne_u32_e32 vcc, v87, v8
	v_max3_u32 v9, v9, v15, v86
	v_cmp_ne_u32_e64 s[98:99], v88, v8
	v_cndmask_b32_e32 v87, 0, v87, vcc
	v_cmp_ne_u32_e64 s[100:101], v89, v8
	v_cndmask_b32_e64 v88, 0, v88, s[98:99]
	v_max3_u32 v9, v9, v87, v88
	v_cndmask_b32_e64 v89, 0, v89, s[100:101]
	v_cmp_ne_u32_e32 vcc, v164, v8
	v_cmp_ne_u32_e64 s[98:99], v165, v8
	v_cmp_ne_u32_e64 s[100:101], v166, v8
	v_cndmask_b32_e32 v164, 0, v164, vcc
	v_max3_u32 v9, v9, v89, v164
	v_cndmask_b32_e64 v165, 0, v165, s[98:99]
	v_cndmask_b32_e64 v166, 0, v166, s[100:101]
	v_cmp_ne_u32_e32 vcc, v167, v8
	v_max3_u32 v9, v9, v165, v166
	v_cmp_ne_u32_e64 s[98:99], v168, v8
	v_cndmask_b32_e32 v167, 0, v167, vcc
	v_cmp_ne_u32_e64 s[100:101], v169, v8
	v_cndmask_b32_e64 v168, 0, v168, s[98:99]
	v_max3_u32 v9, v9, v167, v168
	v_cndmask_b32_e64 v169, 0, v169, s[100:101]
	v_cmp_ne_u32_e32 vcc, v171, v8
	v_cmp_ne_u32_e64 s[98:99], v172, v8
	v_cmp_ne_u32_e64 s[100:101], v173, v8
	v_cndmask_b32_e32 v171, 0, v171, vcc
	v_max3_u32 v9, v9, v169, v171
	v_cndmask_b32_e64 v172, 0, v172, s[98:99]
	v_cndmask_b32_e64 v173, 0, v173, s[100:101]
	v_cmp_ne_u32_e32 vcc, v176, v8
	v_max3_u32 v9, v9, v172, v173
	v_cmp_ne_u32_e64 s[98:99], v177, v8
	v_cndmask_b32_e32 v176, 0, v176, vcc
	v_cmp_ne_u32_e64 s[100:101], v178, v8
	v_cndmask_b32_e64 v177, 0, v177, s[98:99]
	v_max3_u32 v9, v9, v176, v177
	v_cndmask_b32_e64 v178, 0, v178, s[100:101]
	v_cmp_ne_u32_e32 vcc, v179, v8
	v_cmp_ne_u32_e64 s[98:99], v183, v8
	v_cmp_ne_u32_e64 s[100:101], v180, v8
	v_cndmask_b32_e32 v179, 0, v179, vcc
	v_max3_u32 v9, v9, v178, v179
	v_cndmask_b32_e64 v183, 0, v183, s[98:99]
	v_cndmask_b32_e64 v180, 0, v180, s[100:101]
	v_cmp_ne_u32_e32 vcc, v181, v8
	v_max3_u32 v9, v9, v183, v180
	v_cmp_ne_u32_e64 s[98:99], v182, v8
	v_cndmask_b32_e32 v181, 0, v181, vcc
	s_nop 0
	v_cndmask_b32_e64 v182, 0, v182, s[98:99]
	v_max3_u32 v9, v9, v181, v182
	ds_bpermute_b32 v189, v111, v9
	s_waitcnt lgkmcnt(0)
	v_max_u32_e32 v9, v9, v189
	ds_bpermute_b32 v189, v112, v9
	s_waitcnt lgkmcnt(0)
	v_max_u32_e32 v9, v9, v189
	v_cmp_ne_u32_e32 vcc, v184, v9
	v_cmp_ne_u32_e64 s[98:99], v185, v9
	v_cmp_ne_u32_e64 s[100:101], v186, v9
	v_cndmask_b32_e32 v184, 0, v184, vcc
	v_cndmask_b32_e64 v185, 0, v185, s[98:99]
	v_cndmask_b32_e64 v186, 0, v186, s[100:101]
	v_cmp_ne_u32_e32 vcc, v187, v9
	v_cmp_ne_u32_e64 s[98:99], v188, v9
	v_cmp_ne_u32_e64 s[100:101], v10, v9
	v_cndmask_b32_e32 v187, 0, v187, vcc
	v_cndmask_b32_e64 v188, 0, v188, s[98:99]
	v_cndmask_b32_e64 v189, 0, v10, s[100:101]
	v_cmp_ne_u32_e32 vcc, v11, v9
	v_max_u32_e32 v10, v184, v185
	v_max3_u32 v10, v10, v186, v187
	v_cndmask_b32_e32 v11, 0, v11, vcc
	v_cmp_ne_u32_e64 s[98:99], v12, v9
	v_max3_u32 v10, v10, v188, v189
	v_cmp_ne_u32_e64 s[100:101], v13, v9
	v_cndmask_b32_e64 v12, 0, v12, s[98:99]
	v_max3_u32 v10, v10, v11, v12
	v_cndmask_b32_e64 v13, 0, v13, s[100:101]
	v_cmp_ne_u32_e32 vcc, v14, v9
	v_cmp_ne_u32_e64 s[98:99], v15, v9
	v_cmp_ne_u32_e64 s[100:101], v86, v9
	v_cndmask_b32_e32 v14, 0, v14, vcc
	v_max3_u32 v10, v10, v13, v14
	v_cndmask_b32_e64 v15, 0, v15, s[98:99]
	v_cndmask_b32_e64 v86, 0, v86, s[100:101]
	v_cmp_ne_u32_e32 vcc, v87, v9
	v_max3_u32 v10, v10, v15, v86
	v_cmp_ne_u32_e64 s[98:99], v88, v9
	v_cndmask_b32_e32 v87, 0, v87, vcc
	v_cmp_ne_u32_e64 s[100:101], v89, v9
	v_cndmask_b32_e64 v88, 0, v88, s[98:99]
	v_max3_u32 v10, v10, v87, v88
	v_cndmask_b32_e64 v89, 0, v89, s[100:101]
	v_cmp_ne_u32_e32 vcc, v164, v9
	v_cmp_ne_u32_e64 s[98:99], v165, v9
	v_cmp_ne_u32_e64 s[100:101], v166, v9
	v_cndmask_b32_e32 v164, 0, v164, vcc
	v_max3_u32 v10, v10, v89, v164
	v_cndmask_b32_e64 v165, 0, v165, s[98:99]
	v_cndmask_b32_e64 v166, 0, v166, s[100:101]
	v_cmp_ne_u32_e32 vcc, v167, v9
	v_max3_u32 v10, v10, v165, v166
	v_cmp_ne_u32_e64 s[98:99], v168, v9
	v_cndmask_b32_e32 v167, 0, v167, vcc
	v_cmp_ne_u32_e64 s[100:101], v169, v9
	v_cndmask_b32_e64 v168, 0, v168, s[98:99]
	v_max3_u32 v10, v10, v167, v168
	v_cndmask_b32_e64 v169, 0, v169, s[100:101]
	v_cmp_ne_u32_e32 vcc, v171, v9
	v_cmp_ne_u32_e64 s[98:99], v172, v9
	v_cmp_ne_u32_e64 s[100:101], v173, v9
	v_cndmask_b32_e32 v171, 0, v171, vcc
	v_max3_u32 v10, v10, v169, v171
	v_cndmask_b32_e64 v172, 0, v172, s[98:99]
	v_cndmask_b32_e64 v173, 0, v173, s[100:101]
	v_cmp_ne_u32_e32 vcc, v176, v9
	v_max3_u32 v10, v10, v172, v173
	v_cmp_ne_u32_e64 s[98:99], v177, v9
	v_cndmask_b32_e32 v176, 0, v176, vcc
	v_cmp_ne_u32_e64 s[100:101], v178, v9
	v_cndmask_b32_e64 v177, 0, v177, s[98:99]
	v_max3_u32 v10, v10, v176, v177
	v_cndmask_b32_e64 v178, 0, v178, s[100:101]
	v_cmp_ne_u32_e32 vcc, v179, v9
	v_cmp_ne_u32_e64 s[98:99], v183, v9
	v_cmp_ne_u32_e64 s[100:101], v180, v9
	v_cndmask_b32_e32 v179, 0, v179, vcc
	v_max3_u32 v10, v10, v178, v179
	v_cndmask_b32_e64 v183, 0, v183, s[98:99]
	v_cndmask_b32_e64 v180, 0, v180, s[100:101]
	v_cmp_ne_u32_e32 vcc, v181, v9
	v_max3_u32 v10, v10, v183, v180
	v_cmp_ne_u32_e64 s[98:99], v182, v9
	v_cndmask_b32_e32 v181, 0, v181, vcc
	s_nop 0
	v_cndmask_b32_e64 v182, 0, v182, s[98:99]
	v_max3_u32 v10, v10, v181, v182
	ds_bpermute_b32 v190, v111, v10
	s_waitcnt lgkmcnt(0)
; DI void peer_topk_wave(const Params& p, int item, unsigned* lds  ) {
;     ...
; #pragma unroll
;     for (int rr = 0; rr < 16; ++rr) {
;       unsigned m = 0;
; #pragma unroll
;       for (int i = 0; i < 32; ++i) m = umax(m, kk[i]);
;       m = umax(m, (unsigned)__shfl_xor((int)m, 16));
;       m = umax(m, (unsigned)__shfl_xor((int)m, 32));
;       win[pp][rr] = m;
; #pragma unroll
;       for (int i = 0; i < 32; ++i) kk[i] = (kk[i] == m) ? 0u : kk[i];
;     }
	v_max_u32_e32 v10, v10, v190
	ds_bpermute_b32 v190, v112, v10
	s_waitcnt lgkmcnt(0)
	v_max_u32_e32 v10, v10, v190
	v_cmp_ne_u32_e32 vcc, v184, v10
	v_cmp_ne_u32_e64 s[98:99], v185, v10
	v_cmp_ne_u32_e64 s[100:101], v186, v10
	v_cndmask_b32_e32 v184, 0, v184, vcc
	v_cndmask_b32_e64 v185, 0, v185, s[98:99]
	v_cndmask_b32_e64 v186, 0, v186, s[100:101]
	v_cmp_ne_u32_e32 vcc, v187, v10
	v_cmp_ne_u32_e64 s[98:99], v188, v10
	v_cmp_ne_u32_e64 s[100:101], v189, v10
	v_cndmask_b32_e32 v187, 0, v187, vcc
	v_cndmask_b32_e64 v188, 0, v188, s[98:99]
	v_cndmask_b32_e64 v189, 0, v189, s[100:101]
	v_cmp_ne_u32_e32 vcc, v11, v10
	v_cmp_ne_u32_e64 s[98:99], v12, v10
	v_cmp_ne_u32_e64 s[100:101], v13, v10
	v_cndmask_b32_e32 v190, 0, v11, vcc
	v_max_u32_e32 v11, v184, v185
	v_max3_u32 v11, v11, v186, v187
	v_cndmask_b32_e64 v12, 0, v12, s[98:99]
	v_max3_u32 v11, v11, v188, v189
	v_max3_u32 v11, v11, v190, v12
	v_cndmask_b32_e64 v13, 0, v13, s[100:101]
	v_cmp_ne_u32_e32 vcc, v14, v10
	v_cmp_ne_u32_e64 s[98:99], v15, v10
	v_cmp_ne_u32_e64 s[100:101], v86, v10
	v_cndmask_b32_e32 v14, 0, v14, vcc
	v_max3_u32 v11, v11, v13, v14
	v_cndmask_b32_e64 v15, 0, v15, s[98:99]
	v_cndmask_b32_e64 v86, 0, v86, s[100:101]
	v_cmp_ne_u32_e32 vcc, v87, v10
	v_max3_u32 v11, v11, v15, v86
	v_cmp_ne_u32_e64 s[98:99], v88, v10
	v_cndmask_b32_e32 v87, 0, v87, vcc
	v_cmp_ne_u32_e64 s[100:101], v89, v10
	v_cndmask_b32_e64 v88, 0, v88, s[98:99]
	v_max3_u32 v11, v11, v87, v88
	v_cndmask_b32_e64 v89, 0, v89, s[100:101]
	v_cmp_ne_u32_e32 vcc, v164, v10
	v_cmp_ne_u32_e64 s[98:99], v165, v10
	v_cmp_ne_u32_e64 s[100:101], v166, v10
	v_cndmask_b32_e32 v164, 0, v164, vcc
	v_max3_u32 v11, v11, v89, v164
	v_cndmask_b32_e64 v165, 0, v165, s[98:99]
	v_cndmask_b32_e64 v166, 0, v166, s[100:101]
	v_cmp_ne_u32_e32 vcc, v167, v10
	v_max3_u32 v11, v11, v165, v166
	v_cmp_ne_u32_e64 s[98:99], v168, v10
	v_cndmask_b32_e32 v167, 0, v167, vcc
	v_cmp_ne_u32_e64 s[100:101], v169, v10
	v_cndmask_b32_e64 v168, 0, v168, s[98:99]
	v_max3_u32 v11, v11, v167, v168
	v_cndmask_b32_e64 v169, 0, v169, s[100:101]
	v_cmp_ne_u32_e32 vcc, v171, v10
	v_cmp_ne_u32_e64 s[98:99], v172, v10
	v_cmp_ne_u32_e64 s[100:101], v173, v10
	v_cndmask_b32_e32 v171, 0, v171, vcc
	v_max3_u32 v11, v11, v169, v171
	v_cndmask_b32_e64 v172, 0, v172, s[98:99]
	v_cndmask_b32_e64 v173, 0, v173, s[100:101]
	v_cmp_ne_u32_e32 vcc, v176, v10
	v_max3_u32 v11, v11, v172, v173
	v_cmp_ne_u32_e64 s[98:99], v177, v10
	v_cndmask_b32_e32 v176, 0, v176, vcc
	v_cmp_ne_u32_e64 s[100:101], v178, v10
	v_cndmask_b32_e64 v177, 0, v177, s[98:99]
	v_max3_u32 v11, v11, v176, v177
	v_cndmask_b32_e64 v178, 0, v178, s[100:101]
	v_cmp_ne_u32_e32 vcc, v179, v10
	v_cmp_ne_u32_e64 s[98:99], v183, v10
	v_cmp_ne_u32_e64 s[100:101], v180, v10
	v_cndmask_b32_e32 v179, 0, v179, vcc
	v_max3_u32 v11, v11, v178, v179
	v_cndmask_b32_e64 v183, 0, v183, s[98:99]
	v_cndmask_b32_e64 v180, 0, v180, s[100:101]
	v_cmp_ne_u32_e32 vcc, v181, v10
	v_max3_u32 v11, v11, v183, v180
	v_cmp_ne_u32_e64 s[98:99], v182, v10
	v_cndmask_b32_e32 v181, 0, v181, vcc
	s_nop 0
	v_cndmask_b32_e64 v182, 0, v182, s[98:99]
	v_max3_u32 v11, v11, v181, v182
	ds_bpermute_b32 v191, v111, v11
	s_waitcnt lgkmcnt(0)
	v_max_u32_e32 v11, v11, v191
	ds_bpermute_b32 v191, v112, v11
	s_waitcnt lgkmcnt(0)
	v_max_u32_e32 v11, v11, v191
	v_cmp_ne_u32_e32 vcc, v184, v11
	v_cmp_ne_u32_e64 s[98:99], v185, v11
	v_cmp_ne_u32_e64 s[100:101], v186, v11
	v_cndmask_b32_e32 v184, 0, v184, vcc
	v_cndmask_b32_e64 v185, 0, v185, s[98:99]
	v_cndmask_b32_e64 v186, 0, v186, s[100:101]
	v_cmp_ne_u32_e32 vcc, v187, v11
	v_cmp_ne_u32_e64 s[98:99], v188, v11
	v_cmp_ne_u32_e64 s[100:101], v189, v11
	v_cndmask_b32_e32 v187, 0, v187, vcc
	v_cndmask_b32_e64 v188, 0, v188, s[98:99]
	v_cndmask_b32_e64 v189, 0, v189, s[100:101]
	v_cmp_ne_u32_e32 vcc, v190, v11
	v_cmp_ne_u32_e64 s[98:99], v12, v11
	v_cmp_ne_u32_e64 s[100:101], v13, v11
	v_cndmask_b32_e32 v190, 0, v190, vcc
	v_cndmask_b32_e64 v191, 0, v12, s[98:99]
	v_max_u32_e32 v12, v184, v185
	v_max3_u32 v12, v12, v186, v187
	v_cndmask_b32_e64 v13, 0, v13, s[100:101]
	v_cmp_ne_u32_e32 vcc, v14, v11
	v_max3_u32 v12, v12, v188, v189
	v_max3_u32 v12, v12, v190, v191
	v_cndmask_b32_e32 v14, 0, v14, vcc
	v_cmp_ne_u32_e64 s[98:99], v15, v11
	v_max3_u32 v12, v12, v13, v14
	v_cmp_ne_u32_e64 s[100:101], v86, v11
	v_cndmask_b32_e64 v15, 0, v15, s[98:99]
	v_cmp_ne_u32_e32 vcc, v87, v11
	v_cndmask_b32_e64 v86, 0, v86, s[100:101]
	v_max3_u32 v12, v12, v15, v86
	v_cndmask_b32_e32 v87, 0, v87, vcc
	v_cmp_ne_u32_e64 s[98:99], v88, v11
	v_cmp_ne_u32_e64 s[100:101], v89, v11
	v_cmp_ne_u32_e32 vcc, v164, v11
	v_cndmask_b32_e64 v88, 0, v88, s[98:99]
	v_max3_u32 v12, v12, v87, v88
	v_cndmask_b32_e64 v89, 0, v89, s[100:101]
	v_cndmask_b32_e32 v164, 0, v164, vcc
	v_cmp_ne_u32_e64 s[98:99], v165, v11
	v_max3_u32 v12, v12, v89, v164
	v_cmp_ne_u32_e64 s[100:101], v166, v11
	v_cndmask_b32_e64 v165, 0, v165, s[98:99]
	v_cmp_ne_u32_e32 vcc, v167, v11
	v_cndmask_b32_e64 v166, 0, v166, s[100:101]
	v_max3_u32 v12, v12, v165, v166
	v_cndmask_b32_e32 v167, 0, v167, vcc
	v_cmp_ne_u32_e64 s[98:99], v168, v11
	v_cmp_ne_u32_e64 s[100:101], v169, v11
	v_cmp_ne_u32_e32 vcc, v171, v11
	v_cndmask_b32_e64 v168, 0, v168, s[98:99]
	v_max3_u32 v12, v12, v167, v168
	v_cndmask_b32_e64 v169, 0, v169, s[100:101]
	v_cndmask_b32_e32 v171, 0, v171, vcc
	v_cmp_ne_u32_e64 s[98:99], v172, v11
	v_max3_u32 v12, v12, v169, v171
	v_cmp_ne_u32_e64 s[100:101], v173, v11
	v_cndmask_b32_e64 v172, 0, v172, s[98:99]
	v_cmp_ne_u32_e32 vcc, v176, v11
	v_cndmask_b32_e64 v173, 0, v173, s[100:101]
	v_max3_u32 v12, v12, v172, v173
	v_cndmask_b32_e32 v176, 0, v176, vcc
	v_cmp_ne_u32_e64 s[98:99], v177, v11
	v_cmp_ne_u32_e64 s[100:101], v178, v11
	v_cmp_ne_u32_e32 vcc, v179, v11
	v_cndmask_b32_e64 v177, 0, v177, s[98:99]
	v_max3_u32 v12, v12, v176, v177
	v_cndmask_b32_e64 v178, 0, v178, s[100:101]
	v_cndmask_b32_e32 v179, 0, v179, vcc
	v_cmp_ne_u32_e64 s[98:99], v183, v11
	v_max3_u32 v12, v12, v178, v179
	v_cmp_ne_u32_e64 s[100:101], v180, v11
	v_cndmask_b32_e64 v183, 0, v183, s[98:99]
	v_cmp_ne_u32_e32 vcc, v181, v11
	v_cndmask_b32_e64 v180, 0, v180, s[100:101]
	v_max3_u32 v12, v12, v183, v180
	v_cndmask_b32_e32 v181, 0, v181, vcc
	v_cmp_ne_u32_e64 s[98:99], v182, v11
	s_nop 0
	s_nop 0
	v_cndmask_b32_e64 v182, 0, v182, s[98:99]
	v_max3_u32 v12, v12, v181, v182
	ds_bpermute_b32 v192, v111, v12
	s_waitcnt lgkmcnt(0)
; DI void peer_topk_wave(const Params& p, int item, unsigned* lds  ) {
;     ...
; #pragma unroll
;     for (int rr = 0; rr < 16; ++rr) {
;       unsigned m = 0;
; #pragma unroll
;       for (int i = 0; i < 32; ++i) m = umax(m, kk[i]);
;       m = umax(m, (unsigned)__shfl_xor((int)m, 16));
;       m = umax(m, (unsigned)__shfl_xor((int)m, 32));
;       win[pp][rr] = m;
; #pragma unroll
;       for (int i = 0; i < 32; ++i) kk[i] = (kk[i] == m) ? 0u : kk[i];
;     }
	v_max_u32_e32 v12, v12, v192
	ds_bpermute_b32 v192, v112, v12
	s_waitcnt lgkmcnt(0)
	v_max_u32_e32 v12, v12, v192
	v_cmp_ne_u32_e32 vcc, v184, v12
	v_cmp_ne_u32_e64 s[98:99], v185, v12
	v_cmp_ne_u32_e64 s[100:101], v186, v12
	v_cndmask_b32_e32 v184, 0, v184, vcc
	v_cndmask_b32_e64 v185, 0, v185, s[98:99]
	v_cndmask_b32_e64 v186, 0, v186, s[100:101]
	v_cmp_ne_u32_e32 vcc, v187, v12
	v_cmp_ne_u32_e64 s[98:99], v188, v12
	v_cmp_ne_u32_e64 s[100:101], v189, v12
	v_cndmask_b32_e32 v187, 0, v187, vcc
	v_cndmask_b32_e64 v188, 0, v188, s[98:99]
	v_cndmask_b32_e64 v189, 0, v189, s[100:101]
	v_cmp_ne_u32_e32 vcc, v190, v12
	v_cmp_ne_u32_e64 s[98:99], v191, v12
	v_cmp_ne_u32_e64 s[100:101], v13, v12
	v_cndmask_b32_e32 v190, 0, v190, vcc
	v_cndmask_b32_e64 v191, 0, v191, s[98:99]
	v_cndmask_b32_e64 v192, 0, v13, s[100:101]
	v_cmp_ne_u32_e32 vcc, v14, v12
	v_max_u32_e32 v13, v184, v185
	v_max3_u32 v13, v13, v186, v187
	v_cndmask_b32_e32 v14, 0, v14, vcc
	v_cmp_ne_u32_e64 s[98:99], v15, v12
	v_max3_u32 v13, v13, v188, v189
	v_max3_u32 v13, v13, v190, v191
	v_cndmask_b32_e64 v15, 0, v15, s[98:99]
	v_cmp_ne_u32_e64 s[100:101], v86, v12
	v_max3_u32 v13, v13, v192, v14
	v_cmp_ne_u32_e32 vcc, v87, v12
	v_cndmask_b32_e64 v86, 0, v86, s[100:101]
	v_max3_u32 v13, v13, v15, v86
	v_cndmask_b32_e32 v87, 0, v87, vcc
	v_cmp_ne_u32_e64 s[98:99], v88, v12
	v_cmp_ne_u32_e64 s[100:101], v89, v12
	v_cmp_ne_u32_e32 vcc, v164, v12
	v_cndmask_b32_e64 v88, 0, v88, s[98:99]
	v_max3_u32 v13, v13, v87, v88
	v_cndmask_b32_e64 v89, 0, v89, s[100:101]
	v_cndmask_b32_e32 v164, 0, v164, vcc
	v_cmp_ne_u32_e64 s[98:99], v165, v12
	v_max3_u32 v13, v13, v89, v164
	v_cmp_ne_u32_e64 s[100:101], v166, v12
	v_cndmask_b32_e64 v165, 0, v165, s[98:99]
	v_cmp_ne_u32_e32 vcc, v167, v12
	v_cndmask_b32_e64 v166, 0, v166, s[100:101]
	v_max3_u32 v13, v13, v165, v166
	v_cndmask_b32_e32 v167, 0, v167, vcc
	v_cmp_ne_u32_e64 s[98:99], v168, v12
	v_cmp_ne_u32_e64 s[100:101], v169, v12
	v_cmp_ne_u32_e32 vcc, v171, v12
	v_cndmask_b32_e64 v168, 0, v168, s[98:99]
	v_max3_u32 v13, v13, v167, v168
	v_cndmask_b32_e64 v169, 0, v169, s[100:101]
	v_cndmask_b32_e32 v171, 0, v171, vcc
	v_cmp_ne_u32_e64 s[98:99], v172, v12
	v_max3_u32 v13, v13, v169, v171
	v_cmp_ne_u32_e64 s[100:101], v173, v12
	v_cndmask_b32_e64 v172, 0, v172, s[98:99]
	v_cmp_ne_u32_e32 vcc, v176, v12
	v_cndmask_b32_e64 v173, 0, v173, s[100:101]
	v_max3_u32 v13, v13, v172, v173
	v_cndmask_b32_e32 v176, 0, v176, vcc
	v_cmp_ne_u32_e64 s[98:99], v177, v12
	v_cmp_ne_u32_e64 s[100:101], v178, v12
	v_cmp_ne_u32_e32 vcc, v179, v12
	v_cndmask_b32_e64 v177, 0, v177, s[98:99]
	v_max3_u32 v13, v13, v176, v177
	v_cndmask_b32_e64 v178, 0, v178, s[100:101]
	v_cndmask_b32_e32 v179, 0, v179, vcc
	v_cmp_ne_u32_e64 s[98:99], v183, v12
	v_max3_u32 v13, v13, v178, v179
	v_cmp_ne_u32_e64 s[100:101], v180, v12
	v_cndmask_b32_e64 v183, 0, v183, s[98:99]
	v_cmp_ne_u32_e32 vcc, v181, v12
	v_cndmask_b32_e64 v180, 0, v180, s[100:101]
	v_max3_u32 v13, v13, v183, v180
	v_cndmask_b32_e32 v181, 0, v181, vcc
	v_cmp_ne_u32_e64 s[98:99], v182, v12
	s_nop 0
	s_nop 0
	v_cndmask_b32_e64 v182, 0, v182, s[98:99]
	v_max3_u32 v13, v13, v181, v182
	ds_bpermute_b32 v193, v111, v13
	s_waitcnt lgkmcnt(0)
	v_max_u32_e32 v13, v13, v193
	ds_bpermute_b32 v193, v112, v13
	s_waitcnt lgkmcnt(0)
	v_max_u32_e32 v13, v13, v193
	v_cmp_ne_u32_e32 vcc, v184, v13
	v_cmp_ne_u32_e64 s[98:99], v185, v13
	v_cmp_ne_u32_e64 s[100:101], v186, v13
	v_cndmask_b32_e32 v184, 0, v184, vcc
	v_cndmask_b32_e64 v185, 0, v185, s[98:99]
	v_cndmask_b32_e64 v186, 0, v186, s[100:101]
	v_cmp_ne_u32_e32 vcc, v187, v13
	v_cmp_ne_u32_e64 s[98:99], v188, v13
	v_cmp_ne_u32_e64 s[100:101], v189, v13
	v_cndmask_b32_e32 v187, 0, v187, vcc
	v_cndmask_b32_e64 v188, 0, v188, s[98:99]
	v_cndmask_b32_e64 v189, 0, v189, s[100:101]
	v_cmp_ne_u32_e32 vcc, v190, v13
	v_cmp_ne_u32_e64 s[98:99], v191, v13
	v_cmp_ne_u32_e64 s[100:101], v192, v13
	v_cndmask_b32_e32 v190, 0, v190, vcc
	v_cndmask_b32_e64 v191, 0, v191, s[98:99]
	v_cndmask_b32_e64 v192, 0, v192, s[100:101]
	v_cmp_ne_u32_e32 vcc, v14, v13
	v_cmp_ne_u32_e64 s[98:99], v15, v13
	v_cmp_ne_u32_e64 s[100:101], v86, v13
	v_cndmask_b32_e32 v193, 0, v14, vcc
	v_max_u32_e32 v14, v184, v185
	v_max3_u32 v14, v14, v186, v187
	v_cndmask_b32_e64 v15, 0, v15, s[98:99]
	v_max3_u32 v14, v14, v188, v189
	v_max3_u32 v14, v14, v190, v191
	v_cndmask_b32_e64 v86, 0, v86, s[100:101]
	v_cmp_ne_u32_e32 vcc, v87, v13
	v_max3_u32 v14, v14, v192, v193
	v_max3_u32 v14, v14, v15, v86
	v_cndmask_b32_e32 v87, 0, v87, vcc
	v_cmp_ne_u32_e64 s[98:99], v88, v13
	v_cmp_ne_u32_e64 s[100:101], v89, v13
	v_cmp_ne_u32_e32 vcc, v164, v13
	v_cndmask_b32_e64 v88, 0, v88, s[98:99]
	v_max3_u32 v14, v14, v87, v88
	v_cndmask_b32_e64 v89, 0, v89, s[100:101]
	v_cndmask_b32_e32 v164, 0, v164, vcc
	v_cmp_ne_u32_e64 s[98:99], v165, v13
	v_max3_u32 v14, v14, v89, v164
	v_cmp_ne_u32_e64 s[100:101], v166, v13
	v_cndmask_b32_e64 v165, 0, v165, s[98:99]
	v_cmp_ne_u32_e32 vcc, v167, v13
	v_cndmask_b32_e64 v166, 0, v166, s[100:101]
	v_max3_u32 v14, v14, v165, v166
	v_cndmask_b32_e32 v167, 0, v167, vcc
	v_cmp_ne_u32_e64 s[98:99], v168, v13
	v_cmp_ne_u32_e64 s[100:101], v169, v13
	v_cmp_ne_u32_e32 vcc, v171, v13
	v_cndmask_b32_e64 v168, 0, v168, s[98:99]
	v_max3_u32 v14, v14, v167, v168
	v_cndmask_b32_e64 v169, 0, v169, s[100:101]
	v_cndmask_b32_e32 v171, 0, v171, vcc
	v_cmp_ne_u32_e64 s[98:99], v172, v13
	v_max3_u32 v14, v14, v169, v171
	v_cmp_ne_u32_e64 s[100:101], v173, v13
	v_cndmask_b32_e64 v172, 0, v172, s[98:99]
	v_cmp_ne_u32_e32 vcc, v176, v13
	v_cndmask_b32_e64 v173, 0, v173, s[100:101]
	v_max3_u32 v14, v14, v172, v173
	v_cndmask_b32_e32 v176, 0, v176, vcc
	v_cmp_ne_u32_e64 s[98:99], v177, v13
	v_cmp_ne_u32_e64 s[100:101], v178, v13
	v_cmp_ne_u32_e32 vcc, v179, v13
	v_cndmask_b32_e64 v177, 0, v177, s[98:99]
	v_max3_u32 v14, v14, v176, v177
	v_cndmask_b32_e64 v178, 0, v178, s[100:101]
	v_cndmask_b32_e32 v179, 0, v179, vcc
	v_cmp_ne_u32_e64 s[98:99], v183, v13
	v_max3_u32 v14, v14, v178, v179
	v_cmp_ne_u32_e64 s[100:101], v180, v13
	v_cndmask_b32_e64 v183, 0, v183, s[98:99]
	v_cmp_ne_u32_e32 vcc, v181, v13
	v_cndmask_b32_e64 v180, 0, v180, s[100:101]
	v_max3_u32 v14, v14, v183, v180
	v_cndmask_b32_e32 v181, 0, v181, vcc
	v_cmp_ne_u32_e64 s[98:99], v182, v13
	s_nop 0
	s_nop 0
	v_cndmask_b32_e64 v182, 0, v182, s[98:99]
	v_max3_u32 v14, v14, v181, v182
	ds_bpermute_b32 v194, v111, v14
	s_waitcnt lgkmcnt(0)
; DI float unordf(unsigned k) { unsigned u = (k & 0x80000000u) ? (k & 0x7fffffffu) : ~k; return __uint_as_float(u); }
; DI void peer_topk_wave(const Params& p, int item, unsigned* lds  ) {
;     ...
; #pragma unroll
;     for (int rr = 0; rr < 16; ++rr) {
;       unsigned m = 0;
; #pragma unroll
;       for (int i = 0; i < 32; ++i) m = umax(m, kk[i]);
;       m = umax(m, (unsigned)__shfl_xor((int)m, 16));
;       m = umax(m, (unsigned)__shfl_xor((int)m, 32));
;       win[pp][rr] = m;
; #pragma unroll
;       for (int i = 0; i < 32; ++i) kk[i] = (kk[i] == m) ? 0u : kk[i];
;     }
;   }
;   float f0[16], f1[16];
; #pragma unroll
;   for (int i = 0; i < 16; ++i) { f0[i] = unordf(win[0][i] & ~127u); f1[i] = unordf(win[1][i] & ~127u); }
;   unsigned cand[13];
	v_max_u32_e32 v14, v14, v194
	ds_bpermute_b32 v194, v112, v14
	s_waitcnt lgkmcnt(0)
	v_max_u32_e32 v14, v14, v194
	v_cmp_ne_u32_e32 vcc, v185, v14
	v_cmp_eq_u32_e64 s[68:69], v184, v14
	v_cmp_eq_u32_e64 s[70:71], v186, v14
	v_cndmask_b32_e32 v185, 0, v185, vcc
	v_max_u32_e32 v184, v184, v185
	v_cndmask_b32_e64 v184, v184, v185, s[68:69]
	v_max_u32_e32 v185, v184, v186
	v_cndmask_b32_e64 v184, v185, v184, s[70:71]
	v_cmp_eq_u32_e64 s[66:67], v187, v14
	v_max_u32_e32 v185, v184, v187
	v_cmp_eq_u32_e64 s[64:65], v188, v14
	v_cndmask_b32_e64 v184, v185, v184, s[66:67]
	v_max_u32_e32 v185, v184, v188
	v_cndmask_b32_e64 v184, v185, v184, s[64:65]
	v_cmp_eq_u32_e64 s[62:63], v189, v14
	v_max_u32_e32 v185, v184, v189
	v_cmp_eq_u32_e64 s[60:61], v190, v14
	v_cndmask_b32_e64 v184, v185, v184, s[62:63]
	v_max_u32_e32 v185, v184, v190
	v_cndmask_b32_e64 v184, v185, v184, s[60:61]
	v_cmp_eq_u32_e64 s[58:59], v191, v14
	v_max_u32_e32 v185, v184, v191
	v_cmp_eq_u32_e64 s[56:57], v192, v14
	v_cndmask_b32_e64 v184, v185, v184, s[58:59]
	v_max_u32_e32 v185, v184, v192
	v_cndmask_b32_e64 v184, v185, v184, s[56:57]
	v_cmp_eq_u32_e64 s[54:55], v193, v14
	v_max_u32_e32 v185, v184, v193
	v_cmp_eq_u32_e64 s[52:53], v15, v14
	v_cndmask_b32_e64 v184, v185, v184, s[54:55]
	v_max_u32_e32 v15, v184, v15
	v_cndmask_b32_e64 v15, v15, v184, s[52:53]
	v_cmp_eq_u32_e64 s[50:51], v86, v14
	v_max_u32_e32 v86, v15, v86
	v_cmp_eq_u32_e64 s[48:49], v87, v14
	v_cndmask_b32_e64 v15, v86, v15, s[50:51]
	v_max_u32_e32 v86, v15, v87
	v_cndmask_b32_e64 v15, v86, v15, s[48:49]
	v_cmp_eq_u32_e64 s[46:47], v88, v14
	v_max_u32_e32 v86, v15, v88
	v_cmp_eq_u32_e64 s[44:45], v89, v14
	v_cndmask_b32_e64 v15, v86, v15, s[46:47]
	v_max_u32_e32 v86, v15, v89
	v_cndmask_b32_e64 v15, v86, v15, s[44:45]
	v_cmp_eq_u32_e64 s[42:43], v164, v14
	v_max_u32_e32 v86, v15, v164
	v_cmp_eq_u32_e64 s[40:41], v165, v14
	v_cndmask_b32_e64 v15, v86, v15, s[42:43]
	v_max_u32_e32 v86, v15, v165
	v_cndmask_b32_e64 v15, v86, v15, s[40:41]
	v_cmp_eq_u32_e64 s[38:39], v166, v14
	v_max_u32_e32 v86, v15, v166
	v_cmp_eq_u32_e64 s[36:37], v167, v14
	v_cndmask_b32_e64 v15, v86, v15, s[38:39]
	v_max_u32_e32 v86, v15, v167
	v_cndmask_b32_e64 v15, v86, v15, s[36:37]
	v_cmp_eq_u32_e64 s[34:35], v168, v14
	v_max_u32_e32 v86, v15, v168
	v_cmp_eq_u32_e64 s[30:31], v169, v14
	v_cndmask_b32_e64 v15, v86, v15, s[34:35]
	v_max_u32_e32 v86, v15, v169
	v_cndmask_b32_e64 v15, v86, v15, s[30:31]
	v_cmp_eq_u32_e64 s[28:29], v171, v14
	v_max_u32_e32 v86, v15, v171
	v_cmp_eq_u32_e64 s[26:27], v172, v14
	v_cndmask_b32_e64 v15, v86, v15, s[28:29]
	v_max_u32_e32 v86, v15, v172
	v_cndmask_b32_e64 v15, v86, v15, s[26:27]
	v_cmp_eq_u32_e64 s[24:25], v173, v14
	v_max_u32_e32 v86, v15, v173
	v_cmp_eq_u32_e64 s[22:23], v176, v14
	v_cndmask_b32_e64 v15, v86, v15, s[24:25]
	v_max_u32_e32 v86, v15, v176
	v_cndmask_b32_e64 v15, v86, v15, s[22:23]
	v_cmp_eq_u32_e64 s[20:21], v177, v14
	v_max_u32_e32 v86, v15, v177
	v_cmp_eq_u32_e64 s[18:19], v178, v14
	v_cndmask_b32_e64 v15, v86, v15, s[20:21]
	v_max_u32_e32 v86, v15, v178
	v_cndmask_b32_e64 v15, v86, v15, s[18:19]
	v_cmp_eq_u32_e64 s[16:17], v179, v14
	v_max_u32_e32 v86, v15, v179
	v_cmp_eq_u32_e64 s[14:15], v183, v14
	v_cndmask_b32_e64 v15, v86, v15, s[16:17]
	v_max_u32_e32 v86, v15, v183
	v_cndmask_b32_e64 v15, v86, v15, s[14:15]
	v_cmp_eq_u32_e64 s[2:3], v180, v14
	v_max_u32_e32 v86, v15, v180
	v_cmp_eq_u32_e64 s[0:1], v181, v14
	v_cndmask_b32_e64 v15, v86, v15, s[2:3]
	v_max_u32_e32 v86, v15, v181
	v_cndmask_b32_e64 v15, v86, v15, s[0:1]
	v_cmp_eq_u32_e32 vcc, v182, v14
	v_max_u32_e32 v86, v15, v182
	v_bitop3_b32 v87, v0, s81, v0 bitop3:0xcf
	v_cndmask_b32_e32 v15, v86, v15, vcc
	ds_bpermute_b32 v86, v111, v15
	v_cmp_gt_i32_e32 vcc, 0, v0
	s_waitcnt lgkmcnt(0)
	v_max_u32_e32 v15, v15, v86
	ds_bpermute_b32 v166, v112, v15
	v_and_b32_e32 v86, 0x7fffff80, v0
	v_cndmask_b32_e32 v89, v87, v86, vcc
	v_and_b32_e32 v86, 0x7fffff80, v1
	v_bitop3_b32 v87, v1, s81, v1 bitop3:0xcf
	v_cmp_gt_i32_e32 vcc, 0, v1
	s_nop 1
	v_cndmask_b32_e32 v164, v87, v86, vcc
	v_cmp_lt_i32_e32 vcc, 0, v175
	v_mov_b32_e32 v86, v89
	s_and_saveexec_b64 s[0:1], vcc
	s_cbranch_execz .LBB0_1097
	v_cmp_ne_u32_e32 vcc, 1, v175
	s_and_saveexec_b64 s[2:3], vcc
	s_xor_b64 s[2:3], exec, s[2:3]
	v_cndmask_b32_e64 v86, v164, v89, s[10:11]
	s_andn2_saveexec_b64 s[2:3], s[2:3]
	v_and_b32_e32 v86, 0x7fffff80, v13
	v_bitop3_b32 v87, v13, s81, v13 bitop3:0xcf
	v_cmp_gt_i32_e32 vcc, 0, v13
	s_nop 1
	v_cndmask_b32_e32 v86, v87, v86, vcc
	s_or_b64 exec, exec, s[2:3]

; DI void peer_topk_wave(const Params& p, int item, unsigned* lds  ) {
;     ...
;   unsigned cand[13];
;     ...
;   CAND(0, 0, 0, 0, 13, 2, 0, 6, 1)
;   CAND(1, 0, 1, 0, 14, 2, 1, 7, 0)
;   CAND(2, 0, 2, 0, 15, 2, 2, 7, 1)
;   CAND(3, 0, 3, 1, 0, 2, 3, 8, 0)
;   CAND(4, 0, 4, 1, 1, 2, 4, 9, 0)
;   CAND(5, 0, 5, 1, 2, 3, 0, 10, 0)
;   CAND(6, 0, 6, 1, 3, 3, 1, 11, 0)
;   CAND(7, 0, 7, 1, 4, 3, 2, 12, 0)
;   CAND(8, 0, 8, 1, 5, 3, 3, 13, 0)
;   CAND(9, 0, 9, 1, 6, 4, 2, 14, 0)
;   CAND(10, 0, 10, 1, 7, 5, 0, 15, 0)
;   CAND(11, 0, 11, 4, 0, 5, 1, -1, -1)
;   CAND(12, 0, 12, 4, 1, 6, 0, -1, -1)
;     ...
;   unsigned w2[16];
; #pragma unroll
;   for (int rr = 0; rr < 16; ++rr) {
;     unsigned m = 0;
; #pragma unroll
;     for (int i = 0; i < 13; ++i) m = umax(m, cand[i]);
;     m = umax(m, (unsigned)__shfl_xor((int)m, 16));
;     m = umax(m, (unsigned)__shfl_xor((int)m, 32));
;     w2[rr] = m;
; #pragma unroll
;     for (int i = 0; i < 13; ++i) cand[i] = (cand[i] == m) ? 0u : cand[i];
;   }
.LBB0_1279:
	s_or_b64 exec, exec, s[0:1]
	v_add_f32_e32 v164, v197, v198
	v_not_b32_e32 v197, v164
	v_or_b32_e32 v198, 0x80000000, v164
	v_cmp_gt_i32_e32 vcc, 0, v164
	v_add_f32_e32 v162, v162, v183
	v_not_b32_e32 v183, v162
	v_cndmask_b32_e32 v164, v198, v197, vcc
	v_or_b32_e32 v197, 0x80000000, v162
	v_cmp_gt_i32_e32 vcc, 0, v162
	v_add_f32_e32 v187, v187, v188
	v_not_b32_e32 v188, v187
	v_cndmask_b32_e32 v162, v197, v183, vcc
	v_add_f32_e32 v183, v193, v194
	v_not_b32_e32 v193, v183
	v_or_b32_e32 v194, 0x80000000, v183
	v_cmp_gt_i32_e32 vcc, 0, v183
	v_add_f32_e32 v184, v184, v185
	v_not_b32_e32 v185, v184
	v_cndmask_b32_e32 v183, v194, v193, vcc
	v_and_or_b32 v182, v183, s82, v182
	v_add_f32_e32 v183, v190, v192
	v_not_b32_e32 v190, v183
	v_or_b32_e32 v192, 0x80000000, v183
	v_cmp_gt_i32_e32 vcc, 0, v183
	v_add_f32_e32 v179, v179, v180
	v_not_b32_e32 v180, v179
	v_cndmask_b32_e32 v183, v192, v190, vcc
	v_or_b32_e32 v190, 0x80000000, v187
	v_cmp_gt_i32_e32 vcc, 0, v187
	v_add_f32_e32 v176, v176, v177
	v_not_b32_e32 v177, v176
	v_cndmask_b32_e32 v187, v190, v188, vcc
	v_or_b32_e32 v188, 0x80000000, v184
	v_cmp_gt_i32_e32 vcc, 0, v184
	v_add_f32_e32 v171, v171, v172
	v_not_b32_e32 v172, v171
	v_cndmask_b32_e32 v184, v188, v185, vcc
	v_or_b32_e32 v185, 0x80000000, v179
	v_cmp_gt_i32_e32 vcc, 0, v179
	v_and_or_b32 v184, v184, s82, v186
	v_and_or_b32 v183, v183, s82, v191
	v_cndmask_b32_e32 v179, v185, v180, vcc
	v_or_b32_e32 v180, 0x80000000, v176
	v_cmp_gt_i32_e32 vcc, 0, v176
	v_and_or_b32 v179, v179, s82, v181
	v_and_or_b32 v187, v187, s82, v189
	v_cndmask_b32_e32 v176, v180, v177, vcc
	v_or_b32_e32 v177, 0x80000000, v171
	v_cmp_gt_i32_e32 vcc, 0, v171
	v_and_or_b32 v176, v176, s82, v178
	v_and_or_b32 v164, v164, s82, v201
	v_cndmask_b32_e32 v171, v177, v172, vcc
	v_and_or_b32 v171, v171, s82, v173
	v_and_b32_e32 v172, 0x7fffff80, v153
	v_bitop3_b32 v173, v153, s81, v153 bitop3:0xcf
	v_cmp_gt_i32_e32 vcc, 0, v153
	v_and_or_b32 v162, v162, s82, v195
	v_cndmask_b32_e64 v164, v164, 0, s[12:13]
	v_cndmask_b32_e32 v172, v173, v172, vcc
	v_cndmask_b32_e64 v172, v172, v169, s[10:11]
	v_cndmask_b32_e64 v172, v172, v168, s[4:5]
	v_add_f32_e32 v166, v172, v166
	v_not_b32_e32 v173, v166
	v_or_b32_e32 v177, 0x80000000, v166
	v_cmp_gt_i32_e32 vcc, 0, v166
	v_add_f32_e32 v88, v172, v88
	v_or_b32_e32 v172, 0x80000000, v88
	v_cndmask_b32_e32 v166, v177, v173, vcc
	v_and_or_b32 v167, v166, s82, v167
	v_not_b32_e32 v166, v88
	v_cmp_gt_i32_e32 vcc, 0, v88
	s_nop 1
	v_cndmask_b32_e32 v88, v172, v166, vcc
	v_and_or_b32 v88, v88, s82, v165
	v_cndmask_b32_e64 v165, v200, v169, s[10:11]
	v_cndmask_b32_e64 v165, v165, v168, s[4:5]
	v_add_f32_e32 v86, v165, v86
	v_not_b32_e32 v165, v86
	v_or_b32_e32 v166, 0x80000000, v86
	v_cmp_gt_i32_e32 vcc, 0, v86
	s_nop 1
	v_cndmask_b32_e32 v86, v166, v165, vcc
	v_and_or_b32 v86, v86, s82, v87
	v_add_f32_e32 v87, v199, v196
	v_not_b32_e32 v165, v87
	v_or_b32_e32 v166, 0x80000000, v87
	v_cmp_gt_i32_e32 vcc, 0, v87
	s_nop 1
	v_cndmask_b32_e32 v87, v166, v165, vcc
	v_and_or_b32 v87, v87, s82, v89
	v_max3_u32 v89, v86, v88, v167
	v_max3_u32 v89, v89, v171, v176
	v_max3_u32 v89, v89, v179, v184
	v_max3_u32 v89, v89, v187, v183
	v_cndmask_b32_e64 v87, v87, 0, s[12:13]
	v_max3_u32 v89, v89, v182, v162
	v_max3_u32 v89, v89, v164, v87
	ds_bpermute_b32 v165, v111, v89
	s_waitcnt lgkmcnt(0)
	v_max_u32_e32 v89, v89, v165
	ds_bpermute_b32 v165, v112, v89
	s_waitcnt lgkmcnt(0)
	v_max_u32_e32 v166, v89, v165
	v_cmp_ne_u32_e32 vcc, v86, v166
	v_cmp_ne_u32_e64 s[98:99], v88, v166
	v_cmp_ne_u32_e64 s[100:101], v167, v166
	v_cndmask_b32_e32 v86, 0, v86, vcc
	v_cndmask_b32_e64 v89, 0, v88, s[98:99]
	v_cndmask_b32_e64 v165, 0, v167, s[100:101]
	v_cmp_ne_u32_e32 vcc, v171, v166
	v_max3_u32 v88, v86, v89, v165
	v_cmp_ne_u32_e64 s[98:99], v176, v166
	v_cndmask_b32_e32 v167, 0, v171, vcc
	v_cmp_ne_u32_e64 s[100:101], v179, v166
	v_cndmask_b32_e64 v168, 0, v176, s[98:99]
	v_max3_u32 v88, v88, v167, v168
	v_cndmask_b32_e64 v169, 0, v179, s[100:101]
	v_cmp_ne_u32_e32 vcc, v184, v166
	v_cmp_ne_u32_e64 s[98:99], v187, v166
	v_cmp_ne_u32_e64 s[100:101], v183, v166
	v_cndmask_b32_e32 v171, 0, v184, vcc
	v_max3_u32 v88, v88, v169, v171
	v_cndmask_b32_e64 v172, 0, v187, s[98:99]
	v_cndmask_b32_e64 v173, 0, v183, s[100:101]
	v_cmp_ne_u32_e32 vcc, v182, v166
	v_max3_u32 v88, v88, v172, v173
	v_cmp_ne_u32_e64 s[98:99], v162, v166
	v_cndmask_b32_e32 v176, 0, v182, vcc
	v_cmp_ne_u32_e64 s[100:101], v164, v166
	v_cndmask_b32_e64 v162, 0, v162, s[98:99]
	v_max3_u32 v88, v88, v176, v162
	v_cndmask_b32_e64 v164, 0, v164, s[100:101]
	v_cmp_ne_u32_e32 vcc, v87, v166
	s_nop 0
	s_nop 0
	v_cndmask_b32_e32 v87, 0, v87, vcc
	v_max3_u32 v88, v88, v164, v87
	ds_bpermute_b32 v177, v111, v88
	s_waitcnt lgkmcnt(0)
	v_max_u32_e32 v88, v88, v177
	ds_bpermute_b32 v177, v112, v88
	s_waitcnt lgkmcnt(0)
	v_max_u32_e32 v88, v88, v177
	v_cmp_ne_u32_e32 vcc, v86, v88
	v_cmp_ne_u32_e64 s[98:99], v89, v88
	v_cmp_ne_u32_e64 s[100:101], v165, v88
	v_cndmask_b32_e32 v86, 0, v86, vcc
	v_cndmask_b32_e64 v89, 0, v89, s[98:99]
	v_cndmask_b32_e64 v165, 0, v165, s[100:101]
	v_cmp_ne_u32_e32 vcc, v167, v88
	v_cmp_ne_u32_e64 s[98:99], v168, v88
	v_cmp_ne_u32_e64 s[100:101], v169, v88
	v_cndmask_b32_e32 v167, 0, v167, vcc
	v_cndmask_b32_e64 v168, 0, v168, s[98:99]
	v_cndmask_b32_e64 v169, 0, v169, s[100:101]
	v_cmp_ne_u32_e32 vcc, v171, v88
	v_cmp_ne_u32_e64 s[98:99], v172, v88
	v_cmp_ne_u32_e64 s[100:101], v173, v88
	v_cndmask_b32_e32 v171, 0, v171, vcc
	v_cndmask_b32_e64 v172, 0, v172, s[98:99]
	v_cndmask_b32_e64 v173, 0, v173, s[100:101]
	v_cmp_ne_u32_e32 vcc, v176, v88
	v_cmp_ne_u32_e64 s[98:99], v162, v88
	v_cmp_ne_u32_e64 s[100:101], v164, v88
	v_cndmask_b32_e32 v176, 0, v176, vcc
	v_cndmask_b32_e64 v162, 0, v162, s[98:99]
	v_cndmask_b32_e64 v164, 0, v164, s[100:101]
	v_cmp_ne_u32_e32 vcc, v87, v88
	s_nop 0
	s_nop 0
	v_cndmask_b32_e32 v177, 0, v87, vcc
	v_max3_u32 v87, v86, v89, v165
	v_max3_u32 v87, v87, v167, v168
	v_max3_u32 v87, v87, v169, v171
	v_max3_u32 v87, v87, v172, v173
	v_max3_u32 v87, v87, v176, v162
	v_max3_u32 v87, v87, v164, v177
	ds_bpermute_b32 v178, v111, v87
	s_waitcnt lgkmcnt(0)
; DI void peer_topk_wave(const Params& p, int item, unsigned* lds  ) {
;     ...
; #pragma unroll
;   for (int rr = 0; rr < 16; ++rr) {
;     unsigned m = 0;
; #pragma unroll
;     for (int i = 0; i < 13; ++i) m = umax(m, cand[i]);
;     m = umax(m, (unsigned)__shfl_xor((int)m, 16));
;     m = umax(m, (unsigned)__shfl_xor((int)m, 32));
;     w2[rr] = m;
; #pragma unroll
;     for (int i = 0; i < 13; ++i) cand[i] = (cand[i] == m) ? 0u : cand[i];
;   }
	v_max_u32_e32 v87, v87, v178
	ds_bpermute_b32 v178, v112, v87
	s_waitcnt lgkmcnt(0)
	v_max_u32_e32 v87, v87, v178
	v_cmp_ne_u32_e32 vcc, v86, v87
	v_cmp_ne_u32_e64 s[98:99], v89, v87
	v_cmp_ne_u32_e64 s[100:101], v165, v87
	v_cndmask_b32_e32 v178, 0, v86, vcc
	v_cndmask_b32_e64 v89, 0, v89, s[98:99]
	v_cndmask_b32_e64 v165, 0, v165, s[100:101]
	v_cmp_ne_u32_e32 vcc, v167, v87
	v_max3_u32 v86, v178, v89, v165
	v_cmp_ne_u32_e64 s[98:99], v168, v87
	v_cndmask_b32_e32 v167, 0, v167, vcc
	v_cmp_ne_u32_e64 s[100:101], v169, v87
	v_cndmask_b32_e64 v168, 0, v168, s[98:99]
	v_max3_u32 v86, v86, v167, v168
	v_cndmask_b32_e64 v169, 0, v169, s[100:101]
	v_cmp_ne_u32_e32 vcc, v171, v87
	v_cmp_ne_u32_e64 s[98:99], v172, v87
	v_cmp_ne_u32_e64 s[100:101], v173, v87
	v_cndmask_b32_e32 v171, 0, v171, vcc
	v_max3_u32 v86, v86, v169, v171
	v_cndmask_b32_e64 v172, 0, v172, s[98:99]
	v_cndmask_b32_e64 v173, 0, v173, s[100:101]
	v_cmp_ne_u32_e32 vcc, v176, v87
	v_max3_u32 v86, v86, v172, v173
	v_cmp_ne_u32_e64 s[98:99], v162, v87
	v_cndmask_b32_e32 v176, 0, v176, vcc
	v_cmp_ne_u32_e64 s[100:101], v164, v87
	v_cndmask_b32_e64 v162, 0, v162, s[98:99]
	v_max3_u32 v86, v86, v176, v162
	v_cndmask_b32_e64 v164, 0, v164, s[100:101]
	v_cmp_ne_u32_e32 vcc, v177, v87
	s_nop 0
	s_nop 0
	v_cndmask_b32_e32 v177, 0, v177, vcc
	v_max3_u32 v86, v86, v164, v177
	ds_bpermute_b32 v179, v111, v86
	s_waitcnt lgkmcnt(0)
	v_max_u32_e32 v86, v86, v179
	ds_bpermute_b32 v179, v112, v86
	s_waitcnt lgkmcnt(0)
	v_max_u32_e32 v86, v86, v179
	v_cmp_ne_u32_e32 vcc, v178, v86
	v_cmp_ne_u32_e64 s[98:99], v89, v86
	v_cmp_ne_u32_e64 s[100:101], v165, v86
	v_cndmask_b32_e32 v178, 0, v178, vcc
	v_cndmask_b32_e64 v89, 0, v89, s[98:99]
	v_cndmask_b32_e64 v165, 0, v165, s[100:101]
	v_cmp_ne_u32_e32 vcc, v167, v86
	v_cmp_ne_u32_e64 s[98:99], v168, v86
	v_cmp_ne_u32_e64 s[100:101], v169, v86
	v_cndmask_b32_e32 v167, 0, v167, vcc
	v_cndmask_b32_e64 v168, 0, v168, s[98:99]
	v_cndmask_b32_e64 v179, 0, v169, s[100:101]
	v_cmp_ne_u32_e32 vcc, v171, v86
	v_max3_u32 v169, v178, v89, v165
	v_max3_u32 v169, v169, v167, v168
	v_cndmask_b32_e32 v171, 0, v171, vcc
	v_cmp_ne_u32_e64 s[98:99], v172, v86
	v_max3_u32 v169, v169, v179, v171
	v_cmp_ne_u32_e64 s[100:101], v173, v86
	v_cndmask_b32_e64 v172, 0, v172, s[98:99]
	v_cmp_ne_u32_e32 vcc, v176, v86
	v_cndmask_b32_e64 v173, 0, v173, s[100:101]
	v_max3_u32 v169, v169, v172, v173
	v_cndmask_b32_e32 v176, 0, v176, vcc
	v_cmp_ne_u32_e64 s[98:99], v162, v86
	v_cmp_ne_u32_e64 s[100:101], v164, v86
	v_cmp_ne_u32_e32 vcc, v177, v86
	v_cndmask_b32_e64 v162, 0, v162, s[98:99]
	v_max3_u32 v169, v169, v176, v162
	v_cndmask_b32_e64 v164, 0, v164, s[100:101]
	v_cndmask_b32_e32 v177, 0, v177, vcc
	v_max3_u32 v169, v169, v164, v177
	ds_bpermute_b32 v180, v111, v169
	s_waitcnt lgkmcnt(0)
	v_max_u32_e32 v169, v169, v180
	ds_bpermute_b32 v180, v112, v169
	s_waitcnt lgkmcnt(0)
	v_max_u32_e32 v169, v169, v180
	v_cmp_ne_u32_e32 vcc, v178, v169
	v_cmp_ne_u32_e64 s[98:99], v89, v169
	v_cmp_ne_u32_e64 s[100:101], v165, v169
	v_cndmask_b32_e32 v178, 0, v178, vcc
	v_cndmask_b32_e64 v89, 0, v89, s[98:99]
	v_cndmask_b32_e64 v165, 0, v165, s[100:101]
	v_cmp_ne_u32_e32 vcc, v167, v169
	v_cmp_ne_u32_e64 s[98:99], v168, v169
	v_cmp_ne_u32_e64 s[100:101], v179, v169
	v_cndmask_b32_e32 v167, 0, v167, vcc
	v_cndmask_b32_e64 v168, 0, v168, s[98:99]
	v_cndmask_b32_e64 v179, 0, v179, s[100:101]
	v_cmp_ne_u32_e32 vcc, v171, v169
	v_cmp_ne_u32_e64 s[98:99], v172, v169
	v_cmp_ne_u32_e64 s[100:101], v173, v169
	v_cndmask_b32_e32 v171, 0, v171, vcc
	v_cndmask_b32_e64 v172, 0, v172, s[98:99]
	v_cndmask_b32_e64 v173, 0, v173, s[100:101]
	v_cmp_ne_u32_e32 vcc, v176, v169
	v_cmp_ne_u32_e64 s[98:99], v162, v169
	v_cmp_ne_u32_e64 s[100:101], v164, v169
	v_cndmask_b32_e32 v176, 0, v176, vcc
	v_cndmask_b32_e64 v162, 0, v162, s[98:99]
	v_cndmask_b32_e64 v180, 0, v164, s[100:101]
	v_max3_u32 v164, v178, v89, v165
	v_max3_u32 v164, v164, v167, v168
	v_max3_u32 v164, v164, v179, v171
	v_cmp_ne_u32_e32 vcc, v177, v169
	v_max3_u32 v164, v164, v172, v173
	v_max3_u32 v164, v164, v176, v162
	v_cndmask_b32_e32 v177, 0, v177, vcc
	v_max3_u32 v164, v164, v180, v177
	ds_bpermute_b32 v181, v111, v164
	s_waitcnt lgkmcnt(0)
	v_max_u32_e32 v164, v164, v181
	ds_bpermute_b32 v181, v112, v164
	s_waitcnt lgkmcnt(0)
	v_max_u32_e32 v164, v164, v181
	v_cmp_ne_u32_e32 vcc, v178, v164
	v_cmp_ne_u32_e64 s[98:99], v89, v164
	v_cmp_ne_u32_e64 s[100:101], v165, v164
	v_cndmask_b32_e32 v178, 0, v178, vcc
	v_cndmask_b32_e64 v89, 0, v89, s[98:99]
	v_cndmask_b32_e64 v165, 0, v165, s[100:101]
	v_cmp_ne_u32_e32 vcc, v167, v164
	v_cmp_ne_u32_e64 s[98:99], v168, v164
	v_cmp_ne_u32_e64 s[100:101], v179, v164
	v_cndmask_b32_e32 v167, 0, v167, vcc
	v_cndmask_b32_e64 v168, 0, v168, s[98:99]
	v_cndmask_b32_e64 v179, 0, v179, s[100:101]
	v_cmp_ne_u32_e32 vcc, v171, v164
	v_cmp_ne_u32_e64 s[98:99], v172, v164
	v_cmp_ne_u32_e64 s[100:101], v173, v164
	v_cndmask_b32_e32 v171, 0, v171, vcc
	v_cndmask_b32_e64 v172, 0, v172, s[98:99]
	v_cndmask_b32_e64 v173, 0, v173, s[100:101]
	v_cmp_ne_u32_e32 vcc, v176, v164
	v_cmp_ne_u32_e64 s[98:99], v162, v164
	v_cmp_ne_u32_e64 s[100:101], v180, v164
	v_cndmask_b32_e32 v176, 0, v176, vcc
	v_cndmask_b32_e64 v181, 0, v162, s[98:99]
	v_max3_u32 v162, v178, v89, v165
	v_max3_u32 v162, v162, v167, v168
	v_max3_u32 v162, v162, v179, v171
	v_max3_u32 v162, v162, v172, v173
	v_cndmask_b32_e64 v180, 0, v180, s[100:101]
	v_cmp_ne_u32_e32 vcc, v177, v164
	v_max3_u32 v162, v162, v176, v181
	s_nop 0
	v_cndmask_b32_e32 v177, 0, v177, vcc
	v_max3_u32 v162, v162, v180, v177
	ds_bpermute_b32 v182, v111, v162
	s_waitcnt lgkmcnt(0)
; DI void peer_topk_wave(const Params& p, int item, unsigned* lds  ) {
;     ...
; #pragma unroll
;   for (int rr = 0; rr < 16; ++rr) {
;     unsigned m = 0;
; #pragma unroll
;     for (int i = 0; i < 13; ++i) m = umax(m, cand[i]);
;     m = umax(m, (unsigned)__shfl_xor((int)m, 16));
;     m = umax(m, (unsigned)__shfl_xor((int)m, 32));
;     w2[rr] = m;
; #pragma unroll
;     for (int i = 0; i < 13; ++i) cand[i] = (cand[i] == m) ? 0u : cand[i];
;   }
	v_max_u32_e32 v162, v162, v182
	ds_bpermute_b32 v182, v112, v162
	s_waitcnt lgkmcnt(0)
	v_max_u32_e32 v162, v162, v182
	v_cmp_ne_u32_e32 vcc, v178, v162
	v_cmp_ne_u32_e64 s[98:99], v89, v162
	v_cmp_ne_u32_e64 s[100:101], v165, v162
	v_cndmask_b32_e32 v178, 0, v178, vcc
	v_cndmask_b32_e64 v182, 0, v89, s[98:99]
	v_cndmask_b32_e64 v165, 0, v165, s[100:101]
	v_cmp_ne_u32_e32 vcc, v167, v162
	v_max3_u32 v89, v178, v182, v165
	v_cmp_ne_u32_e64 s[98:99], v168, v162
	v_cndmask_b32_e32 v167, 0, v167, vcc
	v_cmp_ne_u32_e64 s[100:101], v179, v162
	v_cndmask_b32_e64 v168, 0, v168, s[98:99]
	v_max3_u32 v89, v89, v167, v168
	v_cndmask_b32_e64 v179, 0, v179, s[100:101]
	v_cmp_ne_u32_e32 vcc, v171, v162
	v_cmp_ne_u32_e64 s[98:99], v172, v162
	v_cmp_ne_u32_e64 s[100:101], v173, v162
	v_cndmask_b32_e32 v171, 0, v171, vcc
	v_max3_u32 v89, v89, v179, v171
	v_cndmask_b32_e64 v172, 0, v172, s[98:99]
	v_cndmask_b32_e64 v173, 0, v173, s[100:101]
	v_cmp_ne_u32_e32 vcc, v176, v162
	v_max3_u32 v89, v89, v172, v173
	v_cmp_ne_u32_e64 s[98:99], v181, v162
	v_cndmask_b32_e32 v176, 0, v176, vcc
	v_cmp_ne_u32_e64 s[100:101], v180, v162
	v_cndmask_b32_e64 v181, 0, v181, s[98:99]
	v_max3_u32 v89, v89, v176, v181
	v_cndmask_b32_e64 v180, 0, v180, s[100:101]
	v_cmp_ne_u32_e32 vcc, v177, v162
	s_nop 0
	s_nop 0
	v_cndmask_b32_e32 v177, 0, v177, vcc
	v_max3_u32 v89, v89, v180, v177
	ds_bpermute_b32 v183, v111, v89
	s_waitcnt lgkmcnt(0)
	v_max_u32_e32 v89, v89, v183
	ds_bpermute_b32 v183, v112, v89
	s_waitcnt lgkmcnt(0)
	v_max_u32_e32 v89, v89, v183
	v_cmp_ne_u32_e32 vcc, v178, v89
	v_cmp_ne_u32_e64 s[98:99], v182, v89
	v_cmp_ne_u32_e64 s[100:101], v165, v89
	v_cndmask_b32_e32 v178, 0, v178, vcc
	v_cndmask_b32_e64 v182, 0, v182, s[98:99]
	v_cndmask_b32_e64 v165, 0, v165, s[100:101]
	v_cmp_ne_u32_e32 vcc, v167, v89
	v_cmp_ne_u32_e64 s[98:99], v168, v89
	v_cmp_ne_u32_e64 s[100:101], v179, v89
	v_cndmask_b32_e32 v167, 0, v167, vcc
	v_cndmask_b32_e64 v168, 0, v168, s[98:99]
	v_cndmask_b32_e64 v179, 0, v179, s[100:101]
	v_cmp_ne_u32_e32 vcc, v171, v89
	v_cmp_ne_u32_e64 s[98:99], v172, v89
	v_cmp_ne_u32_e64 s[100:101], v173, v89
	v_cndmask_b32_e32 v171, 0, v171, vcc
	v_cndmask_b32_e64 v183, 0, v172, s[98:99]
	v_max3_u32 v172, v178, v182, v165
	v_max3_u32 v172, v172, v167, v168
	v_cndmask_b32_e64 v173, 0, v173, s[100:101]
	v_cmp_ne_u32_e32 vcc, v176, v89
	v_max3_u32 v172, v172, v179, v171
	v_max3_u32 v172, v172, v183, v173
	v_cndmask_b32_e32 v176, 0, v176, vcc
	v_cmp_ne_u32_e64 s[98:99], v181, v89
	v_cmp_ne_u32_e64 s[100:101], v180, v89
	v_cmp_ne_u32_e32 vcc, v177, v89
	v_cndmask_b32_e64 v181, 0, v181, s[98:99]
	v_max3_u32 v172, v172, v176, v181
	v_cndmask_b32_e64 v180, 0, v180, s[100:101]
	v_cndmask_b32_e32 v177, 0, v177, vcc
	v_max3_u32 v172, v172, v180, v177
	ds_bpermute_b32 v184, v111, v172
	s_waitcnt lgkmcnt(0)
	v_max_u32_e32 v172, v172, v184
	ds_bpermute_b32 v184, v112, v172
	s_waitcnt lgkmcnt(0)
	v_max_u32_e32 v172, v172, v184
	v_cmp_ne_u32_e32 vcc, v178, v172
	v_cmp_ne_u32_e64 s[98:99], v182, v172
	v_cmp_ne_u32_e64 s[100:101], v165, v172
	v_cndmask_b32_e32 v178, 0, v178, vcc
	v_cndmask_b32_e64 v182, 0, v182, s[98:99]
	v_cndmask_b32_e64 v165, 0, v165, s[100:101]
	v_cmp_ne_u32_e32 vcc, v167, v172
	v_cmp_ne_u32_e64 s[98:99], v168, v172
	v_cmp_ne_u32_e64 s[100:101], v179, v172
	v_cndmask_b32_e32 v167, 0, v167, vcc
	v_cndmask_b32_e64 v184, 0, v168, s[98:99]
	v_max3_u32 v168, v178, v182, v165
	v_max3_u32 v168, v168, v167, v184
	v_cndmask_b32_e64 v179, 0, v179, s[100:101]
	v_cmp_ne_u32_e32 vcc, v171, v172
	v_cmp_ne_u32_e64 s[98:99], v183, v172
	v_cmp_ne_u32_e64 s[100:101], v173, v172
	v_cndmask_b32_e32 v171, 0, v171, vcc
	v_max3_u32 v168, v168, v179, v171
	v_cndmask_b32_e64 v183, 0, v183, s[98:99]
	v_cndmask_b32_e64 v173, 0, v173, s[100:101]
	v_cmp_ne_u32_e32 vcc, v176, v172
	v_max3_u32 v168, v168, v183, v173
	v_cmp_ne_u32_e64 s[98:99], v181, v172
	v_cndmask_b32_e32 v176, 0, v176, vcc
	v_cmp_ne_u32_e64 s[100:101], v180, v172
	v_cndmask_b32_e64 v181, 0, v181, s[98:99]
	v_max3_u32 v168, v168, v176, v181
	v_cndmask_b32_e64 v180, 0, v180, s[100:101]
	v_cmp_ne_u32_e32 vcc, v177, v172
	s_nop 0
	s_nop 0
	v_cndmask_b32_e32 v177, 0, v177, vcc
	v_max3_u32 v168, v168, v180, v177
	ds_bpermute_b32 v185, v111, v168
	s_waitcnt lgkmcnt(0)
	v_max_u32_e32 v168, v168, v185
	ds_bpermute_b32 v185, v112, v168
	s_waitcnt lgkmcnt(0)
	v_max_u32_e32 v168, v168, v185
	v_cmp_ne_u32_e32 vcc, v178, v168
	v_cmp_ne_u32_e64 s[98:99], v182, v168
	v_cmp_ne_u32_e64 s[100:101], v165, v168
	v_cndmask_b32_e32 v178, 0, v178, vcc
	v_cndmask_b32_e64 v182, 0, v182, s[98:99]
	v_cndmask_b32_e64 v165, 0, v165, s[100:101]
	v_cmp_ne_u32_e32 vcc, v167, v168
	v_cmp_ne_u32_e64 s[98:99], v184, v168
	v_cmp_ne_u32_e64 s[100:101], v179, v168
	v_cndmask_b32_e32 v185, 0, v167, vcc
	v_max3_u32 v167, v178, v182, v165
	v_cndmask_b32_e64 v184, 0, v184, s[98:99]
	v_max3_u32 v167, v167, v185, v184
	v_cndmask_b32_e64 v179, 0, v179, s[100:101]
	v_cmp_ne_u32_e32 vcc, v171, v168
	v_cmp_ne_u32_e64 s[98:99], v183, v168
	v_cmp_ne_u32_e64 s[100:101], v173, v168
	v_cndmask_b32_e32 v171, 0, v171, vcc
	v_max3_u32 v167, v167, v179, v171
	v_cndmask_b32_e64 v183, 0, v183, s[98:99]
	v_cndmask_b32_e64 v173, 0, v173, s[100:101]
	v_cmp_ne_u32_e32 vcc, v176, v168
	v_max3_u32 v167, v167, v183, v173
	v_cmp_ne_u32_e64 s[98:99], v181, v168
	v_cndmask_b32_e32 v176, 0, v176, vcc
	v_cmp_ne_u32_e64 s[100:101], v180, v168
	v_cndmask_b32_e64 v181, 0, v181, s[98:99]
	v_max3_u32 v167, v167, v176, v181
	v_cndmask_b32_e64 v180, 0, v180, s[100:101]
	v_cmp_ne_u32_e32 vcc, v177, v168
	s_nop 0
	s_nop 0
	v_cndmask_b32_e32 v177, 0, v177, vcc
	v_max3_u32 v167, v167, v180, v177
	ds_bpermute_b32 v186, v111, v167
	s_waitcnt lgkmcnt(0)
; DI void peer_topk_wave(const Params& p, int item, unsigned* lds  ) {
;     ...
; #pragma unroll
;   for (int rr = 0; rr < 16; ++rr) {
;     unsigned m = 0;
; #pragma unroll
;     for (int i = 0; i < 13; ++i) m = umax(m, cand[i]);
;     m = umax(m, (unsigned)__shfl_xor((int)m, 16));
;     m = umax(m, (unsigned)__shfl_xor((int)m, 32));
;     w2[rr] = m;
; #pragma unroll
;     for (int i = 0; i < 13; ++i) cand[i] = (cand[i] == m) ? 0u : cand[i];
;   }
	v_max_u32_e32 v167, v167, v186
	ds_bpermute_b32 v186, v112, v167
	s_waitcnt lgkmcnt(0)
	v_max_u32_e32 v167, v167, v186
	v_cmp_ne_u32_e32 vcc, v178, v167
	v_cmp_ne_u32_e64 s[98:99], v182, v167
	v_cmp_ne_u32_e64 s[100:101], v165, v167
	v_cndmask_b32_e32 v178, 0, v178, vcc
	v_cndmask_b32_e64 v182, 0, v182, s[98:99]
	v_cndmask_b32_e64 v186, 0, v165, s[100:101]
	v_cmp_ne_u32_e32 vcc, v185, v167
	v_max3_u32 v165, v178, v182, v186
	v_cmp_ne_u32_e64 s[98:99], v184, v167
	v_cndmask_b32_e32 v185, 0, v185, vcc
	v_cmp_ne_u32_e64 s[100:101], v179, v167
	v_cndmask_b32_e64 v184, 0, v184, s[98:99]
	v_max3_u32 v165, v165, v185, v184
	v_cndmask_b32_e64 v179, 0, v179, s[100:101]
	v_cmp_ne_u32_e32 vcc, v171, v167
	v_cmp_ne_u32_e64 s[98:99], v183, v167
	v_cmp_ne_u32_e64 s[100:101], v173, v167
	v_cndmask_b32_e32 v171, 0, v171, vcc
	v_max3_u32 v165, v165, v179, v171
	v_cndmask_b32_e64 v183, 0, v183, s[98:99]
	v_cndmask_b32_e64 v173, 0, v173, s[100:101]
	v_cmp_ne_u32_e32 vcc, v176, v167
	v_max3_u32 v165, v165, v183, v173
	v_cmp_ne_u32_e64 s[98:99], v181, v167
	v_cndmask_b32_e32 v176, 0, v176, vcc
	v_cmp_ne_u32_e64 s[100:101], v180, v167
	v_cndmask_b32_e64 v181, 0, v181, s[98:99]
	v_max3_u32 v165, v165, v176, v181
	v_cndmask_b32_e64 v180, 0, v180, s[100:101]
	v_cmp_ne_u32_e32 vcc, v177, v167
	s_nop 0
	s_nop 0
	v_cndmask_b32_e32 v177, 0, v177, vcc
	v_max3_u32 v165, v165, v180, v177
	ds_bpermute_b32 v187, v111, v165
	s_waitcnt lgkmcnt(0)
	v_max_u32_e32 v165, v165, v187
	ds_bpermute_b32 v187, v112, v165
	s_waitcnt lgkmcnt(0)
	v_max_u32_e32 v165, v165, v187
	v_cmp_ne_u32_e32 vcc, v178, v165
	v_cmp_ne_u32_e64 s[98:99], v182, v165
	v_cmp_ne_u32_e64 s[100:101], v186, v165
	v_cndmask_b32_e32 v178, 0, v178, vcc
	v_cndmask_b32_e64 v182, 0, v182, s[98:99]
	v_cndmask_b32_e64 v186, 0, v186, s[100:101]
	v_cmp_ne_u32_e32 vcc, v185, v165
	v_cmp_ne_u32_e64 s[98:99], v184, v165
	v_cmp_ne_u32_e64 s[100:101], v179, v165
	v_cndmask_b32_e32 v185, 0, v185, vcc
	v_cndmask_b32_e64 v184, 0, v184, s[98:99]
	v_cndmask_b32_e64 v179, 0, v179, s[100:101]
	v_cmp_ne_u32_e32 vcc, v171, v165
	v_cmp_ne_u32_e64 s[98:99], v183, v165
	v_cmp_ne_u32_e64 s[100:101], v173, v165
	v_cndmask_b32_e32 v171, 0, v171, vcc
	v_cndmask_b32_e64 v183, 0, v183, s[98:99]
	v_cndmask_b32_e64 v173, 0, v173, s[100:101]
	v_cmp_ne_u32_e32 vcc, v176, v165
	v_cmp_ne_u32_e64 s[98:99], v181, v165
	v_cmp_ne_u32_e64 s[100:101], v180, v165
	v_cndmask_b32_e32 v187, 0, v176, vcc
	v_max3_u32 v176, v178, v182, v186
	v_max3_u32 v176, v176, v185, v184
	v_max3_u32 v176, v176, v179, v171
	v_cndmask_b32_e64 v181, 0, v181, s[98:99]
	v_max3_u32 v176, v176, v183, v173
	v_max3_u32 v176, v176, v187, v181
	v_cndmask_b32_e64 v180, 0, v180, s[100:101]
	v_cmp_ne_u32_e32 vcc, v177, v165
	s_nop 0
	s_nop 0
	v_cndmask_b32_e32 v177, 0, v177, vcc
	v_max3_u32 v176, v176, v180, v177
	ds_bpermute_b32 v188, v111, v176
	s_waitcnt lgkmcnt(0)
	v_max_u32_e32 v176, v176, v188
	ds_bpermute_b32 v188, v112, v176
	s_waitcnt lgkmcnt(0)
	v_max_u32_e32 v176, v176, v188
	v_cmp_ne_u32_e32 vcc, v178, v176
	v_cmp_ne_u32_e64 s[98:99], v182, v176
	v_cmp_ne_u32_e64 s[100:101], v186, v176
	v_cndmask_b32_e32 v178, 0, v178, vcc
	v_cndmask_b32_e64 v182, 0, v182, s[98:99]
	v_cndmask_b32_e64 v186, 0, v186, s[100:101]
	v_cmp_ne_u32_e32 vcc, v185, v176
	v_cmp_ne_u32_e64 s[98:99], v184, v176
	v_cmp_ne_u32_e64 s[100:101], v179, v176
	v_cndmask_b32_e32 v185, 0, v185, vcc
	v_cndmask_b32_e64 v184, 0, v184, s[98:99]
	v_cndmask_b32_e64 v179, 0, v179, s[100:101]
	v_cmp_ne_u32_e32 vcc, v171, v176
	v_cmp_ne_u32_e64 s[98:99], v183, v176
	v_cmp_ne_u32_e64 s[100:101], v173, v176
	v_cndmask_b32_e32 v171, 0, v171, vcc
	v_cndmask_b32_e64 v183, 0, v183, s[98:99]
	v_cndmask_b32_e64 v188, 0, v173, s[100:101]
	v_cmp_ne_u32_e32 vcc, v187, v176
	v_max3_u32 v173, v178, v182, v186
	v_max3_u32 v173, v173, v185, v184
	v_cndmask_b32_e32 v187, 0, v187, vcc
	v_cmp_ne_u32_e64 s[98:99], v181, v176
	v_max3_u32 v173, v173, v179, v171
	v_max3_u32 v173, v173, v183, v188
	v_cndmask_b32_e64 v181, 0, v181, s[98:99]
	v_cmp_ne_u32_e64 s[100:101], v180, v176
	v_max3_u32 v173, v173, v187, v181
	v_cmp_ne_u32_e32 vcc, v177, v176
	v_cndmask_b32_e64 v180, 0, v180, s[100:101]
	s_nop 0
	v_cndmask_b32_e32 v177, 0, v177, vcc
	v_max3_u32 v173, v173, v180, v177
	ds_bpermute_b32 v189, v111, v173
	s_waitcnt lgkmcnt(0)
	v_max_u32_e32 v173, v173, v189
	ds_bpermute_b32 v189, v112, v173
	s_waitcnt lgkmcnt(0)
; DI void peer_topk_wave(const Params& p, int item, unsigned* lds  ) {
;     ...
; #pragma unroll
;   for (int rr = 0; rr < 16; ++rr) {
;     unsigned m = 0;
; #pragma unroll
;     for (int i = 0; i < 13; ++i) m = umax(m, cand[i]);
;     m = umax(m, (unsigned)__shfl_xor((int)m, 16));
;     m = umax(m, (unsigned)__shfl_xor((int)m, 32));
;     w2[rr] = m;
; #pragma unroll
;     for (int i = 0; i < 13; ++i) cand[i] = (cand[i] == m) ? 0u : cand[i];
;   }
;   if (kg == 0) {
; #pragma unroll
;     for (int i = 0; i < 16; ++i) { lds[r * 32 + i] = win[0][i] & 127u; lds[r * 32 + 16 + i] = win[1][i] & 127u; }
	v_max_u32_e32 v173, v173, v189
	v_cmp_ne_u32_e32 vcc, v178, v173
	v_cmp_ne_u32_e64 s[98:99], v182, v173
	v_cmp_ne_u32_e64 s[100:101], v186, v173
	v_cndmask_b32_e32 v178, 0, v178, vcc
	v_cndmask_b32_e64 v182, 0, v182, s[98:99]
	v_cndmask_b32_e64 v186, 0, v186, s[100:101]
	v_cmp_ne_u32_e32 vcc, v185, v173
	v_cmp_ne_u32_e64 s[98:99], v184, v173
	v_cmp_ne_u32_e64 s[100:101], v179, v173
	v_cndmask_b32_e32 v185, 0, v185, vcc
	v_cndmask_b32_e64 v184, 0, v184, s[98:99]
	v_cndmask_b32_e64 v179, 0, v179, s[100:101]
	v_cmp_ne_u32_e32 vcc, v171, v173
	v_cmp_ne_u32_e64 s[98:99], v183, v173
	v_cmp_ne_u32_e64 s[100:101], v188, v173
	v_cndmask_b32_e32 v189, 0, v171, vcc
	v_max3_u32 v171, v178, v182, v186
	v_max3_u32 v171, v171, v185, v184
	v_cndmask_b32_e64 v183, 0, v183, s[98:99]
	v_max3_u32 v171, v171, v179, v189
	v_cndmask_b32_e64 v188, 0, v188, s[100:101]
	v_cmp_ne_u32_e32 vcc, v187, v173
	v_max3_u32 v171, v171, v183, v188
	v_cmp_ne_u32_e64 s[98:99], v181, v173
	v_cndmask_b32_e32 v187, 0, v187, vcc
	v_cmp_ne_u32_e64 s[100:101], v180, v173
	v_cndmask_b32_e64 v181, 0, v181, s[98:99]
	v_max3_u32 v171, v171, v187, v181
	v_cndmask_b32_e64 v180, 0, v180, s[100:101]
	v_cmp_ne_u32_e32 vcc, v177, v173
	s_nop 0
	s_nop 0
	v_cndmask_b32_e32 v177, 0, v177, vcc
	v_max3_u32 v171, v171, v180, v177
	ds_bpermute_b32 v190, v111, v171
	s_waitcnt lgkmcnt(0)
	v_max_u32_e32 v171, v171, v190
	ds_bpermute_b32 v190, v112, v171
	s_waitcnt lgkmcnt(0)
	v_max_u32_e32 v171, v171, v190
	v_cmp_ne_u32_e32 vcc, v182, v171
	s_nop 1
	v_cndmask_b32_e32 v182, 0, v182, vcc
	v_max_u32_e32 v190, v178, v182
	v_cmp_eq_u32_e32 vcc, v178, v171
	s_nop 1
	v_cndmask_b32_e32 v178, v190, v182, vcc
	v_max_u32_e32 v182, v178, v186
	v_cmp_eq_u32_e32 vcc, v186, v171
	s_nop 1
	v_cndmask_b32_e32 v178, v182, v178, vcc
	v_max_u32_e32 v182, v178, v185
	v_cmp_eq_u32_e32 vcc, v185, v171
	s_nop 1
	v_cndmask_b32_e32 v178, v182, v178, vcc
	v_max_u32_e32 v182, v178, v184
	v_cmp_eq_u32_e32 vcc, v184, v171
	s_nop 1
	v_cndmask_b32_e32 v178, v182, v178, vcc
	v_max_u32_e32 v182, v178, v179
	v_cmp_eq_u32_e32 vcc, v179, v171
	s_nop 1
	v_cndmask_b32_e32 v178, v182, v178, vcc
	v_max_u32_e32 v179, v178, v189
	v_cmp_eq_u32_e32 vcc, v189, v171
	s_nop 1
	v_cndmask_b32_e32 v178, v179, v178, vcc
	v_max_u32_e32 v179, v178, v183
	v_cmp_eq_u32_e32 vcc, v183, v171
	s_nop 1
	v_cndmask_b32_e32 v178, v179, v178, vcc
	v_max_u32_e32 v179, v178, v188
	v_cmp_eq_u32_e32 vcc, v188, v171
	s_nop 1
	v_cndmask_b32_e32 v178, v179, v178, vcc
	v_max_u32_e32 v179, v178, v187
	v_cmp_eq_u32_e32 vcc, v187, v171
	s_nop 1
	v_cndmask_b32_e32 v178, v179, v178, vcc
	v_max_u32_e32 v179, v178, v181
	v_cmp_eq_u32_e32 vcc, v181, v171
	s_nop 1
	v_cndmask_b32_e32 v178, v179, v178, vcc
	v_max_u32_e32 v179, v178, v180
	v_cmp_eq_u32_e32 vcc, v180, v171
	s_nop 1
	v_cndmask_b32_e32 v178, v179, v178, vcc
	v_max_u32_e32 v179, v178, v177
	v_cmp_eq_u32_e32 vcc, v177, v171
	s_nop 1
	v_cndmask_b32_e32 v177, v179, v178, vcc
	ds_bpermute_b32 v178, v111, v177
	s_waitcnt lgkmcnt(0)
	v_max_u32_e32 v177, v177, v178
	ds_bpermute_b32 v178, v112, v177
	s_and_saveexec_b64 s[0:1], s[6:7]
	s_cbranch_execz .LBB0_1281
	v_and_b32_e32 v181, 0x7f, v147
	v_and_b32_e32 v180, 0x7f, v16
	v_and_b32_e32 v1, 0x7f, v1
	v_and_b32_e32 v0, 0x7f, v0
	v_and_b32_e32 v183, 0x7f, v149
	v_and_b32_e32 v182, 0x7f, v148
	v_and_b32_e32 v3, 0x7f, v3
	v_and_b32_e32 v2, 0x7f, v2
	ds_write_b128 v110, v[180:183]
	ds_write_b128 v110, v[0:3] offset:64
	v_and_b32_e32 v1, 0x7f, v151
	v_and_b32_e32 v0, 0x7f, v150
	v_and_b32_e32 v3, 0x7f, v153
	v_and_b32_e32 v2, 0x7f, v152
	v_and_b32_e32 v5, 0x7f, v5
	v_and_b32_e32 v4, 0x7f, v4
	v_and_b32_e32 v7, 0x7f, v7
	v_and_b32_e32 v6, 0x7f, v6
	ds_write_b128 v110, v[0:3] offset:16
	ds_write_b128 v110, v[4:7] offset:80
	v_and_b32_e32 v1, 0x7f, v155
	v_and_b32_e32 v0, 0x7f, v154
	v_and_b32_e32 v3, 0x7f, v157
	v_and_b32_e32 v2, 0x7f, v156
	v_and_b32_e32 v5, 0x7f, v9
	v_and_b32_e32 v4, 0x7f, v8
	v_and_b32_e32 v7, 0x7f, v11
	v_and_b32_e32 v6, 0x7f, v10
	ds_write_b128 v110, v[0:3] offset:32
	ds_write_b128 v110, v[4:7] offset:96
	v_and_b32_e32 v1, 0x7f, v159
	v_and_b32_e32 v0, 0x7f, v158
	v_and_b32_e32 v3, 0x7f, v161
	v_and_b32_e32 v2, 0x7f, v160
	v_and_b32_e32 v5, 0x7f, v13
	v_and_b32_e32 v4, 0x7f, v12
	v_and_b32_e32 v7, 0x7f, v15
	v_and_b32_e32 v6, 0x7f, v14
	ds_write_b128 v110, v[0:3] offset:48
	ds_write_b128 v110, v[4:7] offset:112

; #define AS1 __attribute__((address_space(1)))
; DI void axpy16_fp8(float* o, float w, u32x4 u) {
;   const unsigned d[4] = {u[0], u[1], u[2], u[3]};
; #pragma unroll
;   for (int i = 0; i < 4; ++i) {
;     f32x2 a = __builtin_amdgcn_cvt_pk_f32_fp8((int)d[i], false);
;     f32x2 b = __builtin_amdgcn_cvt_pk_f32_fp8((int)d[i], true);
;     o[4 * i] += w * a[0]; o[4 * i + 1] += w * a[1]; o[4 * i + 2] += w * b[0]; o[4 * i + 3] += w * b[1];
;   }
; }
; DI void peer_v_group(const Params& p, int gw, int nw, int g, const float* wlw  ) {
;     ...
;         float we[8];
; #pragma unroll
;         for (int k = 0; k < 8; ++k) {
;           we[k] = 0.f;
;           v[k] = (u32x4){0u, 0u, 0u, 0u};
;           if ((m0 | m1) != 0ull) {
;             int l, id;
;             if (m0 != 0ull) {
;               l = __builtin_ctzll(m0); m0 &= m0 - 1ull;
;               id = __builtin_amdgcn_readlane(e0[ts], l);
;               we[k] = __int_as_float(__builtin_amdgcn_readlane(__float_as_int(w0[ts]), l));
;             } else {
;               l = __builtin_ctzll(m1); m1 &= m1 - 1ull;
;               id = __builtin_amdgcn_readlane(e1[ts], l);
;               we[k] = __int_as_float(__builtin_amdgcn_readlane(__float_as_int(w1[ts]), l));
;             }
;             v[k] = *(const u32x4 AS1*)(EV8 + (size_t)id * 1024 + lane * 16);
;           }
;         }
; #pragma unroll
;         for (int k = 0; k < 8; ++k) axpy16_fp8(out[ts], we[k], v[k]);
.LBB0_1372:
	v_mov_b32_e32 v35, 0
	s_mov_b32 s26, 0
	v_mov_b32_e32 v34, v35
	v_mov_b32_e32 v33, v35
	v_mov_b32_e32 v32, v35
	s_branch .Lvb_g0
.LBB0_1373:
	s_waitcnt vmcnt(0)
	v_cvt_pk_f32_fp8_e32 v[148:149], v4
	v_cvt_pk_f32_fp8_sdwa v[150:151], v4 src0_sel:WORD_1
	v_cvt_pk_f32_fp8_e32 v[152:153], v5
	v_cvt_pk_f32_fp8_sdwa v[4:5], v5 src0_sel:WORD_1
	v_pk_fma_f32 v[112:113], s[12:13], v[148:149], v[112:113] op_sel_hi:[0,1,1]
	v_pk_fma_f32 v[114:115], s[12:13], v[150:151], v[114:115] op_sel_hi:[0,1,1]
	v_cvt_pk_f32_fp8_sdwa v[148:149], v6 src0_sel:WORD_1
	v_pk_fma_f32 v[4:5], s[12:13], v[4:5], v[118:119] op_sel_hi:[0,1,1]
	v_cvt_pk_f32_fp8_e32 v[118:119], v6
	v_cvt_pk_f32_fp8_e32 v[150:151], v7
	v_cvt_pk_f32_fp8_sdwa v[6:7], v7 src0_sel:WORD_1
	v_pk_fma_f32 v[122:123], s[12:13], v[148:149], v[122:123] op_sel_hi:[0,1,1]
	v_pk_fma_f32 v[120:121], s[12:13], v[118:119], v[120:121] op_sel_hi:[0,1,1]
	v_cvt_pk_f32_fp8_e32 v[118:119], v8
	v_pk_fma_f32 v[6:7], s[12:13], v[6:7], v[126:127] op_sel_hi:[0,1,1]
	v_cvt_pk_f32_fp8_sdwa v[126:127], v8 src0_sel:WORD_1
	v_cvt_pk_f32_fp8_e32 v[148:149], v9
	v_cvt_pk_f32_fp8_sdwa v[8:9], v9 src0_sel:WORD_1
	v_cvt_pk_f32_fp8_e32 v[156:157], v12
	v_cvt_pk_f32_fp8_sdwa v[158:159], v12 src0_sel:WORD_1
	v_cvt_pk_f32_fp8_e32 v[160:161], v13
	v_cvt_pk_f32_fp8_sdwa v[12:13], v13 src0_sel:WORD_1
	v_cvt_pk_f32_fp8_e32 v[170:171], v16
	v_cvt_pk_f32_fp8_sdwa v[172:173], v16 src0_sel:WORD_1
	v_cvt_pk_f32_fp8_e32 v[174:175], v17
	v_cvt_pk_f32_fp8_sdwa v[16:17], v17 src0_sel:WORD_1
	v_pk_fma_f32 v[116:117], s[12:13], v[152:153], v[116:117] op_sel_hi:[0,1,1]
	v_cvt_pk_f32_fp8_e32 v[182:183], v20
	v_cvt_pk_f32_fp8_sdwa v[184:185], v20 src0_sel:WORD_1
	v_cvt_pk_f32_fp8_e32 v[186:187], v21
	v_cvt_pk_f32_fp8_sdwa v[20:21], v21 src0_sel:WORD_1
	v_pk_fma_f32 v[124:125], s[12:13], v[150:151], v[124:125] op_sel_hi:[0,1,1]
	v_cvt_pk_f32_fp8_e32 v[150:151], v10
	v_cvt_pk_f32_fp8_e32 v[194:195], v24
	v_cvt_pk_f32_fp8_sdwa v[196:197], v24 src0_sel:WORD_1
	v_cvt_pk_f32_fp8_e32 v[198:199], v25
	v_cvt_pk_f32_fp8_sdwa v[24:25], v25 src0_sel:WORD_1
	v_pk_fma_f32 v[116:117], s[14:15], v[148:149], v[116:117] op_sel_hi:[0,1,1]
	v_pk_fma_f32 v[4:5], s[14:15], v[8:9], v[4:5] op_sel_hi:[0,1,1]
	v_cvt_pk_f32_fp8_e32 v[164:165], v14
	v_cvt_pk_f32_fp8_e32 v[206:207], v28
	v_cvt_pk_f32_fp8_sdwa v[208:209], v28 src0_sel:WORD_1
	v_cvt_pk_f32_fp8_e32 v[210:211], v29
	v_cvt_pk_f32_fp8_sdwa v[28:29], v29 src0_sel:WORD_1
	v_pk_fma_f32 v[116:117], s[16:17], v[160:161], v[116:117] op_sel_hi:[0,1,1]
	v_pk_fma_f32 v[4:5], s[16:17], v[12:13], v[4:5] op_sel_hi:[0,1,1]
	v_cvt_pk_f32_fp8_e32 v[176:177], v18
	v_cvt_pk_f32_fp8_e32 v[218:219], v32
	v_cvt_pk_f32_fp8_sdwa v[220:221], v32 src0_sel:WORD_1
	v_pk_fma_f32 v[112:113], s[14:15], v[118:119], v[112:113] op_sel_hi:[0,1,1]
	v_cvt_pk_f32_fp8_e32 v[118:119], v33
	v_cvt_pk_f32_fp8_sdwa v[32:33], v33 src0_sel:WORD_1
	v_pk_fma_f32 v[116:117], s[18:19], v[174:175], v[116:117] op_sel_hi:[0,1,1]
	v_pk_fma_f32 v[4:5], s[18:19], v[16:17], v[4:5] op_sel_hi:[0,1,1]
	v_cvt_pk_f32_fp8_e32 v[188:189], v22
	v_pk_fma_f32 v[116:117], s[20:21], v[186:187], v[116:117] op_sel_hi:[0,1,1]
	v_pk_fma_f32 v[4:5], s[20:21], v[20:21], v[4:5] op_sel_hi:[0,1,1]
	v_cvt_pk_f32_fp8_e32 v[200:201], v26
	v_pk_fma_f32 v[116:117], s[22:23], v[198:199], v[116:117] op_sel_hi:[0,1,1]
	v_pk_fma_f32 v[4:5], s[22:23], v[24:25], v[4:5] op_sel_hi:[0,1,1]
	v_pk_fma_f32 v[12:13], s[14:15], v[150:151], v[120:121] op_sel_hi:[0,1,1]
	v_cvt_pk_f32_fp8_e32 v[212:213], v30
	v_pk_fma_f32 v[116:117], s[24:25], v[210:211], v[116:117] op_sel_hi:[0,1,1]
	v_pk_fma_f32 v[4:5], s[24:25], v[28:29], v[4:5] op_sel_hi:[0,1,1]
	v_pk_fma_f32 v[12:13], s[16:17], v[164:165], v[12:13] op_sel_hi:[0,1,1]
	v_cvt_pk_f32_fp8_sdwa v[152:153], v10 src0_sel:WORD_1
	v_pk_fma_f32 v[116:117], s[26:27], v[118:119], v[116:117] op_sel_hi:[0,1,1]
	v_pk_fma_f32 v[118:119], s[26:27], v[32:33], v[4:5] op_sel_hi:[0,1,1]
	v_cvt_pk_f32_fp8_e32 v[4:5], v34
	v_pk_fma_f32 v[12:13], s[18:19], v[176:177], v[12:13] op_sel_hi:[0,1,1]
	v_cvt_pk_f32_fp8_sdwa v[166:167], v14 src0_sel:WORD_1
	v_pk_fma_f32 v[12:13], s[20:21], v[188:189], v[12:13] op_sel_hi:[0,1,1]
	v_cvt_pk_f32_fp8_sdwa v[178:179], v18 src0_sel:WORD_1
	v_pk_fma_f32 v[12:13], s[22:23], v[200:201], v[12:13] op_sel_hi:[0,1,1]
	v_cvt_pk_f32_fp8_sdwa v[190:191], v22 src0_sel:WORD_1
	v_pk_fma_f32 v[12:13], s[24:25], v[212:213], v[12:13] op_sel_hi:[0,1,1]
	v_cvt_pk_f32_fp8_e32 v[154:155], v11
	v_cvt_pk_f32_fp8_sdwa v[202:203], v26 src0_sel:WORD_1
	v_pk_fma_f32 v[120:121], s[26:27], v[4:5], v[12:13] op_sel_hi:[0,1,1]
	v_pk_fma_f32 v[4:5], s[14:15], v[152:153], v[122:123] op_sel_hi:[0,1,1]
	v_cvt_pk_f32_fp8_e32 v[168:169], v15
	v_cvt_pk_f32_fp8_sdwa v[214:215], v30 src0_sel:WORD_1
	v_pk_fma_f32 v[4:5], s[16:17], v[166:167], v[4:5] op_sel_hi:[0,1,1]
	v_cvt_pk_f32_fp8_e32 v[180:181], v19
	v_cvt_pk_f32_fp8_sdwa v[8:9], v34 src0_sel:WORD_1
	v_pk_fma_f32 v[4:5], s[18:19], v[178:179], v[4:5] op_sel_hi:[0,1,1]
	v_cvt_pk_f32_fp8_e32 v[192:193], v23
	v_pk_fma_f32 v[4:5], s[20:21], v[190:191], v[4:5] op_sel_hi:[0,1,1]
	v_cvt_pk_f32_fp8_e32 v[204:205], v27
	v_pk_fma_f32 v[4:5], s[22:23], v[202:203], v[4:5] op_sel_hi:[0,1,1]
	v_pk_fma_f32 v[12:13], s[14:15], v[154:155], v[124:125] op_sel_hi:[0,1,1]
	v_cvt_pk_f32_fp8_e32 v[216:217], v31
	v_pk_fma_f32 v[4:5], s[24:25], v[214:215], v[4:5] op_sel_hi:[0,1,1]
	v_pk_fma_f32 v[12:13], s[16:17], v[168:169], v[12:13] op_sel_hi:[0,1,1]
	v_cvt_pk_f32_fp8_sdwa v[10:11], v11 src0_sel:WORD_1
	v_pk_fma_f32 v[122:123], s[26:27], v[8:9], v[4:5] op_sel_hi:[0,1,1]
	v_cvt_pk_f32_fp8_e32 v[4:5], v35
	v_pk_fma_f32 v[12:13], s[18:19], v[180:181], v[12:13] op_sel_hi:[0,1,1]
; #define AS1 __attribute__((address_space(1)))
; DI void axpy16_fp8(float* o, float w, u32x4 u) {
;   const unsigned d[4] = {u[0], u[1], u[2], u[3]};
; #pragma unroll
;   for (int i = 0; i < 4; ++i) {
;     f32x2 a = __builtin_amdgcn_cvt_pk_f32_fp8((int)d[i], false);
;     f32x2 b = __builtin_amdgcn_cvt_pk_f32_fp8((int)d[i], true);
;     o[4 * i] += w * a[0]; o[4 * i + 1] += w * a[1]; o[4 * i + 2] += w * b[0]; o[4 * i + 3] += w * b[1];
;   }
; }
; DI void peer_v_group(const Params& p, int gw, int nw, int g, const float* wlw  ) {
;     ...
;         float we[8];
; #pragma unroll
;         for (int k = 0; k < 8; ++k) {
;           we[k] = 0.f;
;           v[k] = (u32x4){0u, 0u, 0u, 0u};
;           if ((m0 | m1) != 0ull) {
;             int l, id;
;             if (m0 != 0ull) {
;               l = __builtin_ctzll(m0); m0 &= m0 - 1ull;
;               id = __builtin_amdgcn_readlane(e0[ts], l);
;               we[k] = __int_as_float(__builtin_amdgcn_readlane(__float_as_int(w0[ts]), l));
;             } else {
;               l = __builtin_ctzll(m1); m1 &= m1 - 1ull;
;               id = __builtin_amdgcn_readlane(e1[ts], l);
;               we[k] = __int_as_float(__builtin_amdgcn_readlane(__float_as_int(w1[ts]), l));
;             }
;             v[k] = *(const u32x4 AS1*)(EV8 + (size_t)id * 1024 + lane * 16);
;           }
;         }
; #pragma unroll
;         for (int k = 0; k < 8; ++k) axpy16_fp8(out[ts], we[k], v[k]);
	v_cvt_pk_f32_fp8_sdwa v[14:15], v15 src0_sel:WORD_1
	v_pk_fma_f32 v[12:13], s[20:21], v[192:193], v[12:13] op_sel_hi:[0,1,1]
	v_cvt_pk_f32_fp8_sdwa v[18:19], v19 src0_sel:WORD_1
	v_pk_fma_f32 v[12:13], s[22:23], v[204:205], v[12:13] op_sel_hi:[0,1,1]
	v_cvt_pk_f32_fp8_sdwa v[22:23], v23 src0_sel:WORD_1
	v_pk_fma_f32 v[12:13], s[24:25], v[216:217], v[12:13] op_sel_hi:[0,1,1]
	v_cvt_pk_f32_fp8_sdwa v[26:27], v27 src0_sel:WORD_1
	v_pk_fma_f32 v[114:115], s[14:15], v[126:127], v[114:115] op_sel_hi:[0,1,1]
	v_pk_fma_f32 v[124:125], s[26:27], v[4:5], v[12:13] op_sel_hi:[0,1,1]
	v_pk_fma_f32 v[4:5], s[14:15], v[10:11], v[6:7] op_sel_hi:[0,1,1]
	v_cvt_pk_f32_fp8_sdwa v[30:31], v31 src0_sel:WORD_1
	v_pk_fma_f32 v[112:113], s[16:17], v[156:157], v[112:113] op_sel_hi:[0,1,1]
	v_pk_fma_f32 v[114:115], s[16:17], v[158:159], v[114:115] op_sel_hi:[0,1,1]
	v_pk_fma_f32 v[4:5], s[16:17], v[14:15], v[4:5] op_sel_hi:[0,1,1]
	v_pk_fma_f32 v[112:113], s[18:19], v[170:171], v[112:113] op_sel_hi:[0,1,1]
	v_pk_fma_f32 v[114:115], s[18:19], v[172:173], v[114:115] op_sel_hi:[0,1,1]
	v_cvt_pk_f32_fp8_sdwa v[8:9], v35 src0_sel:WORD_1
	v_pk_fma_f32 v[4:5], s[18:19], v[18:19], v[4:5] op_sel_hi:[0,1,1]
	v_pk_fma_f32 v[112:113], s[20:21], v[182:183], v[112:113] op_sel_hi:[0,1,1]
	v_pk_fma_f32 v[114:115], s[20:21], v[184:185], v[114:115] op_sel_hi:[0,1,1]
	v_pk_fma_f32 v[4:5], s[20:21], v[22:23], v[4:5] op_sel_hi:[0,1,1]
	v_pk_fma_f32 v[112:113], s[22:23], v[194:195], v[112:113] op_sel_hi:[0,1,1]
	v_pk_fma_f32 v[114:115], s[22:23], v[196:197], v[114:115] op_sel_hi:[0,1,1]
	v_pk_fma_f32 v[4:5], s[22:23], v[26:27], v[4:5] op_sel_hi:[0,1,1]
	v_pk_fma_f32 v[112:113], s[24:25], v[206:207], v[112:113] op_sel_hi:[0,1,1]
	v_pk_fma_f32 v[114:115], s[24:25], v[208:209], v[114:115] op_sel_hi:[0,1,1]
	v_pk_fma_f32 v[4:5], s[24:25], v[30:31], v[4:5] op_sel_hi:[0,1,1]
	s_or_b64 s[14:15], s[10:11], s[6:7]
	v_pk_fma_f32 v[112:113], s[26:27], v[218:219], v[112:113] op_sel_hi:[0,1,1]
	v_pk_fma_f32 v[114:115], s[26:27], v[220:221], v[114:115] op_sel_hi:[0,1,1]
	s_cmp_lg_u64 s[14:15], 0
	v_pk_fma_f32 v[126:127], s[26:27], v[8:9], v[4:5] op_sel_hi:[0,1,1]
	s_cmp_eq_u64 s[60:61], 0
	s_cbranch_scc1 .Lvb_skip0
	v_cvt_pk_f32_fp8_e32 v[148:149], v222
	v_cvt_pk_f32_fp8_sdwa v[150:151], v222 src0_sel:WORD_1
	v_cvt_pk_f32_fp8_e32 v[152:153], v223
	v_cvt_pk_f32_fp8_sdwa v[222:223], v223 src0_sel:WORD_1
	v_pk_fma_f32 v[112:113], s[42:43], v[148:149], v[112:113] op_sel_hi:[0,1,1]
	v_pk_fma_f32 v[114:115], s[42:43], v[150:151], v[114:115] op_sel_hi:[0,1,1]
	v_cvt_pk_f32_fp8_sdwa v[148:149], v224 src0_sel:WORD_1
	v_pk_fma_f32 v[222:223], s[42:43], v[222:223], v[118:119] op_sel_hi:[0,1,1]
	v_cvt_pk_f32_fp8_e32 v[118:119], v224
	v_cvt_pk_f32_fp8_e32 v[150:151], v225
	v_cvt_pk_f32_fp8_sdwa v[224:225], v225 src0_sel:WORD_1
	v_pk_fma_f32 v[122:123], s[42:43], v[148:149], v[122:123] op_sel_hi:[0,1,1]
	v_pk_fma_f32 v[120:121], s[42:43], v[118:119], v[120:121] op_sel_hi:[0,1,1]
	v_cvt_pk_f32_fp8_e32 v[118:119], v226
	v_pk_fma_f32 v[224:225], s[42:43], v[224:225], v[126:127] op_sel_hi:[0,1,1]
	v_cvt_pk_f32_fp8_sdwa v[126:127], v226 src0_sel:WORD_1
	v_cvt_pk_f32_fp8_e32 v[148:149], v227
	v_cvt_pk_f32_fp8_sdwa v[226:227], v227 src0_sel:WORD_1
	v_cvt_pk_f32_fp8_e32 v[156:157], v230
	v_cvt_pk_f32_fp8_sdwa v[158:159], v230 src0_sel:WORD_1
	v_cvt_pk_f32_fp8_e32 v[160:161], v231
	v_cvt_pk_f32_fp8_sdwa v[230:231], v231 src0_sel:WORD_1
	v_cvt_pk_f32_fp8_e32 v[170:171], v234
	v_cvt_pk_f32_fp8_sdwa v[172:173], v234 src0_sel:WORD_1
	v_cvt_pk_f32_fp8_e32 v[174:175], v235
	v_cvt_pk_f32_fp8_sdwa v[234:235], v235 src0_sel:WORD_1
	v_pk_fma_f32 v[116:117], s[42:43], v[152:153], v[116:117] op_sel_hi:[0,1,1]
	v_cvt_pk_f32_fp8_e32 v[182:183], v238
	v_cvt_pk_f32_fp8_sdwa v[184:185], v238 src0_sel:WORD_1
	v_cvt_pk_f32_fp8_e32 v[186:187], v239
	v_cvt_pk_f32_fp8_sdwa v[238:239], v239 src0_sel:WORD_1
	v_pk_fma_f32 v[124:125], s[42:43], v[150:151], v[124:125] op_sel_hi:[0,1,1]
	v_cvt_pk_f32_fp8_e32 v[150:151], v228
	v_cvt_pk_f32_fp8_e32 v[194:195], v242
	v_cvt_pk_f32_fp8_sdwa v[196:197], v242 src0_sel:WORD_1
	v_cvt_pk_f32_fp8_e32 v[198:199], v243
	v_cvt_pk_f32_fp8_sdwa v[242:243], v243 src0_sel:WORD_1
	v_pk_fma_f32 v[116:117], s[44:45], v[148:149], v[116:117] op_sel_hi:[0,1,1]
	v_pk_fma_f32 v[222:223], s[44:45], v[226:227], v[222:223] op_sel_hi:[0,1,1]
	v_cvt_pk_f32_fp8_e32 v[164:165], v232
	v_cvt_pk_f32_fp8_e32 v[206:207], v246
	v_cvt_pk_f32_fp8_sdwa v[208:209], v246 src0_sel:WORD_1
	v_cvt_pk_f32_fp8_e32 v[210:211], v247
	v_cvt_pk_f32_fp8_sdwa v[246:247], v247 src0_sel:WORD_1
	v_pk_fma_f32 v[116:117], s[46:47], v[160:161], v[116:117] op_sel_hi:[0,1,1]
	v_pk_fma_f32 v[222:223], s[46:47], v[230:231], v[222:223] op_sel_hi:[0,1,1]
	v_cvt_pk_f32_fp8_e32 v[176:177], v236
	v_cvt_pk_f32_fp8_e32 v[218:219], v250
	v_cvt_pk_f32_fp8_sdwa v[220:221], v250 src0_sel:WORD_1
	v_pk_fma_f32 v[112:113], s[44:45], v[118:119], v[112:113] op_sel_hi:[0,1,1]
	v_cvt_pk_f32_fp8_e32 v[118:119], v251
	v_cvt_pk_f32_fp8_sdwa v[250:251], v251 src0_sel:WORD_1
	v_pk_fma_f32 v[116:117], s[48:49], v[174:175], v[116:117] op_sel_hi:[0,1,1]
; #define AS1 __attribute__((address_space(1)))
; DI void axpy16_fp8(float* o, float w, u32x4 u) {
;   const unsigned d[4] = {u[0], u[1], u[2], u[3]};
; #pragma unroll
;   for (int i = 0; i < 4; ++i) {
;     f32x2 a = __builtin_amdgcn_cvt_pk_f32_fp8((int)d[i], false);
;     f32x2 b = __builtin_amdgcn_cvt_pk_f32_fp8((int)d[i], true);
;     o[4 * i] += w * a[0]; o[4 * i + 1] += w * a[1]; o[4 * i + 2] += w * b[0]; o[4 * i + 3] += w * b[1];
;   }
; }
; DI void peer_v_group(const Params& p, int gw, int nw, int g, const float* wlw  ) {
;     ...
;       while ((m0 | m1) != 0ull) {
;         u32x4 v[8];
;         float we[8];
; #pragma unroll
;         for (int k = 0; k < 8; ++k) {
;           we[k] = 0.f;
;           v[k] = (u32x4){0u, 0u, 0u, 0u};
;           if ((m0 | m1) != 0ull) {
;             int l, id;
;             if (m0 != 0ull) {
;               l = __builtin_ctzll(m0); m0 &= m0 - 1ull;
;               id = __builtin_amdgcn_readlane(e0[ts], l);
;               we[k] = __int_as_float(__builtin_amdgcn_readlane(__float_as_int(w0[ts]), l));
;             } else {
;               l = __builtin_ctzll(m1); m1 &= m1 - 1ull;
;               id = __builtin_amdgcn_readlane(e1[ts], l);
;               we[k] = __int_as_float(__builtin_amdgcn_readlane(__float_as_int(w1[ts]), l));
;             }
;             v[k] = *(const u32x4 AS1*)(EV8 + (size_t)id * 1024 + lane * 16);
;           }
;         }
; #pragma unroll
;         for (int k = 0; k < 8; ++k) axpy16_fp8(out[ts], we[k], v[k]);
	v_pk_fma_f32 v[222:223], s[48:49], v[234:235], v[222:223] op_sel_hi:[0,1,1]
	v_cvt_pk_f32_fp8_e32 v[188:189], v240
	v_pk_fma_f32 v[116:117], s[50:51], v[186:187], v[116:117] op_sel_hi:[0,1,1]
	v_pk_fma_f32 v[222:223], s[50:51], v[238:239], v[222:223] op_sel_hi:[0,1,1]
	v_cvt_pk_f32_fp8_e32 v[200:201], v244
	v_pk_fma_f32 v[116:117], s[52:53], v[198:199], v[116:117] op_sel_hi:[0,1,1]
	v_pk_fma_f32 v[222:223], s[52:53], v[242:243], v[222:223] op_sel_hi:[0,1,1]
	v_pk_fma_f32 v[230:231], s[44:45], v[150:151], v[120:121] op_sel_hi:[0,1,1]
	v_cvt_pk_f32_fp8_e32 v[212:213], v248
	v_pk_fma_f32 v[116:117], s[54:55], v[210:211], v[116:117] op_sel_hi:[0,1,1]
	v_pk_fma_f32 v[222:223], s[54:55], v[246:247], v[222:223] op_sel_hi:[0,1,1]
	v_pk_fma_f32 v[230:231], s[46:47], v[164:165], v[230:231] op_sel_hi:[0,1,1]
	v_cvt_pk_f32_fp8_sdwa v[152:153], v228 src0_sel:WORD_1
	v_pk_fma_f32 v[116:117], s[56:57], v[118:119], v[116:117] op_sel_hi:[0,1,1]
	v_pk_fma_f32 v[118:119], s[56:57], v[250:251], v[222:223] op_sel_hi:[0,1,1]
	v_cvt_pk_f32_fp8_e32 v[222:223], v252
	v_pk_fma_f32 v[230:231], s[48:49], v[176:177], v[230:231] op_sel_hi:[0,1,1]
	v_cvt_pk_f32_fp8_sdwa v[166:167], v232 src0_sel:WORD_1
	v_pk_fma_f32 v[230:231], s[50:51], v[188:189], v[230:231] op_sel_hi:[0,1,1]
	v_cvt_pk_f32_fp8_sdwa v[178:179], v236 src0_sel:WORD_1
	v_pk_fma_f32 v[230:231], s[52:53], v[200:201], v[230:231] op_sel_hi:[0,1,1]
	v_cvt_pk_f32_fp8_sdwa v[190:191], v240 src0_sel:WORD_1
	v_pk_fma_f32 v[230:231], s[54:55], v[212:213], v[230:231] op_sel_hi:[0,1,1]
	v_cvt_pk_f32_fp8_e32 v[154:155], v229
	v_cvt_pk_f32_fp8_sdwa v[202:203], v244 src0_sel:WORD_1
	v_pk_fma_f32 v[120:121], s[56:57], v[222:223], v[230:231] op_sel_hi:[0,1,1]
	v_pk_fma_f32 v[222:223], s[44:45], v[152:153], v[122:123] op_sel_hi:[0,1,1]
	v_cvt_pk_f32_fp8_e32 v[168:169], v233
	v_cvt_pk_f32_fp8_sdwa v[214:215], v248 src0_sel:WORD_1
	v_pk_fma_f32 v[222:223], s[46:47], v[166:167], v[222:223] op_sel_hi:[0,1,1]
	v_cvt_pk_f32_fp8_e32 v[180:181], v237
	v_cvt_pk_f32_fp8_sdwa v[226:227], v252 src0_sel:WORD_1
	v_pk_fma_f32 v[222:223], s[48:49], v[178:179], v[222:223] op_sel_hi:[0,1,1]
	v_cvt_pk_f32_fp8_e32 v[192:193], v241
	v_pk_fma_f32 v[222:223], s[50:51], v[190:191], v[222:223] op_sel_hi:[0,1,1]
	v_cvt_pk_f32_fp8_e32 v[204:205], v245
	v_pk_fma_f32 v[222:223], s[52:53], v[202:203], v[222:223] op_sel_hi:[0,1,1]
	v_pk_fma_f32 v[230:231], s[44:45], v[154:155], v[124:125] op_sel_hi:[0,1,1]
	v_cvt_pk_f32_fp8_e32 v[216:217], v249
	v_pk_fma_f32 v[222:223], s[54:55], v[214:215], v[222:223] op_sel_hi:[0,1,1]
	v_pk_fma_f32 v[230:231], s[46:47], v[168:169], v[230:231] op_sel_hi:[0,1,1]
	v_cvt_pk_f32_fp8_sdwa v[228:229], v229 src0_sel:WORD_1
	v_pk_fma_f32 v[122:123], s[56:57], v[226:227], v[222:223] op_sel_hi:[0,1,1]
	v_cvt_pk_f32_fp8_e32 v[222:223], v253
	v_pk_fma_f32 v[230:231], s[48:49], v[180:181], v[230:231] op_sel_hi:[0,1,1]
	v_cvt_pk_f32_fp8_sdwa v[232:233], v233 src0_sel:WORD_1
	v_pk_fma_f32 v[230:231], s[50:51], v[192:193], v[230:231] op_sel_hi:[0,1,1]
	v_cvt_pk_f32_fp8_sdwa v[236:237], v237 src0_sel:WORD_1
	v_pk_fma_f32 v[230:231], s[52:53], v[204:205], v[230:231] op_sel_hi:[0,1,1]
	v_cvt_pk_f32_fp8_sdwa v[240:241], v241 src0_sel:WORD_1
	v_pk_fma_f32 v[230:231], s[54:55], v[216:217], v[230:231] op_sel_hi:[0,1,1]
	v_cvt_pk_f32_fp8_sdwa v[244:245], v245 src0_sel:WORD_1
	v_pk_fma_f32 v[114:115], s[44:45], v[126:127], v[114:115] op_sel_hi:[0,1,1]
	v_pk_fma_f32 v[124:125], s[56:57], v[222:223], v[230:231] op_sel_hi:[0,1,1]
	v_pk_fma_f32 v[222:223], s[44:45], v[228:229], v[224:225] op_sel_hi:[0,1,1]
	v_cvt_pk_f32_fp8_sdwa v[248:249], v249 src0_sel:WORD_1
	v_pk_fma_f32 v[112:113], s[46:47], v[156:157], v[112:113] op_sel_hi:[0,1,1]
	v_pk_fma_f32 v[114:115], s[46:47], v[158:159], v[114:115] op_sel_hi:[0,1,1]
	v_pk_fma_f32 v[222:223], s[46:47], v[232:233], v[222:223] op_sel_hi:[0,1,1]
	v_pk_fma_f32 v[112:113], s[48:49], v[170:171], v[112:113] op_sel_hi:[0,1,1]
	v_pk_fma_f32 v[114:115], s[48:49], v[172:173], v[114:115] op_sel_hi:[0,1,1]
	v_cvt_pk_f32_fp8_sdwa v[226:227], v253 src0_sel:WORD_1
	v_pk_fma_f32 v[222:223], s[48:49], v[236:237], v[222:223] op_sel_hi:[0,1,1]
	v_pk_fma_f32 v[112:113], s[50:51], v[182:183], v[112:113] op_sel_hi:[0,1,1]
	v_pk_fma_f32 v[114:115], s[50:51], v[184:185], v[114:115] op_sel_hi:[0,1,1]
	v_pk_fma_f32 v[222:223], s[50:51], v[240:241], v[222:223] op_sel_hi:[0,1,1]
	v_pk_fma_f32 v[112:113], s[52:53], v[194:195], v[112:113] op_sel_hi:[0,1,1]
	v_pk_fma_f32 v[114:115], s[52:53], v[196:197], v[114:115] op_sel_hi:[0,1,1]
	v_pk_fma_f32 v[222:223], s[52:53], v[244:245], v[222:223] op_sel_hi:[0,1,1]
	v_pk_fma_f32 v[112:113], s[54:55], v[206:207], v[112:113] op_sel_hi:[0,1,1]
	v_pk_fma_f32 v[114:115], s[54:55], v[208:209], v[114:115] op_sel_hi:[0,1,1]
	v_pk_fma_f32 v[222:223], s[54:55], v[248:249], v[222:223] op_sel_hi:[0,1,1]
	v_pk_fma_f32 v[112:113], s[56:57], v[218:219], v[112:113] op_sel_hi:[0,1,1]
	v_pk_fma_f32 v[114:115], s[56:57], v[220:221], v[114:115] op_sel_hi:[0,1,1]
	v_pk_fma_f32 v[126:127], s[56:57], v[226:227], v[222:223] op_sel_hi:[0,1,1]
.Lvb_skip0:
	s_or_b64 s[14:15], s[10:11], s[6:7]
	s_cmp_lg_u64 s[14:15], 0
	s_cbranch_scc0 .LBB0_1369

; #define AS1 __attribute__((address_space(1)))
; DI void peer_v_group(const Params& p, int gw, int nw, int g, const float* wlw  ) {
;     ...
;       while ((m0 | m1) != 0ull) {
;         u32x4 v[8];
;         float we[8];
; #pragma unroll
;         for (int k = 0; k < 8; ++k) {
;           we[k] = 0.f;
;           v[k] = (u32x4){0u, 0u, 0u, 0u};
;           if ((m0 | m1) != 0ull) {
;             int l, id;
;             if (m0 != 0ull) {
;               l = __builtin_ctzll(m0); m0 &= m0 - 1ull;
;               id = __builtin_amdgcn_readlane(e0[ts], l);
;               we[k] = __int_as_float(__builtin_amdgcn_readlane(__float_as_int(w0[ts]), l));
;             } else {
;               l = __builtin_ctzll(m1); m1 &= m1 - 1ull;
;               id = __builtin_amdgcn_readlane(e1[ts], l);
;               we[k] = __int_as_float(__builtin_amdgcn_readlane(__float_as_int(w1[ts]), l));
;             }
;             v[k] = *(const u32x4 AS1*)(EV8 + (size_t)id * 1024 + lane * 16);
;           }
.Lvb_z0:
	v_mov_b32_e32 v253, 0
	s_mov_b32 s56, 0
	v_mov_b32_e32 v252, v253
	v_mov_b32_e32 v251, v253
	v_mov_b32_e32 v250, v253
	s_branch .LBB0_1373
.Lvb_g0:
	s_or_b64 s[60:61], s[6:7], s[10:11]
	s_or_b64 s[44:45], s[6:7], s[10:11]
	s_cmp_eq_u64 s[44:45], 0
	s_cbranch_scc1 .Lvb0_1388
	s_cmp_eq_u64 s[10:11], 0
	s_cbranch_scc1 .Lvb0_1414
	s_add_u32 s44, s10, -1
	s_ff1_i32_b64 s42, s[10:11]
	s_addc_u32 s45, s11, -1
	s_and_b64 s[10:11], s[44:45], s[10:11]
	v_readlane_b32 s44, v135, s42
	s_waitcnt lgkmcnt(0)
	v_readlane_b32 s42, v104, s42
	s_cbranch_execnz .Lvb0_1378
.Lvb0_1377:
	s_add_u32 s10, s6, -1
	s_ff1_i32_b64 s42, s[6:7]
	s_addc_u32 s11, s7, -1
	s_and_b64 s[6:7], s[10:11], s[6:7]
	v_readlane_b32 s44, v136, s42
	s_waitcnt lgkmcnt(0)
	v_readlane_b32 s42, v105, s42
	s_mov_b64 s[10:11], 0
.Lvb0_1378:
	s_ashr_i32 s45, s44, 31
	s_lshl_b64 s[44:45], s[44:45], 10
	v_lshl_add_u64 v[222:223], v[40:41], 0, s[44:45]
	global_load_dwordx4 v[222:225], v[222:223], off
	s_or_b64 s[44:45], s[10:11], s[6:7]
	s_cmp_eq_u64 s[44:45], 0
	s_cselect_b64 s[44:45], -1, 0
	s_and_b64 vcc, exec, s[44:45]
	s_cbranch_vccnz .Lvb0_1389
.Lvb0_1379:
	s_cmp_eq_u64 s[10:11], 0
	s_cbranch_scc1 .Lvb0_1415
	s_add_u32 s44, s10, -1
	s_ff1_i32_b64 s47, s[10:11]
	s_addc_u32 s45, s11, -1
	s_and_b64 s[10:11], s[44:45], s[10:11]
	v_readlane_b32 s46, v135, s47
	s_waitcnt lgkmcnt(0)
	v_readlane_b32 s44, v104, s47
	s_cbranch_execnz .Lvb0_1382
.Lvb0_1381:
	s_add_u32 s10, s6, -1
	s_ff1_i32_b64 s44, s[6:7]
	s_addc_u32 s11, s7, -1
	s_and_b64 s[6:7], s[10:11], s[6:7]
	v_readlane_b32 s46, v136, s44
	s_waitcnt lgkmcnt(0)
	v_readlane_b32 s44, v105, s44
	s_mov_b64 s[10:11], 0
.Lvb0_1382:
	s_ashr_i32 s47, s46, 31
	s_lshl_b64 s[46:47], s[46:47], 10
	v_lshl_add_u64 v[226:227], v[40:41], 0, s[46:47]
	global_load_dwordx4 v[226:229], v[226:227], off
	s_or_b64 s[46:47], s[10:11], s[6:7]
	s_cmp_eq_u64 s[46:47], 0
	s_cselect_b64 s[46:47], -1, 0
	s_and_b64 vcc, exec, s[46:47]
	s_cbranch_vccz .Lvb0_1390
.Lvb0_1383:
	v_mov_b32_e32 v233, 0
	s_mov_b32 s46, 0
	v_mov_b32_e32 v232, v233
	v_mov_b32_e32 v231, v233
	v_mov_b32_e32 v230, v233
	s_cbranch_execz .Lvb0_1394
.Lvb0_1384:
	v_mov_b32_e32 v237, 0
	s_mov_b32 s48, 0
	v_mov_b32_e32 v236, v237
	v_mov_b32_e32 v235, v237
	v_mov_b32_e32 v234, v237
	s_cbranch_execz .Lvb0_1398
.Lvb0_1385:
	v_mov_b32_e32 v241, 0
	s_mov_b32 s50, 0
	v_mov_b32_e32 v240, v241
	v_mov_b32_e32 v239, v241
	v_mov_b32_e32 v238, v241
	s_cbranch_execz .Lvb0_1402
.Lvb0_1386:
	v_mov_b32_e32 v245, 0
	s_mov_b32 s52, 0
	v_mov_b32_e32 v244, v245
	v_mov_b32_e32 v243, v245
	v_mov_b32_e32 v242, v245
	s_cbranch_execz .Lvb0_1406
.Lvb0_1387:
	v_mov_b32_e32 v249, 0
	s_mov_b32 s54, 0
	v_mov_b32_e32 v248, v249
	v_mov_b32_e32 v247, v249
	v_mov_b32_e32 v246, v249
	s_cbranch_execnz .Lvb_z0
	s_branch .Lvb0_1410
.Lvb0_1388:
	v_mov_b32_e32 v225, 0
	s_mov_b32 s42, 0
	v_mov_b32_e32 v224, v225
	v_mov_b32_e32 v223, v225
	v_mov_b32_e32 v222, v225
	s_cbranch_execz .Lvb0_1379
.Lvb0_1389:
	v_mov_b32_e32 v229, 0
	s_mov_b32 s44, 0
	v_mov_b32_e32 v228, v229
	v_mov_b32_e32 v227, v229
	v_mov_b32_e32 v226, v229
	s_cbranch_execnz .Lvb0_1383
.Lvb0_1390:
	s_cmp_eq_u64 s[10:11], 0
	s_cbranch_scc1 .Lvb0_1416
	s_add_u32 s46, s10, -1
	s_ff1_i32_b64 s45, s[10:11]
	s_addc_u32 s47, s11, -1
	s_and_b64 s[10:11], s[46:47], s[10:11]
	v_readlane_b32 s48, v135, s45
	s_waitcnt lgkmcnt(0)
	v_readlane_b32 s46, v104, s45
	s_cbranch_execnz .Lvb0_1393
.Lvb0_1392:
	s_add_u32 s10, s6, -1
	s_ff1_i32_b64 s45, s[6:7]
	s_addc_u32 s11, s7, -1
	s_and_b64 s[6:7], s[10:11], s[6:7]
	v_readlane_b32 s48, v136, s45
	s_waitcnt lgkmcnt(0)
	v_readlane_b32 s46, v105, s45
	s_mov_b64 s[10:11], 0
.Lvb0_1393:
	s_ashr_i32 s49, s48, 31
	s_lshl_b64 s[48:49], s[48:49], 10
	v_lshl_add_u64 v[230:231], v[40:41], 0, s[48:49]
	global_load_dwordx4 v[230:233], v[230:231], off
	s_or_b64 s[48:49], s[10:11], s[6:7]
	s_cmp_eq_u64 s[48:49], 0
	s_cselect_b64 s[48:49], -1, 0
	s_and_b64 vcc, exec, s[48:49]
	s_cbranch_vccnz .Lvb0_1384
; #define AS1 __attribute__((address_space(1)))
; DI void peer_v_group(const Params& p, int gw, int nw, int g, const float* wlw  ) {
;     ...
;       while ((m0 | m1) != 0ull) {
;         u32x4 v[8];
;         float we[8];
; #pragma unroll
;         for (int k = 0; k < 8; ++k) {
;           we[k] = 0.f;
;           v[k] = (u32x4){0u, 0u, 0u, 0u};
;           if ((m0 | m1) != 0ull) {
;             int l, id;
;             if (m0 != 0ull) {
;               l = __builtin_ctzll(m0); m0 &= m0 - 1ull;
;               id = __builtin_amdgcn_readlane(e0[ts], l);
;               we[k] = __int_as_float(__builtin_amdgcn_readlane(__float_as_int(w0[ts]), l));
;             } else {
;               l = __builtin_ctzll(m1); m1 &= m1 - 1ull;
;               id = __builtin_amdgcn_readlane(e1[ts], l);
;               we[k] = __int_as_float(__builtin_amdgcn_readlane(__float_as_int(w1[ts]), l));
;             }
;             v[k] = *(const u32x4 AS1*)(EV8 + (size_t)id * 1024 + lane * 16);
;           }
.Lvb0_1394:
	s_cmp_eq_u64 s[10:11], 0
	s_cbranch_scc1 .Lvb0_1417
	s_add_u32 s48, s10, -1
	s_ff1_i32_b64 s45, s[10:11]
	s_addc_u32 s49, s11, -1
	s_and_b64 s[10:11], s[48:49], s[10:11]
	v_readlane_b32 s50, v135, s45
	s_waitcnt lgkmcnt(0)
	v_readlane_b32 s48, v104, s45
	s_cbranch_execnz .Lvb0_1397
.Lvb0_1396:
	s_add_u32 s10, s6, -1
	s_ff1_i32_b64 s45, s[6:7]
	s_addc_u32 s11, s7, -1
	s_and_b64 s[6:7], s[10:11], s[6:7]
	v_readlane_b32 s50, v136, s45
	s_waitcnt lgkmcnt(0)
	v_readlane_b32 s48, v105, s45
	s_mov_b64 s[10:11], 0
.Lvb0_1397:
	s_ashr_i32 s51, s50, 31
	s_lshl_b64 s[50:51], s[50:51], 10
	v_lshl_add_u64 v[234:235], v[40:41], 0, s[50:51]
	global_load_dwordx4 v[234:237], v[234:235], off
	s_or_b64 s[50:51], s[10:11], s[6:7]
	s_cmp_eq_u64 s[50:51], 0
	s_cselect_b64 s[50:51], -1, 0
	s_and_b64 vcc, exec, s[50:51]
	s_cbranch_vccnz .Lvb0_1385
.Lvb0_1398:
	s_cmp_eq_u64 s[10:11], 0
	s_cbranch_scc1 .Lvb0_1418
	s_add_u32 s50, s10, -1
	s_ff1_i32_b64 s45, s[10:11]
	s_addc_u32 s51, s11, -1
	s_and_b64 s[10:11], s[50:51], s[10:11]
	v_readlane_b32 s52, v135, s45
	s_waitcnt lgkmcnt(0)
	v_readlane_b32 s50, v104, s45
	s_cbranch_execnz .Lvb0_1401
.Lvb0_1400:
	s_add_u32 s10, s6, -1
	s_ff1_i32_b64 s45, s[6:7]
	s_addc_u32 s11, s7, -1
	s_and_b64 s[6:7], s[10:11], s[6:7]
	v_readlane_b32 s52, v136, s45
	s_waitcnt lgkmcnt(0)
	v_readlane_b32 s50, v105, s45
	s_mov_b64 s[10:11], 0
.Lvb0_1401:
	s_ashr_i32 s53, s52, 31
	s_lshl_b64 s[52:53], s[52:53], 10
	v_lshl_add_u64 v[238:239], v[40:41], 0, s[52:53]
	global_load_dwordx4 v[238:241], v[238:239], off
	s_or_b64 s[52:53], s[10:11], s[6:7]
	s_cmp_eq_u64 s[52:53], 0
	s_cselect_b64 s[52:53], -1, 0
	s_and_b64 vcc, exec, s[52:53]
	s_cbranch_vccnz .Lvb0_1386
.Lvb0_1402:
	s_cmp_eq_u64 s[10:11], 0
	s_cbranch_scc1 .Lvb0_1419
	s_add_u32 s52, s10, -1
	s_ff1_i32_b64 s45, s[10:11]
	s_addc_u32 s53, s11, -1
	s_and_b64 s[10:11], s[52:53], s[10:11]
	v_readlane_b32 s54, v135, s45
	s_waitcnt lgkmcnt(0)
	v_readlane_b32 s52, v104, s45
	s_cbranch_execnz .Lvb0_1405
.Lvb0_1404:
	s_add_u32 s10, s6, -1
	s_ff1_i32_b64 s45, s[6:7]
	s_addc_u32 s11, s7, -1
	s_and_b64 s[6:7], s[10:11], s[6:7]
	v_readlane_b32 s54, v136, s45
	s_waitcnt lgkmcnt(0)
	v_readlane_b32 s52, v105, s45
	s_mov_b64 s[10:11], 0
.Lvb0_1405:
	s_ashr_i32 s55, s54, 31
	s_lshl_b64 s[54:55], s[54:55], 10
	v_lshl_add_u64 v[242:243], v[40:41], 0, s[54:55]
	global_load_dwordx4 v[242:245], v[242:243], off
	s_or_b64 s[54:55], s[10:11], s[6:7]
	s_cmp_eq_u64 s[54:55], 0
	s_cselect_b64 s[54:55], -1, 0
	s_and_b64 vcc, exec, s[54:55]
	s_cbranch_vccnz .Lvb0_1387
.Lvb0_1406:
	s_cmp_eq_u64 s[10:11], 0
	s_cbranch_scc1 .Lvb0_1420
	s_add_u32 s54, s10, -1
	s_ff1_i32_b64 s45, s[10:11]
	s_addc_u32 s55, s11, -1
	s_and_b64 s[10:11], s[54:55], s[10:11]
	v_readlane_b32 s56, v135, s45
	s_waitcnt lgkmcnt(0)
	v_readlane_b32 s54, v104, s45
	s_cbranch_execnz .Lvb0_1409
.Lvb0_1408:
	s_add_u32 s10, s6, -1
	s_ff1_i32_b64 s45, s[6:7]
	s_addc_u32 s11, s7, -1
	s_and_b64 s[6:7], s[10:11], s[6:7]
	v_readlane_b32 s56, v136, s45
	s_waitcnt lgkmcnt(0)
	v_readlane_b32 s54, v105, s45
	s_mov_b64 s[10:11], 0
.Lvb0_1409:
	s_ashr_i32 s57, s56, 31
	s_lshl_b64 s[56:57], s[56:57], 10
	v_lshl_add_u64 v[246:247], v[40:41], 0, s[56:57]
	global_load_dwordx4 v[246:249], v[246:247], off
	s_or_b64 s[56:57], s[10:11], s[6:7]
	s_cmp_eq_u64 s[56:57], 0
	s_cselect_b64 s[56:57], -1, 0
	s_and_b64 vcc, exec, s[56:57]
	s_cbranch_vccnz .Lvb_z0
.Lvb0_1410:
	s_cmp_eq_u64 s[10:11], 0
	s_cbranch_scc1 .Lvb0_1421
	s_add_u32 s56, s10, -1
	s_ff1_i32_b64 s45, s[10:11]
	s_addc_u32 s57, s11, -1
	s_and_b64 s[10:11], s[56:57], s[10:11]
	v_readlane_b32 s58, v135, s45
	s_waitcnt lgkmcnt(0)
	v_readlane_b32 s56, v104, s45
	s_cbranch_execnz .Lvb0_1413
.Lvb0_1412:
	s_add_u32 s10, s6, -1
	s_ff1_i32_b64 s45, s[6:7]
	s_addc_u32 s11, s7, -1
	s_and_b64 s[6:7], s[10:11], s[6:7]
	v_readlane_b32 s58, v136, s45
	s_waitcnt lgkmcnt(0)
	v_readlane_b32 s56, v105, s45
	s_mov_b64 s[10:11], 0
.Lvb0_1413:
	s_ashr_i32 s59, s58, 31
	s_lshl_b64 s[58:59], s[58:59], 10
	v_lshl_add_u64 v[250:251], v[40:41], 0, s[58:59]
	global_load_dwordx4 v[250:253], v[250:251], off
	s_branch .LBB0_1373

; DI void axpy16_fp8(float* o, float w, u32x4 u) {
;   const unsigned d[4] = {u[0], u[1], u[2], u[3]};
; #pragma unroll
;   for (int i = 0; i < 4; ++i) {
;     f32x2 a = __builtin_amdgcn_cvt_pk_f32_fp8((int)d[i], false);
;     f32x2 b = __builtin_amdgcn_cvt_pk_f32_fp8((int)d[i], true);
;     o[4 * i] += w * a[0]; o[4 * i + 1] += w * a[1]; o[4 * i + 2] += w * b[0]; o[4 * i + 3] += w * b[1];
;   }
; }
; DI void peer_v_group(const Params& p, int gw, int nw, int g, const float* wlw  ) {
;     ...
; #pragma unroll
;         for (int k = 0; k < 8; ++k) axpy16_fp8(out[ts], we[k], v[k]);
.LBB0_1423:
	s_waitcnt vmcnt(0)
	v_cvt_pk_f32_fp8_e32 v[148:149], v4
	v_cvt_pk_f32_fp8_sdwa v[150:151], v4 src0_sel:WORD_1
	v_cvt_pk_f32_fp8_e32 v[152:153], v5
	v_cvt_pk_f32_fp8_sdwa v[4:5], v5 src0_sel:WORD_1
	v_pk_fma_f32 v[88:89], s[12:13], v[148:149], v[88:89] op_sel_hi:[0,1,1]
	v_pk_fma_f32 v[90:91], s[12:13], v[150:151], v[90:91] op_sel_hi:[0,1,1]
	v_cvt_pk_f32_fp8_sdwa v[148:149], v6 src0_sel:WORD_1
	v_pk_fma_f32 v[4:5], s[12:13], v[4:5], v[94:95] op_sel_hi:[0,1,1]
	v_cvt_pk_f32_fp8_e32 v[94:95], v6
	v_cvt_pk_f32_fp8_e32 v[150:151], v7
	v_cvt_pk_f32_fp8_sdwa v[6:7], v7 src0_sel:WORD_1
	v_pk_fma_f32 v[98:99], s[12:13], v[148:149], v[98:99] op_sel_hi:[0,1,1]
	v_pk_fma_f32 v[96:97], s[12:13], v[94:95], v[96:97] op_sel_hi:[0,1,1]
	v_cvt_pk_f32_fp8_e32 v[94:95], v8
	v_pk_fma_f32 v[6:7], s[12:13], v[6:7], v[102:103] op_sel_hi:[0,1,1]
	v_cvt_pk_f32_fp8_sdwa v[102:103], v8 src0_sel:WORD_1
	v_cvt_pk_f32_fp8_e32 v[148:149], v9
	v_cvt_pk_f32_fp8_sdwa v[8:9], v9 src0_sel:WORD_1
	v_cvt_pk_f32_fp8_e32 v[156:157], v12
	v_cvt_pk_f32_fp8_sdwa v[158:159], v12 src0_sel:WORD_1
	v_cvt_pk_f32_fp8_e32 v[160:161], v13
	v_cvt_pk_f32_fp8_sdwa v[12:13], v13 src0_sel:WORD_1
	v_cvt_pk_f32_fp8_e32 v[170:171], v16
	v_cvt_pk_f32_fp8_sdwa v[172:173], v16 src0_sel:WORD_1
	v_cvt_pk_f32_fp8_e32 v[174:175], v17
	v_cvt_pk_f32_fp8_sdwa v[16:17], v17 src0_sel:WORD_1
	v_pk_fma_f32 v[92:93], s[12:13], v[152:153], v[92:93] op_sel_hi:[0,1,1]
	v_cvt_pk_f32_fp8_e32 v[182:183], v20
	v_cvt_pk_f32_fp8_sdwa v[184:185], v20 src0_sel:WORD_1
	v_cvt_pk_f32_fp8_e32 v[186:187], v21
	v_cvt_pk_f32_fp8_sdwa v[20:21], v21 src0_sel:WORD_1
	v_pk_fma_f32 v[100:101], s[12:13], v[150:151], v[100:101] op_sel_hi:[0,1,1]
	v_cvt_pk_f32_fp8_e32 v[150:151], v10
	v_cvt_pk_f32_fp8_e32 v[194:195], v24
	v_cvt_pk_f32_fp8_sdwa v[196:197], v24 src0_sel:WORD_1
	v_cvt_pk_f32_fp8_e32 v[198:199], v25
	v_cvt_pk_f32_fp8_sdwa v[24:25], v25 src0_sel:WORD_1
	v_pk_fma_f32 v[92:93], s[14:15], v[148:149], v[92:93] op_sel_hi:[0,1,1]
	v_pk_fma_f32 v[4:5], s[14:15], v[8:9], v[4:5] op_sel_hi:[0,1,1]
	v_cvt_pk_f32_fp8_e32 v[164:165], v14
	v_cvt_pk_f32_fp8_e32 v[206:207], v28
	v_cvt_pk_f32_fp8_sdwa v[208:209], v28 src0_sel:WORD_1
	v_cvt_pk_f32_fp8_e32 v[210:211], v29
	v_cvt_pk_f32_fp8_sdwa v[28:29], v29 src0_sel:WORD_1
	v_pk_fma_f32 v[92:93], s[16:17], v[160:161], v[92:93] op_sel_hi:[0,1,1]
	v_pk_fma_f32 v[4:5], s[16:17], v[12:13], v[4:5] op_sel_hi:[0,1,1]
	v_cvt_pk_f32_fp8_e32 v[176:177], v18
	v_cvt_pk_f32_fp8_e32 v[218:219], v32
	v_cvt_pk_f32_fp8_sdwa v[220:221], v32 src0_sel:WORD_1
	v_pk_fma_f32 v[88:89], s[14:15], v[94:95], v[88:89] op_sel_hi:[0,1,1]
	v_cvt_pk_f32_fp8_e32 v[94:95], v33
	v_cvt_pk_f32_fp8_sdwa v[32:33], v33 src0_sel:WORD_1
	v_pk_fma_f32 v[92:93], s[18:19], v[174:175], v[92:93] op_sel_hi:[0,1,1]
	v_pk_fma_f32 v[4:5], s[18:19], v[16:17], v[4:5] op_sel_hi:[0,1,1]
	v_cvt_pk_f32_fp8_e32 v[188:189], v22
	v_pk_fma_f32 v[92:93], s[20:21], v[186:187], v[92:93] op_sel_hi:[0,1,1]
	v_pk_fma_f32 v[4:5], s[20:21], v[20:21], v[4:5] op_sel_hi:[0,1,1]
	v_cvt_pk_f32_fp8_e32 v[200:201], v26
	v_pk_fma_f32 v[92:93], s[22:23], v[198:199], v[92:93] op_sel_hi:[0,1,1]
	v_pk_fma_f32 v[4:5], s[22:23], v[24:25], v[4:5] op_sel_hi:[0,1,1]
	v_pk_fma_f32 v[12:13], s[14:15], v[150:151], v[96:97] op_sel_hi:[0,1,1]
	v_cvt_pk_f32_fp8_e32 v[212:213], v30
	v_pk_fma_f32 v[92:93], s[24:25], v[210:211], v[92:93] op_sel_hi:[0,1,1]
	v_pk_fma_f32 v[4:5], s[24:25], v[28:29], v[4:5] op_sel_hi:[0,1,1]
	v_pk_fma_f32 v[12:13], s[16:17], v[164:165], v[12:13] op_sel_hi:[0,1,1]
	v_cvt_pk_f32_fp8_sdwa v[152:153], v10 src0_sel:WORD_1
	v_pk_fma_f32 v[92:93], s[26:27], v[94:95], v[92:93] op_sel_hi:[0,1,1]
	v_pk_fma_f32 v[94:95], s[26:27], v[32:33], v[4:5] op_sel_hi:[0,1,1]
	v_cvt_pk_f32_fp8_e32 v[4:5], v34
	v_pk_fma_f32 v[12:13], s[18:19], v[176:177], v[12:13] op_sel_hi:[0,1,1]
	v_cvt_pk_f32_fp8_sdwa v[166:167], v14 src0_sel:WORD_1
	v_pk_fma_f32 v[12:13], s[20:21], v[188:189], v[12:13] op_sel_hi:[0,1,1]
	v_cvt_pk_f32_fp8_sdwa v[178:179], v18 src0_sel:WORD_1
	v_pk_fma_f32 v[12:13], s[22:23], v[200:201], v[12:13] op_sel_hi:[0,1,1]
	v_cvt_pk_f32_fp8_sdwa v[190:191], v22 src0_sel:WORD_1
	v_pk_fma_f32 v[12:13], s[24:25], v[212:213], v[12:13] op_sel_hi:[0,1,1]
	v_cvt_pk_f32_fp8_e32 v[154:155], v11
	v_cvt_pk_f32_fp8_sdwa v[202:203], v26 src0_sel:WORD_1
	v_pk_fma_f32 v[96:97], s[26:27], v[4:5], v[12:13] op_sel_hi:[0,1,1]
	v_pk_fma_f32 v[4:5], s[14:15], v[152:153], v[98:99] op_sel_hi:[0,1,1]
	v_cvt_pk_f32_fp8_e32 v[168:169], v15
	v_cvt_pk_f32_fp8_sdwa v[214:215], v30 src0_sel:WORD_1
	v_pk_fma_f32 v[4:5], s[16:17], v[166:167], v[4:5] op_sel_hi:[0,1,1]
	v_cvt_pk_f32_fp8_e32 v[180:181], v19
	v_cvt_pk_f32_fp8_sdwa v[8:9], v34 src0_sel:WORD_1
	v_pk_fma_f32 v[4:5], s[18:19], v[178:179], v[4:5] op_sel_hi:[0,1,1]
	v_cvt_pk_f32_fp8_e32 v[192:193], v23
	v_pk_fma_f32 v[4:5], s[20:21], v[190:191], v[4:5] op_sel_hi:[0,1,1]
	v_cvt_pk_f32_fp8_e32 v[204:205], v27
	v_pk_fma_f32 v[4:5], s[22:23], v[202:203], v[4:5] op_sel_hi:[0,1,1]
	v_pk_fma_f32 v[12:13], s[14:15], v[154:155], v[100:101] op_sel_hi:[0,1,1]
	v_cvt_pk_f32_fp8_e32 v[216:217], v31
	v_pk_fma_f32 v[4:5], s[24:25], v[214:215], v[4:5] op_sel_hi:[0,1,1]
	v_pk_fma_f32 v[12:13], s[16:17], v[168:169], v[12:13] op_sel_hi:[0,1,1]
	v_cvt_pk_f32_fp8_sdwa v[10:11], v11 src0_sel:WORD_1
	v_pk_fma_f32 v[98:99], s[26:27], v[8:9], v[4:5] op_sel_hi:[0,1,1]
	v_cvt_pk_f32_fp8_e32 v[4:5], v35
	v_pk_fma_f32 v[12:13], s[18:19], v[180:181], v[12:13] op_sel_hi:[0,1,1]
	v_cvt_pk_f32_fp8_sdwa v[14:15], v15 src0_sel:WORD_1
	v_pk_fma_f32 v[12:13], s[20:21], v[192:193], v[12:13] op_sel_hi:[0,1,1]
	v_cvt_pk_f32_fp8_sdwa v[18:19], v19 src0_sel:WORD_1
; DI void axpy16_fp8(float* o, float w, u32x4 u) {
;   const unsigned d[4] = {u[0], u[1], u[2], u[3]};
; #pragma unroll
;   for (int i = 0; i < 4; ++i) {
;     f32x2 a = __builtin_amdgcn_cvt_pk_f32_fp8((int)d[i], false);
;     f32x2 b = __builtin_amdgcn_cvt_pk_f32_fp8((int)d[i], true);
;     o[4 * i] += w * a[0]; o[4 * i + 1] += w * a[1]; o[4 * i + 2] += w * b[0]; o[4 * i + 3] += w * b[1];
;   }
; }
; DI void peer_v_group(const Params& p, int gw, int nw, int g, const float* wlw  ) {
;     ...
; #pragma unroll
;         for (int k = 0; k < 8; ++k) axpy16_fp8(out[ts], we[k], v[k]);
	v_pk_fma_f32 v[12:13], s[22:23], v[204:205], v[12:13] op_sel_hi:[0,1,1]
	v_cvt_pk_f32_fp8_sdwa v[22:23], v23 src0_sel:WORD_1
	v_pk_fma_f32 v[12:13], s[24:25], v[216:217], v[12:13] op_sel_hi:[0,1,1]
	v_cvt_pk_f32_fp8_sdwa v[26:27], v27 src0_sel:WORD_1
	v_pk_fma_f32 v[90:91], s[14:15], v[102:103], v[90:91] op_sel_hi:[0,1,1]
	v_pk_fma_f32 v[100:101], s[26:27], v[4:5], v[12:13] op_sel_hi:[0,1,1]
	v_pk_fma_f32 v[4:5], s[14:15], v[10:11], v[6:7] op_sel_hi:[0,1,1]
	v_cvt_pk_f32_fp8_sdwa v[30:31], v31 src0_sel:WORD_1
	v_pk_fma_f32 v[88:89], s[16:17], v[156:157], v[88:89] op_sel_hi:[0,1,1]
	v_pk_fma_f32 v[90:91], s[16:17], v[158:159], v[90:91] op_sel_hi:[0,1,1]
	v_pk_fma_f32 v[4:5], s[16:17], v[14:15], v[4:5] op_sel_hi:[0,1,1]
	v_pk_fma_f32 v[88:89], s[18:19], v[170:171], v[88:89] op_sel_hi:[0,1,1]
	v_pk_fma_f32 v[90:91], s[18:19], v[172:173], v[90:91] op_sel_hi:[0,1,1]
	v_cvt_pk_f32_fp8_sdwa v[8:9], v35 src0_sel:WORD_1
	v_pk_fma_f32 v[4:5], s[18:19], v[18:19], v[4:5] op_sel_hi:[0,1,1]
	v_pk_fma_f32 v[88:89], s[20:21], v[182:183], v[88:89] op_sel_hi:[0,1,1]
	v_pk_fma_f32 v[90:91], s[20:21], v[184:185], v[90:91] op_sel_hi:[0,1,1]
	v_pk_fma_f32 v[4:5], s[20:21], v[22:23], v[4:5] op_sel_hi:[0,1,1]
	v_pk_fma_f32 v[88:89], s[22:23], v[194:195], v[88:89] op_sel_hi:[0,1,1]
	v_pk_fma_f32 v[90:91], s[22:23], v[196:197], v[90:91] op_sel_hi:[0,1,1]
	v_pk_fma_f32 v[4:5], s[22:23], v[26:27], v[4:5] op_sel_hi:[0,1,1]
	v_pk_fma_f32 v[88:89], s[24:25], v[206:207], v[88:89] op_sel_hi:[0,1,1]
	v_pk_fma_f32 v[90:91], s[24:25], v[208:209], v[90:91] op_sel_hi:[0,1,1]
	v_pk_fma_f32 v[4:5], s[24:25], v[30:31], v[4:5] op_sel_hi:[0,1,1]
	s_or_b64 s[14:15], s[10:11], s[6:7]
	v_pk_fma_f32 v[88:89], s[26:27], v[218:219], v[88:89] op_sel_hi:[0,1,1]
	v_pk_fma_f32 v[90:91], s[26:27], v[220:221], v[90:91] op_sel_hi:[0,1,1]
	s_cmp_lg_u64 s[14:15], 0
	v_pk_fma_f32 v[102:103], s[26:27], v[8:9], v[4:5] op_sel_hi:[0,1,1]
	s_cmp_eq_u64 s[60:61], 0
	s_cbranch_scc1 .Lvb_skip1
	v_cvt_pk_f32_fp8_e32 v[148:149], v222
	v_cvt_pk_f32_fp8_sdwa v[150:151], v222 src0_sel:WORD_1
	v_cvt_pk_f32_fp8_e32 v[152:153], v223
	v_cvt_pk_f32_fp8_sdwa v[222:223], v223 src0_sel:WORD_1
	v_pk_fma_f32 v[88:89], s[42:43], v[148:149], v[88:89] op_sel_hi:[0,1,1]
	v_pk_fma_f32 v[90:91], s[42:43], v[150:151], v[90:91] op_sel_hi:[0,1,1]
	v_cvt_pk_f32_fp8_sdwa v[148:149], v224 src0_sel:WORD_1
	v_pk_fma_f32 v[222:223], s[42:43], v[222:223], v[94:95] op_sel_hi:[0,1,1]
	v_cvt_pk_f32_fp8_e32 v[94:95], v224
	v_cvt_pk_f32_fp8_e32 v[150:151], v225
	v_cvt_pk_f32_fp8_sdwa v[224:225], v225 src0_sel:WORD_1
	v_pk_fma_f32 v[98:99], s[42:43], v[148:149], v[98:99] op_sel_hi:[0,1,1]
	v_pk_fma_f32 v[96:97], s[42:43], v[94:95], v[96:97] op_sel_hi:[0,1,1]
	v_cvt_pk_f32_fp8_e32 v[94:95], v226
	v_pk_fma_f32 v[224:225], s[42:43], v[224:225], v[102:103] op_sel_hi:[0,1,1]
	v_cvt_pk_f32_fp8_sdwa v[102:103], v226 src0_sel:WORD_1
	v_cvt_pk_f32_fp8_e32 v[148:149], v227
	v_cvt_pk_f32_fp8_sdwa v[226:227], v227 src0_sel:WORD_1
	v_cvt_pk_f32_fp8_e32 v[156:157], v230
	v_cvt_pk_f32_fp8_sdwa v[158:159], v230 src0_sel:WORD_1
	v_cvt_pk_f32_fp8_e32 v[160:161], v231
	v_cvt_pk_f32_fp8_sdwa v[230:231], v231 src0_sel:WORD_1
	v_cvt_pk_f32_fp8_e32 v[170:171], v234
	v_cvt_pk_f32_fp8_sdwa v[172:173], v234 src0_sel:WORD_1
	v_cvt_pk_f32_fp8_e32 v[174:175], v235
	v_cvt_pk_f32_fp8_sdwa v[234:235], v235 src0_sel:WORD_1
	v_pk_fma_f32 v[92:93], s[42:43], v[152:153], v[92:93] op_sel_hi:[0,1,1]
	v_cvt_pk_f32_fp8_e32 v[182:183], v238
	v_cvt_pk_f32_fp8_sdwa v[184:185], v238 src0_sel:WORD_1
	v_cvt_pk_f32_fp8_e32 v[186:187], v239
	v_cvt_pk_f32_fp8_sdwa v[238:239], v239 src0_sel:WORD_1
	v_pk_fma_f32 v[100:101], s[42:43], v[150:151], v[100:101] op_sel_hi:[0,1,1]
	v_cvt_pk_f32_fp8_e32 v[150:151], v228
	v_cvt_pk_f32_fp8_e32 v[194:195], v242
	v_cvt_pk_f32_fp8_sdwa v[196:197], v242 src0_sel:WORD_1
	v_cvt_pk_f32_fp8_e32 v[198:199], v243
	v_cvt_pk_f32_fp8_sdwa v[242:243], v243 src0_sel:WORD_1
	v_pk_fma_f32 v[92:93], s[44:45], v[148:149], v[92:93] op_sel_hi:[0,1,1]
	v_pk_fma_f32 v[222:223], s[44:45], v[226:227], v[222:223] op_sel_hi:[0,1,1]
	v_cvt_pk_f32_fp8_e32 v[164:165], v232
	v_cvt_pk_f32_fp8_e32 v[206:207], v246
	v_cvt_pk_f32_fp8_sdwa v[208:209], v246 src0_sel:WORD_1
	v_cvt_pk_f32_fp8_e32 v[210:211], v247
	v_cvt_pk_f32_fp8_sdwa v[246:247], v247 src0_sel:WORD_1
	v_pk_fma_f32 v[92:93], s[46:47], v[160:161], v[92:93] op_sel_hi:[0,1,1]
	v_pk_fma_f32 v[222:223], s[46:47], v[230:231], v[222:223] op_sel_hi:[0,1,1]
	v_cvt_pk_f32_fp8_e32 v[176:177], v236
	v_cvt_pk_f32_fp8_e32 v[218:219], v250
	v_cvt_pk_f32_fp8_sdwa v[220:221], v250 src0_sel:WORD_1
	v_pk_fma_f32 v[88:89], s[44:45], v[94:95], v[88:89] op_sel_hi:[0,1,1]
	v_cvt_pk_f32_fp8_e32 v[94:95], v251
	v_cvt_pk_f32_fp8_sdwa v[250:251], v251 src0_sel:WORD_1
	v_pk_fma_f32 v[92:93], s[48:49], v[174:175], v[92:93] op_sel_hi:[0,1,1]
	v_pk_fma_f32 v[222:223], s[48:49], v[234:235], v[222:223] op_sel_hi:[0,1,1]
; DI void axpy16_fp8(float* o, float w, u32x4 u) {
;   const unsigned d[4] = {u[0], u[1], u[2], u[3]};
; #pragma unroll
;   for (int i = 0; i < 4; ++i) {
;     f32x2 a = __builtin_amdgcn_cvt_pk_f32_fp8((int)d[i], false);
;     f32x2 b = __builtin_amdgcn_cvt_pk_f32_fp8((int)d[i], true);
;     o[4 * i] += w * a[0]; o[4 * i + 1] += w * a[1]; o[4 * i + 2] += w * b[0]; o[4 * i + 3] += w * b[1];
;   }
; }
; DI void peer_v_group(const Params& p, int gw, int nw, int g, const float* wlw  ) {
;     ...
; #pragma unroll
;         for (int k = 0; k < 8; ++k) axpy16_fp8(out[ts], we[k], v[k]);
	v_cvt_pk_f32_fp8_e32 v[188:189], v240
	v_pk_fma_f32 v[92:93], s[50:51], v[186:187], v[92:93] op_sel_hi:[0,1,1]
	v_pk_fma_f32 v[222:223], s[50:51], v[238:239], v[222:223] op_sel_hi:[0,1,1]
	v_cvt_pk_f32_fp8_e32 v[200:201], v244
	v_pk_fma_f32 v[92:93], s[52:53], v[198:199], v[92:93] op_sel_hi:[0,1,1]
	v_pk_fma_f32 v[222:223], s[52:53], v[242:243], v[222:223] op_sel_hi:[0,1,1]
	v_pk_fma_f32 v[230:231], s[44:45], v[150:151], v[96:97] op_sel_hi:[0,1,1]
	v_cvt_pk_f32_fp8_e32 v[212:213], v248
	v_pk_fma_f32 v[92:93], s[54:55], v[210:211], v[92:93] op_sel_hi:[0,1,1]
	v_pk_fma_f32 v[222:223], s[54:55], v[246:247], v[222:223] op_sel_hi:[0,1,1]
	v_pk_fma_f32 v[230:231], s[46:47], v[164:165], v[230:231] op_sel_hi:[0,1,1]
	v_cvt_pk_f32_fp8_sdwa v[152:153], v228 src0_sel:WORD_1
	v_pk_fma_f32 v[92:93], s[56:57], v[94:95], v[92:93] op_sel_hi:[0,1,1]
	v_pk_fma_f32 v[94:95], s[56:57], v[250:251], v[222:223] op_sel_hi:[0,1,1]
	v_cvt_pk_f32_fp8_e32 v[222:223], v252
	v_pk_fma_f32 v[230:231], s[48:49], v[176:177], v[230:231] op_sel_hi:[0,1,1]
	v_cvt_pk_f32_fp8_sdwa v[166:167], v232 src0_sel:WORD_1
	v_pk_fma_f32 v[230:231], s[50:51], v[188:189], v[230:231] op_sel_hi:[0,1,1]
	v_cvt_pk_f32_fp8_sdwa v[178:179], v236 src0_sel:WORD_1
	v_pk_fma_f32 v[230:231], s[52:53], v[200:201], v[230:231] op_sel_hi:[0,1,1]
	v_cvt_pk_f32_fp8_sdwa v[190:191], v240 src0_sel:WORD_1
	v_pk_fma_f32 v[230:231], s[54:55], v[212:213], v[230:231] op_sel_hi:[0,1,1]
	v_cvt_pk_f32_fp8_e32 v[154:155], v229
	v_cvt_pk_f32_fp8_sdwa v[202:203], v244 src0_sel:WORD_1
	v_pk_fma_f32 v[96:97], s[56:57], v[222:223], v[230:231] op_sel_hi:[0,1,1]
	v_pk_fma_f32 v[222:223], s[44:45], v[152:153], v[98:99] op_sel_hi:[0,1,1]
	v_cvt_pk_f32_fp8_e32 v[168:169], v233
	v_cvt_pk_f32_fp8_sdwa v[214:215], v248 src0_sel:WORD_1
	v_pk_fma_f32 v[222:223], s[46:47], v[166:167], v[222:223] op_sel_hi:[0,1,1]
	v_cvt_pk_f32_fp8_e32 v[180:181], v237
	v_cvt_pk_f32_fp8_sdwa v[226:227], v252 src0_sel:WORD_1
	v_pk_fma_f32 v[222:223], s[48:49], v[178:179], v[222:223] op_sel_hi:[0,1,1]
	v_cvt_pk_f32_fp8_e32 v[192:193], v241
	v_pk_fma_f32 v[222:223], s[50:51], v[190:191], v[222:223] op_sel_hi:[0,1,1]
	v_cvt_pk_f32_fp8_e32 v[204:205], v245
	v_pk_fma_f32 v[222:223], s[52:53], v[202:203], v[222:223] op_sel_hi:[0,1,1]
	v_pk_fma_f32 v[230:231], s[44:45], v[154:155], v[100:101] op_sel_hi:[0,1,1]
	v_cvt_pk_f32_fp8_e32 v[216:217], v249
	v_pk_fma_f32 v[222:223], s[54:55], v[214:215], v[222:223] op_sel_hi:[0,1,1]
	v_pk_fma_f32 v[230:231], s[46:47], v[168:169], v[230:231] op_sel_hi:[0,1,1]
	v_cvt_pk_f32_fp8_sdwa v[228:229], v229 src0_sel:WORD_1
	v_pk_fma_f32 v[98:99], s[56:57], v[226:227], v[222:223] op_sel_hi:[0,1,1]
	v_cvt_pk_f32_fp8_e32 v[222:223], v253
	v_pk_fma_f32 v[230:231], s[48:49], v[180:181], v[230:231] op_sel_hi:[0,1,1]
	v_cvt_pk_f32_fp8_sdwa v[232:233], v233 src0_sel:WORD_1
	v_pk_fma_f32 v[230:231], s[50:51], v[192:193], v[230:231] op_sel_hi:[0,1,1]
	v_cvt_pk_f32_fp8_sdwa v[236:237], v237 src0_sel:WORD_1
	v_pk_fma_f32 v[230:231], s[52:53], v[204:205], v[230:231] op_sel_hi:[0,1,1]
	v_cvt_pk_f32_fp8_sdwa v[240:241], v241 src0_sel:WORD_1
	v_pk_fma_f32 v[230:231], s[54:55], v[216:217], v[230:231] op_sel_hi:[0,1,1]
	v_cvt_pk_f32_fp8_sdwa v[244:245], v245 src0_sel:WORD_1
	v_pk_fma_f32 v[90:91], s[44:45], v[102:103], v[90:91] op_sel_hi:[0,1,1]
	v_pk_fma_f32 v[100:101], s[56:57], v[222:223], v[230:231] op_sel_hi:[0,1,1]
	v_pk_fma_f32 v[222:223], s[44:45], v[228:229], v[224:225] op_sel_hi:[0,1,1]
	v_cvt_pk_f32_fp8_sdwa v[248:249], v249 src0_sel:WORD_1
	v_pk_fma_f32 v[88:89], s[46:47], v[156:157], v[88:89] op_sel_hi:[0,1,1]
	v_pk_fma_f32 v[90:91], s[46:47], v[158:159], v[90:91] op_sel_hi:[0,1,1]
	v_pk_fma_f32 v[222:223], s[46:47], v[232:233], v[222:223] op_sel_hi:[0,1,1]
	v_pk_fma_f32 v[88:89], s[48:49], v[170:171], v[88:89] op_sel_hi:[0,1,1]
	v_pk_fma_f32 v[90:91], s[48:49], v[172:173], v[90:91] op_sel_hi:[0,1,1]
	v_cvt_pk_f32_fp8_sdwa v[226:227], v253 src0_sel:WORD_1
	v_pk_fma_f32 v[222:223], s[48:49], v[236:237], v[222:223] op_sel_hi:[0,1,1]
	v_pk_fma_f32 v[88:89], s[50:51], v[182:183], v[88:89] op_sel_hi:[0,1,1]
	v_pk_fma_f32 v[90:91], s[50:51], v[184:185], v[90:91] op_sel_hi:[0,1,1]
	v_pk_fma_f32 v[222:223], s[50:51], v[240:241], v[222:223] op_sel_hi:[0,1,1]
	v_pk_fma_f32 v[88:89], s[52:53], v[194:195], v[88:89] op_sel_hi:[0,1,1]
	v_pk_fma_f32 v[90:91], s[52:53], v[196:197], v[90:91] op_sel_hi:[0,1,1]
	v_pk_fma_f32 v[222:223], s[52:53], v[244:245], v[222:223] op_sel_hi:[0,1,1]
	v_pk_fma_f32 v[88:89], s[54:55], v[206:207], v[88:89] op_sel_hi:[0,1,1]
	v_pk_fma_f32 v[90:91], s[54:55], v[208:209], v[90:91] op_sel_hi:[0,1,1]
	v_pk_fma_f32 v[222:223], s[54:55], v[248:249], v[222:223] op_sel_hi:[0,1,1]
	v_pk_fma_f32 v[88:89], s[56:57], v[218:219], v[88:89] op_sel_hi:[0,1,1]
	v_pk_fma_f32 v[90:91], s[56:57], v[220:221], v[90:91] op_sel_hi:[0,1,1]
	v_pk_fma_f32 v[102:103], s[56:57], v[226:227], v[222:223] op_sel_hi:[0,1,1]

; #define AS1 __attribute__((address_space(1)))
; DI void peer_v_group(const Params& p, int gw, int nw, int g, const float* wlw  ) {
;     ...
;       while ((m0 | m1) != 0ull) {
;         u32x4 v[8];
;         float we[8];
; #pragma unroll
;         for (int k = 0; k < 8; ++k) {
;           we[k] = 0.f;
;           v[k] = (u32x4){0u, 0u, 0u, 0u};
;           if ((m0 | m1) != 0ull) {
;             int l, id;
;             if (m0 != 0ull) {
;               l = __builtin_ctzll(m0); m0 &= m0 - 1ull;
;               id = __builtin_amdgcn_readlane(e0[ts], l);
;               we[k] = __int_as_float(__builtin_amdgcn_readlane(__float_as_int(w0[ts]), l));
;             } else {
;               l = __builtin_ctzll(m1); m1 &= m1 - 1ull;
;               id = __builtin_amdgcn_readlane(e1[ts], l);
;               we[k] = __int_as_float(__builtin_amdgcn_readlane(__float_as_int(w1[ts]), l));
;             }
;             v[k] = *(const u32x4 AS1*)(EV8 + (size_t)id * 1024 + lane * 16);
;           }
.Lvb_g1:
	s_or_b64 s[60:61], s[6:7], s[10:11]
	s_or_b64 s[44:45], s[6:7], s[10:11]
	s_cmp_eq_u64 s[44:45], 0
	s_cbranch_scc1 .Lvb1_1438
	s_cmp_eq_u64 s[10:11], 0
	s_cbranch_scc1 .Lvb1_1464
	s_add_u32 s44, s10, -1
	s_ff1_i32_b64 s42, s[10:11]
	s_addc_u32 s45, s11, -1
	s_and_b64 s[10:11], s[44:45], s[10:11]
	v_readlane_b32 s44, v69, s42
	s_waitcnt lgkmcnt(0)
	v_readlane_b32 s42, v106, s42
	s_cbranch_execnz .Lvb1_1428
.Lvb1_1427:
	s_add_u32 s10, s6, -1
	s_ff1_i32_b64 s42, s[6:7]
	s_addc_u32 s11, s7, -1
	s_and_b64 s[6:7], s[10:11], s[6:7]
	v_readlane_b32 s44, v137, s42
	s_waitcnt lgkmcnt(0)
	v_readlane_b32 s42, v107, s42
	s_mov_b64 s[10:11], 0

; #define AS1 __attribute__((address_space(1)))
; DI void peer_v_group(const Params& p, int gw, int nw, int g, const float* wlw  ) {
;     ...
;         for (int k = 0; k < 8; ++k) {
;           we[k] = 0.f;
;           v[k] = (u32x4){0u, 0u, 0u, 0u};
;           if ((m0 | m1) != 0ull) {
;             int l, id;
;             if (m0 != 0ull) {
;               l = __builtin_ctzll(m0); m0 &= m0 - 1ull;
;               id = __builtin_amdgcn_readlane(e0[ts], l);
;               we[k] = __int_as_float(__builtin_amdgcn_readlane(__float_as_int(w0[ts]), l));
;             } else {
;               l = __builtin_ctzll(m1); m1 &= m1 - 1ull;
;               id = __builtin_amdgcn_readlane(e1[ts], l);
;               we[k] = __int_as_float(__builtin_amdgcn_readlane(__float_as_int(w1[ts]), l));
;             }
;             v[k] = *(const u32x4 AS1*)(EV8 + (size_t)id * 1024 + lane * 16);
;           }
.Lvb1_1429:
	s_cmp_eq_u64 s[10:11], 0
	s_cbranch_scc1 .Lvb1_1465
	s_add_u32 s44, s10, -1
	s_ff1_i32_b64 s47, s[10:11]
	s_addc_u32 s45, s11, -1
	s_and_b64 s[10:11], s[44:45], s[10:11]
	v_readlane_b32 s46, v69, s47
	s_waitcnt lgkmcnt(0)
	v_readlane_b32 s44, v106, s47
	s_cbranch_execnz .Lvb1_1432
.Lvb1_1431:
	s_add_u32 s10, s6, -1
	s_ff1_i32_b64 s44, s[6:7]
	s_addc_u32 s11, s7, -1
	s_and_b64 s[6:7], s[10:11], s[6:7]
	v_readlane_b32 s46, v137, s44
	s_waitcnt lgkmcnt(0)
	v_readlane_b32 s44, v107, s44
	s_mov_b64 s[10:11], 0

; #define AS1 __attribute__((address_space(1)))
; DI void peer_v_group(const Params& p, int gw, int nw, int g, const float* wlw  ) {
;     ...
;         for (int k = 0; k < 8; ++k) {
;           we[k] = 0.f;
;           v[k] = (u32x4){0u, 0u, 0u, 0u};
;           if ((m0 | m1) != 0ull) {
;             int l, id;
;             if (m0 != 0ull) {
;               l = __builtin_ctzll(m0); m0 &= m0 - 1ull;
;               id = __builtin_amdgcn_readlane(e0[ts], l);
;               we[k] = __int_as_float(__builtin_amdgcn_readlane(__float_as_int(w0[ts]), l));
;             } else {
;               l = __builtin_ctzll(m1); m1 &= m1 - 1ull;
;               id = __builtin_amdgcn_readlane(e1[ts], l);
;               we[k] = __int_as_float(__builtin_amdgcn_readlane(__float_as_int(w1[ts]), l));
;             }
;             v[k] = *(const u32x4 AS1*)(EV8 + (size_t)id * 1024 + lane * 16);
;           }
.Lvb1_1440:
	s_cmp_eq_u64 s[10:11], 0
	s_cbranch_scc1 .Lvb1_1466
	s_add_u32 s46, s10, -1
	s_ff1_i32_b64 s45, s[10:11]
	s_addc_u32 s47, s11, -1
	s_and_b64 s[10:11], s[46:47], s[10:11]
	v_readlane_b32 s48, v69, s45
	s_waitcnt lgkmcnt(0)
	v_readlane_b32 s46, v106, s45
	s_cbranch_execnz .Lvb1_1443
.Lvb1_1442:
	s_add_u32 s10, s6, -1
	s_ff1_i32_b64 s45, s[6:7]
	s_addc_u32 s11, s7, -1
	s_and_b64 s[6:7], s[10:11], s[6:7]
	v_readlane_b32 s48, v137, s45
	s_waitcnt lgkmcnt(0)
	v_readlane_b32 s46, v107, s45
	s_mov_b64 s[10:11], 0

; #define AS1 __attribute__((address_space(1)))
; DI void peer_v_group(const Params& p, int gw, int nw, int g, const float* wlw  ) {
;     ...
;         for (int k = 0; k < 8; ++k) {
;           we[k] = 0.f;
;           v[k] = (u32x4){0u, 0u, 0u, 0u};
;           if ((m0 | m1) != 0ull) {
;             int l, id;
;             if (m0 != 0ull) {
;               l = __builtin_ctzll(m0); m0 &= m0 - 1ull;
;               id = __builtin_amdgcn_readlane(e0[ts], l);
;               we[k] = __int_as_float(__builtin_amdgcn_readlane(__float_as_int(w0[ts]), l));
;             } else {
;               l = __builtin_ctzll(m1); m1 &= m1 - 1ull;
;               id = __builtin_amdgcn_readlane(e1[ts], l);
;               we[k] = __int_as_float(__builtin_amdgcn_readlane(__float_as_int(w1[ts]), l));
;             }
;             v[k] = *(const u32x4 AS1*)(EV8 + (size_t)id * 1024 + lane * 16);
;           }
.Lvb1_1444:
	s_cmp_eq_u64 s[10:11], 0
	s_cbranch_scc1 .Lvb1_1467
	s_add_u32 s48, s10, -1
	s_ff1_i32_b64 s45, s[10:11]
	s_addc_u32 s49, s11, -1
	s_and_b64 s[10:11], s[48:49], s[10:11]
	v_readlane_b32 s50, v69, s45
	s_waitcnt lgkmcnt(0)
	v_readlane_b32 s48, v106, s45
	s_cbranch_execnz .Lvb1_1447
.Lvb1_1446:
	s_add_u32 s10, s6, -1
	s_ff1_i32_b64 s45, s[6:7]
	s_addc_u32 s11, s7, -1
	s_and_b64 s[6:7], s[10:11], s[6:7]
	v_readlane_b32 s50, v137, s45
	s_waitcnt lgkmcnt(0)
	v_readlane_b32 s48, v107, s45
	s_mov_b64 s[10:11], 0

; #define AS1 __attribute__((address_space(1)))
; DI void peer_v_group(const Params& p, int gw, int nw, int g, const float* wlw  ) {
;     ...
;         for (int k = 0; k < 8; ++k) {
;           we[k] = 0.f;
;           v[k] = (u32x4){0u, 0u, 0u, 0u};
;           if ((m0 | m1) != 0ull) {
;             int l, id;
;             if (m0 != 0ull) {
;               l = __builtin_ctzll(m0); m0 &= m0 - 1ull;
;               id = __builtin_amdgcn_readlane(e0[ts], l);
;               we[k] = __int_as_float(__builtin_amdgcn_readlane(__float_as_int(w0[ts]), l));
;             } else {
;               l = __builtin_ctzll(m1); m1 &= m1 - 1ull;
;               id = __builtin_amdgcn_readlane(e1[ts], l);
;               we[k] = __int_as_float(__builtin_amdgcn_readlane(__float_as_int(w1[ts]), l));
;             }
;             v[k] = *(const u32x4 AS1*)(EV8 + (size_t)id * 1024 + lane * 16);
;           }
.Lvb1_1448:
	s_cmp_eq_u64 s[10:11], 0
	s_cbranch_scc1 .Lvb1_1468
	s_add_u32 s50, s10, -1
	s_ff1_i32_b64 s45, s[10:11]
	s_addc_u32 s51, s11, -1
	s_and_b64 s[10:11], s[50:51], s[10:11]
	v_readlane_b32 s52, v69, s45
	s_waitcnt lgkmcnt(0)
	v_readlane_b32 s50, v106, s45
	s_cbranch_execnz .Lvb1_1451
.Lvb1_1450:
	s_add_u32 s10, s6, -1
	s_ff1_i32_b64 s45, s[6:7]
	s_addc_u32 s11, s7, -1
	s_and_b64 s[6:7], s[10:11], s[6:7]
	v_readlane_b32 s52, v137, s45
	s_waitcnt lgkmcnt(0)
	v_readlane_b32 s50, v107, s45
	s_mov_b64 s[10:11], 0

; #define AS1 __attribute__((address_space(1)))
; DI void peer_v_group(const Params& p, int gw, int nw, int g, const float* wlw  ) {
;     ...
;         for (int k = 0; k < 8; ++k) {
;           we[k] = 0.f;
;           v[k] = (u32x4){0u, 0u, 0u, 0u};
;           if ((m0 | m1) != 0ull) {
;             int l, id;
;             if (m0 != 0ull) {
;               l = __builtin_ctzll(m0); m0 &= m0 - 1ull;
;               id = __builtin_amdgcn_readlane(e0[ts], l);
;               we[k] = __int_as_float(__builtin_amdgcn_readlane(__float_as_int(w0[ts]), l));
;             } else {
;               l = __builtin_ctzll(m1); m1 &= m1 - 1ull;
;               id = __builtin_amdgcn_readlane(e1[ts], l);
;               we[k] = __int_as_float(__builtin_amdgcn_readlane(__float_as_int(w1[ts]), l));
;             }
;             v[k] = *(const u32x4 AS1*)(EV8 + (size_t)id * 1024 + lane * 16);
;           }
.Lvb1_1452:
	s_cmp_eq_u64 s[10:11], 0
	s_cbranch_scc1 .Lvb1_1469
	s_add_u32 s52, s10, -1
	s_ff1_i32_b64 s45, s[10:11]
	s_addc_u32 s53, s11, -1
	s_and_b64 s[10:11], s[52:53], s[10:11]
	v_readlane_b32 s54, v69, s45
	s_waitcnt lgkmcnt(0)
	v_readlane_b32 s52, v106, s45
	s_cbranch_execnz .Lvb1_1455
.Lvb1_1454:
	s_add_u32 s10, s6, -1
	s_ff1_i32_b64 s45, s[6:7]
	s_addc_u32 s11, s7, -1
	s_and_b64 s[6:7], s[10:11], s[6:7]
	v_readlane_b32 s54, v137, s45
	s_waitcnt lgkmcnt(0)
	v_readlane_b32 s52, v107, s45
	s_mov_b64 s[10:11], 0

; #define AS1 __attribute__((address_space(1)))
; DI void peer_v_group(const Params& p, int gw, int nw, int g, const float* wlw  ) {
;     ...
;         for (int k = 0; k < 8; ++k) {
;           we[k] = 0.f;
;           v[k] = (u32x4){0u, 0u, 0u, 0u};
;           if ((m0 | m1) != 0ull) {
;             int l, id;
;             if (m0 != 0ull) {
;               l = __builtin_ctzll(m0); m0 &= m0 - 1ull;
;               id = __builtin_amdgcn_readlane(e0[ts], l);
;               we[k] = __int_as_float(__builtin_amdgcn_readlane(__float_as_int(w0[ts]), l));
;             } else {
;               l = __builtin_ctzll(m1); m1 &= m1 - 1ull;
;               id = __builtin_amdgcn_readlane(e1[ts], l);
;               we[k] = __int_as_float(__builtin_amdgcn_readlane(__float_as_int(w1[ts]), l));
;             }
;             v[k] = *(const u32x4 AS1*)(EV8 + (size_t)id * 1024 + lane * 16);
;           }
.Lvb1_1456:
	s_cmp_eq_u64 s[10:11], 0
	s_cbranch_scc1 .Lvb1_1470
	s_add_u32 s54, s10, -1
	s_ff1_i32_b64 s45, s[10:11]
	s_addc_u32 s55, s11, -1
	s_and_b64 s[10:11], s[54:55], s[10:11]
	v_readlane_b32 s56, v69, s45
	s_waitcnt lgkmcnt(0)
	v_readlane_b32 s54, v106, s45
	s_cbranch_execnz .Lvb1_1459
.Lvb1_1458:
	s_add_u32 s10, s6, -1
	s_ff1_i32_b64 s45, s[6:7]
	s_addc_u32 s11, s7, -1
	s_and_b64 s[6:7], s[10:11], s[6:7]
	v_readlane_b32 s56, v137, s45
	s_waitcnt lgkmcnt(0)
	v_readlane_b32 s54, v107, s45
	s_mov_b64 s[10:11], 0

; #define AS1 __attribute__((address_space(1)))
; DI void peer_v_group(const Params& p, int gw, int nw, int g, const float* wlw  ) {
;     ...
;         for (int k = 0; k < 8; ++k) {
;           we[k] = 0.f;
;           v[k] = (u32x4){0u, 0u, 0u, 0u};
;           if ((m0 | m1) != 0ull) {
;             int l, id;
;             if (m0 != 0ull) {
;               l = __builtin_ctzll(m0); m0 &= m0 - 1ull;
;               id = __builtin_amdgcn_readlane(e0[ts], l);
;               we[k] = __int_as_float(__builtin_amdgcn_readlane(__float_as_int(w0[ts]), l));
;             } else {
;               l = __builtin_ctzll(m1); m1 &= m1 - 1ull;
;               id = __builtin_amdgcn_readlane(e1[ts], l);
;               we[k] = __int_as_float(__builtin_amdgcn_readlane(__float_as_int(w1[ts]), l));
;             }
;             v[k] = *(const u32x4 AS1*)(EV8 + (size_t)id * 1024 + lane * 16);
;           }
.Lvb1_1460:
	s_cmp_eq_u64 s[10:11], 0
	s_cbranch_scc1 .Lvb1_1471
	s_add_u32 s56, s10, -1
	s_ff1_i32_b64 s45, s[10:11]
	s_addc_u32 s57, s11, -1
	s_and_b64 s[10:11], s[56:57], s[10:11]
	v_readlane_b32 s58, v69, s45
	s_waitcnt lgkmcnt(0)
	v_readlane_b32 s56, v106, s45
	s_cbranch_execnz .Lvb1_1463
.Lvb1_1462:
	s_add_u32 s10, s6, -1
	s_ff1_i32_b64 s45, s[6:7]
	s_addc_u32 s11, s7, -1
	s_and_b64 s[6:7], s[10:11], s[6:7]
	v_readlane_b32 s58, v137, s45
	s_waitcnt lgkmcnt(0)
	v_readlane_b32 s56, v107, s45
	s_mov_b64 s[10:11], 0

; DI void axpy16_fp8(float* o, float w, u32x4 u) {
;   const unsigned d[4] = {u[0], u[1], u[2], u[3]};
; #pragma unroll
;   for (int i = 0; i < 4; ++i) {
;     f32x2 a = __builtin_amdgcn_cvt_pk_f32_fp8((int)d[i], false);
;     f32x2 b = __builtin_amdgcn_cvt_pk_f32_fp8((int)d[i], true);
;     o[4 * i] += w * a[0]; o[4 * i + 1] += w * a[1]; o[4 * i + 2] += w * b[0]; o[4 * i + 3] += w * b[1];
;   }
; }
; DI void peer_v_group(const Params& p, int gw, int nw, int g, const float* wlw  ) {
;     ...
; #pragma unroll
;         for (int k = 0; k < 8; ++k) axpy16_fp8(out[ts], we[k], v[k]);
.LBB0_1473:
	s_waitcnt vmcnt(0)
	v_cvt_pk_f32_fp8_e32 v[148:149], v4
	v_cvt_pk_f32_fp8_sdwa v[150:151], v4 src0_sel:WORD_1
	v_cvt_pk_f32_fp8_e32 v[152:153], v5
	v_cvt_pk_f32_fp8_sdwa v[4:5], v5 src0_sel:WORD_1
	v_pk_fma_f32 v[70:71], s[12:13], v[148:149], v[70:71] op_sel_hi:[0,1,1]
	v_pk_fma_f32 v[72:73], s[12:13], v[150:151], v[72:73] op_sel_hi:[0,1,1]
	v_cvt_pk_f32_fp8_sdwa v[148:149], v6 src0_sel:WORD_1
	v_pk_fma_f32 v[4:5], s[12:13], v[4:5], v[76:77] op_sel_hi:[0,1,1]
	v_cvt_pk_f32_fp8_e32 v[76:77], v6
	v_cvt_pk_f32_fp8_e32 v[150:151], v7
	v_cvt_pk_f32_fp8_sdwa v[6:7], v7 src0_sel:WORD_1
	v_pk_fma_f32 v[80:81], s[12:13], v[148:149], v[80:81] op_sel_hi:[0,1,1]
	v_pk_fma_f32 v[78:79], s[12:13], v[76:77], v[78:79] op_sel_hi:[0,1,1]
	v_cvt_pk_f32_fp8_e32 v[76:77], v8
	v_pk_fma_f32 v[6:7], s[12:13], v[6:7], v[84:85] op_sel_hi:[0,1,1]
	v_cvt_pk_f32_fp8_sdwa v[84:85], v8 src0_sel:WORD_1
	v_cvt_pk_f32_fp8_e32 v[148:149], v9
	v_cvt_pk_f32_fp8_sdwa v[8:9], v9 src0_sel:WORD_1
	v_cvt_pk_f32_fp8_e32 v[156:157], v12
	v_cvt_pk_f32_fp8_sdwa v[158:159], v12 src0_sel:WORD_1
	v_cvt_pk_f32_fp8_e32 v[160:161], v13
	v_cvt_pk_f32_fp8_sdwa v[12:13], v13 src0_sel:WORD_1
	v_cvt_pk_f32_fp8_e32 v[170:171], v16
	v_cvt_pk_f32_fp8_sdwa v[172:173], v16 src0_sel:WORD_1
	v_cvt_pk_f32_fp8_e32 v[174:175], v17
	v_cvt_pk_f32_fp8_sdwa v[16:17], v17 src0_sel:WORD_1
	v_pk_fma_f32 v[74:75], s[12:13], v[152:153], v[74:75] op_sel_hi:[0,1,1]
	v_cvt_pk_f32_fp8_e32 v[182:183], v20
	v_cvt_pk_f32_fp8_sdwa v[184:185], v20 src0_sel:WORD_1
	v_cvt_pk_f32_fp8_e32 v[186:187], v21
	v_cvt_pk_f32_fp8_sdwa v[20:21], v21 src0_sel:WORD_1
	v_pk_fma_f32 v[82:83], s[12:13], v[150:151], v[82:83] op_sel_hi:[0,1,1]
	v_cvt_pk_f32_fp8_e32 v[150:151], v10
	v_cvt_pk_f32_fp8_e32 v[194:195], v24
	v_cvt_pk_f32_fp8_sdwa v[196:197], v24 src0_sel:WORD_1
	v_cvt_pk_f32_fp8_e32 v[198:199], v25
	v_cvt_pk_f32_fp8_sdwa v[24:25], v25 src0_sel:WORD_1
	v_pk_fma_f32 v[74:75], s[14:15], v[148:149], v[74:75] op_sel_hi:[0,1,1]
	v_pk_fma_f32 v[4:5], s[14:15], v[8:9], v[4:5] op_sel_hi:[0,1,1]
	v_cvt_pk_f32_fp8_e32 v[164:165], v14
	v_cvt_pk_f32_fp8_e32 v[206:207], v28
	v_cvt_pk_f32_fp8_sdwa v[208:209], v28 src0_sel:WORD_1
	v_cvt_pk_f32_fp8_e32 v[210:211], v29
	v_cvt_pk_f32_fp8_sdwa v[28:29], v29 src0_sel:WORD_1
	v_pk_fma_f32 v[74:75], s[16:17], v[160:161], v[74:75] op_sel_hi:[0,1,1]
	v_pk_fma_f32 v[4:5], s[16:17], v[12:13], v[4:5] op_sel_hi:[0,1,1]
	v_cvt_pk_f32_fp8_e32 v[176:177], v18
	v_cvt_pk_f32_fp8_e32 v[218:219], v32
	v_cvt_pk_f32_fp8_sdwa v[220:221], v32 src0_sel:WORD_1
	v_pk_fma_f32 v[70:71], s[14:15], v[76:77], v[70:71] op_sel_hi:[0,1,1]
	v_cvt_pk_f32_fp8_e32 v[76:77], v33
	v_cvt_pk_f32_fp8_sdwa v[32:33], v33 src0_sel:WORD_1
	v_pk_fma_f32 v[74:75], s[18:19], v[174:175], v[74:75] op_sel_hi:[0,1,1]
	v_pk_fma_f32 v[4:5], s[18:19], v[16:17], v[4:5] op_sel_hi:[0,1,1]
	v_cvt_pk_f32_fp8_e32 v[188:189], v22
	v_pk_fma_f32 v[74:75], s[20:21], v[186:187], v[74:75] op_sel_hi:[0,1,1]
	v_pk_fma_f32 v[4:5], s[20:21], v[20:21], v[4:5] op_sel_hi:[0,1,1]
	v_cvt_pk_f32_fp8_e32 v[200:201], v26
	v_pk_fma_f32 v[74:75], s[22:23], v[198:199], v[74:75] op_sel_hi:[0,1,1]
	v_pk_fma_f32 v[4:5], s[22:23], v[24:25], v[4:5] op_sel_hi:[0,1,1]
	v_pk_fma_f32 v[12:13], s[14:15], v[150:151], v[78:79] op_sel_hi:[0,1,1]
	v_cvt_pk_f32_fp8_e32 v[212:213], v30
	v_pk_fma_f32 v[74:75], s[24:25], v[210:211], v[74:75] op_sel_hi:[0,1,1]
	v_pk_fma_f32 v[4:5], s[24:25], v[28:29], v[4:5] op_sel_hi:[0,1,1]
	v_pk_fma_f32 v[12:13], s[16:17], v[164:165], v[12:13] op_sel_hi:[0,1,1]
	v_cvt_pk_f32_fp8_sdwa v[152:153], v10 src0_sel:WORD_1
	v_pk_fma_f32 v[74:75], s[26:27], v[76:77], v[74:75] op_sel_hi:[0,1,1]
	v_pk_fma_f32 v[76:77], s[26:27], v[32:33], v[4:5] op_sel_hi:[0,1,1]
	v_cvt_pk_f32_fp8_e32 v[4:5], v34
	v_pk_fma_f32 v[12:13], s[18:19], v[176:177], v[12:13] op_sel_hi:[0,1,1]
	v_cvt_pk_f32_fp8_sdwa v[166:167], v14 src0_sel:WORD_1
	v_pk_fma_f32 v[12:13], s[20:21], v[188:189], v[12:13] op_sel_hi:[0,1,1]
	v_cvt_pk_f32_fp8_sdwa v[178:179], v18 src0_sel:WORD_1
	v_pk_fma_f32 v[12:13], s[22:23], v[200:201], v[12:13] op_sel_hi:[0,1,1]
	v_cvt_pk_f32_fp8_sdwa v[190:191], v22 src0_sel:WORD_1
	v_pk_fma_f32 v[12:13], s[24:25], v[212:213], v[12:13] op_sel_hi:[0,1,1]
	v_cvt_pk_f32_fp8_e32 v[154:155], v11
	v_cvt_pk_f32_fp8_sdwa v[202:203], v26 src0_sel:WORD_1
	v_pk_fma_f32 v[78:79], s[26:27], v[4:5], v[12:13] op_sel_hi:[0,1,1]
	v_pk_fma_f32 v[4:5], s[14:15], v[152:153], v[80:81] op_sel_hi:[0,1,1]
	v_cvt_pk_f32_fp8_e32 v[168:169], v15
	v_cvt_pk_f32_fp8_sdwa v[214:215], v30 src0_sel:WORD_1
	v_pk_fma_f32 v[4:5], s[16:17], v[166:167], v[4:5] op_sel_hi:[0,1,1]
	v_cvt_pk_f32_fp8_e32 v[180:181], v19
	v_cvt_pk_f32_fp8_sdwa v[8:9], v34 src0_sel:WORD_1
	v_pk_fma_f32 v[4:5], s[18:19], v[178:179], v[4:5] op_sel_hi:[0,1,1]
	v_cvt_pk_f32_fp8_e32 v[192:193], v23
	v_pk_fma_f32 v[4:5], s[20:21], v[190:191], v[4:5] op_sel_hi:[0,1,1]
	v_cvt_pk_f32_fp8_e32 v[204:205], v27
	v_pk_fma_f32 v[4:5], s[22:23], v[202:203], v[4:5] op_sel_hi:[0,1,1]
	v_pk_fma_f32 v[12:13], s[14:15], v[154:155], v[82:83] op_sel_hi:[0,1,1]
	v_cvt_pk_f32_fp8_e32 v[216:217], v31
	v_pk_fma_f32 v[4:5], s[24:25], v[214:215], v[4:5] op_sel_hi:[0,1,1]
	v_pk_fma_f32 v[12:13], s[16:17], v[168:169], v[12:13] op_sel_hi:[0,1,1]
	v_cvt_pk_f32_fp8_sdwa v[10:11], v11 src0_sel:WORD_1
	v_pk_fma_f32 v[80:81], s[26:27], v[8:9], v[4:5] op_sel_hi:[0,1,1]
	v_cvt_pk_f32_fp8_e32 v[4:5], v35
	v_pk_fma_f32 v[12:13], s[18:19], v[180:181], v[12:13] op_sel_hi:[0,1,1]
	v_cvt_pk_f32_fp8_sdwa v[14:15], v15 src0_sel:WORD_1
	v_pk_fma_f32 v[12:13], s[20:21], v[192:193], v[12:13] op_sel_hi:[0,1,1]
	v_cvt_pk_f32_fp8_sdwa v[18:19], v19 src0_sel:WORD_1
; DI void axpy16_fp8(float* o, float w, u32x4 u) {
;   const unsigned d[4] = {u[0], u[1], u[2], u[3]};
; #pragma unroll
;   for (int i = 0; i < 4; ++i) {
;     f32x2 a = __builtin_amdgcn_cvt_pk_f32_fp8((int)d[i], false);
;     f32x2 b = __builtin_amdgcn_cvt_pk_f32_fp8((int)d[i], true);
;     o[4 * i] += w * a[0]; o[4 * i + 1] += w * a[1]; o[4 * i + 2] += w * b[0]; o[4 * i + 3] += w * b[1];
;   }
; }
; DI void peer_v_group(const Params& p, int gw, int nw, int g, const float* wlw  ) {
;     ...
; #pragma unroll
;         for (int k = 0; k < 8; ++k) axpy16_fp8(out[ts], we[k], v[k]);
	v_pk_fma_f32 v[12:13], s[22:23], v[204:205], v[12:13] op_sel_hi:[0,1,1]
	v_cvt_pk_f32_fp8_sdwa v[22:23], v23 src0_sel:WORD_1
	v_pk_fma_f32 v[12:13], s[24:25], v[216:217], v[12:13] op_sel_hi:[0,1,1]
	v_cvt_pk_f32_fp8_sdwa v[26:27], v27 src0_sel:WORD_1
	v_pk_fma_f32 v[72:73], s[14:15], v[84:85], v[72:73] op_sel_hi:[0,1,1]
	v_pk_fma_f32 v[82:83], s[26:27], v[4:5], v[12:13] op_sel_hi:[0,1,1]
	v_pk_fma_f32 v[4:5], s[14:15], v[10:11], v[6:7] op_sel_hi:[0,1,1]
	v_cvt_pk_f32_fp8_sdwa v[30:31], v31 src0_sel:WORD_1
	v_pk_fma_f32 v[70:71], s[16:17], v[156:157], v[70:71] op_sel_hi:[0,1,1]
	v_pk_fma_f32 v[72:73], s[16:17], v[158:159], v[72:73] op_sel_hi:[0,1,1]
	v_pk_fma_f32 v[4:5], s[16:17], v[14:15], v[4:5] op_sel_hi:[0,1,1]
	v_pk_fma_f32 v[70:71], s[18:19], v[170:171], v[70:71] op_sel_hi:[0,1,1]
	v_pk_fma_f32 v[72:73], s[18:19], v[172:173], v[72:73] op_sel_hi:[0,1,1]
	v_cvt_pk_f32_fp8_sdwa v[8:9], v35 src0_sel:WORD_1
	v_pk_fma_f32 v[4:5], s[18:19], v[18:19], v[4:5] op_sel_hi:[0,1,1]
	v_pk_fma_f32 v[70:71], s[20:21], v[182:183], v[70:71] op_sel_hi:[0,1,1]
	v_pk_fma_f32 v[72:73], s[20:21], v[184:185], v[72:73] op_sel_hi:[0,1,1]
	v_pk_fma_f32 v[4:5], s[20:21], v[22:23], v[4:5] op_sel_hi:[0,1,1]
	v_pk_fma_f32 v[70:71], s[22:23], v[194:195], v[70:71] op_sel_hi:[0,1,1]
	v_pk_fma_f32 v[72:73], s[22:23], v[196:197], v[72:73] op_sel_hi:[0,1,1]
	v_pk_fma_f32 v[4:5], s[22:23], v[26:27], v[4:5] op_sel_hi:[0,1,1]
	v_pk_fma_f32 v[70:71], s[24:25], v[206:207], v[70:71] op_sel_hi:[0,1,1]
	v_pk_fma_f32 v[72:73], s[24:25], v[208:209], v[72:73] op_sel_hi:[0,1,1]
	v_pk_fma_f32 v[4:5], s[24:25], v[30:31], v[4:5] op_sel_hi:[0,1,1]
	s_or_b64 s[14:15], s[10:11], s[6:7]
	v_pk_fma_f32 v[70:71], s[26:27], v[218:219], v[70:71] op_sel_hi:[0,1,1]
	v_pk_fma_f32 v[72:73], s[26:27], v[220:221], v[72:73] op_sel_hi:[0,1,1]
	s_cmp_lg_u64 s[14:15], 0
	v_pk_fma_f32 v[84:85], s[26:27], v[8:9], v[4:5] op_sel_hi:[0,1,1]
	s_cmp_eq_u64 s[60:61], 0
	s_cbranch_scc1 .Lvb_skip2
	v_cvt_pk_f32_fp8_e32 v[148:149], v222
	v_cvt_pk_f32_fp8_sdwa v[150:151], v222 src0_sel:WORD_1
	v_cvt_pk_f32_fp8_e32 v[152:153], v223
	v_cvt_pk_f32_fp8_sdwa v[222:223], v223 src0_sel:WORD_1
	v_pk_fma_f32 v[70:71], s[42:43], v[148:149], v[70:71] op_sel_hi:[0,1,1]
	v_pk_fma_f32 v[72:73], s[42:43], v[150:151], v[72:73] op_sel_hi:[0,1,1]
	v_cvt_pk_f32_fp8_sdwa v[148:149], v224 src0_sel:WORD_1
	v_pk_fma_f32 v[222:223], s[42:43], v[222:223], v[76:77] op_sel_hi:[0,1,1]
	v_cvt_pk_f32_fp8_e32 v[76:77], v224
	v_cvt_pk_f32_fp8_e32 v[150:151], v225
	v_cvt_pk_f32_fp8_sdwa v[224:225], v225 src0_sel:WORD_1
	v_pk_fma_f32 v[80:81], s[42:43], v[148:149], v[80:81] op_sel_hi:[0,1,1]
	v_pk_fma_f32 v[78:79], s[42:43], v[76:77], v[78:79] op_sel_hi:[0,1,1]
	v_cvt_pk_f32_fp8_e32 v[76:77], v226
	v_pk_fma_f32 v[224:225], s[42:43], v[224:225], v[84:85] op_sel_hi:[0,1,1]
	v_cvt_pk_f32_fp8_sdwa v[84:85], v226 src0_sel:WORD_1
	v_cvt_pk_f32_fp8_e32 v[148:149], v227
	v_cvt_pk_f32_fp8_sdwa v[226:227], v227 src0_sel:WORD_1
	v_cvt_pk_f32_fp8_e32 v[156:157], v230
	v_cvt_pk_f32_fp8_sdwa v[158:159], v230 src0_sel:WORD_1
	v_cvt_pk_f32_fp8_e32 v[160:161], v231
	v_cvt_pk_f32_fp8_sdwa v[230:231], v231 src0_sel:WORD_1
	v_cvt_pk_f32_fp8_e32 v[170:171], v234
	v_cvt_pk_f32_fp8_sdwa v[172:173], v234 src0_sel:WORD_1
	v_cvt_pk_f32_fp8_e32 v[174:175], v235
	v_cvt_pk_f32_fp8_sdwa v[234:235], v235 src0_sel:WORD_1
	v_pk_fma_f32 v[74:75], s[42:43], v[152:153], v[74:75] op_sel_hi:[0,1,1]
	v_cvt_pk_f32_fp8_e32 v[182:183], v238
	v_cvt_pk_f32_fp8_sdwa v[184:185], v238 src0_sel:WORD_1
	v_cvt_pk_f32_fp8_e32 v[186:187], v239
	v_cvt_pk_f32_fp8_sdwa v[238:239], v239 src0_sel:WORD_1
	v_pk_fma_f32 v[82:83], s[42:43], v[150:151], v[82:83] op_sel_hi:[0,1,1]
	v_cvt_pk_f32_fp8_e32 v[150:151], v228
	v_cvt_pk_f32_fp8_e32 v[194:195], v242
	v_cvt_pk_f32_fp8_sdwa v[196:197], v242 src0_sel:WORD_1
	v_cvt_pk_f32_fp8_e32 v[198:199], v243
	v_cvt_pk_f32_fp8_sdwa v[242:243], v243 src0_sel:WORD_1
	v_pk_fma_f32 v[74:75], s[44:45], v[148:149], v[74:75] op_sel_hi:[0,1,1]
	v_pk_fma_f32 v[222:223], s[44:45], v[226:227], v[222:223] op_sel_hi:[0,1,1]
	v_cvt_pk_f32_fp8_e32 v[164:165], v232
	v_cvt_pk_f32_fp8_e32 v[206:207], v246
	v_cvt_pk_f32_fp8_sdwa v[208:209], v246 src0_sel:WORD_1
	v_cvt_pk_f32_fp8_e32 v[210:211], v247
	v_cvt_pk_f32_fp8_sdwa v[246:247], v247 src0_sel:WORD_1
	v_pk_fma_f32 v[74:75], s[46:47], v[160:161], v[74:75] op_sel_hi:[0,1,1]
	v_pk_fma_f32 v[222:223], s[46:47], v[230:231], v[222:223] op_sel_hi:[0,1,1]
	v_cvt_pk_f32_fp8_e32 v[176:177], v236
	v_cvt_pk_f32_fp8_e32 v[218:219], v250
	v_cvt_pk_f32_fp8_sdwa v[220:221], v250 src0_sel:WORD_1
	v_pk_fma_f32 v[70:71], s[44:45], v[76:77], v[70:71] op_sel_hi:[0,1,1]
	v_cvt_pk_f32_fp8_e32 v[76:77], v251
	v_cvt_pk_f32_fp8_sdwa v[250:251], v251 src0_sel:WORD_1
	v_pk_fma_f32 v[74:75], s[48:49], v[174:175], v[74:75] op_sel_hi:[0,1,1]
	v_pk_fma_f32 v[222:223], s[48:49], v[234:235], v[222:223] op_sel_hi:[0,1,1]
; DI void axpy16_fp8(float* o, float w, u32x4 u) {
;   const unsigned d[4] = {u[0], u[1], u[2], u[3]};
; #pragma unroll
;   for (int i = 0; i < 4; ++i) {
;     f32x2 a = __builtin_amdgcn_cvt_pk_f32_fp8((int)d[i], false);
;     f32x2 b = __builtin_amdgcn_cvt_pk_f32_fp8((int)d[i], true);
;     o[4 * i] += w * a[0]; o[4 * i + 1] += w * a[1]; o[4 * i + 2] += w * b[0]; o[4 * i + 3] += w * b[1];
;   }
; }
; DI void peer_v_group(const Params& p, int gw, int nw, int g, const float* wlw  ) {
;     ...
; #pragma unroll
;         for (int k = 0; k < 8; ++k) axpy16_fp8(out[ts], we[k], v[k]);
	v_cvt_pk_f32_fp8_e32 v[188:189], v240
	v_pk_fma_f32 v[74:75], s[50:51], v[186:187], v[74:75] op_sel_hi:[0,1,1]
	v_pk_fma_f32 v[222:223], s[50:51], v[238:239], v[222:223] op_sel_hi:[0,1,1]
	v_cvt_pk_f32_fp8_e32 v[200:201], v244
	v_pk_fma_f32 v[74:75], s[52:53], v[198:199], v[74:75] op_sel_hi:[0,1,1]
	v_pk_fma_f32 v[222:223], s[52:53], v[242:243], v[222:223] op_sel_hi:[0,1,1]
	v_pk_fma_f32 v[230:231], s[44:45], v[150:151], v[78:79] op_sel_hi:[0,1,1]
	v_cvt_pk_f32_fp8_e32 v[212:213], v248
	v_pk_fma_f32 v[74:75], s[54:55], v[210:211], v[74:75] op_sel_hi:[0,1,1]
	v_pk_fma_f32 v[222:223], s[54:55], v[246:247], v[222:223] op_sel_hi:[0,1,1]
	v_pk_fma_f32 v[230:231], s[46:47], v[164:165], v[230:231] op_sel_hi:[0,1,1]
	v_cvt_pk_f32_fp8_sdwa v[152:153], v228 src0_sel:WORD_1
	v_pk_fma_f32 v[74:75], s[56:57], v[76:77], v[74:75] op_sel_hi:[0,1,1]
	v_pk_fma_f32 v[76:77], s[56:57], v[250:251], v[222:223] op_sel_hi:[0,1,1]
	v_cvt_pk_f32_fp8_e32 v[222:223], v252
	v_pk_fma_f32 v[230:231], s[48:49], v[176:177], v[230:231] op_sel_hi:[0,1,1]
	v_cvt_pk_f32_fp8_sdwa v[166:167], v232 src0_sel:WORD_1
	v_pk_fma_f32 v[230:231], s[50:51], v[188:189], v[230:231] op_sel_hi:[0,1,1]
	v_cvt_pk_f32_fp8_sdwa v[178:179], v236 src0_sel:WORD_1
	v_pk_fma_f32 v[230:231], s[52:53], v[200:201], v[230:231] op_sel_hi:[0,1,1]
	v_cvt_pk_f32_fp8_sdwa v[190:191], v240 src0_sel:WORD_1
	v_pk_fma_f32 v[230:231], s[54:55], v[212:213], v[230:231] op_sel_hi:[0,1,1]
	v_cvt_pk_f32_fp8_e32 v[154:155], v229
	v_cvt_pk_f32_fp8_sdwa v[202:203], v244 src0_sel:WORD_1
	v_pk_fma_f32 v[78:79], s[56:57], v[222:223], v[230:231] op_sel_hi:[0,1,1]
	v_pk_fma_f32 v[222:223], s[44:45], v[152:153], v[80:81] op_sel_hi:[0,1,1]
	v_cvt_pk_f32_fp8_e32 v[168:169], v233
	v_cvt_pk_f32_fp8_sdwa v[214:215], v248 src0_sel:WORD_1
	v_pk_fma_f32 v[222:223], s[46:47], v[166:167], v[222:223] op_sel_hi:[0,1,1]
	v_cvt_pk_f32_fp8_e32 v[180:181], v237
	v_cvt_pk_f32_fp8_sdwa v[226:227], v252 src0_sel:WORD_1
	v_pk_fma_f32 v[222:223], s[48:49], v[178:179], v[222:223] op_sel_hi:[0,1,1]
	v_cvt_pk_f32_fp8_e32 v[192:193], v241
	v_pk_fma_f32 v[222:223], s[50:51], v[190:191], v[222:223] op_sel_hi:[0,1,1]
	v_cvt_pk_f32_fp8_e32 v[204:205], v245
	v_pk_fma_f32 v[222:223], s[52:53], v[202:203], v[222:223] op_sel_hi:[0,1,1]
	v_pk_fma_f32 v[230:231], s[44:45], v[154:155], v[82:83] op_sel_hi:[0,1,1]
	v_cvt_pk_f32_fp8_e32 v[216:217], v249
	v_pk_fma_f32 v[222:223], s[54:55], v[214:215], v[222:223] op_sel_hi:[0,1,1]
	v_pk_fma_f32 v[230:231], s[46:47], v[168:169], v[230:231] op_sel_hi:[0,1,1]
	v_cvt_pk_f32_fp8_sdwa v[228:229], v229 src0_sel:WORD_1
	v_pk_fma_f32 v[80:81], s[56:57], v[226:227], v[222:223] op_sel_hi:[0,1,1]
	v_cvt_pk_f32_fp8_e32 v[222:223], v253
	v_pk_fma_f32 v[230:231], s[48:49], v[180:181], v[230:231] op_sel_hi:[0,1,1]
	v_cvt_pk_f32_fp8_sdwa v[232:233], v233 src0_sel:WORD_1
	v_pk_fma_f32 v[230:231], s[50:51], v[192:193], v[230:231] op_sel_hi:[0,1,1]
	v_cvt_pk_f32_fp8_sdwa v[236:237], v237 src0_sel:WORD_1
	v_pk_fma_f32 v[230:231], s[52:53], v[204:205], v[230:231] op_sel_hi:[0,1,1]
	v_cvt_pk_f32_fp8_sdwa v[240:241], v241 src0_sel:WORD_1
	v_pk_fma_f32 v[230:231], s[54:55], v[216:217], v[230:231] op_sel_hi:[0,1,1]
	v_cvt_pk_f32_fp8_sdwa v[244:245], v245 src0_sel:WORD_1
	v_pk_fma_f32 v[72:73], s[44:45], v[84:85], v[72:73] op_sel_hi:[0,1,1]
	v_pk_fma_f32 v[82:83], s[56:57], v[222:223], v[230:231] op_sel_hi:[0,1,1]
	v_pk_fma_f32 v[222:223], s[44:45], v[228:229], v[224:225] op_sel_hi:[0,1,1]
	v_cvt_pk_f32_fp8_sdwa v[248:249], v249 src0_sel:WORD_1
	v_pk_fma_f32 v[70:71], s[46:47], v[156:157], v[70:71] op_sel_hi:[0,1,1]
	v_pk_fma_f32 v[72:73], s[46:47], v[158:159], v[72:73] op_sel_hi:[0,1,1]
	v_pk_fma_f32 v[222:223], s[46:47], v[232:233], v[222:223] op_sel_hi:[0,1,1]
	v_pk_fma_f32 v[70:71], s[48:49], v[170:171], v[70:71] op_sel_hi:[0,1,1]
	v_pk_fma_f32 v[72:73], s[48:49], v[172:173], v[72:73] op_sel_hi:[0,1,1]
	v_cvt_pk_f32_fp8_sdwa v[226:227], v253 src0_sel:WORD_1
	v_pk_fma_f32 v[222:223], s[48:49], v[236:237], v[222:223] op_sel_hi:[0,1,1]
	v_pk_fma_f32 v[70:71], s[50:51], v[182:183], v[70:71] op_sel_hi:[0,1,1]
	v_pk_fma_f32 v[72:73], s[50:51], v[184:185], v[72:73] op_sel_hi:[0,1,1]
	v_pk_fma_f32 v[222:223], s[50:51], v[240:241], v[222:223] op_sel_hi:[0,1,1]
	v_pk_fma_f32 v[70:71], s[52:53], v[194:195], v[70:71] op_sel_hi:[0,1,1]
	v_pk_fma_f32 v[72:73], s[52:53], v[196:197], v[72:73] op_sel_hi:[0,1,1]
	v_pk_fma_f32 v[222:223], s[52:53], v[244:245], v[222:223] op_sel_hi:[0,1,1]
	v_pk_fma_f32 v[70:71], s[54:55], v[206:207], v[70:71] op_sel_hi:[0,1,1]
	v_pk_fma_f32 v[72:73], s[54:55], v[208:209], v[72:73] op_sel_hi:[0,1,1]
	v_pk_fma_f32 v[222:223], s[54:55], v[248:249], v[222:223] op_sel_hi:[0,1,1]
	v_pk_fma_f32 v[70:71], s[56:57], v[218:219], v[70:71] op_sel_hi:[0,1,1]
	v_pk_fma_f32 v[72:73], s[56:57], v[220:221], v[72:73] op_sel_hi:[0,1,1]
	v_pk_fma_f32 v[84:85], s[56:57], v[226:227], v[222:223] op_sel_hi:[0,1,1]

; #define AS1 __attribute__((address_space(1)))
; DI void peer_v_group(const Params& p, int gw, int nw, int g, const float* wlw  ) {
;     ...
;       while ((m0 | m1) != 0ull) {
;         u32x4 v[8];
;         float we[8];
; #pragma unroll
;         for (int k = 0; k < 8; ++k) {
;           we[k] = 0.f;
;           v[k] = (u32x4){0u, 0u, 0u, 0u};
;           if ((m0 | m1) != 0ull) {
;             int l, id;
;             if (m0 != 0ull) {
;               l = __builtin_ctzll(m0); m0 &= m0 - 1ull;
;               id = __builtin_amdgcn_readlane(e0[ts], l);
;               we[k] = __int_as_float(__builtin_amdgcn_readlane(__float_as_int(w0[ts]), l));
;             } else {
;               l = __builtin_ctzll(m1); m1 &= m1 - 1ull;
;               id = __builtin_amdgcn_readlane(e1[ts], l);
;               we[k] = __int_as_float(__builtin_amdgcn_readlane(__float_as_int(w1[ts]), l));
;             }
;             v[k] = *(const u32x4 AS1*)(EV8 + (size_t)id * 1024 + lane * 16);
;           }
.Lvb_g2:
	s_or_b64 s[60:61], s[6:7], s[10:11]
	s_or_b64 s[44:45], s[6:7], s[10:11]
	s_cmp_eq_u64 s[44:45], 0
	s_cbranch_scc1 .Lvb2_1488
	s_cmp_eq_u64 s[10:11], 0
	s_cbranch_scc1 .Lvb2_1514
	s_add_u32 s44, s10, -1
	s_ff1_i32_b64 s42, s[10:11]
	s_addc_u32 s45, s11, -1
	s_and_b64 s[10:11], s[44:45], s[10:11]
	v_readlane_b32 s44, v51, s42
	s_waitcnt lgkmcnt(0)
	v_readlane_b32 s42, v110, s42
	s_cbranch_execnz .Lvb2_1478
.Lvb2_1477:
	s_add_u32 s10, s6, -1
	s_ff1_i32_b64 s42, s[6:7]
	s_addc_u32 s11, s7, -1
	s_and_b64 s[6:7], s[10:11], s[6:7]
	v_readlane_b32 s44, v138, s42
	s_waitcnt lgkmcnt(0)
	v_readlane_b32 s42, v111, s42
	s_mov_b64 s[10:11], 0

; #define AS1 __attribute__((address_space(1)))
; DI void peer_v_group(const Params& p, int gw, int nw, int g, const float* wlw  ) {
;     ...
;         for (int k = 0; k < 8; ++k) {
;           we[k] = 0.f;
;           v[k] = (u32x4){0u, 0u, 0u, 0u};
;           if ((m0 | m1) != 0ull) {
;             int l, id;
;             if (m0 != 0ull) {
;               l = __builtin_ctzll(m0); m0 &= m0 - 1ull;
;               id = __builtin_amdgcn_readlane(e0[ts], l);
;               we[k] = __int_as_float(__builtin_amdgcn_readlane(__float_as_int(w0[ts]), l));
;             } else {
;               l = __builtin_ctzll(m1); m1 &= m1 - 1ull;
;               id = __builtin_amdgcn_readlane(e1[ts], l);
;               we[k] = __int_as_float(__builtin_amdgcn_readlane(__float_as_int(w1[ts]), l));
;             }
;             v[k] = *(const u32x4 AS1*)(EV8 + (size_t)id * 1024 + lane * 16);
;           }
.Lvb2_1479:
	s_cmp_eq_u64 s[10:11], 0
	s_cbranch_scc1 .Lvb2_1515
	s_add_u32 s44, s10, -1
	s_ff1_i32_b64 s47, s[10:11]
	s_addc_u32 s45, s11, -1
	s_and_b64 s[10:11], s[44:45], s[10:11]
	v_readlane_b32 s46, v51, s47
	s_waitcnt lgkmcnt(0)
	v_readlane_b32 s44, v110, s47
	s_cbranch_execnz .Lvb2_1482
.Lvb2_1481:
	s_add_u32 s10, s6, -1
	s_ff1_i32_b64 s44, s[6:7]
	s_addc_u32 s11, s7, -1
	s_and_b64 s[6:7], s[10:11], s[6:7]
	v_readlane_b32 s46, v138, s44
	s_waitcnt lgkmcnt(0)
	v_readlane_b32 s44, v111, s44
	s_mov_b64 s[10:11], 0

; #define AS1 __attribute__((address_space(1)))
; DI void peer_v_group(const Params& p, int gw, int nw, int g, const float* wlw  ) {
;     ...
;         for (int k = 0; k < 8; ++k) {
;           we[k] = 0.f;
;           v[k] = (u32x4){0u, 0u, 0u, 0u};
;           if ((m0 | m1) != 0ull) {
;             int l, id;
;             if (m0 != 0ull) {
;               l = __builtin_ctzll(m0); m0 &= m0 - 1ull;
;               id = __builtin_amdgcn_readlane(e0[ts], l);
;               we[k] = __int_as_float(__builtin_amdgcn_readlane(__float_as_int(w0[ts]), l));
;             } else {
;               l = __builtin_ctzll(m1); m1 &= m1 - 1ull;
;               id = __builtin_amdgcn_readlane(e1[ts], l);
;               we[k] = __int_as_float(__builtin_amdgcn_readlane(__float_as_int(w1[ts]), l));
;             }
;             v[k] = *(const u32x4 AS1*)(EV8 + (size_t)id * 1024 + lane * 16);
;           }
.Lvb2_1490:
	s_cmp_eq_u64 s[10:11], 0
	s_cbranch_scc1 .Lvb2_1516
	s_add_u32 s46, s10, -1
	s_ff1_i32_b64 s45, s[10:11]
	s_addc_u32 s47, s11, -1
	s_and_b64 s[10:11], s[46:47], s[10:11]
	v_readlane_b32 s48, v51, s45
	s_waitcnt lgkmcnt(0)
	v_readlane_b32 s46, v110, s45
	s_cbranch_execnz .Lvb2_1493
.Lvb2_1492:
	s_add_u32 s10, s6, -1
	s_ff1_i32_b64 s45, s[6:7]
	s_addc_u32 s11, s7, -1
	s_and_b64 s[6:7], s[10:11], s[6:7]
	v_readlane_b32 s48, v138, s45
	s_waitcnt lgkmcnt(0)
	v_readlane_b32 s46, v111, s45
	s_mov_b64 s[10:11], 0

; #define AS1 __attribute__((address_space(1)))
; DI void peer_v_group(const Params& p, int gw, int nw, int g, const float* wlw  ) {
;     ...
;         for (int k = 0; k < 8; ++k) {
;           we[k] = 0.f;
;           v[k] = (u32x4){0u, 0u, 0u, 0u};
;           if ((m0 | m1) != 0ull) {
;             int l, id;
;             if (m0 != 0ull) {
;               l = __builtin_ctzll(m0); m0 &= m0 - 1ull;
;               id = __builtin_amdgcn_readlane(e0[ts], l);
;               we[k] = __int_as_float(__builtin_amdgcn_readlane(__float_as_int(w0[ts]), l));
;             } else {
;               l = __builtin_ctzll(m1); m1 &= m1 - 1ull;
;               id = __builtin_amdgcn_readlane(e1[ts], l);
;               we[k] = __int_as_float(__builtin_amdgcn_readlane(__float_as_int(w1[ts]), l));
;             }
;             v[k] = *(const u32x4 AS1*)(EV8 + (size_t)id * 1024 + lane * 16);
;           }
.Lvb2_1494:
	s_cmp_eq_u64 s[10:11], 0
	s_cbranch_scc1 .Lvb2_1517
	s_add_u32 s48, s10, -1
	s_ff1_i32_b64 s45, s[10:11]
	s_addc_u32 s49, s11, -1
	s_and_b64 s[10:11], s[48:49], s[10:11]
	v_readlane_b32 s50, v51, s45
	s_waitcnt lgkmcnt(0)
	v_readlane_b32 s48, v110, s45
	s_cbranch_execnz .Lvb2_1497
.Lvb2_1496:
	s_add_u32 s10, s6, -1
	s_ff1_i32_b64 s45, s[6:7]
	s_addc_u32 s11, s7, -1
	s_and_b64 s[6:7], s[10:11], s[6:7]
	v_readlane_b32 s50, v138, s45
	s_waitcnt lgkmcnt(0)
	v_readlane_b32 s48, v111, s45
	s_mov_b64 s[10:11], 0

; #define AS1 __attribute__((address_space(1)))
; DI void peer_v_group(const Params& p, int gw, int nw, int g, const float* wlw  ) {
;     ...
;         for (int k = 0; k < 8; ++k) {
;           we[k] = 0.f;
;           v[k] = (u32x4){0u, 0u, 0u, 0u};
;           if ((m0 | m1) != 0ull) {
;             int l, id;
;             if (m0 != 0ull) {
;               l = __builtin_ctzll(m0); m0 &= m0 - 1ull;
;               id = __builtin_amdgcn_readlane(e0[ts], l);
;               we[k] = __int_as_float(__builtin_amdgcn_readlane(__float_as_int(w0[ts]), l));
;             } else {
;               l = __builtin_ctzll(m1); m1 &= m1 - 1ull;
;               id = __builtin_amdgcn_readlane(e1[ts], l);
;               we[k] = __int_as_float(__builtin_amdgcn_readlane(__float_as_int(w1[ts]), l));
;             }
;             v[k] = *(const u32x4 AS1*)(EV8 + (size_t)id * 1024 + lane * 16);
;           }
.Lvb2_1498:
	s_cmp_eq_u64 s[10:11], 0
	s_cbranch_scc1 .Lvb2_1518
	s_add_u32 s50, s10, -1
	s_ff1_i32_b64 s45, s[10:11]
	s_addc_u32 s51, s11, -1
	s_and_b64 s[10:11], s[50:51], s[10:11]
	v_readlane_b32 s52, v51, s45
	s_waitcnt lgkmcnt(0)
	v_readlane_b32 s50, v110, s45
	s_cbranch_execnz .Lvb2_1501
.Lvb2_1500:
	s_add_u32 s10, s6, -1
	s_ff1_i32_b64 s45, s[6:7]
	s_addc_u32 s11, s7, -1
	s_and_b64 s[6:7], s[10:11], s[6:7]
	v_readlane_b32 s52, v138, s45
	s_waitcnt lgkmcnt(0)
	v_readlane_b32 s50, v111, s45
	s_mov_b64 s[10:11], 0

; #define AS1 __attribute__((address_space(1)))
; DI void peer_v_group(const Params& p, int gw, int nw, int g, const float* wlw  ) {
;     ...
;         for (int k = 0; k < 8; ++k) {
;           we[k] = 0.f;
;           v[k] = (u32x4){0u, 0u, 0u, 0u};
;           if ((m0 | m1) != 0ull) {
;             int l, id;
;             if (m0 != 0ull) {
;               l = __builtin_ctzll(m0); m0 &= m0 - 1ull;
;               id = __builtin_amdgcn_readlane(e0[ts], l);
;               we[k] = __int_as_float(__builtin_amdgcn_readlane(__float_as_int(w0[ts]), l));
;             } else {
;               l = __builtin_ctzll(m1); m1 &= m1 - 1ull;
;               id = __builtin_amdgcn_readlane(e1[ts], l);
;               we[k] = __int_as_float(__builtin_amdgcn_readlane(__float_as_int(w1[ts]), l));
;             }
;             v[k] = *(const u32x4 AS1*)(EV8 + (size_t)id * 1024 + lane * 16);
;           }
.Lvb2_1502:
	s_cmp_eq_u64 s[10:11], 0
	s_cbranch_scc1 .Lvb2_1519
	s_add_u32 s52, s10, -1
	s_ff1_i32_b64 s45, s[10:11]
	s_addc_u32 s53, s11, -1
	s_and_b64 s[10:11], s[52:53], s[10:11]
	v_readlane_b32 s54, v51, s45
	s_waitcnt lgkmcnt(0)
	v_readlane_b32 s52, v110, s45
	s_cbranch_execnz .Lvb2_1505
.Lvb2_1504:
	s_add_u32 s10, s6, -1
	s_ff1_i32_b64 s45, s[6:7]
	s_addc_u32 s11, s7, -1
	s_and_b64 s[6:7], s[10:11], s[6:7]
	v_readlane_b32 s54, v138, s45
	s_waitcnt lgkmcnt(0)
	v_readlane_b32 s52, v111, s45
	s_mov_b64 s[10:11], 0

; #define AS1 __attribute__((address_space(1)))
; DI void peer_v_group(const Params& p, int gw, int nw, int g, const float* wlw  ) {
;     ...
;         for (int k = 0; k < 8; ++k) {
;           we[k] = 0.f;
;           v[k] = (u32x4){0u, 0u, 0u, 0u};
;           if ((m0 | m1) != 0ull) {
;             int l, id;
;             if (m0 != 0ull) {
;               l = __builtin_ctzll(m0); m0 &= m0 - 1ull;
;               id = __builtin_amdgcn_readlane(e0[ts], l);
;               we[k] = __int_as_float(__builtin_amdgcn_readlane(__float_as_int(w0[ts]), l));
;             } else {
;               l = __builtin_ctzll(m1); m1 &= m1 - 1ull;
;               id = __builtin_amdgcn_readlane(e1[ts], l);
;               we[k] = __int_as_float(__builtin_amdgcn_readlane(__float_as_int(w1[ts]), l));
;             }
;             v[k] = *(const u32x4 AS1*)(EV8 + (size_t)id * 1024 + lane * 16);
;           }
.Lvb2_1506:
	s_cmp_eq_u64 s[10:11], 0
	s_cbranch_scc1 .Lvb2_1520
	s_add_u32 s54, s10, -1
	s_ff1_i32_b64 s45, s[10:11]
	s_addc_u32 s55, s11, -1
	s_and_b64 s[10:11], s[54:55], s[10:11]
	v_readlane_b32 s56, v51, s45
	s_waitcnt lgkmcnt(0)
	v_readlane_b32 s54, v110, s45
	s_cbranch_execnz .Lvb2_1509
.Lvb2_1508:
	s_add_u32 s10, s6, -1
	s_ff1_i32_b64 s45, s[6:7]
	s_addc_u32 s11, s7, -1
	s_and_b64 s[6:7], s[10:11], s[6:7]
	v_readlane_b32 s56, v138, s45
	s_waitcnt lgkmcnt(0)
	v_readlane_b32 s54, v111, s45
	s_mov_b64 s[10:11], 0

; #define AS1 __attribute__((address_space(1)))
; DI void peer_v_group(const Params& p, int gw, int nw, int g, const float* wlw  ) {
;     ...
;         for (int k = 0; k < 8; ++k) {
;           we[k] = 0.f;
;           v[k] = (u32x4){0u, 0u, 0u, 0u};
;           if ((m0 | m1) != 0ull) {
;             int l, id;
;             if (m0 != 0ull) {
;               l = __builtin_ctzll(m0); m0 &= m0 - 1ull;
;               id = __builtin_amdgcn_readlane(e0[ts], l);
;               we[k] = __int_as_float(__builtin_amdgcn_readlane(__float_as_int(w0[ts]), l));
;             } else {
;               l = __builtin_ctzll(m1); m1 &= m1 - 1ull;
;               id = __builtin_amdgcn_readlane(e1[ts], l);
;               we[k] = __int_as_float(__builtin_amdgcn_readlane(__float_as_int(w1[ts]), l));
;             }
;             v[k] = *(const u32x4 AS1*)(EV8 + (size_t)id * 1024 + lane * 16);
;           }
.Lvb2_1510:
	s_cmp_eq_u64 s[10:11], 0
	s_cbranch_scc1 .Lvb2_1521
	s_add_u32 s56, s10, -1
	s_ff1_i32_b64 s45, s[10:11]
	s_addc_u32 s57, s11, -1
	s_and_b64 s[10:11], s[56:57], s[10:11]
	v_readlane_b32 s58, v51, s45
	s_waitcnt lgkmcnt(0)
	v_readlane_b32 s56, v110, s45
	s_cbranch_execnz .Lvb2_1513
.Lvb2_1512:
	s_add_u32 s10, s6, -1
	s_ff1_i32_b64 s45, s[6:7]
	s_addc_u32 s11, s7, -1
	s_and_b64 s[6:7], s[10:11], s[6:7]
	v_readlane_b32 s58, v138, s45
	s_waitcnt lgkmcnt(0)
	v_readlane_b32 s56, v111, s45
	s_mov_b64 s[10:11], 0

; DI void axpy16_fp8(float* o, float w, u32x4 u) {
;   const unsigned d[4] = {u[0], u[1], u[2], u[3]};
; #pragma unroll
;   for (int i = 0; i < 4; ++i) {
;     f32x2 a = __builtin_amdgcn_cvt_pk_f32_fp8((int)d[i], false);
;     f32x2 b = __builtin_amdgcn_cvt_pk_f32_fp8((int)d[i], true);
;     o[4 * i] += w * a[0]; o[4 * i + 1] += w * a[1]; o[4 * i + 2] += w * b[0]; o[4 * i + 3] += w * b[1];
;   }
; }
; DI void peer_v_group(const Params& p, int gw, int nw, int g, const float* wlw  ) {
;     ...
; #pragma unroll
;         for (int k = 0; k < 8; ++k) axpy16_fp8(out[ts], we[k], v[k]);
.LBB0_1523:
	s_waitcnt vmcnt(0)
	v_cvt_pk_f32_fp8_e32 v[148:149], v4
	v_cvt_pk_f32_fp8_sdwa v[150:151], v4 src0_sel:WORD_1
	v_cvt_pk_f32_fp8_e32 v[152:153], v5
	v_cvt_pk_f32_fp8_sdwa v[4:5], v5 src0_sel:WORD_1
	v_pk_fma_f32 v[52:53], s[12:13], v[148:149], v[52:53] op_sel_hi:[0,1,1]
	v_pk_fma_f32 v[54:55], s[12:13], v[150:151], v[54:55] op_sel_hi:[0,1,1]
	v_cvt_pk_f32_fp8_sdwa v[148:149], v6 src0_sel:WORD_1
	v_pk_fma_f32 v[4:5], s[12:13], v[4:5], v[58:59] op_sel_hi:[0,1,1]
	v_cvt_pk_f32_fp8_e32 v[58:59], v6
	v_cvt_pk_f32_fp8_e32 v[150:151], v7
	v_cvt_pk_f32_fp8_sdwa v[6:7], v7 src0_sel:WORD_1
	v_pk_fma_f32 v[62:63], s[12:13], v[148:149], v[62:63] op_sel_hi:[0,1,1]
	v_pk_fma_f32 v[60:61], s[12:13], v[58:59], v[60:61] op_sel_hi:[0,1,1]
	v_cvt_pk_f32_fp8_e32 v[58:59], v8
	v_pk_fma_f32 v[6:7], s[12:13], v[6:7], v[66:67] op_sel_hi:[0,1,1]
	v_cvt_pk_f32_fp8_sdwa v[66:67], v8 src0_sel:WORD_1
	v_cvt_pk_f32_fp8_e32 v[148:149], v9
	v_cvt_pk_f32_fp8_sdwa v[8:9], v9 src0_sel:WORD_1
	v_cvt_pk_f32_fp8_e32 v[156:157], v12
	v_cvt_pk_f32_fp8_sdwa v[158:159], v12 src0_sel:WORD_1
	v_cvt_pk_f32_fp8_e32 v[160:161], v13
	v_cvt_pk_f32_fp8_sdwa v[12:13], v13 src0_sel:WORD_1
	v_cvt_pk_f32_fp8_e32 v[170:171], v16
	v_cvt_pk_f32_fp8_sdwa v[172:173], v16 src0_sel:WORD_1
	v_cvt_pk_f32_fp8_e32 v[174:175], v17
	v_cvt_pk_f32_fp8_sdwa v[16:17], v17 src0_sel:WORD_1
	v_pk_fma_f32 v[56:57], s[12:13], v[152:153], v[56:57] op_sel_hi:[0,1,1]
	v_cvt_pk_f32_fp8_e32 v[182:183], v20
	v_cvt_pk_f32_fp8_sdwa v[184:185], v20 src0_sel:WORD_1
	v_cvt_pk_f32_fp8_e32 v[186:187], v21
	v_cvt_pk_f32_fp8_sdwa v[20:21], v21 src0_sel:WORD_1
	v_pk_fma_f32 v[64:65], s[12:13], v[150:151], v[64:65] op_sel_hi:[0,1,1]
	v_cvt_pk_f32_fp8_e32 v[150:151], v10
	v_cvt_pk_f32_fp8_e32 v[194:195], v24
	v_cvt_pk_f32_fp8_sdwa v[196:197], v24 src0_sel:WORD_1
	v_cvt_pk_f32_fp8_e32 v[198:199], v25
	v_cvt_pk_f32_fp8_sdwa v[24:25], v25 src0_sel:WORD_1
	v_pk_fma_f32 v[56:57], s[14:15], v[148:149], v[56:57] op_sel_hi:[0,1,1]
	v_pk_fma_f32 v[4:5], s[14:15], v[8:9], v[4:5] op_sel_hi:[0,1,1]
	v_cvt_pk_f32_fp8_e32 v[164:165], v14
	v_cvt_pk_f32_fp8_e32 v[206:207], v28
	v_cvt_pk_f32_fp8_sdwa v[208:209], v28 src0_sel:WORD_1
	v_cvt_pk_f32_fp8_e32 v[210:211], v29
	v_cvt_pk_f32_fp8_sdwa v[28:29], v29 src0_sel:WORD_1
	v_pk_fma_f32 v[56:57], s[16:17], v[160:161], v[56:57] op_sel_hi:[0,1,1]
	v_pk_fma_f32 v[4:5], s[16:17], v[12:13], v[4:5] op_sel_hi:[0,1,1]
	v_cvt_pk_f32_fp8_e32 v[176:177], v18
	v_cvt_pk_f32_fp8_e32 v[218:219], v32
	v_cvt_pk_f32_fp8_sdwa v[220:221], v32 src0_sel:WORD_1
	v_pk_fma_f32 v[52:53], s[14:15], v[58:59], v[52:53] op_sel_hi:[0,1,1]
	v_cvt_pk_f32_fp8_e32 v[58:59], v33
	v_cvt_pk_f32_fp8_sdwa v[32:33], v33 src0_sel:WORD_1
	v_pk_fma_f32 v[56:57], s[18:19], v[174:175], v[56:57] op_sel_hi:[0,1,1]
	v_pk_fma_f32 v[4:5], s[18:19], v[16:17], v[4:5] op_sel_hi:[0,1,1]
	v_cvt_pk_f32_fp8_e32 v[188:189], v22
	v_pk_fma_f32 v[56:57], s[20:21], v[186:187], v[56:57] op_sel_hi:[0,1,1]
	v_pk_fma_f32 v[4:5], s[20:21], v[20:21], v[4:5] op_sel_hi:[0,1,1]
	v_cvt_pk_f32_fp8_e32 v[200:201], v26
	v_pk_fma_f32 v[56:57], s[22:23], v[198:199], v[56:57] op_sel_hi:[0,1,1]
	v_pk_fma_f32 v[4:5], s[22:23], v[24:25], v[4:5] op_sel_hi:[0,1,1]
	v_pk_fma_f32 v[12:13], s[14:15], v[150:151], v[60:61] op_sel_hi:[0,1,1]
	v_cvt_pk_f32_fp8_e32 v[212:213], v30
	v_pk_fma_f32 v[56:57], s[24:25], v[210:211], v[56:57] op_sel_hi:[0,1,1]
	v_pk_fma_f32 v[4:5], s[24:25], v[28:29], v[4:5] op_sel_hi:[0,1,1]
	v_pk_fma_f32 v[12:13], s[16:17], v[164:165], v[12:13] op_sel_hi:[0,1,1]
	v_cvt_pk_f32_fp8_sdwa v[152:153], v10 src0_sel:WORD_1
	v_pk_fma_f32 v[56:57], s[26:27], v[58:59], v[56:57] op_sel_hi:[0,1,1]
	v_pk_fma_f32 v[58:59], s[26:27], v[32:33], v[4:5] op_sel_hi:[0,1,1]
	v_cvt_pk_f32_fp8_e32 v[4:5], v34
	v_pk_fma_f32 v[12:13], s[18:19], v[176:177], v[12:13] op_sel_hi:[0,1,1]
	v_cvt_pk_f32_fp8_sdwa v[166:167], v14 src0_sel:WORD_1
	v_pk_fma_f32 v[12:13], s[20:21], v[188:189], v[12:13] op_sel_hi:[0,1,1]
	v_cvt_pk_f32_fp8_sdwa v[178:179], v18 src0_sel:WORD_1
	v_pk_fma_f32 v[12:13], s[22:23], v[200:201], v[12:13] op_sel_hi:[0,1,1]
	v_cvt_pk_f32_fp8_sdwa v[190:191], v22 src0_sel:WORD_1
	v_pk_fma_f32 v[12:13], s[24:25], v[212:213], v[12:13] op_sel_hi:[0,1,1]
	v_cvt_pk_f32_fp8_e32 v[154:155], v11
	v_cvt_pk_f32_fp8_sdwa v[202:203], v26 src0_sel:WORD_1
	v_pk_fma_f32 v[60:61], s[26:27], v[4:5], v[12:13] op_sel_hi:[0,1,1]
	v_pk_fma_f32 v[4:5], s[14:15], v[152:153], v[62:63] op_sel_hi:[0,1,1]
	v_cvt_pk_f32_fp8_e32 v[168:169], v15
	v_cvt_pk_f32_fp8_sdwa v[214:215], v30 src0_sel:WORD_1
	v_pk_fma_f32 v[4:5], s[16:17], v[166:167], v[4:5] op_sel_hi:[0,1,1]
	v_cvt_pk_f32_fp8_e32 v[180:181], v19
	v_cvt_pk_f32_fp8_sdwa v[8:9], v34 src0_sel:WORD_1
	v_pk_fma_f32 v[4:5], s[18:19], v[178:179], v[4:5] op_sel_hi:[0,1,1]
	v_cvt_pk_f32_fp8_e32 v[192:193], v23
	v_pk_fma_f32 v[4:5], s[20:21], v[190:191], v[4:5] op_sel_hi:[0,1,1]
	v_cvt_pk_f32_fp8_e32 v[204:205], v27
	v_pk_fma_f32 v[4:5], s[22:23], v[202:203], v[4:5] op_sel_hi:[0,1,1]
	v_pk_fma_f32 v[12:13], s[14:15], v[154:155], v[64:65] op_sel_hi:[0,1,1]
	v_cvt_pk_f32_fp8_e32 v[216:217], v31
	v_pk_fma_f32 v[4:5], s[24:25], v[214:215], v[4:5] op_sel_hi:[0,1,1]
	v_pk_fma_f32 v[12:13], s[16:17], v[168:169], v[12:13] op_sel_hi:[0,1,1]
	v_cvt_pk_f32_fp8_sdwa v[10:11], v11 src0_sel:WORD_1
	v_pk_fma_f32 v[62:63], s[26:27], v[8:9], v[4:5] op_sel_hi:[0,1,1]
	v_cvt_pk_f32_fp8_e32 v[4:5], v35
	v_pk_fma_f32 v[12:13], s[18:19], v[180:181], v[12:13] op_sel_hi:[0,1,1]
	v_cvt_pk_f32_fp8_sdwa v[14:15], v15 src0_sel:WORD_1
	v_pk_fma_f32 v[12:13], s[20:21], v[192:193], v[12:13] op_sel_hi:[0,1,1]
	v_cvt_pk_f32_fp8_sdwa v[18:19], v19 src0_sel:WORD_1
; DI void axpy16_fp8(float* o, float w, u32x4 u) {
;   const unsigned d[4] = {u[0], u[1], u[2], u[3]};
; #pragma unroll
;   for (int i = 0; i < 4; ++i) {
;     f32x2 a = __builtin_amdgcn_cvt_pk_f32_fp8((int)d[i], false);
;     f32x2 b = __builtin_amdgcn_cvt_pk_f32_fp8((int)d[i], true);
;     o[4 * i] += w * a[0]; o[4 * i + 1] += w * a[1]; o[4 * i + 2] += w * b[0]; o[4 * i + 3] += w * b[1];
;   }
; }
; DI void peer_v_group(const Params& p, int gw, int nw, int g, const float* wlw  ) {
;     ...
; #pragma unroll
;         for (int k = 0; k < 8; ++k) axpy16_fp8(out[ts], we[k], v[k]);
	v_pk_fma_f32 v[12:13], s[22:23], v[204:205], v[12:13] op_sel_hi:[0,1,1]
	v_cvt_pk_f32_fp8_sdwa v[22:23], v23 src0_sel:WORD_1
	v_pk_fma_f32 v[12:13], s[24:25], v[216:217], v[12:13] op_sel_hi:[0,1,1]
	v_cvt_pk_f32_fp8_sdwa v[26:27], v27 src0_sel:WORD_1
	v_pk_fma_f32 v[54:55], s[14:15], v[66:67], v[54:55] op_sel_hi:[0,1,1]
	v_pk_fma_f32 v[64:65], s[26:27], v[4:5], v[12:13] op_sel_hi:[0,1,1]
	v_pk_fma_f32 v[4:5], s[14:15], v[10:11], v[6:7] op_sel_hi:[0,1,1]
	v_cvt_pk_f32_fp8_sdwa v[30:31], v31 src0_sel:WORD_1
	v_pk_fma_f32 v[52:53], s[16:17], v[156:157], v[52:53] op_sel_hi:[0,1,1]
	v_pk_fma_f32 v[54:55], s[16:17], v[158:159], v[54:55] op_sel_hi:[0,1,1]
	v_pk_fma_f32 v[4:5], s[16:17], v[14:15], v[4:5] op_sel_hi:[0,1,1]
	v_pk_fma_f32 v[52:53], s[18:19], v[170:171], v[52:53] op_sel_hi:[0,1,1]
	v_pk_fma_f32 v[54:55], s[18:19], v[172:173], v[54:55] op_sel_hi:[0,1,1]
	v_cvt_pk_f32_fp8_sdwa v[8:9], v35 src0_sel:WORD_1
	v_pk_fma_f32 v[4:5], s[18:19], v[18:19], v[4:5] op_sel_hi:[0,1,1]
	v_pk_fma_f32 v[52:53], s[20:21], v[182:183], v[52:53] op_sel_hi:[0,1,1]
	v_pk_fma_f32 v[54:55], s[20:21], v[184:185], v[54:55] op_sel_hi:[0,1,1]
	v_pk_fma_f32 v[4:5], s[20:21], v[22:23], v[4:5] op_sel_hi:[0,1,1]
	v_pk_fma_f32 v[52:53], s[22:23], v[194:195], v[52:53] op_sel_hi:[0,1,1]
	v_pk_fma_f32 v[54:55], s[22:23], v[196:197], v[54:55] op_sel_hi:[0,1,1]
	v_pk_fma_f32 v[4:5], s[22:23], v[26:27], v[4:5] op_sel_hi:[0,1,1]
	v_pk_fma_f32 v[52:53], s[24:25], v[206:207], v[52:53] op_sel_hi:[0,1,1]
	v_pk_fma_f32 v[54:55], s[24:25], v[208:209], v[54:55] op_sel_hi:[0,1,1]
	v_pk_fma_f32 v[4:5], s[24:25], v[30:31], v[4:5] op_sel_hi:[0,1,1]
	s_or_b64 s[14:15], s[10:11], s[6:7]
	v_pk_fma_f32 v[52:53], s[26:27], v[218:219], v[52:53] op_sel_hi:[0,1,1]
	v_pk_fma_f32 v[54:55], s[26:27], v[220:221], v[54:55] op_sel_hi:[0,1,1]
	s_cmp_lg_u64 s[14:15], 0
	v_pk_fma_f32 v[66:67], s[26:27], v[8:9], v[4:5] op_sel_hi:[0,1,1]
	s_cmp_eq_u64 s[60:61], 0
	s_cbranch_scc1 .Lvb_skip3
	v_cvt_pk_f32_fp8_e32 v[148:149], v222
	v_cvt_pk_f32_fp8_sdwa v[150:151], v222 src0_sel:WORD_1
	v_cvt_pk_f32_fp8_e32 v[152:153], v223
	v_cvt_pk_f32_fp8_sdwa v[222:223], v223 src0_sel:WORD_1
	v_pk_fma_f32 v[52:53], s[42:43], v[148:149], v[52:53] op_sel_hi:[0,1,1]
	v_pk_fma_f32 v[54:55], s[42:43], v[150:151], v[54:55] op_sel_hi:[0,1,1]
	v_cvt_pk_f32_fp8_sdwa v[148:149], v224 src0_sel:WORD_1
	v_pk_fma_f32 v[222:223], s[42:43], v[222:223], v[58:59] op_sel_hi:[0,1,1]
	v_cvt_pk_f32_fp8_e32 v[58:59], v224
	v_cvt_pk_f32_fp8_e32 v[150:151], v225
	v_cvt_pk_f32_fp8_sdwa v[224:225], v225 src0_sel:WORD_1
	v_pk_fma_f32 v[62:63], s[42:43], v[148:149], v[62:63] op_sel_hi:[0,1,1]
	v_pk_fma_f32 v[60:61], s[42:43], v[58:59], v[60:61] op_sel_hi:[0,1,1]
	v_cvt_pk_f32_fp8_e32 v[58:59], v226
	v_pk_fma_f32 v[224:225], s[42:43], v[224:225], v[66:67] op_sel_hi:[0,1,1]
	v_cvt_pk_f32_fp8_sdwa v[66:67], v226 src0_sel:WORD_1
	v_cvt_pk_f32_fp8_e32 v[148:149], v227
	v_cvt_pk_f32_fp8_sdwa v[226:227], v227 src0_sel:WORD_1
	v_cvt_pk_f32_fp8_e32 v[156:157], v230
	v_cvt_pk_f32_fp8_sdwa v[158:159], v230 src0_sel:WORD_1
	v_cvt_pk_f32_fp8_e32 v[160:161], v231
	v_cvt_pk_f32_fp8_sdwa v[230:231], v231 src0_sel:WORD_1
	v_cvt_pk_f32_fp8_e32 v[170:171], v234
	v_cvt_pk_f32_fp8_sdwa v[172:173], v234 src0_sel:WORD_1
	v_cvt_pk_f32_fp8_e32 v[174:175], v235
	v_cvt_pk_f32_fp8_sdwa v[234:235], v235 src0_sel:WORD_1
	v_pk_fma_f32 v[56:57], s[42:43], v[152:153], v[56:57] op_sel_hi:[0,1,1]
	v_cvt_pk_f32_fp8_e32 v[182:183], v238
	v_cvt_pk_f32_fp8_sdwa v[184:185], v238 src0_sel:WORD_1
	v_cvt_pk_f32_fp8_e32 v[186:187], v239
	v_cvt_pk_f32_fp8_sdwa v[238:239], v239 src0_sel:WORD_1
	v_pk_fma_f32 v[64:65], s[42:43], v[150:151], v[64:65] op_sel_hi:[0,1,1]
	v_cvt_pk_f32_fp8_e32 v[150:151], v228
	v_cvt_pk_f32_fp8_e32 v[194:195], v242
	v_cvt_pk_f32_fp8_sdwa v[196:197], v242 src0_sel:WORD_1
	v_cvt_pk_f32_fp8_e32 v[198:199], v243
	v_cvt_pk_f32_fp8_sdwa v[242:243], v243 src0_sel:WORD_1
	v_pk_fma_f32 v[56:57], s[44:45], v[148:149], v[56:57] op_sel_hi:[0,1,1]
	v_pk_fma_f32 v[222:223], s[44:45], v[226:227], v[222:223] op_sel_hi:[0,1,1]
	v_cvt_pk_f32_fp8_e32 v[164:165], v232
	v_cvt_pk_f32_fp8_e32 v[206:207], v246
	v_cvt_pk_f32_fp8_sdwa v[208:209], v246 src0_sel:WORD_1
	v_cvt_pk_f32_fp8_e32 v[210:211], v247
	v_cvt_pk_f32_fp8_sdwa v[246:247], v247 src0_sel:WORD_1
	v_pk_fma_f32 v[56:57], s[46:47], v[160:161], v[56:57] op_sel_hi:[0,1,1]
	v_pk_fma_f32 v[222:223], s[46:47], v[230:231], v[222:223] op_sel_hi:[0,1,1]
	v_cvt_pk_f32_fp8_e32 v[176:177], v236
	v_cvt_pk_f32_fp8_e32 v[218:219], v250
	v_cvt_pk_f32_fp8_sdwa v[220:221], v250 src0_sel:WORD_1
	v_pk_fma_f32 v[52:53], s[44:45], v[58:59], v[52:53] op_sel_hi:[0,1,1]
	v_cvt_pk_f32_fp8_e32 v[58:59], v251
	v_cvt_pk_f32_fp8_sdwa v[250:251], v251 src0_sel:WORD_1
	v_pk_fma_f32 v[56:57], s[48:49], v[174:175], v[56:57] op_sel_hi:[0,1,1]
	v_pk_fma_f32 v[222:223], s[48:49], v[234:235], v[222:223] op_sel_hi:[0,1,1]
; DI void axpy16_fp8(float* o, float w, u32x4 u) {
;   const unsigned d[4] = {u[0], u[1], u[2], u[3]};
; #pragma unroll
;   for (int i = 0; i < 4; ++i) {
;     f32x2 a = __builtin_amdgcn_cvt_pk_f32_fp8((int)d[i], false);
;     f32x2 b = __builtin_amdgcn_cvt_pk_f32_fp8((int)d[i], true);
;     o[4 * i] += w * a[0]; o[4 * i + 1] += w * a[1]; o[4 * i + 2] += w * b[0]; o[4 * i + 3] += w * b[1];
;   }
; }
; DI void peer_v_group(const Params& p, int gw, int nw, int g, const float* wlw  ) {
;     ...
; #pragma unroll
;         for (int k = 0; k < 8; ++k) axpy16_fp8(out[ts], we[k], v[k]);
	v_cvt_pk_f32_fp8_e32 v[188:189], v240
	v_pk_fma_f32 v[56:57], s[50:51], v[186:187], v[56:57] op_sel_hi:[0,1,1]
	v_pk_fma_f32 v[222:223], s[50:51], v[238:239], v[222:223] op_sel_hi:[0,1,1]
	v_cvt_pk_f32_fp8_e32 v[200:201], v244
	v_pk_fma_f32 v[56:57], s[52:53], v[198:199], v[56:57] op_sel_hi:[0,1,1]
	v_pk_fma_f32 v[222:223], s[52:53], v[242:243], v[222:223] op_sel_hi:[0,1,1]
	v_pk_fma_f32 v[230:231], s[44:45], v[150:151], v[60:61] op_sel_hi:[0,1,1]
	v_cvt_pk_f32_fp8_e32 v[212:213], v248
	v_pk_fma_f32 v[56:57], s[54:55], v[210:211], v[56:57] op_sel_hi:[0,1,1]
	v_pk_fma_f32 v[222:223], s[54:55], v[246:247], v[222:223] op_sel_hi:[0,1,1]
	v_pk_fma_f32 v[230:231], s[46:47], v[164:165], v[230:231] op_sel_hi:[0,1,1]
	v_cvt_pk_f32_fp8_sdwa v[152:153], v228 src0_sel:WORD_1
	v_pk_fma_f32 v[56:57], s[56:57], v[58:59], v[56:57] op_sel_hi:[0,1,1]
	v_pk_fma_f32 v[58:59], s[56:57], v[250:251], v[222:223] op_sel_hi:[0,1,1]
	v_cvt_pk_f32_fp8_e32 v[222:223], v252
	v_pk_fma_f32 v[230:231], s[48:49], v[176:177], v[230:231] op_sel_hi:[0,1,1]
	v_cvt_pk_f32_fp8_sdwa v[166:167], v232 src0_sel:WORD_1
	v_pk_fma_f32 v[230:231], s[50:51], v[188:189], v[230:231] op_sel_hi:[0,1,1]
	v_cvt_pk_f32_fp8_sdwa v[178:179], v236 src0_sel:WORD_1
	v_pk_fma_f32 v[230:231], s[52:53], v[200:201], v[230:231] op_sel_hi:[0,1,1]
	v_cvt_pk_f32_fp8_sdwa v[190:191], v240 src0_sel:WORD_1
	v_pk_fma_f32 v[230:231], s[54:55], v[212:213], v[230:231] op_sel_hi:[0,1,1]
	v_cvt_pk_f32_fp8_e32 v[154:155], v229
	v_cvt_pk_f32_fp8_sdwa v[202:203], v244 src0_sel:WORD_1
	v_pk_fma_f32 v[60:61], s[56:57], v[222:223], v[230:231] op_sel_hi:[0,1,1]
	v_pk_fma_f32 v[222:223], s[44:45], v[152:153], v[62:63] op_sel_hi:[0,1,1]
	v_cvt_pk_f32_fp8_e32 v[168:169], v233
	v_cvt_pk_f32_fp8_sdwa v[214:215], v248 src0_sel:WORD_1
	v_pk_fma_f32 v[222:223], s[46:47], v[166:167], v[222:223] op_sel_hi:[0,1,1]
	v_cvt_pk_f32_fp8_e32 v[180:181], v237
	v_cvt_pk_f32_fp8_sdwa v[226:227], v252 src0_sel:WORD_1
	v_pk_fma_f32 v[222:223], s[48:49], v[178:179], v[222:223] op_sel_hi:[0,1,1]
	v_cvt_pk_f32_fp8_e32 v[192:193], v241
	v_pk_fma_f32 v[222:223], s[50:51], v[190:191], v[222:223] op_sel_hi:[0,1,1]
	v_cvt_pk_f32_fp8_e32 v[204:205], v245
	v_pk_fma_f32 v[222:223], s[52:53], v[202:203], v[222:223] op_sel_hi:[0,1,1]
	v_pk_fma_f32 v[230:231], s[44:45], v[154:155], v[64:65] op_sel_hi:[0,1,1]
	v_cvt_pk_f32_fp8_e32 v[216:217], v249
	v_pk_fma_f32 v[222:223], s[54:55], v[214:215], v[222:223] op_sel_hi:[0,1,1]
	v_pk_fma_f32 v[230:231], s[46:47], v[168:169], v[230:231] op_sel_hi:[0,1,1]
	v_cvt_pk_f32_fp8_sdwa v[228:229], v229 src0_sel:WORD_1
	v_pk_fma_f32 v[62:63], s[56:57], v[226:227], v[222:223] op_sel_hi:[0,1,1]
	v_cvt_pk_f32_fp8_e32 v[222:223], v253
	v_pk_fma_f32 v[230:231], s[48:49], v[180:181], v[230:231] op_sel_hi:[0,1,1]
	v_cvt_pk_f32_fp8_sdwa v[232:233], v233 src0_sel:WORD_1
	v_pk_fma_f32 v[230:231], s[50:51], v[192:193], v[230:231] op_sel_hi:[0,1,1]
	v_cvt_pk_f32_fp8_sdwa v[236:237], v237 src0_sel:WORD_1
	v_pk_fma_f32 v[230:231], s[52:53], v[204:205], v[230:231] op_sel_hi:[0,1,1]
	v_cvt_pk_f32_fp8_sdwa v[240:241], v241 src0_sel:WORD_1
	v_pk_fma_f32 v[230:231], s[54:55], v[216:217], v[230:231] op_sel_hi:[0,1,1]
	v_cvt_pk_f32_fp8_sdwa v[244:245], v245 src0_sel:WORD_1
	v_pk_fma_f32 v[54:55], s[44:45], v[66:67], v[54:55] op_sel_hi:[0,1,1]
	v_pk_fma_f32 v[64:65], s[56:57], v[222:223], v[230:231] op_sel_hi:[0,1,1]
	v_pk_fma_f32 v[222:223], s[44:45], v[228:229], v[224:225] op_sel_hi:[0,1,1]
	v_cvt_pk_f32_fp8_sdwa v[248:249], v249 src0_sel:WORD_1
	v_pk_fma_f32 v[52:53], s[46:47], v[156:157], v[52:53] op_sel_hi:[0,1,1]
	v_pk_fma_f32 v[54:55], s[46:47], v[158:159], v[54:55] op_sel_hi:[0,1,1]
	v_pk_fma_f32 v[222:223], s[46:47], v[232:233], v[222:223] op_sel_hi:[0,1,1]
	v_pk_fma_f32 v[52:53], s[48:49], v[170:171], v[52:53] op_sel_hi:[0,1,1]
	v_pk_fma_f32 v[54:55], s[48:49], v[172:173], v[54:55] op_sel_hi:[0,1,1]
	v_cvt_pk_f32_fp8_sdwa v[226:227], v253 src0_sel:WORD_1
	v_pk_fma_f32 v[222:223], s[48:49], v[236:237], v[222:223] op_sel_hi:[0,1,1]
	v_pk_fma_f32 v[52:53], s[50:51], v[182:183], v[52:53] op_sel_hi:[0,1,1]
	v_pk_fma_f32 v[54:55], s[50:51], v[184:185], v[54:55] op_sel_hi:[0,1,1]
	v_pk_fma_f32 v[222:223], s[50:51], v[240:241], v[222:223] op_sel_hi:[0,1,1]
	v_pk_fma_f32 v[52:53], s[52:53], v[194:195], v[52:53] op_sel_hi:[0,1,1]
	v_pk_fma_f32 v[54:55], s[52:53], v[196:197], v[54:55] op_sel_hi:[0,1,1]
	v_pk_fma_f32 v[222:223], s[52:53], v[244:245], v[222:223] op_sel_hi:[0,1,1]
	v_pk_fma_f32 v[52:53], s[54:55], v[206:207], v[52:53] op_sel_hi:[0,1,1]
	v_pk_fma_f32 v[54:55], s[54:55], v[208:209], v[54:55] op_sel_hi:[0,1,1]
	v_pk_fma_f32 v[222:223], s[54:55], v[248:249], v[222:223] op_sel_hi:[0,1,1]
	v_pk_fma_f32 v[52:53], s[56:57], v[218:219], v[52:53] op_sel_hi:[0,1,1]
	v_pk_fma_f32 v[54:55], s[56:57], v[220:221], v[54:55] op_sel_hi:[0,1,1]
	v_pk_fma_f32 v[66:67], s[56:57], v[226:227], v[222:223] op_sel_hi:[0,1,1]

; #define AS1 __attribute__((address_space(1)))
; DI void peer_v_group(const Params& p, int gw, int nw, int g, const float* wlw  ) {
;     ...
;       while ((m0 | m1) != 0ull) {
;         u32x4 v[8];
;         float we[8];
; #pragma unroll
;         for (int k = 0; k < 8; ++k) {
;           we[k] = 0.f;
;           v[k] = (u32x4){0u, 0u, 0u, 0u};
;           if ((m0 | m1) != 0ull) {
;             int l, id;
;             if (m0 != 0ull) {
;               l = __builtin_ctzll(m0); m0 &= m0 - 1ull;
;               id = __builtin_amdgcn_readlane(e0[ts], l);
;               we[k] = __int_as_float(__builtin_amdgcn_readlane(__float_as_int(w0[ts]), l));
;             } else {
;               l = __builtin_ctzll(m1); m1 &= m1 - 1ull;
;               id = __builtin_amdgcn_readlane(e1[ts], l);
;               we[k] = __int_as_float(__builtin_amdgcn_readlane(__float_as_int(w1[ts]), l));
;             }
;             v[k] = *(const u32x4 AS1*)(EV8 + (size_t)id * 1024 + lane * 16);
;           }
.Lvb_g3:
	s_or_b64 s[60:61], s[6:7], s[10:11]
	s_or_b64 s[44:45], s[6:7], s[10:11]
	s_cmp_eq_u64 s[44:45], 0
	s_cbranch_scc1 .Lvb3_1538
	s_cmp_eq_u64 s[10:11], 0
	s_cbranch_scc1 .Lvb3_1564
	s_add_u32 s44, s10, -1
	s_ff1_i32_b64 s42, s[10:11]
	s_addc_u32 s45, s11, -1
	s_and_b64 s[10:11], s[44:45], s[10:11]
	v_readlane_b32 s44, v49, s42
	s_waitcnt lgkmcnt(0)
	v_readlane_b32 s42, v108, s42
	s_cbranch_execnz .Lvb3_1528
.Lvb3_1527:
	s_add_u32 s10, s6, -1
	s_ff1_i32_b64 s42, s[6:7]
	s_addc_u32 s11, s7, -1
	s_and_b64 s[6:7], s[10:11], s[6:7]
	v_readlane_b32 s44, v139, s42
	s_waitcnt lgkmcnt(0)
	v_readlane_b32 s42, v109, s42
	s_mov_b64 s[10:11], 0

; #define AS1 __attribute__((address_space(1)))
; DI void peer_v_group(const Params& p, int gw, int nw, int g, const float* wlw  ) {
;     ...
;         for (int k = 0; k < 8; ++k) {
;           we[k] = 0.f;
;           v[k] = (u32x4){0u, 0u, 0u, 0u};
;           if ((m0 | m1) != 0ull) {
;             int l, id;
;             if (m0 != 0ull) {
;               l = __builtin_ctzll(m0); m0 &= m0 - 1ull;
;               id = __builtin_amdgcn_readlane(e0[ts], l);
;               we[k] = __int_as_float(__builtin_amdgcn_readlane(__float_as_int(w0[ts]), l));
;             } else {
;               l = __builtin_ctzll(m1); m1 &= m1 - 1ull;
;               id = __builtin_amdgcn_readlane(e1[ts], l);
;               we[k] = __int_as_float(__builtin_amdgcn_readlane(__float_as_int(w1[ts]), l));
;             }
;             v[k] = *(const u32x4 AS1*)(EV8 + (size_t)id * 1024 + lane * 16);
;           }
.Lvb3_1529:
	s_cmp_eq_u64 s[10:11], 0
	s_cbranch_scc1 .Lvb3_1565
	s_add_u32 s44, s10, -1
	s_ff1_i32_b64 s47, s[10:11]
	s_addc_u32 s45, s11, -1
	s_and_b64 s[10:11], s[44:45], s[10:11]
	v_readlane_b32 s46, v49, s47
	s_waitcnt lgkmcnt(0)
	v_readlane_b32 s44, v108, s47
	s_cbranch_execnz .Lvb3_1532
.Lvb3_1531:
	s_add_u32 s10, s6, -1
	s_ff1_i32_b64 s44, s[6:7]
	s_addc_u32 s11, s7, -1
	s_and_b64 s[6:7], s[10:11], s[6:7]
	v_readlane_b32 s46, v139, s44
	s_waitcnt lgkmcnt(0)
	v_readlane_b32 s44, v109, s44
	s_mov_b64 s[10:11], 0

; #define AS1 __attribute__((address_space(1)))
; DI void peer_v_group(const Params& p, int gw, int nw, int g, const float* wlw  ) {
;     ...
;         for (int k = 0; k < 8; ++k) {
;           we[k] = 0.f;
;           v[k] = (u32x4){0u, 0u, 0u, 0u};
;           if ((m0 | m1) != 0ull) {
;             int l, id;
;             if (m0 != 0ull) {
;               l = __builtin_ctzll(m0); m0 &= m0 - 1ull;
;               id = __builtin_amdgcn_readlane(e0[ts], l);
;               we[k] = __int_as_float(__builtin_amdgcn_readlane(__float_as_int(w0[ts]), l));
;             } else {
;               l = __builtin_ctzll(m1); m1 &= m1 - 1ull;
;               id = __builtin_amdgcn_readlane(e1[ts], l);
;               we[k] = __int_as_float(__builtin_amdgcn_readlane(__float_as_int(w1[ts]), l));
;             }
;             v[k] = *(const u32x4 AS1*)(EV8 + (size_t)id * 1024 + lane * 16);
;           }
.Lvb3_1540:
	s_cmp_eq_u64 s[10:11], 0
	s_cbranch_scc1 .Lvb3_1566
	s_add_u32 s46, s10, -1
	s_ff1_i32_b64 s45, s[10:11]
	s_addc_u32 s47, s11, -1
	s_and_b64 s[10:11], s[46:47], s[10:11]
	v_readlane_b32 s48, v49, s45
	s_waitcnt lgkmcnt(0)
	v_readlane_b32 s46, v108, s45
	s_cbranch_execnz .Lvb3_1543
.Lvb3_1542:
	s_add_u32 s10, s6, -1
	s_ff1_i32_b64 s45, s[6:7]
	s_addc_u32 s11, s7, -1
	s_and_b64 s[6:7], s[10:11], s[6:7]
	v_readlane_b32 s48, v139, s45
	s_waitcnt lgkmcnt(0)
	v_readlane_b32 s46, v109, s45
	s_mov_b64 s[10:11], 0

; #define AS1 __attribute__((address_space(1)))
; DI void peer_v_group(const Params& p, int gw, int nw, int g, const float* wlw  ) {
;     ...
;         for (int k = 0; k < 8; ++k) {
;           we[k] = 0.f;
;           v[k] = (u32x4){0u, 0u, 0u, 0u};
;           if ((m0 | m1) != 0ull) {
;             int l, id;
;             if (m0 != 0ull) {
;               l = __builtin_ctzll(m0); m0 &= m0 - 1ull;
;               id = __builtin_amdgcn_readlane(e0[ts], l);
;               we[k] = __int_as_float(__builtin_amdgcn_readlane(__float_as_int(w0[ts]), l));
;             } else {
;               l = __builtin_ctzll(m1); m1 &= m1 - 1ull;
;               id = __builtin_amdgcn_readlane(e1[ts], l);
;               we[k] = __int_as_float(__builtin_amdgcn_readlane(__float_as_int(w1[ts]), l));
;             }
;             v[k] = *(const u32x4 AS1*)(EV8 + (size_t)id * 1024 + lane * 16);
;           }
.Lvb3_1544:
	s_cmp_eq_u64 s[10:11], 0
	s_cbranch_scc1 .Lvb3_1567
	s_add_u32 s48, s10, -1
	s_ff1_i32_b64 s45, s[10:11]
	s_addc_u32 s49, s11, -1
	s_and_b64 s[10:11], s[48:49], s[10:11]
	v_readlane_b32 s50, v49, s45
	s_waitcnt lgkmcnt(0)
	v_readlane_b32 s48, v108, s45
	s_cbranch_execnz .Lvb3_1547
.Lvb3_1546:
	s_add_u32 s10, s6, -1
	s_ff1_i32_b64 s45, s[6:7]
	s_addc_u32 s11, s7, -1
	s_and_b64 s[6:7], s[10:11], s[6:7]
	v_readlane_b32 s50, v139, s45
	s_waitcnt lgkmcnt(0)
	v_readlane_b32 s48, v109, s45
	s_mov_b64 s[10:11], 0

; #define AS1 __attribute__((address_space(1)))
; DI void peer_v_group(const Params& p, int gw, int nw, int g, const float* wlw  ) {
;     ...
;         for (int k = 0; k < 8; ++k) {
;           we[k] = 0.f;
;           v[k] = (u32x4){0u, 0u, 0u, 0u};
;           if ((m0 | m1) != 0ull) {
;             int l, id;
;             if (m0 != 0ull) {
;               l = __builtin_ctzll(m0); m0 &= m0 - 1ull;
;               id = __builtin_amdgcn_readlane(e0[ts], l);
;               we[k] = __int_as_float(__builtin_amdgcn_readlane(__float_as_int(w0[ts]), l));
;             } else {
;               l = __builtin_ctzll(m1); m1 &= m1 - 1ull;
;               id = __builtin_amdgcn_readlane(e1[ts], l);
;               we[k] = __int_as_float(__builtin_amdgcn_readlane(__float_as_int(w1[ts]), l));
;             }
;             v[k] = *(const u32x4 AS1*)(EV8 + (size_t)id * 1024 + lane * 16);
;           }
.Lvb3_1548:
	s_cmp_eq_u64 s[10:11], 0
	s_cbranch_scc1 .Lvb3_1568
	s_add_u32 s50, s10, -1
	s_ff1_i32_b64 s45, s[10:11]
	s_addc_u32 s51, s11, -1
	s_and_b64 s[10:11], s[50:51], s[10:11]
	v_readlane_b32 s52, v49, s45
	s_waitcnt lgkmcnt(0)
	v_readlane_b32 s50, v108, s45
	s_cbranch_execnz .Lvb3_1551
.Lvb3_1550:
	s_add_u32 s10, s6, -1
	s_ff1_i32_b64 s45, s[6:7]
	s_addc_u32 s11, s7, -1
	s_and_b64 s[6:7], s[10:11], s[6:7]
	v_readlane_b32 s52, v139, s45
	s_waitcnt lgkmcnt(0)
	v_readlane_b32 s50, v109, s45
	s_mov_b64 s[10:11], 0

; #define AS1 __attribute__((address_space(1)))
; DI void peer_v_group(const Params& p, int gw, int nw, int g, const float* wlw  ) {
;     ...
;         for (int k = 0; k < 8; ++k) {
;           we[k] = 0.f;
;           v[k] = (u32x4){0u, 0u, 0u, 0u};
;           if ((m0 | m1) != 0ull) {
;             int l, id;
;             if (m0 != 0ull) {
;               l = __builtin_ctzll(m0); m0 &= m0 - 1ull;
;               id = __builtin_amdgcn_readlane(e0[ts], l);
;               we[k] = __int_as_float(__builtin_amdgcn_readlane(__float_as_int(w0[ts]), l));
;             } else {
;               l = __builtin_ctzll(m1); m1 &= m1 - 1ull;
;               id = __builtin_amdgcn_readlane(e1[ts], l);
;               we[k] = __int_as_float(__builtin_amdgcn_readlane(__float_as_int(w1[ts]), l));
;             }
;             v[k] = *(const u32x4 AS1*)(EV8 + (size_t)id * 1024 + lane * 16);
;           }
.Lvb3_1552:
	s_cmp_eq_u64 s[10:11], 0
	s_cbranch_scc1 .Lvb3_1569
	s_add_u32 s52, s10, -1
	s_ff1_i32_b64 s45, s[10:11]
	s_addc_u32 s53, s11, -1
	s_and_b64 s[10:11], s[52:53], s[10:11]
	v_readlane_b32 s54, v49, s45
	s_waitcnt lgkmcnt(0)
	v_readlane_b32 s52, v108, s45
	s_cbranch_execnz .Lvb3_1555
.Lvb3_1554:
	s_add_u32 s10, s6, -1
	s_ff1_i32_b64 s45, s[6:7]
	s_addc_u32 s11, s7, -1
	s_and_b64 s[6:7], s[10:11], s[6:7]
	v_readlane_b32 s54, v139, s45
	s_waitcnt lgkmcnt(0)
	v_readlane_b32 s52, v109, s45
	s_mov_b64 s[10:11], 0

; #define AS1 __attribute__((address_space(1)))
; DI void peer_v_group(const Params& p, int gw, int nw, int g, const float* wlw  ) {
;     ...
;         for (int k = 0; k < 8; ++k) {
;           we[k] = 0.f;
;           v[k] = (u32x4){0u, 0u, 0u, 0u};
;           if ((m0 | m1) != 0ull) {
;             int l, id;
;             if (m0 != 0ull) {
;               l = __builtin_ctzll(m0); m0 &= m0 - 1ull;
;               id = __builtin_amdgcn_readlane(e0[ts], l);
;               we[k] = __int_as_float(__builtin_amdgcn_readlane(__float_as_int(w0[ts]), l));
;             } else {
;               l = __builtin_ctzll(m1); m1 &= m1 - 1ull;
;               id = __builtin_amdgcn_readlane(e1[ts], l);
;               we[k] = __int_as_float(__builtin_amdgcn_readlane(__float_as_int(w1[ts]), l));
;             }
;             v[k] = *(const u32x4 AS1*)(EV8 + (size_t)id * 1024 + lane * 16);
;           }
.Lvb3_1556:
	s_cmp_eq_u64 s[10:11], 0
	s_cbranch_scc1 .Lvb3_1570
	s_add_u32 s54, s10, -1
	s_ff1_i32_b64 s45, s[10:11]
	s_addc_u32 s55, s11, -1
	s_and_b64 s[10:11], s[54:55], s[10:11]
	v_readlane_b32 s56, v49, s45
	s_waitcnt lgkmcnt(0)
	v_readlane_b32 s54, v108, s45
	s_cbranch_execnz .Lvb3_1559
.Lvb3_1558:
	s_add_u32 s10, s6, -1
	s_ff1_i32_b64 s45, s[6:7]
	s_addc_u32 s11, s7, -1
	s_and_b64 s[6:7], s[10:11], s[6:7]
	v_readlane_b32 s56, v139, s45
	s_waitcnt lgkmcnt(0)
	v_readlane_b32 s54, v109, s45
	s_mov_b64 s[10:11], 0

; #define AS1 __attribute__((address_space(1)))
; DI void peer_v_group(const Params& p, int gw, int nw, int g, const float* wlw  ) {
;     ...
;         for (int k = 0; k < 8; ++k) {
;           we[k] = 0.f;
;           v[k] = (u32x4){0u, 0u, 0u, 0u};
;           if ((m0 | m1) != 0ull) {
;             int l, id;
;             if (m0 != 0ull) {
;               l = __builtin_ctzll(m0); m0 &= m0 - 1ull;
;               id = __builtin_amdgcn_readlane(e0[ts], l);
;               we[k] = __int_as_float(__builtin_amdgcn_readlane(__float_as_int(w0[ts]), l));
;             } else {
;               l = __builtin_ctzll(m1); m1 &= m1 - 1ull;
;               id = __builtin_amdgcn_readlane(e1[ts], l);
;               we[k] = __int_as_float(__builtin_amdgcn_readlane(__float_as_int(w1[ts]), l));
;             }
;             v[k] = *(const u32x4 AS1*)(EV8 + (size_t)id * 1024 + lane * 16);
;           }
.Lvb3_1560:
	s_cmp_eq_u64 s[10:11], 0
	s_cbranch_scc1 .Lvb3_1571
	s_add_u32 s56, s10, -1
	s_ff1_i32_b64 s45, s[10:11]
	s_addc_u32 s57, s11, -1
	s_and_b64 s[10:11], s[56:57], s[10:11]
	v_readlane_b32 s58, v49, s45
	s_waitcnt lgkmcnt(0)
	v_readlane_b32 s56, v108, s45
	s_cbranch_execnz .Lvb3_1563
.Lvb3_1562:
	s_add_u32 s10, s6, -1
	s_ff1_i32_b64 s45, s[6:7]
	s_addc_u32 s11, s7, -1
	s_and_b64 s[6:7], s[10:11], s[6:7]
	v_readlane_b32 s58, v139, s45
	s_waitcnt lgkmcnt(0)
	v_readlane_b32 s56, v109, s45
	s_mov_b64 s[10:11], 0

; #define LAS __attribute__((address_space(3)))
; __global__ void __launch_bounds__(256, 2) mega(Params pk) {
;   __shared__ __attribute__((aligned(16))) char smem[65536];
;   __shared__ Params sp;
;   cg::grid_group grid = cg::this_grid();
;   const int w = threadIdx.x >> 6;
;   __shared__ uint4 xb_words;
;   if (threadIdx.x == 0) { sp = pk; xb_words = make_uint4(0u, 0u, 0u, 0u); }
;   __syncthreads();
;   const Params& p = sp;
;   XcdBarrier xb = xcd_barrier_post(p.bar, (volatile LAS unsigned*)&xb_words);
;   if (p.never) grid.sync();
	.amdhsa_kernel _Z4mega6Params
		.amdhsa_group_segment_fixed_size 66064
		.amdhsa_private_segment_fixed_size 0
		.amdhsa_kernarg_size 760
		.amdhsa_user_sgpr_count 2
		.amdhsa_user_sgpr_dispatch_ptr 0
		.amdhsa_user_sgpr_queue_ptr 0
		.amdhsa_user_sgpr_kernarg_segment_ptr 1
		.amdhsa_user_sgpr_dispatch_id 0
		.amdhsa_user_sgpr_kernarg_preload_length 0
		.amdhsa_user_sgpr_kernarg_preload_offset 0
		.amdhsa_user_sgpr_private_segment_size 0
		.amdhsa_uses_dynamic_stack 0
		.amdhsa_enable_private_segment 0
		.amdhsa_system_sgpr_workgroup_id_x 1
		.amdhsa_system_sgpr_workgroup_id_y 0
		.amdhsa_system_sgpr_workgroup_id_z 0
		.amdhsa_system_sgpr_workgroup_info 0
		.amdhsa_system_vgpr_workitem_id 2
		.amdhsa_next_free_vgpr 256
		.amdhsa_next_free_sgpr 102
		.amdhsa_accum_offset 256
		.amdhsa_reserve_vcc 1
		.amdhsa_float_round_mode_32 0
		.amdhsa_float_round_mode_16_64 0
		.amdhsa_float_denorm_mode_32 3
		.amdhsa_float_denorm_mode_16_64 3
		.amdhsa_dx10_clamp 1
		.amdhsa_ieee_mode 1
		.amdhsa_fp16_overflow 0
		.amdhsa_tg_split 0
		.amdhsa_exception_fp_ieee_invalid_op 0
		.amdhsa_exception_fp_denorm_src 0
		.amdhsa_exception_fp_ieee_div_zero 0
		.amdhsa_exception_fp_ieee_overflow 0
		.amdhsa_exception_fp_ieee_underflow 0
		.amdhsa_exception_fp_ieee_inexact 0
		.amdhsa_exception_int_div_zero 0
	.end_amdhsa_kernel

; #define LAS __attribute__((address_space(3)))
; __global__ void __launch_bounds__(256, 2) mega(Params pk) {
;   __shared__ __attribute__((aligned(16))) char smem[65536];
;   __shared__ Params sp;
;   cg::grid_group grid = cg::this_grid();
;   const int w = threadIdx.x >> 6;
;   __shared__ uint4 xb_words;
;   if (threadIdx.x == 0) { sp = pk; xb_words = make_uint4(0u, 0u, 0u, 0u); }
;   __syncthreads();
;   const Params& p = sp;
;   XcdBarrier xb = xcd_barrier_post(p.bar, (volatile LAS unsigned*)&xb_words);
;   if (p.never) grid.sync();
amdhsa.kernels:
  - .agpr_count:     0
    .args:
      - .offset:         0
        .size:           504
        .value_kind:     by_value
      - .offset:         504
        .size:           4
        .value_kind:     hidden_block_count_x
      - .offset:         508
        .size:           4
        .value_kind:     hidden_block_count_y
      - .offset:         512
        .size:           4
        .value_kind:     hidden_block_count_z
      - .offset:         516
        .size:           2
        .value_kind:     hidden_group_size_x
      - .offset:         518
        .size:           2
        .value_kind:     hidden_group_size_y
      - .offset:         520
        .size:           2
        .value_kind:     hidden_group_size_z
      - .offset:         522
        .size:           2
        .value_kind:     hidden_remainder_x
      - .offset:         524
        .size:           2
        .value_kind:     hidden_remainder_y
      - .offset:         526
        .size:           2
        .value_kind:     hidden_remainder_z
      - .offset:         544
        .size:           8
        .value_kind:     hidden_global_offset_x
      - .offset:         552
        .size:           8
        .value_kind:     hidden_global_offset_y
      - .offset:         560
        .size:           8
        .value_kind:     hidden_global_offset_z
      - .offset:         568
        .size:           2
        .value_kind:     hidden_grid_dims
      - .offset:         592
        .size:           8
        .value_kind:     hidden_multigrid_sync_arg
    .group_segment_fixed_size: 66064
    .kernarg_segment_align: 8
    .kernarg_segment_size: 760
    .language:       OpenCL C
    .language_version:
      - 2
      - 0
    .max_flat_workgroup_size: 256
    .name:           _Z4mega6Params
    .private_segment_fixed_size: 0
    .sgpr_count:     108
    .sgpr_spill_count: 56
    .symbol:         _Z4mega6Params.kd
    .uniform_work_group_size: 1
    .uses_dynamic_stack: false
    .vgpr_count:     256
    .vgpr_spill_count: 0
    .wavefront_size: 64
